# F12 (gate/up GEMM) epilogue rewritten by hand: all loads up front, two packed chains interleaved (no pk forwarding nops), exec-masked side-buffer stores without branches; same op-for-op arithmetic
# speedup vs baseline: 1.0627x; 1.0274x over previous
; __device__ void phase_mix2(const Params& P, LAS unsigned char* lds, const int G, const int bid) {
;     ...
;             for (int f = 0; f < nfold; ++f) { const int sp = dir ? nseg - 1 - f : f; const int slot = tot_slot(sg0 + sp, hd, dir);
;                 const float mseg = tots[slot * 2], aseg = tots[slot * 2 + 1];
;                 const float mnew = fmaxf(aseg + m, mseg), d0 = __expf(aseg + m - mnew), d1 = __expf(mseg - mnew);
;                 const float* tp = tot + ((size_t)slot * 512 + threadIdx.x) * 36;
; #pragma unroll
;                 for (int i = 0; i < 9; ++i) C[i] = C[i] * d0 + *(const f32x4*)(tp + 4 * i) * d1;
;                 m = mnew; }
.LBB0_77:
	s_lshl_b32 s14, s10, 1
	s_ashr_i32 s15, s14, 31
	s_lshl_b64 s[14:15], s[14:15], 2
	s_add_u32 s14, s28, s14
	s_addc_u32 s15, s96, s15
	s_waitcnt lgkmcnt(0)
	global_load_dwordx2 v[2:3], v1, s[14:15]
	s_ashr_i32 s11, s10, 31
	s_lshl_b64 s[10:11], s[10:11], 9
	v_lshl_add_u64 v[42:43], s[10:11], 0, v[162:163]
	v_mov_b64_e32 v[40:41], s[52:53]
	v_mad_u64_u32 v[40:41], s[10:11], v42, s1, v[40:41]
	v_mad_i32_i24 v41, v43, s1, v41
	global_load_dwordx4 v[42:45], v[40:41], off offset:48
	global_load_dwordx4 v[46:49], v[40:41], off offset:32
	global_load_dwordx4 v[50:53], v[40:41], off offset:16
	global_load_dwordx4 v[54:57], v[40:41], off
	s_add_i32 s18, s18, 1
	s_add_i32 s19, s19, -1
	s_cmp_eq_u32 s17, s18
	s_waitcnt vmcnt(4)
	v_add_f32_e32 v0, v160, v3
	v_max_f32_e32 v3, v2, v2
	v_max_f32_e32 v160, v0, v3
	v_sub_f32_e32 v2, v2, v160
	v_sub_f32_e32 v0, v0, v160
	v_mul_f32_e32 v2, 0x3fb8aa3b, v2
	v_mul_f32_e32 v0, 0x3fb8aa3b, v0
	v_exp_f32_e32 v2, v2
	v_exp_f32_e32 v0, v0
	s_waitcnt vmcnt(0)
	v_pk_mul_f32 v[56:57], v[56:57], v[2:3] op_sel_hi:[1,0]
	v_pk_mul_f32 v[54:55], v[54:55], v[2:3] op_sel_hi:[1,0]
	v_pk_mul_f32 v[52:53], v[52:53], v[2:3] op_sel_hi:[1,0]
	v_pk_mul_f32 v[50:51], v[50:51], v[2:3] op_sel_hi:[1,0]
	v_pk_mul_f32 v[48:49], v[48:49], v[2:3] op_sel_hi:[1,0]
	v_pk_mul_f32 v[46:47], v[46:47], v[2:3] op_sel_hi:[1,0]
	v_pk_mul_f32 v[44:45], v[44:45], v[2:3] op_sel_hi:[1,0]
	v_pk_mul_f32 v[42:43], v[42:43], v[2:3] op_sel_hi:[1,0]
	v_pk_fma_f32 v[34:35], v[34:35], v[0:1], v[56:57] op_sel_hi:[1,0,1]
	v_pk_fma_f32 v[32:33], v[32:33], v[0:1], v[54:55] op_sel_hi:[1,0,1]
	v_pk_fma_f32 v[30:31], v[30:31], v[0:1], v[52:53] op_sel_hi:[1,0,1]
	v_pk_fma_f32 v[28:29], v[28:29], v[0:1], v[50:51] op_sel_hi:[1,0,1]
	v_pk_fma_f32 v[26:27], v[26:27], v[0:1], v[48:49] op_sel_hi:[1,0,1]
	v_pk_fma_f32 v[24:25], v[24:25], v[0:1], v[46:47] op_sel_hi:[1,0,1]
	v_pk_fma_f32 v[22:23], v[22:23], v[0:1], v[44:45] op_sel_hi:[1,0,1]
	v_pk_fma_f32 v[20:21], v[20:21], v[0:1], v[42:43] op_sel_hi:[1,0,1]
	global_load_dwordx4 v[42:45], v[40:41], off offset:112
	global_load_dwordx4 v[46:49], v[40:41], off offset:96
	global_load_dwordx4 v[50:53], v[40:41], off offset:80
	global_load_dwordx4 v[54:57], v[40:41], off offset:64
	s_waitcnt vmcnt(3)
	v_pk_mul_f32 v[42:43], v[2:3], v[42:43] op_sel_hi:[0,1]
	s_nop 0
	v_pk_fma_f32 v[4:5], v[4:5], v[0:1], v[42:43] op_sel_hi:[1,0,1]
	global_load_dwordx4 v[40:43], v[40:41], off offset:128
	s_waitcnt vmcnt(1)
	v_pk_mul_f32 v[56:57], v[56:57], v[2:3] op_sel_hi:[1,0]
	v_pk_mul_f32 v[54:55], v[54:55], v[2:3] op_sel_hi:[1,0]
	v_pk_mul_f32 v[52:53], v[52:53], v[2:3] op_sel_hi:[1,0]
	v_pk_mul_f32 v[50:51], v[50:51], v[2:3] op_sel_hi:[1,0]
	v_pk_mul_f32 v[48:49], v[2:3], v[48:49] op_sel_hi:[0,1]
	v_pk_mul_f32 v[46:47], v[2:3], v[46:47] op_sel_hi:[0,1]
	v_pk_mul_f32 v[44:45], v[2:3], v[44:45] op_sel_hi:[0,1]
	v_pk_fma_f32 v[18:19], v[18:19], v[0:1], v[56:57] op_sel_hi:[1,0,1]
	v_pk_fma_f32 v[16:17], v[16:17], v[0:1], v[54:55] op_sel_hi:[1,0,1]
	v_pk_fma_f32 v[14:15], v[14:15], v[0:1], v[52:53] op_sel_hi:[1,0,1]
	v_pk_fma_f32 v[12:13], v[12:13], v[0:1], v[50:51] op_sel_hi:[1,0,1]
	v_pk_fma_f32 v[10:11], v[10:11], v[0:1], v[48:49] op_sel_hi:[1,0,1]
	v_pk_fma_f32 v[8:9], v[8:9], v[0:1], v[46:47] op_sel_hi:[1,0,1]
	v_pk_fma_f32 v[6:7], v[6:7], v[0:1], v[44:45] op_sel_hi:[1,0,1]
	s_waitcnt vmcnt(0)
	v_pk_mul_f32 v[42:43], v[2:3], v[42:43] op_sel_hi:[0,1]
	v_pk_mul_f32 v[2:3], v[2:3], v[40:41] op_sel_hi:[0,1]
	v_pk_fma_f32 v[38:39], v[38:39], v[0:1], v[42:43] op_sel_hi:[1,0,1]
	v_pk_fma_f32 v[36:37], v[36:37], v[0:1], v[2:3] op_sel_hi:[1,0,1]
	s_cbranch_scc1 .LBB0_83

; __device__ __forceinline__ float logsigmoidf_(float x) { return fminf(x, 0.0f) - log1pf(__expf(-fabsf(x))); }
; __device__ __forceinline__ float head_lgam(const Params& P, int hd, int dir) { return hd < 4 ? logsigmoidf_(P.in[9][dir * 4 + hd]) : 0.f; }
.LBB0_83:
	v_cndmask_b32_e64 v0, 0, 1, s[92:93]
	s_xor_b64 s[10:11], s[12:13], -1
	s_xor_b64 s[12:13], s[8:9], -1
	v_cmp_ne_u32_e64 s[42:43], 1, v0
	s_andn2_b64 vcc, exec, s[92:93]
	v_mov_b32_e32 v3, 0
	s_cbranch_vccnz .LBB0_85
	s_lshl_b32 s14, s7, 2
	s_or_b32 s38, s14, s0
	v_readlane_b32 s60, v254, 50
	s_lshl_b64 s[14:15], s[38:39], 2
	v_readlane_b32 s62, v254, 52
	v_readlane_b32 s63, v254, 53
	s_add_u32 s14, s62, s14
	s_addc_u32 s15, s63, s15
	global_load_dword v2, v1, s[14:15]
	s_mov_b32 s14, 0xbfb8aa3b
	v_readlane_b32 s61, v254, 51
	v_readlane_b32 s64, v254, 54
	v_readlane_b32 s65, v254, 55
	v_readlane_b32 s66, v254, 56
	v_readlane_b32 s67, v254, 57
	v_readlane_b32 s68, v254, 58
	v_readlane_b32 s69, v254, 59
	v_readlane_b32 s70, v254, 60
	v_readlane_b32 s71, v254, 61
	v_readlane_b32 s72, v254, 62
	v_readlane_b32 s73, v254, 63
	v_readlane_b32 s74, v255, 0
	v_readlane_b32 s75, v255, 1
	s_waitcnt vmcnt(0)
	v_max_f32_e32 v0, v2, v2
	v_mul_f32_e64 v2, |v2|, s14
	v_exp_f32_e32 v2, v2
	s_mov_b32 s14, 0x3f2aaaab
	v_min_f32_e32 v0, 0, v0
	v_add_f32_e32 v3, 1.0, v2
	v_add_f32_e32 v40, -1.0, v3
	v_sub_f32_e32 v41, v40, v3
	v_add_f32_e32 v41, 1.0, v41
	v_sub_f32_e32 v40, v2, v40
	v_add_f32_e32 v42, v40, v41
	v_frexp_mant_f32_e32 v40, v3
	v_cmp_gt_f32_e32 vcc, s14, v40
	v_cvt_f64_f32_e32 v[40:41], v3
	v_frexp_exp_i32_f64_e32 v40, v[40:41]
	v_subbrev_co_u32_e32 v48, vcc, 0, v40, vcc
	v_sub_u32_e32 v40, 0, v48
	v_ldexp_f32 v3, v3, v40
	v_ldexp_f32 v40, v42, v40
	v_add_f32_e32 v42, -1.0, v3
	v_add_f32_e32 v41, 1.0, v42
	v_sub_f32_e32 v41, v3, v41
	v_add_f32_e32 v43, v40, v41
	v_add_f32_e32 v41, 1.0, v3
	v_add_f32_e32 v44, -1.0, v41
	v_sub_f32_e32 v3, v3, v44
	v_add_f32_e32 v3, v40, v3
	v_add_f32_e32 v49, v41, v3
	v_rcp_f32_e32 v50, v49
	v_sub_f32_e32 v40, v49, v41
	v_add_f32_e32 v41, v42, v43
	v_sub_f32_e32 v3, v3, v40
	v_mul_f32_e32 v52, v41, v50
	v_sub_f32_e32 v40, v41, v42
	v_mul_f32_e32 v42, v49, v52
	v_fma_f32 v44, v52, v49, -v42
	v_fmac_f32_e32 v44, v52, v3
	v_sub_f32_e32 v51, v43, v40
	v_add_f32_e32 v40, v42, v44
	v_sub_f32_e32 v43, v41, v40
	v_pk_add_f32 v[46:47], v[40:41], v[42:43] neg_lo:[0,1] neg_hi:[0,1]
	v_mov_b32_e32 v45, v40
	v_pk_add_f32 v[40:41], v[46:47], v[44:45] neg_lo:[0,1] neg_hi:[0,1]
	s_mov_b32 s14, 0x3f317218
	v_add_f32_e32 v41, v51, v41
	v_add_f32_e32 v40, v40, v41
	v_add_f32_e32 v41, v43, v40
	v_mul_f32_e32 v51, v50, v41
	v_mul_f32_e32 v42, v49, v51
	v_fma_f32 v44, v51, v49, -v42
	v_fmac_f32_e32 v44, v51, v3
	v_sub_f32_e32 v3, v43, v41
	v_add_f32_e32 v3, v40, v3
	v_add_f32_e32 v40, v42, v44
	v_sub_f32_e32 v43, v41, v40
	v_pk_add_f32 v[46:47], v[40:41], v[42:43] neg_lo:[0,1] neg_hi:[0,1]
	v_mov_b32_e32 v45, v40
	v_pk_add_f32 v[40:41], v[46:47], v[44:45] neg_lo:[0,1] neg_hi:[0,1]
	s_nop 0
	v_add_f32_e32 v3, v3, v41
	v_add_f32_e32 v3, v40, v3
	v_add_f32_e32 v41, v52, v51
	v_add_f32_e32 v3, v43, v3
	v_sub_f32_e32 v40, v41, v52
	v_mul_f32_e32 v3, v50, v3
	v_sub_f32_e32 v40, v51, v40
	v_add_f32_e32 v3, v40, v3
	v_add_f32_e32 v42, v41, v3
	v_mul_f32_e32 v44, v42, v42
	v_fmamk_f32 v40, v44, 0x3e9b6dac, v208
	v_fmaak_f32 v169, v44, v40, 0x3f2aaada
	v_cvt_f32_i32_e32 v40, v48
	v_sub_f32_e32 v41, v42, v41
	v_sub_f32_e32 v3, v3, v41
	v_mul_f32_e32 v41, v42, v44
	v_pk_mul_f32 v[44:45], v[40:41], v[168:169]
	v_ldexp_f32 v43, v42, 1
	v_fma_f32 v42, v40, s14, -v44
	v_fmac_f32_e32 v42, 0xb102e308, v40
	v_pk_add_f32 v[40:41], v[44:45], v[42:43]
	v_ldexp_f32 v3, v3, 1
	v_sub_f32_e32 v43, v41, v43
	v_sub_f32_e32 v43, v45, v43
	v_add_f32_e32 v47, v3, v43
	v_mov_b32_e32 v46, v44
	v_pk_add_f32 v[44:45], v[40:41], v[44:45] neg_lo:[0,1] neg_hi:[0,1]
	v_pk_add_f32 v[48:49], v[40:41], v[46:47]
	v_mov_b32_e32 v43, v40
	v_mov_b32_e32 v45, v49
	v_pk_add_f32 v[50:51], v[42:43], v[44:45] neg_lo:[0,1] neg_hi:[0,1]
	v_pk_add_f32 v[42:43], v[42:43], v[44:45]
	v_mov_b32_e32 v54, v41
	v_pk_add_f32 v[44:45], v[42:43], v[40:41] op_sel:[1,0] op_sel_hi:[0,1] neg_lo:[0,1] neg_hi:[0,1]
	s_nop 0
	v_pk_add_f32 v[52:53], v[48:49], v[44:45] op_sel_hi:[1,0] neg_lo:[0,1] neg_hi:[0,1]
	v_mov_b32_e32 v48, v49
	v_mov_b32_e32 v49, v43
	v_mov_b32_e32 v55, v44
	v_pk_add_f32 v[44:45], v[48:49], v[54:55] neg_lo:[0,1] neg_hi:[0,1]
	v_mov_b32_e32 v46, v47
	v_mov_b32_e32 v47, v40
	v_pk_add_f32 v[40:41], v[46:47], v[44:45] neg_lo:[0,1] neg_hi:[0,1]
	v_mov_b32_e32 v52, v50
	v_pk_add_f32 v[44:45], v[52:53], v[40:41]
	v_mov_b32_e32 v51, v43
	v_pk_add_f32 v[46:47], v[44:45], v[44:45] op_sel:[0,1] op_sel_hi:[1,0]
	s_mov_b32 s14, 0x7f800000
	v_pk_add_f32 v[42:43], v[42:43], v[46:47] op_sel:[1,0] op_sel_hi:[0,1]
	s_nop 0
	v_mov_b32_e32 v45, v42
	v_pk_add_f32 v[48:49], v[44:45], v[50:51] neg_lo:[0,1] neg_hi:[0,1]
	v_mov_b32_e32 v41, v46
	v_sub_f32_e32 v3, v44, v48
	v_pk_add_f32 v[40:41], v[40:41], v[48:49] neg_lo:[0,1] neg_hi:[0,1]
	v_sub_f32_e32 v3, v50, v3
	v_add_f32_e32 v3, v40, v3
	v_add_f32_e32 v3, v3, v41
	v_add_f32_e32 v3, v42, v3
	v_cmp_neq_f32_e32 vcc, s14, v2
	s_mov_b32 s14, 0x33800000
	s_nop 0
	v_cndmask_b32_e32 v3, v212, v3, vcc
	v_cmp_ngt_f32_e32 vcc, -1.0, v2
	s_nop 1
	v_cndmask_b32_e32 v3, v213, v3, vcc
	v_cmp_neq_f32_e32 vcc, -1.0, v2
	s_nop 1
	v_cndmask_b32_e32 v3, v214, v3, vcc
	v_cmp_lt_f32_e64 vcc, |v2|, s14
	s_nop 1
	v_cndmask_b32_e32 v2, v3, v2, vcc
	v_sub_f32_e32 v3, v0, v2

; __device__ __forceinline__ float logsigmoidf_(float x) { return fminf(x, 0.0f) - log1pf(__expf(-fabsf(x))); }
; __device__ __forceinline__ float head_lgam(const Params& P, int hd, int dir) { return hd < 4 ? logsigmoidf_(P.in[9][dir * 4 + hd]) : 0.f; }
.LBB0_379:
	s_lshl_b32 s8, s12, 2
	s_or_b32 s38, s13, s8
	v_readlane_b32 s40, v254, 50
	s_lshl_b64 s[8:9], s[38:39], 2
	v_readlane_b32 s42, v254, 52
	v_readlane_b32 s43, v254, 53
	s_add_u32 s8, s42, s8
	s_addc_u32 s9, s43, s9
	global_load_dword v2, v1, s[8:9]
	s_mov_b32 s8, 0xbfb8aa3b
	v_readlane_b32 s41, v254, 51
	v_readlane_b32 s44, v254, 54
	v_readlane_b32 s45, v254, 55
	v_readlane_b32 s46, v254, 56
	v_readlane_b32 s47, v254, 57
	v_readlane_b32 s48, v254, 58
	v_readlane_b32 s49, v254, 59
	v_readlane_b32 s50, v254, 60
	v_readlane_b32 s51, v254, 61
	v_readlane_b32 s52, v254, 62
	v_readlane_b32 s53, v254, 63
	v_readlane_b32 s54, v255, 0
	v_readlane_b32 s55, v255, 1
	s_waitcnt vmcnt(0)
	v_max_f32_e32 v0, v2, v2
	v_mul_f32_e64 v2, |v2|, s8
	v_exp_f32_e32 v2, v2
	s_mov_b32 s8, 0x3f2aaaab
	v_min_f32_e32 v0, 0, v0
	s_waitcnt lgkmcnt(0)
	v_add_f32_e32 v3, 1.0, v2
	v_add_f32_e32 v4, -1.0, v3
	v_sub_f32_e32 v5, v4, v3
	v_add_f32_e32 v5, 1.0, v5
	v_sub_f32_e32 v4, v2, v4
	v_add_f32_e32 v6, v4, v5
	v_frexp_mant_f32_e32 v4, v3
	v_cmp_gt_f32_e32 vcc, s8, v4
	v_cvt_f64_f32_e32 v[4:5], v3
	v_frexp_exp_i32_f64_e32 v4, v[4:5]
	v_subbrev_co_u32_e32 v12, vcc, 0, v4, vcc
	v_sub_u32_e32 v4, 0, v12
	v_ldexp_f32 v3, v3, v4
	v_ldexp_f32 v4, v6, v4
	v_add_f32_e32 v6, -1.0, v3
	v_add_f32_e32 v5, 1.0, v6
	v_sub_f32_e32 v5, v3, v5
	v_add_f32_e32 v7, v4, v5
	v_add_f32_e32 v5, 1.0, v3
	v_add_f32_e32 v8, -1.0, v5
	v_sub_f32_e32 v3, v3, v8
	v_add_f32_e32 v3, v4, v3
	v_add_f32_e32 v13, v5, v3
	v_rcp_f32_e32 v14, v13
	v_sub_f32_e32 v4, v13, v5
	v_add_f32_e32 v5, v6, v7
	v_sub_f32_e32 v3, v3, v4
	v_mul_f32_e32 v16, v5, v14
	v_sub_f32_e32 v4, v5, v6
	v_mul_f32_e32 v6, v13, v16
	v_fma_f32 v8, v16, v13, -v6
	v_fmac_f32_e32 v8, v16, v3
	v_sub_f32_e32 v15, v7, v4
	v_add_f32_e32 v4, v6, v8
	v_sub_f32_e32 v7, v5, v4
	v_pk_add_f32 v[10:11], v[4:5], v[6:7] neg_lo:[0,1] neg_hi:[0,1]
	v_mov_b32_e32 v9, v4
	v_pk_add_f32 v[4:5], v[10:11], v[8:9] neg_lo:[0,1] neg_hi:[0,1]
	s_mov_b32 s8, 0x3f317218
	v_add_f32_e32 v5, v15, v5
	v_add_f32_e32 v4, v4, v5
	v_add_f32_e32 v5, v7, v4
	v_mul_f32_e32 v15, v14, v5
	v_mul_f32_e32 v6, v13, v15
	v_fma_f32 v8, v15, v13, -v6
	v_fmac_f32_e32 v8, v15, v3
	v_sub_f32_e32 v3, v7, v5
	v_add_f32_e32 v3, v4, v3
	v_add_f32_e32 v4, v6, v8
	v_sub_f32_e32 v7, v5, v4
	v_pk_add_f32 v[10:11], v[4:5], v[6:7] neg_lo:[0,1] neg_hi:[0,1]
	v_mov_b32_e32 v9, v4
	v_pk_add_f32 v[4:5], v[10:11], v[8:9] neg_lo:[0,1] neg_hi:[0,1]
	s_nop 0
	v_add_f32_e32 v3, v3, v5
	v_add_f32_e32 v3, v4, v3
	v_add_f32_e32 v5, v16, v15
	v_add_f32_e32 v3, v7, v3
	v_sub_f32_e32 v4, v5, v16
	v_mul_f32_e32 v3, v14, v3
	v_sub_f32_e32 v4, v15, v4
	v_add_f32_e32 v3, v4, v3
	v_add_f32_e32 v6, v5, v3
	v_mul_f32_e32 v8, v6, v6
	v_fmamk_f32 v4, v8, 0x3e9b6dac, v208
	v_fmaak_f32 v169, v8, v4, 0x3f2aaada
	v_cvt_f32_i32_e32 v4, v12
	v_sub_f32_e32 v5, v6, v5
	v_sub_f32_e32 v3, v3, v5
	v_mul_f32_e32 v5, v6, v8
	v_pk_mul_f32 v[8:9], v[4:5], v[168:169]
	v_ldexp_f32 v7, v6, 1
	v_fma_f32 v6, v4, s8, -v8
	v_fmac_f32_e32 v6, 0xb102e308, v4
	v_pk_add_f32 v[4:5], v[8:9], v[6:7]
	v_ldexp_f32 v3, v3, 1
	v_sub_f32_e32 v7, v5, v7
	v_sub_f32_e32 v7, v9, v7
	v_add_f32_e32 v11, v3, v7
	v_mov_b32_e32 v10, v8
	v_pk_add_f32 v[8:9], v[4:5], v[8:9] neg_lo:[0,1] neg_hi:[0,1]
	v_pk_add_f32 v[12:13], v[4:5], v[10:11]
	v_mov_b32_e32 v7, v4
	v_mov_b32_e32 v9, v13
	v_pk_add_f32 v[14:15], v[6:7], v[8:9] neg_lo:[0,1] neg_hi:[0,1]
	v_pk_add_f32 v[6:7], v[6:7], v[8:9]
	v_mov_b32_e32 v18, v5
	v_pk_add_f32 v[8:9], v[6:7], v[4:5] op_sel:[1,0] op_sel_hi:[0,1] neg_lo:[0,1] neg_hi:[0,1]
	s_nop 0
	v_pk_add_f32 v[16:17], v[12:13], v[8:9] op_sel_hi:[1,0] neg_lo:[0,1] neg_hi:[0,1]
	v_mov_b32_e32 v12, v13
	v_mov_b32_e32 v13, v7
	v_mov_b32_e32 v19, v8
	v_pk_add_f32 v[8:9], v[12:13], v[18:19] neg_lo:[0,1] neg_hi:[0,1]
	v_mov_b32_e32 v10, v11
	v_mov_b32_e32 v11, v4
	v_pk_add_f32 v[4:5], v[10:11], v[8:9] neg_lo:[0,1] neg_hi:[0,1]
	v_mov_b32_e32 v16, v14
	v_pk_add_f32 v[8:9], v[16:17], v[4:5]
	v_mov_b32_e32 v15, v7
	v_pk_add_f32 v[10:11], v[8:9], v[8:9] op_sel:[0,1] op_sel_hi:[1,0]
	s_mov_b32 s8, 0x7f800000
	v_pk_add_f32 v[6:7], v[6:7], v[10:11] op_sel:[1,0] op_sel_hi:[0,1]
	s_nop 0
	v_mov_b32_e32 v9, v6
	v_pk_add_f32 v[12:13], v[8:9], v[14:15] neg_lo:[0,1] neg_hi:[0,1]
	v_mov_b32_e32 v5, v10
	v_sub_f32_e32 v3, v8, v12
	v_pk_add_f32 v[4:5], v[4:5], v[12:13] neg_lo:[0,1] neg_hi:[0,1]
	v_sub_f32_e32 v3, v14, v3
	v_add_f32_e32 v3, v4, v3
	v_add_f32_e32 v3, v3, v5
	v_add_f32_e32 v3, v6, v3
	v_cmp_neq_f32_e32 vcc, s8, v2
	s_mov_b32 s8, 0x33800000
	s_nop 0
	v_cndmask_b32_e32 v3, v212, v3, vcc
	v_cmp_ngt_f32_e32 vcc, -1.0, v2
	s_nop 1
	v_cndmask_b32_e32 v3, v213, v3, vcc
	v_cmp_neq_f32_e32 vcc, -1.0, v2
	s_nop 1
	v_cndmask_b32_e32 v3, v214, v3, vcc
	v_cmp_lt_f32_e64 vcc, |v2|, s8
	s_nop 1
	v_cndmask_b32_e32 v2, v3, v2, vcc
	v_sub_f32_e32 v4, v0, v2

; __global__ void __launch_bounds__(512, 2) mega(Params P0) {
;     ...
;         else if (ph == 11) { const float* r3 = (const float*)(ws + WS_RSS3); const float* fw = P.in[23]; const f32x4* h3 = (const f32x4*)(ws + WS_H1);
;             const int nchunk = NTOK * DM / 4 / 1024; const int wv = bid * 8 + (tid >> 6), lane = tid & 63;
;             for (int ck = wv; ck < nchunk; ck += G * 8) { f32x4 v[16];
; #pragma unroll
;                 for (int j = 0; j < 16; ++j) v[j] = __builtin_nontemporal_load(h3 + (ck * 16 + j) * 64 + lane);
; #pragma unroll
;                 for (int j = 0; j < 16; ++j) { const int i = (ck * 16 + j) * 64 + lane; const int row = i >> 8, c4 = i & 255; const float rstd = rsqrtf(r3[row] * (1.0f / DM) + 1e-6f);
;                     __builtin_nontemporal_store(v[j] * rstd * *(const f32x4*)(fw + 4 * c4), (f32x4*)P.out + i); } } }
.LBB0_725:
	v_add_u32_e32 v96, 0xfffffc40, v70
	v_ashrrev_i32_e32 v97, 31, v96
	v_add_u32_e32 v94, 0xfffffd40, v70
	v_lshl_add_u64 v[2:3], v[96:97], 4, v[66:67]
	v_ashrrev_i32_e32 v95, 31, v94
	v_add_u32_e32 v92, 0xfffffd80, v70
	global_load_dwordx4 v[62:65], v[2:3], off nt
	global_load_dwordx4 v[58:61], v[2:3], off offset:1024 nt
	global_load_dwordx4 v[54:57], v[2:3], off offset:2048 nt
	global_load_dwordx4 v[50:53], v[2:3], off offset:3072 nt
	v_lshl_add_u64 v[2:3], v[94:95], 4, v[66:67]
	v_ashrrev_i32_e32 v93, 31, v92
	v_add_u32_e32 v90, 0xfffffdc0, v70
	global_load_dwordx4 v[46:49], v[2:3], off nt
	v_lshl_add_u64 v[2:3], v[92:93], 4, v[66:67]
	v_ashrrev_i32_e32 v91, 31, v90
	v_add_u32_e32 v88, 0xfffffe00, v70
	global_load_dwordx4 v[42:45], v[2:3], off nt
	v_lshl_add_u64 v[2:3], v[90:91], 4, v[66:67]
	v_ashrrev_i32_e32 v89, 31, v88
	v_add_u32_e32 v86, 0xfffffe40, v70
	global_load_dwordx4 v[38:41], v[2:3], off nt
	v_lshl_add_u64 v[2:3], v[88:89], 4, v[66:67]
	v_ashrrev_i32_e32 v87, 31, v86
	v_add_u32_e32 v84, 0xfffffe80, v70
	global_load_dwordx4 v[34:37], v[2:3], off nt
	v_lshl_add_u64 v[2:3], v[86:87], 4, v[66:67]
	v_ashrrev_i32_e32 v85, 31, v84
	v_add_u32_e32 v82, 0xfffffec0, v70
	global_load_dwordx4 v[30:33], v[2:3], off nt
	v_lshl_add_u64 v[2:3], v[84:85], 4, v[66:67]
	v_ashrrev_i32_e32 v83, 31, v82
	v_add_u32_e32 v80, 0xffffff00, v70
	global_load_dwordx4 v[26:29], v[2:3], off nt
	v_lshl_add_u64 v[2:3], v[82:83], 4, v[66:67]
	v_ashrrev_i32_e32 v81, 31, v80
	v_add_u32_e32 v78, 0xffffff40, v70
	global_load_dwordx4 v[22:25], v[2:3], off nt
	v_lshl_add_u64 v[2:3], v[80:81], 4, v[66:67]
	v_ashrrev_i32_e32 v79, 31, v78
	v_add_u32_e32 v76, 0xffffff80, v70
	global_load_dwordx4 v[18:21], v[2:3], off nt
	v_lshl_add_u64 v[2:3], v[78:79], 4, v[66:67]
	v_ashrrev_i32_e32 v77, 31, v76
	v_subrev_u32_e32 v74, 64, v70
	v_ashrrev_i32_e32 v98, 8, v96
	global_load_dwordx4 v[14:17], v[2:3], off nt
	v_lshl_add_u64 v[2:3], v[76:77], 4, v[66:67]
	v_ashrrev_i32_e32 v75, 31, v74
	v_ashrrev_i32_e32 v99, 31, v98
	global_load_dwordx4 v[10:13], v[2:3], off nt
	v_lshl_add_u64 v[2:3], v[74:75], 4, v[66:67]
	v_ashrrev_i32_e32 v71, 31, v70
	v_lshl_add_u64 v[98:99], v[98:99], 2, s[4:5]
	global_load_dwordx4 v[6:9], v[2:3], off nt
	v_lshl_add_u64 v[2:3], v[70:71], 4, v[66:67]
	global_load_dword v71, v[98:99], off
	v_add_u32_e32 v72, v0, v70
	v_add_u32_e32 v102, 0xfffffc40, v72
	v_ashrrev_i32_e32 v103, 31, v102
	v_lshl_add_u64 v[102:103], v[102:103], 4, s[20:21]
	global_load_dwordx4 v[2:5], v[2:3], off nt
	v_add_u32_e32 v100, s0, v100
	s_movk_i32 s10, 0x1fff
	s_waitcnt vmcnt(1)
	v_fmamk_f32 v71, v71, 0x3a800000, v210
	v_cmp_gt_f32_e32 vcc, s30, v71
	v_mul_f32_e32 v73, 0x4b800000, v71
	s_nop 0
	v_cndmask_b32_e32 v71, v71, v73, vcc
	v_rsq_f32_e32 v71, v71
	s_nop 0
	v_mul_f32_e32 v73, 0x45800000, v71
	v_cndmask_b32_e32 v104, v71, v73, vcc
	v_pk_mul_f32 v[106:107], v[62:63], v[104:105] op_sel_hi:[1,0]
	v_pk_mul_f32 v[104:105], v[64:65], v[104:105] op_sel_hi:[1,0]
	global_load_dwordx4 v[62:65], v[68:69], off
	v_ashrrev_i32_e32 v73, 31, v72
	s_waitcnt vmcnt(0)
	v_pk_mul_f32 v[64:65], v[64:65], v[104:105]
	v_pk_mul_f32 v[62:63], v[62:63], v[106:107]
	s_nop 0
	global_store_dwordx4 v[102:103], v[62:65], off nt
	global_load_dword v62, v[98:99], off
	s_waitcnt vmcnt(0)
	v_fmamk_f32 v62, v62, 0x3a800000, v210
	v_cmp_gt_f32_e32 vcc, s30, v62
	v_mul_f32_e32 v63, 0x4b800000, v62
	s_nop 0
	v_cndmask_b32_e32 v62, v62, v63, vcc
	v_rsq_f32_e32 v62, v62
	s_nop 0
	v_mul_f32_e32 v63, 0x45800000, v62
	v_cndmask_b32_e32 v62, v62, v63, vcc
	v_pk_mul_f32 v[58:59], v[58:59], v[62:63] op_sel_hi:[1,0]
	v_pk_mul_f32 v[60:61], v[60:61], v[62:63] op_sel_hi:[1,0]
	v_add_u32_e32 v62, 0x100, v101
	v_and_b32_e32 v62, 0x1fc, v62
	v_lshlrev_b32_e32 v62, 2, v62
	global_load_dwordx4 v[62:65], v62, s[54:55]
	s_waitcnt vmcnt(0)
	v_pk_mul_f32 v[62:63], v[62:63], v[58:59]
	v_lshl_add_u64 v[58:59], v[96:97], 0, v[0:1]
	v_pk_mul_f32 v[64:65], v[64:65], v[60:61]
	v_lshl_add_u64 v[58:59], v[58:59], 4, s[20:21]
	global_store_dwordx4 v[58:59], v[62:65], off offset:1024 nt
	global_load_dword v60, v[98:99], off
	s_waitcnt vmcnt(0)
	v_fmamk_f32 v60, v60, 0x3a800000, v210
	v_cmp_gt_f32_e32 vcc, s30, v60
	v_mul_f32_e32 v61, 0x4b800000, v60
	s_nop 0
	v_cndmask_b32_e32 v60, v60, v61, vcc
	v_rsq_f32_e32 v60, v60
	s_nop 0
	v_mul_f32_e32 v61, 0x45800000, v60
	v_cndmask_b32_e32 v60, v60, v61, vcc
	v_pk_mul_f32 v[62:63], v[54:55], v[60:61] op_sel_hi:[1,0]
	v_add_u32_e32 v54, 0x200, v101
	v_and_b32_e32 v54, 0x2fc, v54
	v_lshlrev_b32_e32 v54, 2, v54
	v_pk_mul_f32 v[60:61], v[56:57], v[60:61] op_sel_hi:[1,0]
	global_load_dwordx4 v[54:57], v54, s[54:55]
	s_waitcnt vmcnt(0)
	v_pk_mul_f32 v[56:57], v[56:57], v[60:61]
	v_pk_mul_f32 v[54:55], v[54:55], v[62:63]
	s_nop 0
	global_store_dwordx4 v[58:59], v[54:57], off offset:2048 nt
	global_load_dword v54, v[98:99], off
	s_waitcnt vmcnt(0)
	v_fmamk_f32 v54, v54, 0x3a800000, v210
	v_cmp_gt_f32_e32 vcc, s30, v54
	v_mul_f32_e32 v55, 0x4b800000, v54
	s_nop 0
	v_cndmask_b32_e32 v54, v54, v55, vcc
	v_rsq_f32_e32 v54, v54
	s_nop 0
	v_mul_f32_e32 v55, 0x45800000, v54
	v_cndmask_b32_e32 v54, v54, v55, vcc
	v_pk_mul_f32 v[56:57], v[50:51], v[54:55] op_sel_hi:[1,0]
	v_add_u32_e32 v50, 0x300, v101
	v_and_b32_e32 v50, 0x3fc, v50
	v_lshlrev_b32_e32 v50, 2, v50
	v_pk_mul_f32 v[54:55], v[52:53], v[54:55] op_sel_hi:[1,0]
	global_load_dwordx4 v[50:53], v50, s[54:55]
	s_waitcnt vmcnt(0)
	v_pk_mul_f32 v[52:53], v[52:53], v[54:55]
	v_pk_mul_f32 v[50:51], v[50:51], v[56:57]
	s_nop 0
	global_store_dwordx4 v[58:59], v[50:53], off offset:3072 nt
	s_nop 1
	v_ashrrev_i32_e32 v52, 8, v94
	v_ashrrev_i32_e32 v53, 31, v52
	v_lshl_add_u64 v[52:53], v[52:53], 2, s[4:5]
	global_load_dword v51, v[52:53], off
	v_add_u32_e32 v50, 0xfffffd40, v72
	s_waitcnt vmcnt(0)
; __global__ void __launch_bounds__(512, 2) mega(Params P0) {
;     ...
;         else if (ph == 11) { const float* r3 = (const float*)(ws + WS_RSS3); const float* fw = P.in[23]; const f32x4* h3 = (const f32x4*)(ws + WS_H1);
;             const int nchunk = NTOK * DM / 4 / 1024; const int wv = bid * 8 + (tid >> 6), lane = tid & 63;
;             for (int ck = wv; ck < nchunk; ck += G * 8) { f32x4 v[16];
; #pragma unroll
;                 for (int j = 0; j < 16; ++j) v[j] = __builtin_nontemporal_load(h3 + (ck * 16 + j) * 64 + lane);
; #pragma unroll
;                 for (int j = 0; j < 16; ++j) { const int i = (ck * 16 + j) * 64 + lane; const int row = i >> 8, c4 = i & 255; const float rstd = rsqrtf(r3[row] * (1.0f / DM) + 1e-6f);
;                     __builtin_nontemporal_store(v[j] * rstd * *(const f32x4*)(fw + 4 * c4), (f32x4*)P.out + i); } } }
	v_fmamk_f32 v51, v51, 0x3a800000, v210
	v_cmp_gt_f32_e32 vcc, s30, v51
	v_mul_f32_e32 v52, 0x4b800000, v51
	s_nop 0
	v_cndmask_b32_e32 v51, v51, v52, vcc
	v_rsq_f32_e32 v51, v51
	s_nop 0
	v_mul_f32_e32 v52, 0x45800000, v51
	v_cndmask_b32_e32 v52, v51, v52, vcc
	v_pk_mul_f32 v[54:55], v[46:47], v[52:53] op_sel_hi:[1,0]
	v_pk_mul_f32 v[52:53], v[48:49], v[52:53] op_sel_hi:[1,0]
	global_load_dwordx4 v[46:49], v[68:69], off
	v_ashrrev_i32_e32 v51, 31, v50
	v_lshl_add_u64 v[50:51], v[50:51], 4, s[20:21]
	s_waitcnt vmcnt(0)
	v_pk_mul_f32 v[48:49], v[48:49], v[52:53]
	v_pk_mul_f32 v[46:47], v[46:47], v[54:55]
	s_nop 0
	global_store_dwordx4 v[50:51], v[46:49], off nt
	s_nop 1
	v_ashrrev_i32_e32 v48, 8, v92
	v_ashrrev_i32_e32 v49, 31, v48
	v_lshl_add_u64 v[48:49], v[48:49], 2, s[4:5]
	global_load_dword v47, v[48:49], off
	v_add_u32_e32 v46, 0xfffffd80, v72
	s_waitcnt vmcnt(0)
	v_fmamk_f32 v47, v47, 0x3a800000, v210
	v_cmp_gt_f32_e32 vcc, s30, v47
	v_mul_f32_e32 v48, 0x4b800000, v47
	s_nop 0
	v_cndmask_b32_e32 v47, v47, v48, vcc
	v_rsq_f32_e32 v47, v47
	s_nop 0
	v_mul_f32_e32 v48, 0x45800000, v47
	v_cndmask_b32_e32 v48, v47, v48, vcc
	v_pk_mul_f32 v[50:51], v[42:43], v[48:49] op_sel_hi:[1,0]
	v_add_u32_e32 v42, 0x500, v101
	v_and_b32_e32 v42, 0x1fc, v42
	v_lshlrev_b32_e32 v42, 2, v42
	v_pk_mul_f32 v[48:49], v[44:45], v[48:49] op_sel_hi:[1,0]
	global_load_dwordx4 v[42:45], v42, s[54:55]
	v_ashrrev_i32_e32 v47, 31, v46
	v_lshl_add_u64 v[46:47], v[46:47], 4, s[20:21]
	s_waitcnt vmcnt(0)
	v_pk_mul_f32 v[44:45], v[44:45], v[48:49]
	v_pk_mul_f32 v[42:43], v[42:43], v[50:51]
	s_nop 0
	global_store_dwordx4 v[46:47], v[42:45], off nt
	s_nop 1
	v_ashrrev_i32_e32 v44, 8, v90
	v_ashrrev_i32_e32 v45, 31, v44
	v_lshl_add_u64 v[44:45], v[44:45], 2, s[4:5]
	global_load_dword v43, v[44:45], off
	v_add_u32_e32 v42, 0xfffffdc0, v72
	s_waitcnt vmcnt(0)
	v_fmamk_f32 v43, v43, 0x3a800000, v210
	v_cmp_gt_f32_e32 vcc, s30, v43
	v_mul_f32_e32 v44, 0x4b800000, v43
	s_nop 0
	v_cndmask_b32_e32 v43, v43, v44, vcc
	v_rsq_f32_e32 v43, v43
	s_nop 0
	v_mul_f32_e32 v44, 0x45800000, v43
	v_cndmask_b32_e32 v44, v43, v44, vcc
	v_pk_mul_f32 v[46:47], v[38:39], v[44:45] op_sel_hi:[1,0]
	v_add_u32_e32 v38, 0x600, v101
	v_and_b32_e32 v38, 0x2fc, v38
	v_lshlrev_b32_e32 v38, 2, v38
	v_pk_mul_f32 v[44:45], v[40:41], v[44:45] op_sel_hi:[1,0]
	global_load_dwordx4 v[38:41], v38, s[54:55]
	v_ashrrev_i32_e32 v43, 31, v42
	v_lshl_add_u64 v[42:43], v[42:43], 4, s[20:21]
	s_waitcnt vmcnt(0)
	v_pk_mul_f32 v[40:41], v[40:41], v[44:45]
	v_pk_mul_f32 v[38:39], v[38:39], v[46:47]
	s_nop 0
	global_store_dwordx4 v[42:43], v[38:41], off nt
	s_nop 1
	v_ashrrev_i32_e32 v40, 8, v88
	v_ashrrev_i32_e32 v41, 31, v40
	v_lshl_add_u64 v[40:41], v[40:41], 2, s[4:5]
	global_load_dword v39, v[40:41], off
	v_add_u32_e32 v38, 0xfffffe00, v72
	s_waitcnt vmcnt(0)
	v_fmamk_f32 v39, v39, 0x3a800000, v210
	v_cmp_gt_f32_e32 vcc, s30, v39
	v_mul_f32_e32 v40, 0x4b800000, v39
	s_nop 0
	v_cndmask_b32_e32 v39, v39, v40, vcc
	v_rsq_f32_e32 v39, v39
	s_nop 0
	v_mul_f32_e32 v40, 0x45800000, v39
	v_cndmask_b32_e32 v40, v39, v40, vcc
	v_pk_mul_f32 v[42:43], v[34:35], v[40:41] op_sel_hi:[1,0]
	v_add_u32_e32 v34, 0x700, v101
	v_and_b32_e32 v34, 0x3fc, v34
	v_lshlrev_b32_e32 v34, 2, v34
	v_pk_mul_f32 v[40:41], v[36:37], v[40:41] op_sel_hi:[1,0]
	global_load_dwordx4 v[34:37], v34, s[54:55]
	v_ashrrev_i32_e32 v39, 31, v38
	v_lshl_add_u64 v[38:39], v[38:39], 4, s[20:21]
	s_waitcnt vmcnt(0)
	v_pk_mul_f32 v[36:37], v[36:37], v[40:41]
	v_pk_mul_f32 v[34:35], v[34:35], v[42:43]
	s_nop 0
	global_store_dwordx4 v[38:39], v[34:37], off nt
	s_nop 1
	v_ashrrev_i32_e32 v36, 8, v86
	v_ashrrev_i32_e32 v37, 31, v36
	v_lshl_add_u64 v[36:37], v[36:37], 2, s[4:5]
	global_load_dword v35, v[36:37], off
	v_add_u32_e32 v34, 0xfffffe40, v72
	s_waitcnt vmcnt(0)
	v_fmamk_f32 v35, v35, 0x3a800000, v210
	v_cmp_gt_f32_e32 vcc, s30, v35
	v_mul_f32_e32 v36, 0x4b800000, v35
	s_nop 0
	v_cndmask_b32_e32 v35, v35, v36, vcc
	v_rsq_f32_e32 v35, v35
	s_nop 0
	v_mul_f32_e32 v36, 0x45800000, v35
	v_cndmask_b32_e32 v36, v35, v36, vcc
	v_pk_mul_f32 v[38:39], v[30:31], v[36:37] op_sel_hi:[1,0]
	v_pk_mul_f32 v[36:37], v[32:33], v[36:37] op_sel_hi:[1,0]
	global_load_dwordx4 v[30:33], v[68:69], off
	v_ashrrev_i32_e32 v35, 31, v34
	v_lshl_add_u64 v[34:35], v[34:35], 4, s[20:21]
	s_waitcnt vmcnt(0)
	v_pk_mul_f32 v[32:33], v[32:33], v[36:37]
	v_pk_mul_f32 v[30:31], v[30:31], v[38:39]
	s_nop 0
	global_store_dwordx4 v[34:35], v[30:33], off nt
	s_nop 1
	v_ashrrev_i32_e32 v32, 8, v84
	v_ashrrev_i32_e32 v33, 31, v32
	v_lshl_add_u64 v[32:33], v[32:33], 2, s[4:5]
	global_load_dword v31, v[32:33], off
	v_add_u32_e32 v30, 0xfffffe80, v72
	s_waitcnt vmcnt(0)
	v_fmamk_f32 v31, v31, 0x3a800000, v210
	v_cmp_gt_f32_e32 vcc, s30, v31
	v_mul_f32_e32 v32, 0x4b800000, v31
	s_nop 0
	v_cndmask_b32_e32 v31, v31, v32, vcc
	v_rsq_f32_e32 v31, v31
	s_nop 0
	v_mul_f32_e32 v32, 0x45800000, v31
	v_cndmask_b32_e32 v32, v31, v32, vcc
	v_pk_mul_f32 v[34:35], v[26:27], v[32:33] op_sel_hi:[1,0]
	v_add_u32_e32 v26, 0x900, v101
	v_and_b32_e32 v26, 0x1fc, v26
	v_lshlrev_b32_e32 v26, 2, v26
	v_pk_mul_f32 v[32:33], v[28:29], v[32:33] op_sel_hi:[1,0]
	global_load_dwordx4 v[26:29], v26, s[54:55]
	v_ashrrev_i32_e32 v31, 31, v30
	v_lshl_add_u64 v[30:31], v[30:31], 4, s[20:21]
	s_waitcnt vmcnt(0)
	v_pk_mul_f32 v[28:29], v[28:29], v[32:33]
	v_pk_mul_f32 v[26:27], v[26:27], v[34:35]
	s_nop 0
	global_store_dwordx4 v[30:31], v[26:29], off nt
	s_nop 1
	v_ashrrev_i32_e32 v28, 8, v82
	v_ashrrev_i32_e32 v29, 31, v28
	v_lshl_add_u64 v[28:29], v[28:29], 2, s[4:5]
	global_load_dword v27, v[28:29], off
	v_add_u32_e32 v26, 0xfffffec0, v72
	s_waitcnt vmcnt(0)
; __global__ void __launch_bounds__(512, 2) mega(Params P0) {
;     ...
;         else if (ph == 11) { const float* r3 = (const float*)(ws + WS_RSS3); const float* fw = P.in[23]; const f32x4* h3 = (const f32x4*)(ws + WS_H1);
;             const int nchunk = NTOK * DM / 4 / 1024; const int wv = bid * 8 + (tid >> 6), lane = tid & 63;
;             for (int ck = wv; ck < nchunk; ck += G * 8) { f32x4 v[16];
; #pragma unroll
;                 for (int j = 0; j < 16; ++j) v[j] = __builtin_nontemporal_load(h3 + (ck * 16 + j) * 64 + lane);
; #pragma unroll
;                 for (int j = 0; j < 16; ++j) { const int i = (ck * 16 + j) * 64 + lane; const int row = i >> 8, c4 = i & 255; const float rstd = rsqrtf(r3[row] * (1.0f / DM) + 1e-6f);
;                     __builtin_nontemporal_store(v[j] * rstd * *(const f32x4*)(fw + 4 * c4), (f32x4*)P.out + i); } } }
	v_fmamk_f32 v27, v27, 0x3a800000, v210
	v_cmp_gt_f32_e32 vcc, s30, v27
	v_mul_f32_e32 v28, 0x4b800000, v27
	s_nop 0
	v_cndmask_b32_e32 v27, v27, v28, vcc
	v_rsq_f32_e32 v27, v27
	s_nop 0
	v_mul_f32_e32 v28, 0x45800000, v27
	v_cndmask_b32_e32 v28, v27, v28, vcc
	v_pk_mul_f32 v[30:31], v[22:23], v[28:29] op_sel_hi:[1,0]
	v_add_u32_e32 v22, 0xa00, v101
	v_and_b32_e32 v22, 0x2fc, v22
	v_lshlrev_b32_e32 v22, 2, v22
	v_pk_mul_f32 v[28:29], v[24:25], v[28:29] op_sel_hi:[1,0]
	global_load_dwordx4 v[22:25], v22, s[54:55]
	v_ashrrev_i32_e32 v27, 31, v26
	v_lshl_add_u64 v[26:27], v[26:27], 4, s[20:21]
	s_waitcnt vmcnt(0)
	v_pk_mul_f32 v[24:25], v[24:25], v[28:29]
	v_pk_mul_f32 v[22:23], v[22:23], v[30:31]
	s_nop 0
	global_store_dwordx4 v[26:27], v[22:25], off nt
	s_nop 1
	v_ashrrev_i32_e32 v24, 8, v80
	v_ashrrev_i32_e32 v25, 31, v24
	v_lshl_add_u64 v[24:25], v[24:25], 2, s[4:5]
	global_load_dword v23, v[24:25], off
	v_add_u32_e32 v22, 0xffffff00, v72
	s_waitcnt vmcnt(0)
	v_fmamk_f32 v23, v23, 0x3a800000, v210
	v_cmp_gt_f32_e32 vcc, s30, v23
	v_mul_f32_e32 v24, 0x4b800000, v23
	s_nop 0
	v_cndmask_b32_e32 v23, v23, v24, vcc
	v_rsq_f32_e32 v23, v23
	s_nop 0
	v_mul_f32_e32 v24, 0x45800000, v23
	v_cndmask_b32_e32 v24, v23, v24, vcc
	v_pk_mul_f32 v[26:27], v[18:19], v[24:25] op_sel_hi:[1,0]
	v_add_u32_e32 v18, 0xb00, v101
	v_and_b32_e32 v18, 0x3fc, v18
	v_lshlrev_b32_e32 v18, 2, v18
	v_pk_mul_f32 v[24:25], v[20:21], v[24:25] op_sel_hi:[1,0]
	global_load_dwordx4 v[18:21], v18, s[54:55]
	v_ashrrev_i32_e32 v23, 31, v22
	v_lshl_add_u64 v[22:23], v[22:23], 4, s[20:21]
	s_waitcnt vmcnt(0)
	v_pk_mul_f32 v[20:21], v[20:21], v[24:25]
	v_pk_mul_f32 v[18:19], v[18:19], v[26:27]
	s_nop 0
	global_store_dwordx4 v[22:23], v[18:21], off nt
	s_nop 1
	v_ashrrev_i32_e32 v20, 8, v78
	v_ashrrev_i32_e32 v21, 31, v20
	v_lshl_add_u64 v[20:21], v[20:21], 2, s[4:5]
	global_load_dword v19, v[20:21], off
	v_add_u32_e32 v18, 0xffffff40, v72
	s_waitcnt vmcnt(0)
	v_fmamk_f32 v19, v19, 0x3a800000, v210
	v_cmp_gt_f32_e32 vcc, s30, v19
	v_mul_f32_e32 v20, 0x4b800000, v19
	s_nop 0
	v_cndmask_b32_e32 v19, v19, v20, vcc
	v_rsq_f32_e32 v19, v19
	s_nop 0
	v_mul_f32_e32 v20, 0x45800000, v19
	v_cndmask_b32_e32 v20, v19, v20, vcc
	v_pk_mul_f32 v[22:23], v[14:15], v[20:21] op_sel_hi:[1,0]
	v_pk_mul_f32 v[20:21], v[16:17], v[20:21] op_sel_hi:[1,0]
	global_load_dwordx4 v[14:17], v[68:69], off
	v_ashrrev_i32_e32 v19, 31, v18
	v_lshl_add_u64 v[18:19], v[18:19], 4, s[20:21]
	s_waitcnt vmcnt(0)
	v_pk_mul_f32 v[16:17], v[16:17], v[20:21]
	v_pk_mul_f32 v[14:15], v[14:15], v[22:23]
	s_nop 0
	global_store_dwordx4 v[18:19], v[14:17], off nt
	s_nop 1
	v_ashrrev_i32_e32 v16, 8, v76
	v_ashrrev_i32_e32 v17, 31, v16
	v_lshl_add_u64 v[16:17], v[16:17], 2, s[4:5]
	global_load_dword v15, v[16:17], off
	v_add_u32_e32 v14, 0xffffff80, v72
	s_waitcnt vmcnt(0)
	v_fmamk_f32 v15, v15, 0x3a800000, v210
	v_cmp_gt_f32_e32 vcc, s30, v15
	v_mul_f32_e32 v16, 0x4b800000, v15
	s_nop 0
	v_cndmask_b32_e32 v15, v15, v16, vcc
	v_rsq_f32_e32 v15, v15
	s_nop 0
	v_mul_f32_e32 v16, 0x45800000, v15
	v_cndmask_b32_e32 v16, v15, v16, vcc
	v_pk_mul_f32 v[18:19], v[10:11], v[16:17] op_sel_hi:[1,0]
	v_add_u32_e32 v10, 0xd00, v101
	v_and_b32_e32 v10, 0x1fc, v10
	v_lshlrev_b32_e32 v10, 2, v10
	v_pk_mul_f32 v[16:17], v[12:13], v[16:17] op_sel_hi:[1,0]
	global_load_dwordx4 v[10:13], v10, s[54:55]
	v_ashrrev_i32_e32 v15, 31, v14
	v_lshl_add_u64 v[14:15], v[14:15], 4, s[20:21]
	s_waitcnt vmcnt(0)
	v_pk_mul_f32 v[12:13], v[12:13], v[16:17]
	v_pk_mul_f32 v[10:11], v[10:11], v[18:19]
	s_nop 0
	global_store_dwordx4 v[14:15], v[10:13], off nt
	s_nop 1
	v_ashrrev_i32_e32 v12, 8, v74
	v_ashrrev_i32_e32 v13, 31, v12
	v_lshl_add_u64 v[12:13], v[12:13], 2, s[4:5]
	global_load_dword v11, v[12:13], off
	v_subrev_u32_e32 v10, 64, v72
	s_waitcnt vmcnt(0)
	v_fmamk_f32 v11, v11, 0x3a800000, v210
	v_cmp_gt_f32_e32 vcc, s30, v11
	v_mul_f32_e32 v12, 0x4b800000, v11
	s_nop 0
	v_cndmask_b32_e32 v11, v11, v12, vcc
	v_rsq_f32_e32 v11, v11
	s_nop 0
	v_mul_f32_e32 v12, 0x45800000, v11
	v_cndmask_b32_e32 v12, v11, v12, vcc
	v_pk_mul_f32 v[14:15], v[6:7], v[12:13] op_sel_hi:[1,0]
	v_add_u32_e32 v6, 0xe00, v101
	v_and_b32_e32 v6, 0x2fc, v6
	v_lshlrev_b32_e32 v6, 2, v6
	v_pk_mul_f32 v[12:13], v[8:9], v[12:13] op_sel_hi:[1,0]
	global_load_dwordx4 v[6:9], v6, s[54:55]
	v_ashrrev_i32_e32 v11, 31, v10
	v_lshl_add_u64 v[10:11], v[10:11], 4, s[20:21]
	s_waitcnt vmcnt(0)
	v_pk_mul_f32 v[8:9], v[8:9], v[12:13]
	v_pk_mul_f32 v[6:7], v[6:7], v[14:15]
	s_nop 0
	global_store_dwordx4 v[10:11], v[6:9], off nt
	s_nop 1
	v_ashrrev_i32_e32 v6, 8, v70
	v_ashrrev_i32_e32 v7, 31, v6
	v_lshl_add_u64 v[6:7], v[6:7], 2, s[4:5]
	global_load_dword v6, v[6:7], off
	v_add_u32_e32 v70, s9, v70
	s_waitcnt vmcnt(0)
	v_fmamk_f32 v6, v6, 0x3a800000, v210
	v_cmp_gt_f32_e32 vcc, s30, v6
	v_mul_f32_e32 v7, 0x4b800000, v6
	s_nop 0
	v_cndmask_b32_e32 v6, v6, v7, vcc
	v_rsq_f32_e32 v6, v6
	s_nop 0
	v_mul_f32_e32 v7, 0x45800000, v6
	v_cndmask_b32_e32 v6, v6, v7, vcc
	v_pk_mul_f32 v[8:9], v[2:3], v[6:7] op_sel_hi:[1,0]
	v_add_u32_e32 v2, 0xf00, v101
	v_and_b32_e32 v2, 0x3fc, v2
	v_lshlrev_b32_e32 v2, 2, v2
	v_pk_mul_f32 v[6:7], v[4:5], v[6:7] op_sel_hi:[1,0]
	global_load_dwordx4 v[2:5], v2, s[54:55]
	v_cmp_lt_i32_e32 vcc, s10, v100
	v_add_u32_e32 v101, s8, v101
	s_or_b64 s[6:7], vcc, s[6:7]
	s_waitcnt vmcnt(0)
	v_pk_mul_f32 v[4:5], v[4:5], v[6:7]
	v_pk_mul_f32 v[2:3], v[2:3], v[8:9]
	v_lshl_add_u64 v[6:7], v[72:73], 4, s[20:21]
	global_store_dwordx4 v[6:7], v[2:5], off nt
	s_andn2_b64 exec, exec, s[6:7]
	s_cbranch_execnz .LBB0_725

; __device__ __forceinline__ float dppf_prev(float cur, float below) { return __uint_as_float(dpp_prev(__float_as_uint(cur), __float_as_uint(below))); }
; __device__ __forceinline__ float dppf_next(float cur, float above) { return __uint_as_float(dpp_next(__float_as_uint(cur), __float_as_uint(above))); }
;     __device__ __forceinline__ void operator()(AccT& acc, const Unit& u, int wr, int wc, int fr, int fq) const {
;     ...
;         const int fcol = u.pn * 128 + wc * 32 + 8 * fq;
; #pragma unroll
;         for (int ai = 0; ai < 2; ++ai) { const int gidx = u.pm * 4 + ai * 2 + wr;
; #pragma unroll
;             for (int m = 0; m < 4; ++m) { const float rstd = rsqrtf(rss[half * HALF_TOK + gidx * 64 + m * 16 + fr] * (1.0f / DM) + 1e-6f);
; #pragma unroll
;                 for (int n = 0; n < 2; ++n) { acc[ai][0][m][n] = acc[ai][0][m][n] * rstd; acc[ai][1][m][n] = acc[ai][1][m][n] * rstd; } }
; #pragma unroll
;             for (int n = 0; n < 2; ++n) {
;                 const f32x4 w0 = *(const f32x4*)(cw + fcol + 4 * n), w1 = *(const f32x4*)(cw + DFF + fcol + 4 * n), w2 = *(const f32x4*)(cw + 2 * DFF + fcol + 4 * n), b = *(const f32x4*)(cb + fcol + 4 * n);
; #pragma unroll
;                 for (int m = 0; m < 4; ++m) { const int lr = m * 16 + fr;
;                     const f32x4 gc = acc[ai][0][m][n], up = acc[ai][1][m][n]; f32x4 uu;
; #pragma unroll
;                     for (int j = 0; j < 4; ++j) { const float gp = dppf_prev(gc[j], m > 0 ? acc[ai][0][m - 1][n][j] : 0.f), gn = dppf_next(gc[j], m < 3 ? acc[ai][0][m + 1][n][j] : 0.f);
.LBB0_889:
	s_lshl_b32 s89, s48, 2
	s_add_i32 s89, s89, s15
	s_lshl_b32 s36, s49, 7
	s_or_b32 s36, s36, s81
	v_lshl_add_u32 v144, v196, 3, s36
	v_mov_b32_e32 v145, 0
	s_lshl_b32 s90, s89, 6
	s_add_i32 s90, s90, s85
	v_add_u32_e32 v130, s90, v169
	v_mov_b32_e32 v131, 0
	v_lshl_add_u64 v[130:131], v[130:131], 2, s[10:11]
	global_load_dword v156, v[130:131], off
	global_load_dword v158, v[130:131], off offset:64
	global_load_dword v160, v[130:131], off offset:128
	global_load_dword v164, v[130:131], off offset:192
	global_load_dword v166, v[130:131], off offset:512
	global_load_dword v170, v[130:131], off offset:576
	global_load_dword v172, v[130:131], off offset:640
	global_load_dword v194, v[130:131], off offset:704
	v_readlane_b32 s60, v255, 2
	v_readlane_b32 s61, v255, 3
	v_readlane_b32 s36, v255, 29
	v_readlane_b32 s37, v255, 30
	v_readlane_b32 s62, v255, 4
	v_readlane_b32 s63, v255, 5
	v_lshlrev_b64 v[132:133], 2, v[144:145]
	v_mul_u32_u24_e32 v146, 0x1600, v169
	v_mov_b32_e32 v147, 0
	v_mov_b32_e32 v149, 0
	v_lshl_add_u64 v[154:155], s[60:61], 0, v[132:133]
	v_lshl_add_u64 v[222:223], s[36:37], 0, v[132:133]
	v_lshl_add_u64 v[224:225], s[16:17], 0, v[132:133]
	v_lshl_add_u64 v[226:227], s[62:63], 0, v[132:133]
	global_load_dwordx4 v[174:177], v[154:155], off
	global_load_dwordx4 v[178:181], v[222:223], off
	global_load_dwordx4 v[182:185], v[224:225], off
	global_load_dwordx4 v[186:189], v[226:227], off
	v_cmp_eq_u32_e64 s[48:49], 0, v169
	v_cmp_gt_u32_e64 s[50:51], 2, v169
	v_cmp_eq_u32_e64 s[52:53], 15, v169
	v_cmp_lt_u32_e64 s[54:55], 13, v169
	v_add_u32_e32 v148, 0xfffef800, v146
	s_mov_b32 s0, 0x3e6d3388
	s_mov_b32 s12, 0x3f07dc22
	s_mov_b32 s14, 0x3f35f0e3
	s_mov_b32 s56, 0xbe11a98e
	s_mov_b32 s92, 0x3e027906
	s_mov_b32 s94, 0xbf38aa3b
	v_mov_b32_e32 v152, 0xbf3a00e3
	s_mov_b32 s44, 0xb0000
	s_mov_b32 s45, 0
	s_mov_b32 s46, 0x16000
	s_mov_b32 s47, 0
	s_mul_i32 s91, s89, 0x58000
	s_add_u32 s42, s20, s91
	s_addc_u32 s43, s21, 0
	v_lshl_add_u64 v[150:151], v[146:147], 0, s[42:43]
	v_lshl_add_u64 v[150:151], v[144:145], 1, v[150:151]
	s_waitcnt vmcnt(11)
	v_fmamk_f32 v156, v156, 0x3a800000, v210
	s_waitcnt vmcnt(10)
	v_fmamk_f32 v158, v158, 0x3a800000, v210
	s_waitcnt vmcnt(9)
	v_fmamk_f32 v160, v160, 0x3a800000, v210
	s_waitcnt vmcnt(8)
	v_fmamk_f32 v164, v164, 0x3a800000, v210
	s_waitcnt vmcnt(7)
	v_fmamk_f32 v166, v166, 0x3a800000, v210
	s_waitcnt vmcnt(6)
	v_fmamk_f32 v170, v170, 0x3a800000, v210
	s_waitcnt vmcnt(5)
	v_fmamk_f32 v172, v172, 0x3a800000, v210
	s_waitcnt vmcnt(4)
	v_fmamk_f32 v194, v194, 0x3a800000, v210
	v_cmp_gt_f32_e64 s[60:61], s30, v156
	v_mul_f32_e32 v157, 0x4b800000, v156
	v_cmp_gt_f32_e64 s[62:63], s30, v158
	v_mul_f32_e32 v159, 0x4b800000, v158
	v_cmp_gt_f32_e64 s[64:65], s30, v160
	v_mul_f32_e32 v161, 0x4b800000, v160
	v_cmp_gt_f32_e64 s[66:67], s30, v164
	v_mul_f32_e32 v165, 0x4b800000, v164
	v_cmp_gt_f32_e64 s[68:69], s30, v166
	v_mul_f32_e32 v167, 0x4b800000, v166
	v_cmp_gt_f32_e64 s[70:71], s30, v170
	v_mul_f32_e32 v171, 0x4b800000, v170
	v_cmp_gt_f32_e64 s[72:73], s30, v172
	v_mul_f32_e32 v173, 0x4b800000, v172
	v_cmp_gt_f32_e64 s[74:75], s30, v194
	v_mul_f32_e32 v195, 0x4b800000, v194
	v_cndmask_b32_e64 v156, v156, v157, s[60:61]
	v_cndmask_b32_e64 v158, v158, v159, s[62:63]
	v_cndmask_b32_e64 v160, v160, v161, s[64:65]
	v_cndmask_b32_e64 v164, v164, v165, s[66:67]
	v_cndmask_b32_e64 v166, v166, v167, s[68:69]
	v_cndmask_b32_e64 v170, v170, v171, s[70:71]
	v_cndmask_b32_e64 v172, v172, v173, s[72:73]
	v_cndmask_b32_e64 v194, v194, v195, s[74:75]
	v_rsq_f32_e32 v156, v156
	v_rsq_f32_e32 v158, v158
	v_rsq_f32_e32 v160, v160
	v_rsq_f32_e32 v164, v164
	v_rsq_f32_e32 v166, v166
	v_rsq_f32_e32 v170, v170
	v_rsq_f32_e32 v172, v172
	v_rsq_f32_e32 v194, v194
	v_mul_f32_e32 v157, 0x45800000, v156
	v_mul_f32_e32 v159, 0x45800000, v158
	v_mul_f32_e32 v161, 0x45800000, v160
	v_mul_f32_e32 v165, 0x45800000, v164
	v_mul_f32_e32 v167, 0x45800000, v166
	v_mul_f32_e32 v171, 0x45800000, v170
	v_mul_f32_e32 v173, 0x45800000, v172
	v_mul_f32_e32 v195, 0x45800000, v194
	v_cndmask_b32_e64 v156, v156, v157, s[60:61]
	v_cndmask_b32_e64 v158, v158, v159, s[62:63]
	v_cndmask_b32_e64 v160, v160, v161, s[64:65]
	v_cndmask_b32_e64 v164, v164, v165, s[66:67]
	v_cndmask_b32_e64 v166, v166, v167, s[68:69]
	v_cndmask_b32_e64 v170, v170, v171, s[70:71]
	v_cndmask_b32_e64 v172, v172, v173, s[72:73]
	v_cndmask_b32_e64 v194, v194, v195, s[74:75]
	v_pk_mul_f32 v[122:123], v[122:123], v[156:157] op_sel_hi:[1,0]
	v_pk_mul_f32 v[124:125], v[124:125], v[156:157] op_sel_hi:[1,0]
	v_pk_mul_f32 v[126:127], v[126:127], v[156:157] op_sel_hi:[1,0]
	v_pk_mul_f32 v[128:129], v[128:129], v[156:157] op_sel_hi:[1,0]
	v_pk_mul_f32 v[118:119], v[118:119], v[158:159] op_sel_hi:[1,0]
	v_pk_mul_f32 v[120:121], v[120:121], v[158:159] op_sel_hi:[1,0]
	v_pk_mul_f32 v[114:115], v[114:115], v[158:159] op_sel_hi:[1,0]
	v_pk_mul_f32 v[116:117], v[116:117], v[158:159] op_sel_hi:[1,0]
	v_pk_mul_f32 v[110:111], v[110:111], v[160:161] op_sel_hi:[1,0]
	v_pk_mul_f32 v[112:113], v[112:113], v[160:161] op_sel_hi:[1,0]
	v_pk_mul_f32 v[106:107], v[106:107], v[160:161] op_sel_hi:[1,0]
	v_pk_mul_f32 v[108:109], v[108:109], v[160:161] op_sel_hi:[1,0]
	v_pk_mul_f32 v[102:103], v[102:103], v[164:165] op_sel_hi:[1,0]
	v_pk_mul_f32 v[104:105], v[104:105], v[164:165] op_sel_hi:[1,0]
	v_pk_mul_f32 v[98:99], v[98:99], v[164:165] op_sel_hi:[1,0]
	v_pk_mul_f32 v[100:101], v[100:101], v[164:165] op_sel_hi:[1,0]
	v_mov_b64_e32 v[154:155], v[150:151]
	v_mov_b32_e32 v190, 0
	v_mov_b32_e32 v191, 0
	v_mov_b32_e32 v192, 0
	v_mov_b32_e32 v193, 0
	v_mov_b32_dpp v204, v118 row_ror:15 row_mask:0xf bank_mask:0xf
	v_mov_b32_dpp v205, v119 row_ror:15 row_mask:0xf bank_mask:0xf
	v_mov_b32_dpp v206, v120 row_ror:15 row_mask:0xf bank_mask:0xf
	v_mov_b32_dpp v207, v121 row_ror:15 row_mask:0xf bank_mask:0xf
	v_mov_b32_dpp v190, v122 row_shr:1 row_mask:0xf bank_mask:0xf
	v_mov_b32_dpp v191, v123 row_shr:1 row_mask:0xf bank_mask:0xf
	v_mov_b32_dpp v192, v124 row_shr:1 row_mask:0xf bank_mask:0xf
	v_mov_b32_dpp v193, v125 row_shr:1 row_mask:0xf bank_mask:0xf
	v_mov_b32_dpp v204, v122 row_shl:1 row_mask:0xf bank_mask:0xf
	v_mov_b32_dpp v205, v123 row_shl:1 row_mask:0xf bank_mask:0xf
	v_mov_b32_dpp v206, v124 row_shl:1 row_mask:0xf bank_mask:0xf
	v_mov_b32_dpp v207, v125 row_shl:1 row_mask:0xf bank_mask:0xf
	s_waitcnt vmcnt(2)
; __device__ __forceinline__ f32x2 gelu_pk(f32x2 v) {
;     const f32x2 av = __builtin_elementwise_abs(v), d = av * 0.2316418882f + 1.0f;
;     f32x2 t; t.x = __builtin_amdgcn_rcpf(d.x); t.y = __builtin_amdgcn_rcpf(d.y);
;     f32x2 q = t * 0.5307027145f + (-0.7265760135f); q = q * t + 0.7107068705f; q = q * t + (-0.142248368f); q = q * t + 0.127414796f; q = q * t;
;     const f32x2 s = (v * v) * (-0.72134752044f);
;     f32x2 e; e.x = __builtin_amdgcn_exp2f(s.x); e.y = __builtin_amdgcn_exp2f(s.y);
;     const f32x2 m = v * (q * e), r = v - m;
;     f32x2 o; o.x = v.x < 0.f ? m.x : r.x; o.y = v.y < 0.f ? m.y : r.y; return o;
;     __device__ __forceinline__ void operator()(AccT& acc, const Unit& u, int wr, int wc, int fr, int fq) const {
;     ...
;             for (int n = 0; n < 2; ++n) {
;                 const f32x4 w0 = *(const f32x4*)(cw + fcol + 4 * n), w1 = *(const f32x4*)(cw + DFF + fcol + 4 * n), w2 = *(const f32x4*)(cw + 2 * DFF + fcol + 4 * n), b = *(const f32x4*)(cb + fcol + 4 * n);
; #pragma unroll
;                 for (int m = 0; m < 4; ++m) { const int lr = m * 16 + fr;
;                     const f32x4 gc = acc[ai][0][m][n], up = acc[ai][1][m][n]; f32x4 uu;
; #pragma unroll
;                     for (int j = 0; j < 4; ++j) { const float gp = dppf_prev(gc[j], m > 0 ? acc[ai][0][m - 1][n][j] : 0.f), gn = dppf_next(gc[j], m < 3 ? acc[ai][0][m + 1][n][j] : 0.f);
;                         uu[j] = gp * w0[j] + gc[j] * w1[j] + gn * w2[j] + b[j]; }
;                     const f32x2 ga = gelu_pk((f32x2){uu[0], uu[1]}), gb = gelu_pk((f32x2){uu[2], uu[3]});
;                     u32x2 wa; wa.x = cvt_pk_bf16(ga.x * up[0], ga.y * up[1]); wa.y = cvt_pk_bf16(gb.x * up[2], gb.y * up[3]);
;                     *(u32x2*)(ACT + (size_t)(gidx * 64 + lr) * DFF + fcol + 4 * n) = wa;
;                     if (m == 0 || m == 3) {
;                         if (lr == 0 || lr == 63) { u32x2 wu; wu.x = cvt_pk_bf16(up[0], up[1]); wu.y = cvt_pk_bf16(up[2], up[3]); *(u32x2*)(UP + (size_t)(gidx * 2 + (lr == 63 ? 1 : 0)) * DFF + fcol + 4 * n) = wu; }
;                         if (lr < 2 || lr > 61) { u32x2 wg; wg.x = cvt_pk_bf16(gc[0], gc[1]); wg.y = cvt_pk_bf16(gc[2], gc[3]); *(u32x2*)(GR + (size_t)(gidx * 4 + (lr < 2 ? lr : lr - 60)) * DFF + fcol + 4 * n) = wg; } } } }
	v_pk_mul_f32 v[130:131], v[178:179], v[122:123]
	v_pk_mul_f32 v[132:133], v[180:181], v[124:125]
	v_pk_fma_f32 v[130:131], v[174:175], v[190:191], v[130:131]
	v_pk_fma_f32 v[132:133], v[176:177], v[192:193], v[132:133]
	s_waitcnt vmcnt(1)
	v_pk_fma_f32 v[130:131], v[182:183], v[204:205], v[130:131]
	v_pk_fma_f32 v[132:133], v[184:185], v[206:207], v[132:133]
	s_waitcnt vmcnt(0)
	v_pk_add_f32 v[130:131], v[186:187], v[130:131]
	v_pk_add_f32 v[132:133], v[188:189], v[132:133]
	v_cmp_gt_f32_e64 s[60:61], 0, v130
	v_cmp_gt_f32_e64 s[62:63], 0, v131
	v_cmp_gt_f32_e64 s[64:65], 0, v132
	v_cmp_gt_f32_e64 s[66:67], 0, v133
	v_and_b32_e32 v222, 0x7fffffff, v130
	v_and_b32_e32 v223, 0x7fffffff, v131
	v_and_b32_e32 v228, 0x7fffffff, v132
	v_and_b32_e32 v229, 0x7fffffff, v133
	v_pk_fma_f32 v[222:223], v[222:223], s[0:1], 1.0 op_sel_hi:[1,0,0]
	v_pk_fma_f32 v[228:229], v[228:229], s[0:1], 1.0 op_sel_hi:[1,0,0]
	v_pk_mul_f32 v[226:227], v[130:131], v[130:131]
	v_pk_mul_f32 v[232:233], v[132:133], v[132:133]
	v_rcp_f32_e32 v222, v222
	v_rcp_f32_e32 v223, v223
	v_rcp_f32_e32 v228, v228
	v_rcp_f32_e32 v229, v229
	v_pk_mul_f32 v[226:227], v[226:227], s[94:95] op_sel_hi:[1,0]
	v_pk_mul_f32 v[232:233], v[232:233], s[94:95] op_sel_hi:[1,0]
	v_pk_fma_f32 v[224:225], v[222:223], s[12:13], v[152:153] op_sel_hi:[1,0,0]
	v_pk_fma_f32 v[230:231], v[228:229], s[12:13], v[152:153] op_sel_hi:[1,0,0]
	v_exp_f32_e32 v226, v226
	v_exp_f32_e32 v227, v227
	v_exp_f32_e32 v232, v232
	v_exp_f32_e32 v233, v233
	v_pk_fma_f32 v[224:225], v[222:223], v[224:225], s[14:15] op_sel_hi:[1,1,0]
	v_pk_fma_f32 v[230:231], v[228:229], v[230:231], s[14:15] op_sel_hi:[1,1,0]
	v_pk_fma_f32 v[224:225], v[222:223], v[224:225], s[56:57] op_sel_hi:[1,1,0]
	v_pk_fma_f32 v[230:231], v[228:229], v[230:231], s[56:57] op_sel_hi:[1,1,0]
	v_pk_fma_f32 v[224:225], v[222:223], v[224:225], s[92:93] op_sel_hi:[1,1,0]
	v_pk_fma_f32 v[230:231], v[228:229], v[230:231], s[92:93] op_sel_hi:[1,1,0]
	v_pk_mul_f32 v[224:225], v[222:223], v[224:225]
	v_pk_mul_f32 v[230:231], v[228:229], v[230:231]
	v_pk_mul_f32 v[224:225], v[226:227], v[224:225]
	v_pk_mul_f32 v[230:231], v[232:233], v[230:231]
	v_pk_mul_f32 v[226:227], v[130:131], v[224:225]
	v_pk_mul_f32 v[232:233], v[132:133], v[230:231]
	v_pk_fma_f32 v[224:225], v[130:131], v[224:225], v[130:131] neg_lo:[1,0,0] neg_hi:[1,0,0]
	v_pk_fma_f32 v[230:231], v[132:133], v[230:231], v[132:133] neg_lo:[1,0,0] neg_hi:[1,0,0]
	v_cndmask_b32_e64 v130, v224, v226, s[60:61]
	v_cndmask_b32_e64 v131, v225, v227, s[62:63]
	v_cndmask_b32_e64 v132, v230, v232, s[64:65]
	v_cndmask_b32_e64 v133, v231, v233, s[66:67]
	v_mul_f32_e32 v130, v126, v130
	v_mul_f32_e32 v131, v127, v131
	v_mul_f32_e32 v132, v128, v132
	v_mul_f32_e32 v133, v129, v133
	v_cvt_pk_bf16_f32 v200, v130, v131
	v_cvt_pk_bf16_f32 v201, v132, v133
	global_store_dwordx2 v[154:155], v[200:201], off
	v_lshl_add_u64 v[154:155], v[154:155], 0, s[46:47]
	s_add_i32 s90, s89, 0
	s_mul_i32 s91, s90, 0x5800
	s_add_u32 s36, s6, s91
	s_addc_u32 s37, s7, 0
	s_mul_i32 s91, s90, 0x2c00
	s_add_u32 s42, s8, s91
	s_addc_u32 s43, s9, 0
	v_lshl_add_u64 v[222:223], v[146:147], 0, s[36:37]
	v_lshl_add_u64 v[224:225], v[144:145], 1, s[42:43]
	v_lshl_add_u64 v[222:223], v[144:145], 1, v[222:223]
	s_mov_b64 exec, s[50:51]
	v_cvt_pk_bf16_f32 v226, v122, v123
	v_cvt_pk_bf16_f32 v227, v124, v125
	global_store_dwordx2 v[222:223], v[226:227], off
	s_mov_b64 exec, s[48:49]
	v_cvt_pk_bf16_f32 v228, v126, v127
	v_cvt_pk_bf16_f32 v229, v128, v129
	global_store_dwordx2 v[224:225], v[228:229], off
	s_mov_b64 exec, -1
	v_mov_b32_dpp v190, v122 row_ror:1 row_mask:0xf bank_mask:0xf
	v_mov_b32_dpp v191, v123 row_ror:1 row_mask:0xf bank_mask:0xf
	v_mov_b32_dpp v192, v124 row_ror:1 row_mask:0xf bank_mask:0xf
	v_mov_b32_dpp v193, v125 row_ror:1 row_mask:0xf bank_mask:0xf
	v_mov_b32_dpp v204, v110 row_ror:15 row_mask:0xf bank_mask:0xf
	v_mov_b32_dpp v205, v111 row_ror:15 row_mask:0xf bank_mask:0xf
	v_mov_b32_dpp v206, v112 row_ror:15 row_mask:0xf bank_mask:0xf
	v_mov_b32_dpp v207, v113 row_ror:15 row_mask:0xf bank_mask:0xf
	v_mov_b32_dpp v190, v118 row_shr:1 row_mask:0xf bank_mask:0xf
	v_mov_b32_dpp v191, v119 row_shr:1 row_mask:0xf bank_mask:0xf
	v_mov_b32_dpp v192, v120 row_shr:1 row_mask:0xf bank_mask:0xf
	v_mov_b32_dpp v193, v121 row_shr:1 row_mask:0xf bank_mask:0xf
	v_mov_b32_dpp v204, v118 row_shl:1 row_mask:0xf bank_mask:0xf
	v_mov_b32_dpp v205, v119 row_shl:1 row_mask:0xf bank_mask:0xf
	v_mov_b32_dpp v206, v120 row_shl:1 row_mask:0xf bank_mask:0xf
	v_mov_b32_dpp v207, v121 row_shl:1 row_mask:0xf bank_mask:0xf
	v_pk_mul_f32 v[130:131], v[178:179], v[118:119]
	v_pk_mul_f32 v[132:133], v[180:181], v[120:121]
	v_pk_fma_f32 v[130:131], v[174:175], v[190:191], v[130:131]
	v_pk_fma_f32 v[132:133], v[176:177], v[192:193], v[132:133]
	v_pk_fma_f32 v[130:131], v[182:183], v[204:205], v[130:131]
	v_pk_fma_f32 v[132:133], v[184:185], v[206:207], v[132:133]
	v_pk_add_f32 v[130:131], v[186:187], v[130:131]
	v_pk_add_f32 v[132:133], v[188:189], v[132:133]
	v_cmp_gt_f32_e64 s[60:61], 0, v130
	v_cmp_gt_f32_e64 s[62:63], 0, v131
	v_cmp_gt_f32_e64 s[64:65], 0, v132
	v_cmp_gt_f32_e64 s[66:67], 0, v133
	v_and_b32_e32 v222, 0x7fffffff, v130
	v_and_b32_e32 v223, 0x7fffffff, v131
	v_and_b32_e32 v228, 0x7fffffff, v132
	v_and_b32_e32 v229, 0x7fffffff, v133
	v_pk_fma_f32 v[222:223], v[222:223], s[0:1], 1.0 op_sel_hi:[1,0,0]
	v_pk_fma_f32 v[228:229], v[228:229], s[0:1], 1.0 op_sel_hi:[1,0,0]
	v_pk_mul_f32 v[226:227], v[130:131], v[130:131]
	v_pk_mul_f32 v[232:233], v[132:133], v[132:133]
	v_rcp_f32_e32 v222, v222
	v_rcp_f32_e32 v223, v223
	v_rcp_f32_e32 v228, v228
; __device__ __forceinline__ unsigned cvt_pk_bf16(float lo, float hi) { unsigned r; asm volatile("v_cvt_pk_bf16_f32 %0, %1, %2" : "=v"(r) : "v"(lo), "v"(hi)); return r; }
; __device__ __forceinline__ float dppf_prev(float cur, float below) { return __uint_as_float(dpp_prev(__float_as_uint(cur), __float_as_uint(below))); }
; __device__ __forceinline__ float dppf_next(float cur, float above) { return __uint_as_float(dpp_next(__float_as_uint(cur), __float_as_uint(above))); }
; __device__ __forceinline__ f32x2 gelu_pk(f32x2 v) {
;     const f32x2 av = __builtin_elementwise_abs(v), d = av * 0.2316418882f + 1.0f;
;     f32x2 t; t.x = __builtin_amdgcn_rcpf(d.x); t.y = __builtin_amdgcn_rcpf(d.y);
;     f32x2 q = t * 0.5307027145f + (-0.7265760135f); q = q * t + 0.7107068705f; q = q * t + (-0.142248368f); q = q * t + 0.127414796f; q = q * t;
;     const f32x2 s = (v * v) * (-0.72134752044f);
;     f32x2 e; e.x = __builtin_amdgcn_exp2f(s.x); e.y = __builtin_amdgcn_exp2f(s.y);
;     const f32x2 m = v * (q * e), r = v - m;
;     f32x2 o; o.x = v.x < 0.f ? m.x : r.x; o.y = v.y < 0.f ? m.y : r.y; return o;
;     __device__ __forceinline__ void operator()(AccT& acc, const Unit& u, int wr, int wc, int fr, int fq) const {
;     ...
;             for (int n = 0; n < 2; ++n) {
;                 const f32x4 w0 = *(const f32x4*)(cw + fcol + 4 * n), w1 = *(const f32x4*)(cw + DFF + fcol + 4 * n), w2 = *(const f32x4*)(cw + 2 * DFF + fcol + 4 * n), b = *(const f32x4*)(cb + fcol + 4 * n);
; #pragma unroll
;                 for (int m = 0; m < 4; ++m) { const int lr = m * 16 + fr;
;                     const f32x4 gc = acc[ai][0][m][n], up = acc[ai][1][m][n]; f32x4 uu;
; #pragma unroll
;                     for (int j = 0; j < 4; ++j) { const float gp = dppf_prev(gc[j], m > 0 ? acc[ai][0][m - 1][n][j] : 0.f), gn = dppf_next(gc[j], m < 3 ? acc[ai][0][m + 1][n][j] : 0.f);
;                         uu[j] = gp * w0[j] + gc[j] * w1[j] + gn * w2[j] + b[j]; }
;                     const f32x2 ga = gelu_pk((f32x2){uu[0], uu[1]}), gb = gelu_pk((f32x2){uu[2], uu[3]});
;                     u32x2 wa; wa.x = cvt_pk_bf16(ga.x * up[0], ga.y * up[1]); wa.y = cvt_pk_bf16(gb.x * up[2], gb.y * up[3]);
;                     *(u32x2*)(ACT + (size_t)(gidx * 64 + lr) * DFF + fcol + 4 * n) = wa;
	v_rcp_f32_e32 v229, v229
	v_pk_mul_f32 v[226:227], v[226:227], s[94:95] op_sel_hi:[1,0]
	v_pk_mul_f32 v[232:233], v[232:233], s[94:95] op_sel_hi:[1,0]
	v_pk_fma_f32 v[224:225], v[222:223], s[12:13], v[152:153] op_sel_hi:[1,0,0]
	v_pk_fma_f32 v[230:231], v[228:229], s[12:13], v[152:153] op_sel_hi:[1,0,0]
	v_exp_f32_e32 v226, v226
	v_exp_f32_e32 v227, v227
	v_exp_f32_e32 v232, v232
	v_exp_f32_e32 v233, v233
	v_pk_fma_f32 v[224:225], v[222:223], v[224:225], s[14:15] op_sel_hi:[1,1,0]
	v_pk_fma_f32 v[230:231], v[228:229], v[230:231], s[14:15] op_sel_hi:[1,1,0]
	v_pk_fma_f32 v[224:225], v[222:223], v[224:225], s[56:57] op_sel_hi:[1,1,0]
	v_pk_fma_f32 v[230:231], v[228:229], v[230:231], s[56:57] op_sel_hi:[1,1,0]
	v_pk_fma_f32 v[224:225], v[222:223], v[224:225], s[92:93] op_sel_hi:[1,1,0]
	v_pk_fma_f32 v[230:231], v[228:229], v[230:231], s[92:93] op_sel_hi:[1,1,0]
	v_pk_mul_f32 v[224:225], v[222:223], v[224:225]
	v_pk_mul_f32 v[230:231], v[228:229], v[230:231]
	v_pk_mul_f32 v[224:225], v[226:227], v[224:225]
	v_pk_mul_f32 v[230:231], v[232:233], v[230:231]
	v_pk_mul_f32 v[226:227], v[130:131], v[224:225]
	v_pk_mul_f32 v[232:233], v[132:133], v[230:231]
	v_pk_fma_f32 v[224:225], v[130:131], v[224:225], v[130:131] neg_lo:[1,0,0] neg_hi:[1,0,0]
	v_pk_fma_f32 v[230:231], v[132:133], v[230:231], v[132:133] neg_lo:[1,0,0] neg_hi:[1,0,0]
	v_cndmask_b32_e64 v130, v224, v226, s[60:61]
	v_cndmask_b32_e64 v131, v225, v227, s[62:63]
	v_cndmask_b32_e64 v132, v230, v232, s[64:65]
	v_cndmask_b32_e64 v133, v231, v233, s[66:67]
	v_mul_f32_e32 v130, v114, v130
	v_mul_f32_e32 v131, v115, v131
	v_mul_f32_e32 v132, v116, v132
	v_mul_f32_e32 v133, v117, v133
	v_cvt_pk_bf16_f32 v200, v130, v131
	v_cvt_pk_bf16_f32 v201, v132, v133
	global_store_dwordx2 v[154:155], v[200:201], off
	v_lshl_add_u64 v[154:155], v[154:155], 0, s[46:47]
	v_mov_b32_dpp v190, v118 row_ror:1 row_mask:0xf bank_mask:0xf
	v_mov_b32_dpp v191, v119 row_ror:1 row_mask:0xf bank_mask:0xf
	v_mov_b32_dpp v192, v120 row_ror:1 row_mask:0xf bank_mask:0xf
	v_mov_b32_dpp v193, v121 row_ror:1 row_mask:0xf bank_mask:0xf
	v_mov_b32_dpp v204, v102 row_ror:15 row_mask:0xf bank_mask:0xf
	v_mov_b32_dpp v205, v103 row_ror:15 row_mask:0xf bank_mask:0xf
	v_mov_b32_dpp v206, v104 row_ror:15 row_mask:0xf bank_mask:0xf
	v_mov_b32_dpp v207, v105 row_ror:15 row_mask:0xf bank_mask:0xf
	v_mov_b32_dpp v190, v110 row_shr:1 row_mask:0xf bank_mask:0xf
	v_mov_b32_dpp v191, v111 row_shr:1 row_mask:0xf bank_mask:0xf
	v_mov_b32_dpp v192, v112 row_shr:1 row_mask:0xf bank_mask:0xf
	v_mov_b32_dpp v193, v113 row_shr:1 row_mask:0xf bank_mask:0xf
	v_mov_b32_dpp v204, v110 row_shl:1 row_mask:0xf bank_mask:0xf
	v_mov_b32_dpp v205, v111 row_shl:1 row_mask:0xf bank_mask:0xf
	v_mov_b32_dpp v206, v112 row_shl:1 row_mask:0xf bank_mask:0xf
	v_mov_b32_dpp v207, v113 row_shl:1 row_mask:0xf bank_mask:0xf
	v_pk_mul_f32 v[130:131], v[178:179], v[110:111]
	v_pk_mul_f32 v[132:133], v[180:181], v[112:113]
	v_pk_fma_f32 v[130:131], v[174:175], v[190:191], v[130:131]
	v_pk_fma_f32 v[132:133], v[176:177], v[192:193], v[132:133]
	v_pk_fma_f32 v[130:131], v[182:183], v[204:205], v[130:131]
	v_pk_fma_f32 v[132:133], v[184:185], v[206:207], v[132:133]
	v_pk_add_f32 v[130:131], v[186:187], v[130:131]
	v_pk_add_f32 v[132:133], v[188:189], v[132:133]
	v_cmp_gt_f32_e64 s[60:61], 0, v130
	v_cmp_gt_f32_e64 s[62:63], 0, v131
	v_cmp_gt_f32_e64 s[64:65], 0, v132
	v_cmp_gt_f32_e64 s[66:67], 0, v133
	v_and_b32_e32 v222, 0x7fffffff, v130
	v_and_b32_e32 v223, 0x7fffffff, v131
	v_and_b32_e32 v228, 0x7fffffff, v132
	v_and_b32_e32 v229, 0x7fffffff, v133
	v_pk_fma_f32 v[222:223], v[222:223], s[0:1], 1.0 op_sel_hi:[1,0,0]
	v_pk_fma_f32 v[228:229], v[228:229], s[0:1], 1.0 op_sel_hi:[1,0,0]
	v_pk_mul_f32 v[226:227], v[130:131], v[130:131]
	v_pk_mul_f32 v[232:233], v[132:133], v[132:133]
	v_rcp_f32_e32 v222, v222
	v_rcp_f32_e32 v223, v223
	v_rcp_f32_e32 v228, v228
	v_rcp_f32_e32 v229, v229
	v_pk_mul_f32 v[226:227], v[226:227], s[94:95] op_sel_hi:[1,0]
	v_pk_mul_f32 v[232:233], v[232:233], s[94:95] op_sel_hi:[1,0]
	v_pk_fma_f32 v[224:225], v[222:223], s[12:13], v[152:153] op_sel_hi:[1,0,0]
	v_pk_fma_f32 v[230:231], v[228:229], s[12:13], v[152:153] op_sel_hi:[1,0,0]
	v_exp_f32_e32 v226, v226
	v_exp_f32_e32 v227, v227
	v_exp_f32_e32 v232, v232
	v_exp_f32_e32 v233, v233
	v_pk_fma_f32 v[224:225], v[222:223], v[224:225], s[14:15] op_sel_hi:[1,1,0]
	v_pk_fma_f32 v[230:231], v[228:229], v[230:231], s[14:15] op_sel_hi:[1,1,0]
	v_pk_fma_f32 v[224:225], v[222:223], v[224:225], s[56:57] op_sel_hi:[1,1,0]
	v_pk_fma_f32 v[230:231], v[228:229], v[230:231], s[56:57] op_sel_hi:[1,1,0]
	v_pk_fma_f32 v[224:225], v[222:223], v[224:225], s[92:93] op_sel_hi:[1,1,0]
	v_pk_fma_f32 v[230:231], v[228:229], v[230:231], s[92:93] op_sel_hi:[1,1,0]
	v_pk_mul_f32 v[224:225], v[222:223], v[224:225]
	v_pk_mul_f32 v[230:231], v[228:229], v[230:231]
	v_pk_mul_f32 v[224:225], v[226:227], v[224:225]
	v_pk_mul_f32 v[230:231], v[232:233], v[230:231]
	v_pk_mul_f32 v[226:227], v[130:131], v[224:225]
	v_pk_mul_f32 v[232:233], v[132:133], v[230:231]
	v_pk_fma_f32 v[224:225], v[130:131], v[224:225], v[130:131] neg_lo:[1,0,0] neg_hi:[1,0,0]
	v_pk_fma_f32 v[230:231], v[132:133], v[230:231], v[132:133] neg_lo:[1,0,0] neg_hi:[1,0,0]
	v_cndmask_b32_e64 v130, v224, v226, s[60:61]
	v_cndmask_b32_e64 v131, v225, v227, s[62:63]
	v_cndmask_b32_e64 v132, v230, v232, s[64:65]
	v_cndmask_b32_e64 v133, v231, v233, s[66:67]
	v_mul_f32_e32 v130, v106, v130
	v_mul_f32_e32 v131, v107, v131
	v_mul_f32_e32 v132, v108, v132
	v_mul_f32_e32 v133, v109, v133
	v_cvt_pk_bf16_f32 v200, v130, v131
	v_cvt_pk_bf16_f32 v201, v132, v133
; __device__ __forceinline__ unsigned cvt_pk_bf16(float lo, float hi) { unsigned r; asm volatile("v_cvt_pk_bf16_f32 %0, %1, %2" : "=v"(r) : "v"(lo), "v"(hi)); return r; }
; __device__ __forceinline__ float dppf_prev(float cur, float below) { return __uint_as_float(dpp_prev(__float_as_uint(cur), __float_as_uint(below))); }
; __device__ __forceinline__ float dppf_next(float cur, float above) { return __uint_as_float(dpp_next(__float_as_uint(cur), __float_as_uint(above))); }
;     __device__ __forceinline__ void operator()(AccT& acc, const Unit& u, int wr, int wc, int fr, int fq) const {
;     ...
;             for (int m = 0; m < 4; ++m) { const float rstd = rsqrtf(rss[half * HALF_TOK + gidx * 64 + m * 16 + fr] * (1.0f / DM) + 1e-6f);
; #pragma unroll
;                 for (int n = 0; n < 2; ++n) { acc[ai][0][m][n] = acc[ai][0][m][n] * rstd; acc[ai][1][m][n] = acc[ai][1][m][n] * rstd; } }
;     ...
;                 for (int m = 0; m < 4; ++m) { const int lr = m * 16 + fr;
;                     const f32x4 gc = acc[ai][0][m][n], up = acc[ai][1][m][n]; f32x4 uu;
; #pragma unroll
;                     for (int j = 0; j < 4; ++j) { const float gp = dppf_prev(gc[j], m > 0 ? acc[ai][0][m - 1][n][j] : 0.f), gn = dppf_next(gc[j], m < 3 ? acc[ai][0][m + 1][n][j] : 0.f);
;                         uu[j] = gp * w0[j] + gc[j] * w1[j] + gn * w2[j] + b[j]; }
;                     const f32x2 ga = gelu_pk((f32x2){uu[0], uu[1]}), gb = gelu_pk((f32x2){uu[2], uu[3]});
;                     u32x2 wa; wa.x = cvt_pk_bf16(ga.x * up[0], ga.y * up[1]); wa.y = cvt_pk_bf16(gb.x * up[2], gb.y * up[3]);
;                     *(u32x2*)(ACT + (size_t)(gidx * 64 + lr) * DFF + fcol + 4 * n) = wa;
;                     if (m == 0 || m == 3) {
;                         if (lr == 0 || lr == 63) { u32x2 wu; wu.x = cvt_pk_bf16(up[0], up[1]); wu.y = cvt_pk_bf16(up[2], up[3]); *(u32x2*)(UP + (size_t)(gidx * 2 + (lr == 63 ? 1 : 0)) * DFF + fcol + 4 * n) = wu; }
;                         if (lr < 2 || lr > 61) { u32x2 wg; wg.x = cvt_pk_bf16(gc[0], gc[1]); wg.y = cvt_pk_bf16(gc[2], gc[3]); *(u32x2*)(GR + (size_t)(gidx * 4 + (lr < 2 ? lr : lr - 60)) * DFF + fcol + 4 * n) = wg; } } } }
	global_store_dwordx2 v[154:155], v[200:201], off
	v_lshl_add_u64 v[154:155], v[154:155], 0, s[46:47]
	v_mov_b32_dpp v190, v110 row_ror:1 row_mask:0xf bank_mask:0xf
	v_mov_b32_dpp v191, v111 row_ror:1 row_mask:0xf bank_mask:0xf
	v_mov_b32_dpp v192, v112 row_ror:1 row_mask:0xf bank_mask:0xf
	v_mov_b32_dpp v193, v113 row_ror:1 row_mask:0xf bank_mask:0xf
	v_mov_b32_e32 v204, 0
	v_mov_b32_e32 v205, 0
	v_mov_b32_e32 v206, 0
	v_mov_b32_e32 v207, 0
	v_mov_b32_dpp v190, v102 row_shr:1 row_mask:0xf bank_mask:0xf
	v_mov_b32_dpp v191, v103 row_shr:1 row_mask:0xf bank_mask:0xf
	v_mov_b32_dpp v192, v104 row_shr:1 row_mask:0xf bank_mask:0xf
	v_mov_b32_dpp v193, v105 row_shr:1 row_mask:0xf bank_mask:0xf
	v_mov_b32_dpp v204, v102 row_shl:1 row_mask:0xf bank_mask:0xf
	v_mov_b32_dpp v205, v103 row_shl:1 row_mask:0xf bank_mask:0xf
	v_mov_b32_dpp v206, v104 row_shl:1 row_mask:0xf bank_mask:0xf
	v_mov_b32_dpp v207, v105 row_shl:1 row_mask:0xf bank_mask:0xf
	v_pk_mul_f32 v[130:131], v[178:179], v[102:103]
	v_pk_mul_f32 v[132:133], v[180:181], v[104:105]
	v_pk_fma_f32 v[130:131], v[174:175], v[190:191], v[130:131]
	v_pk_fma_f32 v[132:133], v[176:177], v[192:193], v[132:133]
	v_pk_fma_f32 v[130:131], v[182:183], v[204:205], v[130:131]
	v_pk_fma_f32 v[132:133], v[184:185], v[206:207], v[132:133]
	v_pk_add_f32 v[130:131], v[186:187], v[130:131]
	v_pk_add_f32 v[132:133], v[188:189], v[132:133]
	v_cmp_gt_f32_e64 s[60:61], 0, v130
	v_cmp_gt_f32_e64 s[62:63], 0, v131
	v_cmp_gt_f32_e64 s[64:65], 0, v132
	v_cmp_gt_f32_e64 s[66:67], 0, v133
	v_and_b32_e32 v222, 0x7fffffff, v130
	v_and_b32_e32 v223, 0x7fffffff, v131
	v_and_b32_e32 v228, 0x7fffffff, v132
	v_and_b32_e32 v229, 0x7fffffff, v133
	v_pk_fma_f32 v[222:223], v[222:223], s[0:1], 1.0 op_sel_hi:[1,0,0]
	v_pk_fma_f32 v[228:229], v[228:229], s[0:1], 1.0 op_sel_hi:[1,0,0]
	v_pk_mul_f32 v[226:227], v[130:131], v[130:131]
	v_pk_mul_f32 v[232:233], v[132:133], v[132:133]
	v_rcp_f32_e32 v222, v222
	v_rcp_f32_e32 v223, v223
	v_rcp_f32_e32 v228, v228
	v_rcp_f32_e32 v229, v229
	v_pk_mul_f32 v[226:227], v[226:227], s[94:95] op_sel_hi:[1,0]
	v_pk_mul_f32 v[232:233], v[232:233], s[94:95] op_sel_hi:[1,0]
	v_pk_fma_f32 v[224:225], v[222:223], s[12:13], v[152:153] op_sel_hi:[1,0,0]
	v_pk_fma_f32 v[230:231], v[228:229], s[12:13], v[152:153] op_sel_hi:[1,0,0]
	v_exp_f32_e32 v226, v226
	v_exp_f32_e32 v227, v227
	v_exp_f32_e32 v232, v232
	v_exp_f32_e32 v233, v233
	v_pk_fma_f32 v[224:225], v[222:223], v[224:225], s[14:15] op_sel_hi:[1,1,0]
	v_pk_fma_f32 v[230:231], v[228:229], v[230:231], s[14:15] op_sel_hi:[1,1,0]
	v_pk_fma_f32 v[224:225], v[222:223], v[224:225], s[56:57] op_sel_hi:[1,1,0]
	v_pk_fma_f32 v[230:231], v[228:229], v[230:231], s[56:57] op_sel_hi:[1,1,0]
	v_pk_fma_f32 v[224:225], v[222:223], v[224:225], s[92:93] op_sel_hi:[1,1,0]
	v_pk_fma_f32 v[230:231], v[228:229], v[230:231], s[92:93] op_sel_hi:[1,1,0]
	v_pk_mul_f32 v[224:225], v[222:223], v[224:225]
	v_pk_mul_f32 v[230:231], v[228:229], v[230:231]
	v_pk_mul_f32 v[224:225], v[226:227], v[224:225]
	v_pk_mul_f32 v[230:231], v[232:233], v[230:231]
	v_pk_mul_f32 v[226:227], v[130:131], v[224:225]
	v_pk_mul_f32 v[232:233], v[132:133], v[230:231]
	v_pk_fma_f32 v[224:225], v[130:131], v[224:225], v[130:131] neg_lo:[1,0,0] neg_hi:[1,0,0]
	v_pk_fma_f32 v[230:231], v[132:133], v[230:231], v[132:133] neg_lo:[1,0,0] neg_hi:[1,0,0]
	v_cndmask_b32_e64 v130, v224, v226, s[60:61]
	v_cndmask_b32_e64 v131, v225, v227, s[62:63]
	v_cndmask_b32_e64 v132, v230, v232, s[64:65]
	v_cndmask_b32_e64 v133, v231, v233, s[66:67]
	v_mul_f32_e32 v130, v98, v130
	v_mul_f32_e32 v131, v99, v131
	v_mul_f32_e32 v132, v100, v132
	v_mul_f32_e32 v133, v101, v133
	v_cvt_pk_bf16_f32 v200, v130, v131
	v_cvt_pk_bf16_f32 v201, v132, v133
	global_store_dwordx2 v[154:155], v[200:201], off
	s_add_i32 s90, s89, 0
	s_mul_i32 s91, s90, 0x5800
	s_add_u32 s36, s6, s91
	s_addc_u32 s37, s7, 0
	s_mul_i32 s91, s90, 0x2c00
	s_add_i32 s91, s91, 0x1600
	s_add_u32 s42, s8, s91
	s_addc_u32 s43, s9, 0
	v_lshl_add_u64 v[222:223], v[148:149], 0, s[36:37]
	v_lshl_add_u64 v[224:225], v[144:145], 1, s[42:43]
	v_lshl_add_u64 v[222:223], v[144:145], 1, v[222:223]
	s_mov_b64 exec, s[54:55]
	v_cvt_pk_bf16_f32 v226, v102, v103
	v_cvt_pk_bf16_f32 v227, v104, v105
	global_store_dwordx2 v[222:223], v[226:227], off
	s_mov_b64 exec, s[52:53]
	v_cvt_pk_bf16_f32 v228, v98, v99
	v_cvt_pk_bf16_f32 v229, v100, v101
	global_store_dwordx2 v[224:225], v[228:229], off
	s_mov_b64 exec, -1
	v_pk_mul_f32 v[62:63], v[62:63], v[166:167] op_sel_hi:[1,0]
	v_pk_mul_f32 v[64:65], v[64:65], v[166:167] op_sel_hi:[1,0]
	v_pk_mul_f32 v[58:59], v[58:59], v[166:167] op_sel_hi:[1,0]
	v_pk_mul_f32 v[60:61], v[60:61], v[166:167] op_sel_hi:[1,0]
	v_pk_mul_f32 v[54:55], v[54:55], v[170:171] op_sel_hi:[1,0]
	v_pk_mul_f32 v[56:57], v[56:57], v[170:171] op_sel_hi:[1,0]
	v_pk_mul_f32 v[50:51], v[50:51], v[170:171] op_sel_hi:[1,0]
	v_pk_mul_f32 v[52:53], v[52:53], v[170:171] op_sel_hi:[1,0]
	v_pk_mul_f32 v[46:47], v[46:47], v[172:173] op_sel_hi:[1,0]
	v_pk_mul_f32 v[48:49], v[48:49], v[172:173] op_sel_hi:[1,0]
	v_pk_mul_f32 v[42:43], v[42:43], v[172:173] op_sel_hi:[1,0]
	v_pk_mul_f32 v[44:45], v[44:45], v[172:173] op_sel_hi:[1,0]
	v_pk_mul_f32 v[38:39], v[38:39], v[194:195] op_sel_hi:[1,0]
	v_pk_mul_f32 v[40:41], v[40:41], v[194:195] op_sel_hi:[1,0]
	v_pk_mul_f32 v[34:35], v[34:35], v[194:195] op_sel_hi:[1,0]
	v_pk_mul_f32 v[36:37], v[36:37], v[194:195] op_sel_hi:[1,0]
	v_readlane_b32 s36, v255, 2
	v_readlane_b32 s37, v255, 3
	v_readlane_b32 s42, v255, 29
	v_readlane_b32 s43, v255, 30
	v_readlane_b32 s90, v255, 4
	v_readlane_b32 s91, v255, 5
	v_lshlrev_b64 v[132:133], 2, v[144:145]
; __device__ __forceinline__ unsigned cvt_pk_bf16(float lo, float hi) { unsigned r; asm volatile("v_cvt_pk_bf16_f32 %0, %1, %2" : "=v"(r) : "v"(lo), "v"(hi)); return r; }
; __device__ __forceinline__ float dppf_prev(float cur, float below) { return __uint_as_float(dpp_prev(__float_as_uint(cur), __float_as_uint(below))); }
; __device__ __forceinline__ float dppf_next(float cur, float above) { return __uint_as_float(dpp_next(__float_as_uint(cur), __float_as_uint(above))); }
;     __device__ __forceinline__ void operator()(AccT& acc, const Unit& u, int wr, int wc, int fr, int fq) const {
;     ...
;             for (int n = 0; n < 2; ++n) {
;                 const f32x4 w0 = *(const f32x4*)(cw + fcol + 4 * n), w1 = *(const f32x4*)(cw + DFF + fcol + 4 * n), w2 = *(const f32x4*)(cw + 2 * DFF + fcol + 4 * n), b = *(const f32x4*)(cb + fcol + 4 * n);
; #pragma unroll
;                 for (int m = 0; m < 4; ++m) { const int lr = m * 16 + fr;
;                     const f32x4 gc = acc[ai][0][m][n], up = acc[ai][1][m][n]; f32x4 uu;
; #pragma unroll
;                     for (int j = 0; j < 4; ++j) { const float gp = dppf_prev(gc[j], m > 0 ? acc[ai][0][m - 1][n][j] : 0.f), gn = dppf_next(gc[j], m < 3 ? acc[ai][0][m + 1][n][j] : 0.f);
;                         uu[j] = gp * w0[j] + gc[j] * w1[j] + gn * w2[j] + b[j]; }
;                     const f32x2 ga = gelu_pk((f32x2){uu[0], uu[1]}), gb = gelu_pk((f32x2){uu[2], uu[3]});
;                     u32x2 wa; wa.x = cvt_pk_bf16(ga.x * up[0], ga.y * up[1]); wa.y = cvt_pk_bf16(gb.x * up[2], gb.y * up[3]);
;                     *(u32x2*)(ACT + (size_t)(gidx * 64 + lr) * DFF + fcol + 4 * n) = wa;
;                     if (m == 0 || m == 3) {
;                         if (lr == 0 || lr == 63) { u32x2 wu; wu.x = cvt_pk_bf16(up[0], up[1]); wu.y = cvt_pk_bf16(up[2], up[3]); *(u32x2*)(UP + (size_t)(gidx * 2 + (lr == 63 ? 1 : 0)) * DFF + fcol + 4 * n) = wu; }
;                         if (lr < 2 || lr > 61) { u32x2 wg; wg.x = cvt_pk_bf16(gc[0], gc[1]); wg.y = cvt_pk_bf16(gc[2], gc[3]); *(u32x2*)(GR + (size_t)(gidx * 4 + (lr < 2 ? lr : lr - 60)) * DFF + fcol + 4 * n) = wg; } } } }
	s_nop 0
	v_lshl_add_u64 v[222:223], s[36:37], 0, v[132:133]
	v_lshl_add_u64 v[224:225], s[42:43], 0, v[132:133]
	v_lshl_add_u64 v[226:227], s[16:17], 0, v[132:133]
	v_lshl_add_u64 v[228:229], s[90:91], 0, v[132:133]
	global_load_dwordx4 v[122:125], v[222:223], off offset:16
	global_load_dwordx4 v[118:121], v[224:225], off offset:16
	global_load_dwordx4 v[110:113], v[226:227], off offset:16
	global_load_dwordx4 v[102:105], v[228:229], off offset:16
	v_lshl_add_u64 v[154:155], v[150:151], 0, s[44:45]
	v_mov_b32_e32 v190, 0
	v_mov_b32_e32 v191, 0
	v_mov_b32_e32 v192, 0
	v_mov_b32_e32 v193, 0
	v_mov_b32_dpp v204, v54 row_ror:15 row_mask:0xf bank_mask:0xf
	v_mov_b32_dpp v205, v55 row_ror:15 row_mask:0xf bank_mask:0xf
	v_mov_b32_dpp v206, v56 row_ror:15 row_mask:0xf bank_mask:0xf
	v_mov_b32_dpp v207, v57 row_ror:15 row_mask:0xf bank_mask:0xf
	v_mov_b32_dpp v190, v62 row_shr:1 row_mask:0xf bank_mask:0xf
	v_mov_b32_dpp v191, v63 row_shr:1 row_mask:0xf bank_mask:0xf
	v_mov_b32_dpp v192, v64 row_shr:1 row_mask:0xf bank_mask:0xf
	v_mov_b32_dpp v193, v65 row_shr:1 row_mask:0xf bank_mask:0xf
	v_mov_b32_dpp v204, v62 row_shl:1 row_mask:0xf bank_mask:0xf
	v_mov_b32_dpp v205, v63 row_shl:1 row_mask:0xf bank_mask:0xf
	v_mov_b32_dpp v206, v64 row_shl:1 row_mask:0xf bank_mask:0xf
	v_mov_b32_dpp v207, v65 row_shl:1 row_mask:0xf bank_mask:0xf
	v_pk_mul_f32 v[130:131], v[178:179], v[62:63]
	v_pk_mul_f32 v[132:133], v[180:181], v[64:65]
	v_pk_fma_f32 v[130:131], v[174:175], v[190:191], v[130:131]
	v_pk_fma_f32 v[132:133], v[176:177], v[192:193], v[132:133]
	v_pk_fma_f32 v[130:131], v[182:183], v[204:205], v[130:131]
	v_pk_fma_f32 v[132:133], v[184:185], v[206:207], v[132:133]
	v_pk_add_f32 v[130:131], v[186:187], v[130:131]
	v_pk_add_f32 v[132:133], v[188:189], v[132:133]
	v_cmp_gt_f32_e64 s[60:61], 0, v130
	v_cmp_gt_f32_e64 s[62:63], 0, v131
	v_cmp_gt_f32_e64 s[64:65], 0, v132
	v_cmp_gt_f32_e64 s[66:67], 0, v133
	v_and_b32_e32 v222, 0x7fffffff, v130
	v_and_b32_e32 v223, 0x7fffffff, v131
	v_and_b32_e32 v228, 0x7fffffff, v132
	v_and_b32_e32 v229, 0x7fffffff, v133
	v_pk_fma_f32 v[222:223], v[222:223], s[0:1], 1.0 op_sel_hi:[1,0,0]
	v_pk_fma_f32 v[228:229], v[228:229], s[0:1], 1.0 op_sel_hi:[1,0,0]
	v_pk_mul_f32 v[226:227], v[130:131], v[130:131]
	v_pk_mul_f32 v[232:233], v[132:133], v[132:133]
	v_rcp_f32_e32 v222, v222
	v_rcp_f32_e32 v223, v223
	v_rcp_f32_e32 v228, v228
	v_rcp_f32_e32 v229, v229
	v_pk_mul_f32 v[226:227], v[226:227], s[94:95] op_sel_hi:[1,0]
	v_pk_mul_f32 v[232:233], v[232:233], s[94:95] op_sel_hi:[1,0]
	v_pk_fma_f32 v[224:225], v[222:223], s[12:13], v[152:153] op_sel_hi:[1,0,0]
	v_pk_fma_f32 v[230:231], v[228:229], s[12:13], v[152:153] op_sel_hi:[1,0,0]
	v_exp_f32_e32 v226, v226
	v_exp_f32_e32 v227, v227
	v_exp_f32_e32 v232, v232
	v_exp_f32_e32 v233, v233
	v_pk_fma_f32 v[224:225], v[222:223], v[224:225], s[14:15] op_sel_hi:[1,1,0]
	v_pk_fma_f32 v[230:231], v[228:229], v[230:231], s[14:15] op_sel_hi:[1,1,0]
	v_pk_fma_f32 v[224:225], v[222:223], v[224:225], s[56:57] op_sel_hi:[1,1,0]
	v_pk_fma_f32 v[230:231], v[228:229], v[230:231], s[56:57] op_sel_hi:[1,1,0]
	v_pk_fma_f32 v[224:225], v[222:223], v[224:225], s[92:93] op_sel_hi:[1,1,0]
	v_pk_fma_f32 v[230:231], v[228:229], v[230:231], s[92:93] op_sel_hi:[1,1,0]
	v_pk_mul_f32 v[224:225], v[222:223], v[224:225]
	v_pk_mul_f32 v[230:231], v[228:229], v[230:231]
	v_pk_mul_f32 v[224:225], v[226:227], v[224:225]
	v_pk_mul_f32 v[230:231], v[232:233], v[230:231]
	v_pk_mul_f32 v[226:227], v[130:131], v[224:225]
	v_pk_mul_f32 v[232:233], v[132:133], v[230:231]
	v_pk_fma_f32 v[224:225], v[130:131], v[224:225], v[130:131] neg_lo:[1,0,0] neg_hi:[1,0,0]
	v_pk_fma_f32 v[230:231], v[132:133], v[230:231], v[132:133] neg_lo:[1,0,0] neg_hi:[1,0,0]
	v_cndmask_b32_e64 v130, v224, v226, s[60:61]
	v_cndmask_b32_e64 v131, v225, v227, s[62:63]
	v_cndmask_b32_e64 v132, v230, v232, s[64:65]
	v_cndmask_b32_e64 v133, v231, v233, s[66:67]
	v_mul_f32_e32 v130, v58, v130
	v_mul_f32_e32 v131, v59, v131
	v_mul_f32_e32 v132, v60, v132
	v_mul_f32_e32 v133, v61, v133
	v_cvt_pk_bf16_f32 v200, v130, v131
	v_cvt_pk_bf16_f32 v201, v132, v133
	global_store_dwordx2 v[154:155], v[200:201], off
	v_lshl_add_u64 v[154:155], v[154:155], 0, s[46:47]
	s_add_i32 s90, s89, 2
	s_mul_i32 s91, s90, 0x5800
	s_add_u32 s36, s6, s91
	s_addc_u32 s37, s7, 0
	s_mul_i32 s91, s90, 0x2c00
	s_add_u32 s42, s8, s91
	s_addc_u32 s43, s9, 0
	v_lshl_add_u64 v[222:223], v[146:147], 0, s[36:37]
	v_lshl_add_u64 v[224:225], v[144:145], 1, s[42:43]
	v_lshl_add_u64 v[222:223], v[144:145], 1, v[222:223]
	s_mov_b64 exec, s[50:51]
	v_cvt_pk_bf16_f32 v226, v62, v63
	v_cvt_pk_bf16_f32 v227, v64, v65
	global_store_dwordx2 v[222:223], v[226:227], off
	s_mov_b64 exec, s[48:49]
	v_cvt_pk_bf16_f32 v228, v58, v59
	v_cvt_pk_bf16_f32 v229, v60, v61
	global_store_dwordx2 v[224:225], v[228:229], off
	s_mov_b64 exec, -1
	v_mov_b32_dpp v190, v62 row_ror:1 row_mask:0xf bank_mask:0xf
	v_mov_b32_dpp v191, v63 row_ror:1 row_mask:0xf bank_mask:0xf
	v_mov_b32_dpp v192, v64 row_ror:1 row_mask:0xf bank_mask:0xf
	v_mov_b32_dpp v193, v65 row_ror:1 row_mask:0xf bank_mask:0xf
	v_mov_b32_dpp v204, v46 row_ror:15 row_mask:0xf bank_mask:0xf
	v_mov_b32_dpp v205, v47 row_ror:15 row_mask:0xf bank_mask:0xf
	v_mov_b32_dpp v206, v48 row_ror:15 row_mask:0xf bank_mask:0xf
	v_mov_b32_dpp v207, v49 row_ror:15 row_mask:0xf bank_mask:0xf
	v_mov_b32_dpp v190, v54 row_shr:1 row_mask:0xf bank_mask:0xf
	v_mov_b32_dpp v191, v55 row_shr:1 row_mask:0xf bank_mask:0xf
	v_mov_b32_dpp v192, v56 row_shr:1 row_mask:0xf bank_mask:0xf
	v_mov_b32_dpp v193, v57 row_shr:1 row_mask:0xf bank_mask:0xf
	v_mov_b32_dpp v204, v54 row_shl:1 row_mask:0xf bank_mask:0xf
; __device__ __forceinline__ unsigned cvt_pk_bf16(float lo, float hi) { unsigned r; asm volatile("v_cvt_pk_bf16_f32 %0, %1, %2" : "=v"(r) : "v"(lo), "v"(hi)); return r; }
; __device__ __forceinline__ float dppf_prev(float cur, float below) { return __uint_as_float(dpp_prev(__float_as_uint(cur), __float_as_uint(below))); }
; __device__ __forceinline__ float dppf_next(float cur, float above) { return __uint_as_float(dpp_next(__float_as_uint(cur), __float_as_uint(above))); }
; __device__ __forceinline__ f32x2 gelu_pk(f32x2 v) {
;     const f32x2 av = __builtin_elementwise_abs(v), d = av * 0.2316418882f + 1.0f;
;     f32x2 t; t.x = __builtin_amdgcn_rcpf(d.x); t.y = __builtin_amdgcn_rcpf(d.y);
;     f32x2 q = t * 0.5307027145f + (-0.7265760135f); q = q * t + 0.7107068705f; q = q * t + (-0.142248368f); q = q * t + 0.127414796f; q = q * t;
;     const f32x2 s = (v * v) * (-0.72134752044f);
;     f32x2 e; e.x = __builtin_amdgcn_exp2f(s.x); e.y = __builtin_amdgcn_exp2f(s.y);
;     const f32x2 m = v * (q * e), r = v - m;
;     f32x2 o; o.x = v.x < 0.f ? m.x : r.x; o.y = v.y < 0.f ? m.y : r.y; return o;
;     __device__ __forceinline__ void operator()(AccT& acc, const Unit& u, int wr, int wc, int fr, int fq) const {
;     ...
;                 for (int m = 0; m < 4; ++m) { const int lr = m * 16 + fr;
;                     const f32x4 gc = acc[ai][0][m][n], up = acc[ai][1][m][n]; f32x4 uu;
; #pragma unroll
;                     for (int j = 0; j < 4; ++j) { const float gp = dppf_prev(gc[j], m > 0 ? acc[ai][0][m - 1][n][j] : 0.f), gn = dppf_next(gc[j], m < 3 ? acc[ai][0][m + 1][n][j] : 0.f);
;                         uu[j] = gp * w0[j] + gc[j] * w1[j] + gn * w2[j] + b[j]; }
;                     const f32x2 ga = gelu_pk((f32x2){uu[0], uu[1]}), gb = gelu_pk((f32x2){uu[2], uu[3]});
;                     u32x2 wa; wa.x = cvt_pk_bf16(ga.x * up[0], ga.y * up[1]); wa.y = cvt_pk_bf16(gb.x * up[2], gb.y * up[3]);
;                     *(u32x2*)(ACT + (size_t)(gidx * 64 + lr) * DFF + fcol + 4 * n) = wa;
	v_mov_b32_dpp v205, v55 row_shl:1 row_mask:0xf bank_mask:0xf
	v_mov_b32_dpp v206, v56 row_shl:1 row_mask:0xf bank_mask:0xf
	v_mov_b32_dpp v207, v57 row_shl:1 row_mask:0xf bank_mask:0xf
	v_pk_mul_f32 v[130:131], v[178:179], v[54:55]
	v_pk_mul_f32 v[132:133], v[180:181], v[56:57]
	v_pk_fma_f32 v[130:131], v[174:175], v[190:191], v[130:131]
	v_pk_fma_f32 v[132:133], v[176:177], v[192:193], v[132:133]
	v_pk_fma_f32 v[130:131], v[182:183], v[204:205], v[130:131]
	v_pk_fma_f32 v[132:133], v[184:185], v[206:207], v[132:133]
	v_pk_add_f32 v[130:131], v[186:187], v[130:131]
	v_pk_add_f32 v[132:133], v[188:189], v[132:133]
	v_cmp_gt_f32_e64 s[60:61], 0, v130
	v_cmp_gt_f32_e64 s[62:63], 0, v131
	v_cmp_gt_f32_e64 s[64:65], 0, v132
	v_cmp_gt_f32_e64 s[66:67], 0, v133
	v_and_b32_e32 v222, 0x7fffffff, v130
	v_and_b32_e32 v223, 0x7fffffff, v131
	v_and_b32_e32 v228, 0x7fffffff, v132
	v_and_b32_e32 v229, 0x7fffffff, v133
	v_pk_fma_f32 v[222:223], v[222:223], s[0:1], 1.0 op_sel_hi:[1,0,0]
	v_pk_fma_f32 v[228:229], v[228:229], s[0:1], 1.0 op_sel_hi:[1,0,0]
	v_pk_mul_f32 v[226:227], v[130:131], v[130:131]
	v_pk_mul_f32 v[232:233], v[132:133], v[132:133]
	v_rcp_f32_e32 v222, v222
	v_rcp_f32_e32 v223, v223
	v_rcp_f32_e32 v228, v228
	v_rcp_f32_e32 v229, v229
	v_pk_mul_f32 v[226:227], v[226:227], s[94:95] op_sel_hi:[1,0]
	v_pk_mul_f32 v[232:233], v[232:233], s[94:95] op_sel_hi:[1,0]
	v_pk_fma_f32 v[224:225], v[222:223], s[12:13], v[152:153] op_sel_hi:[1,0,0]
	v_pk_fma_f32 v[230:231], v[228:229], s[12:13], v[152:153] op_sel_hi:[1,0,0]
	v_exp_f32_e32 v226, v226
	v_exp_f32_e32 v227, v227
	v_exp_f32_e32 v232, v232
	v_exp_f32_e32 v233, v233
	v_pk_fma_f32 v[224:225], v[222:223], v[224:225], s[14:15] op_sel_hi:[1,1,0]
	v_pk_fma_f32 v[230:231], v[228:229], v[230:231], s[14:15] op_sel_hi:[1,1,0]
	v_pk_fma_f32 v[224:225], v[222:223], v[224:225], s[56:57] op_sel_hi:[1,1,0]
	v_pk_fma_f32 v[230:231], v[228:229], v[230:231], s[56:57] op_sel_hi:[1,1,0]
	v_pk_fma_f32 v[224:225], v[222:223], v[224:225], s[92:93] op_sel_hi:[1,1,0]
	v_pk_fma_f32 v[230:231], v[228:229], v[230:231], s[92:93] op_sel_hi:[1,1,0]
	v_pk_mul_f32 v[224:225], v[222:223], v[224:225]
	v_pk_mul_f32 v[230:231], v[228:229], v[230:231]
	v_pk_mul_f32 v[224:225], v[226:227], v[224:225]
	v_pk_mul_f32 v[230:231], v[232:233], v[230:231]
	v_pk_mul_f32 v[226:227], v[130:131], v[224:225]
	v_pk_mul_f32 v[232:233], v[132:133], v[230:231]
	v_pk_fma_f32 v[224:225], v[130:131], v[224:225], v[130:131] neg_lo:[1,0,0] neg_hi:[1,0,0]
	v_pk_fma_f32 v[230:231], v[132:133], v[230:231], v[132:133] neg_lo:[1,0,0] neg_hi:[1,0,0]
	v_cndmask_b32_e64 v130, v224, v226, s[60:61]
	v_cndmask_b32_e64 v131, v225, v227, s[62:63]
	v_cndmask_b32_e64 v132, v230, v232, s[64:65]
	v_cndmask_b32_e64 v133, v231, v233, s[66:67]
	v_mul_f32_e32 v130, v50, v130
	v_mul_f32_e32 v131, v51, v131
	v_mul_f32_e32 v132, v52, v132
	v_mul_f32_e32 v133, v53, v133
	v_cvt_pk_bf16_f32 v200, v130, v131
	v_cvt_pk_bf16_f32 v201, v132, v133
	global_store_dwordx2 v[154:155], v[200:201], off
	v_lshl_add_u64 v[154:155], v[154:155], 0, s[46:47]
	v_mov_b32_dpp v190, v54 row_ror:1 row_mask:0xf bank_mask:0xf
	v_mov_b32_dpp v191, v55 row_ror:1 row_mask:0xf bank_mask:0xf
	v_mov_b32_dpp v192, v56 row_ror:1 row_mask:0xf bank_mask:0xf
	v_mov_b32_dpp v193, v57 row_ror:1 row_mask:0xf bank_mask:0xf
	v_mov_b32_dpp v204, v38 row_ror:15 row_mask:0xf bank_mask:0xf
	v_mov_b32_dpp v205, v39 row_ror:15 row_mask:0xf bank_mask:0xf
	v_mov_b32_dpp v206, v40 row_ror:15 row_mask:0xf bank_mask:0xf
	v_mov_b32_dpp v207, v41 row_ror:15 row_mask:0xf bank_mask:0xf
	v_mov_b32_dpp v190, v46 row_shr:1 row_mask:0xf bank_mask:0xf
	v_mov_b32_dpp v191, v47 row_shr:1 row_mask:0xf bank_mask:0xf
	v_mov_b32_dpp v192, v48 row_shr:1 row_mask:0xf bank_mask:0xf
	v_mov_b32_dpp v193, v49 row_shr:1 row_mask:0xf bank_mask:0xf
	v_mov_b32_dpp v204, v46 row_shl:1 row_mask:0xf bank_mask:0xf
	v_mov_b32_dpp v205, v47 row_shl:1 row_mask:0xf bank_mask:0xf
	v_mov_b32_dpp v206, v48 row_shl:1 row_mask:0xf bank_mask:0xf
	v_mov_b32_dpp v207, v49 row_shl:1 row_mask:0xf bank_mask:0xf
	v_pk_mul_f32 v[130:131], v[178:179], v[46:47]
	v_pk_mul_f32 v[132:133], v[180:181], v[48:49]
	v_pk_fma_f32 v[130:131], v[174:175], v[190:191], v[130:131]
	v_pk_fma_f32 v[132:133], v[176:177], v[192:193], v[132:133]
	v_pk_fma_f32 v[130:131], v[182:183], v[204:205], v[130:131]
	v_pk_fma_f32 v[132:133], v[184:185], v[206:207], v[132:133]
	v_pk_add_f32 v[130:131], v[186:187], v[130:131]
	v_pk_add_f32 v[132:133], v[188:189], v[132:133]
	v_cmp_gt_f32_e64 s[60:61], 0, v130
	v_cmp_gt_f32_e64 s[62:63], 0, v131
	v_cmp_gt_f32_e64 s[64:65], 0, v132
	v_cmp_gt_f32_e64 s[66:67], 0, v133
	v_and_b32_e32 v222, 0x7fffffff, v130
	v_and_b32_e32 v223, 0x7fffffff, v131
	v_and_b32_e32 v228, 0x7fffffff, v132
	v_and_b32_e32 v229, 0x7fffffff, v133
	v_pk_fma_f32 v[222:223], v[222:223], s[0:1], 1.0 op_sel_hi:[1,0,0]
	v_pk_fma_f32 v[228:229], v[228:229], s[0:1], 1.0 op_sel_hi:[1,0,0]
	v_pk_mul_f32 v[226:227], v[130:131], v[130:131]
	v_pk_mul_f32 v[232:233], v[132:133], v[132:133]
	v_rcp_f32_e32 v222, v222
	v_rcp_f32_e32 v223, v223
	v_rcp_f32_e32 v228, v228
	v_rcp_f32_e32 v229, v229
	v_pk_mul_f32 v[226:227], v[226:227], s[94:95] op_sel_hi:[1,0]
	v_pk_mul_f32 v[232:233], v[232:233], s[94:95] op_sel_hi:[1,0]
	v_pk_fma_f32 v[224:225], v[222:223], s[12:13], v[152:153] op_sel_hi:[1,0,0]
	v_pk_fma_f32 v[230:231], v[228:229], s[12:13], v[152:153] op_sel_hi:[1,0,0]
	v_exp_f32_e32 v226, v226
	v_exp_f32_e32 v227, v227
	v_exp_f32_e32 v232, v232
	v_exp_f32_e32 v233, v233
	v_pk_fma_f32 v[224:225], v[222:223], v[224:225], s[14:15] op_sel_hi:[1,1,0]
	v_pk_fma_f32 v[230:231], v[228:229], v[230:231], s[14:15] op_sel_hi:[1,1,0]
; __device__ __forceinline__ unsigned cvt_pk_bf16(float lo, float hi) { unsigned r; asm volatile("v_cvt_pk_bf16_f32 %0, %1, %2" : "=v"(r) : "v"(lo), "v"(hi)); return r; }
; __device__ __forceinline__ float dppf_prev(float cur, float below) { return __uint_as_float(dpp_prev(__float_as_uint(cur), __float_as_uint(below))); }
; __device__ __forceinline__ float dppf_next(float cur, float above) { return __uint_as_float(dpp_next(__float_as_uint(cur), __float_as_uint(above))); }
;     __device__ __forceinline__ void operator()(AccT& acc, const Unit& u, int wr, int wc, int fr, int fq) const {
;     ...
;                 for (int m = 0; m < 4; ++m) { const int lr = m * 16 + fr;
;                     const f32x4 gc = acc[ai][0][m][n], up = acc[ai][1][m][n]; f32x4 uu;
; #pragma unroll
;                     for (int j = 0; j < 4; ++j) { const float gp = dppf_prev(gc[j], m > 0 ? acc[ai][0][m - 1][n][j] : 0.f), gn = dppf_next(gc[j], m < 3 ? acc[ai][0][m + 1][n][j] : 0.f);
;                         uu[j] = gp * w0[j] + gc[j] * w1[j] + gn * w2[j] + b[j]; }
;                     const f32x2 ga = gelu_pk((f32x2){uu[0], uu[1]}), gb = gelu_pk((f32x2){uu[2], uu[3]});
;                     u32x2 wa; wa.x = cvt_pk_bf16(ga.x * up[0], ga.y * up[1]); wa.y = cvt_pk_bf16(gb.x * up[2], gb.y * up[3]);
;                     *(u32x2*)(ACT + (size_t)(gidx * 64 + lr) * DFF + fcol + 4 * n) = wa;
;                     if (m == 0 || m == 3) {
;                         if (lr == 0 || lr == 63) { u32x2 wu; wu.x = cvt_pk_bf16(up[0], up[1]); wu.y = cvt_pk_bf16(up[2], up[3]); *(u32x2*)(UP + (size_t)(gidx * 2 + (lr == 63 ? 1 : 0)) * DFF + fcol + 4 * n) = wu; }
;                         if (lr < 2 || lr > 61) { u32x2 wg; wg.x = cvt_pk_bf16(gc[0], gc[1]); wg.y = cvt_pk_bf16(gc[2], gc[3]); *(u32x2*)(GR + (size_t)(gidx * 4 + (lr < 2 ? lr : lr - 60)) * DFF + fcol + 4 * n) = wg; } } } }
	v_pk_fma_f32 v[224:225], v[222:223], v[224:225], s[56:57] op_sel_hi:[1,1,0]
	v_pk_fma_f32 v[230:231], v[228:229], v[230:231], s[56:57] op_sel_hi:[1,1,0]
	v_pk_fma_f32 v[224:225], v[222:223], v[224:225], s[92:93] op_sel_hi:[1,1,0]
	v_pk_fma_f32 v[230:231], v[228:229], v[230:231], s[92:93] op_sel_hi:[1,1,0]
	v_pk_mul_f32 v[224:225], v[222:223], v[224:225]
	v_pk_mul_f32 v[230:231], v[228:229], v[230:231]
	v_pk_mul_f32 v[224:225], v[226:227], v[224:225]
	v_pk_mul_f32 v[230:231], v[232:233], v[230:231]
	v_pk_mul_f32 v[226:227], v[130:131], v[224:225]
	v_pk_mul_f32 v[232:233], v[132:133], v[230:231]
	v_pk_fma_f32 v[224:225], v[130:131], v[224:225], v[130:131] neg_lo:[1,0,0] neg_hi:[1,0,0]
	v_pk_fma_f32 v[230:231], v[132:133], v[230:231], v[132:133] neg_lo:[1,0,0] neg_hi:[1,0,0]
	v_cndmask_b32_e64 v130, v224, v226, s[60:61]
	v_cndmask_b32_e64 v131, v225, v227, s[62:63]
	v_cndmask_b32_e64 v132, v230, v232, s[64:65]
	v_cndmask_b32_e64 v133, v231, v233, s[66:67]
	v_mul_f32_e32 v130, v42, v130
	v_mul_f32_e32 v131, v43, v131
	v_mul_f32_e32 v132, v44, v132
	v_mul_f32_e32 v133, v45, v133
	v_cvt_pk_bf16_f32 v200, v130, v131
	v_cvt_pk_bf16_f32 v201, v132, v133
	global_store_dwordx2 v[154:155], v[200:201], off
	v_lshl_add_u64 v[154:155], v[154:155], 0, s[46:47]
	v_mov_b32_dpp v190, v46 row_ror:1 row_mask:0xf bank_mask:0xf
	v_mov_b32_dpp v191, v47 row_ror:1 row_mask:0xf bank_mask:0xf
	v_mov_b32_dpp v192, v48 row_ror:1 row_mask:0xf bank_mask:0xf
	v_mov_b32_dpp v193, v49 row_ror:1 row_mask:0xf bank_mask:0xf
	v_mov_b32_e32 v204, 0
	v_mov_b32_e32 v205, 0
	v_mov_b32_e32 v206, 0
	v_mov_b32_e32 v207, 0
	v_mov_b32_dpp v190, v38 row_shr:1 row_mask:0xf bank_mask:0xf
	v_mov_b32_dpp v191, v39 row_shr:1 row_mask:0xf bank_mask:0xf
	v_mov_b32_dpp v192, v40 row_shr:1 row_mask:0xf bank_mask:0xf
	v_mov_b32_dpp v193, v41 row_shr:1 row_mask:0xf bank_mask:0xf
	v_mov_b32_dpp v204, v38 row_shl:1 row_mask:0xf bank_mask:0xf
	v_mov_b32_dpp v205, v39 row_shl:1 row_mask:0xf bank_mask:0xf
	v_mov_b32_dpp v206, v40 row_shl:1 row_mask:0xf bank_mask:0xf
	v_mov_b32_dpp v207, v41 row_shl:1 row_mask:0xf bank_mask:0xf
	v_pk_mul_f32 v[130:131], v[178:179], v[38:39]
	v_pk_mul_f32 v[132:133], v[180:181], v[40:41]
	v_pk_fma_f32 v[130:131], v[174:175], v[190:191], v[130:131]
	v_pk_fma_f32 v[132:133], v[176:177], v[192:193], v[132:133]
	v_pk_fma_f32 v[130:131], v[182:183], v[204:205], v[130:131]
	v_pk_fma_f32 v[132:133], v[184:185], v[206:207], v[132:133]
	v_pk_add_f32 v[130:131], v[186:187], v[130:131]
	v_pk_add_f32 v[132:133], v[188:189], v[132:133]
	v_cmp_gt_f32_e64 s[60:61], 0, v130
	v_cmp_gt_f32_e64 s[62:63], 0, v131
	v_cmp_gt_f32_e64 s[64:65], 0, v132
	v_cmp_gt_f32_e64 s[66:67], 0, v133
	v_and_b32_e32 v222, 0x7fffffff, v130
	v_and_b32_e32 v223, 0x7fffffff, v131
	v_and_b32_e32 v228, 0x7fffffff, v132
	v_and_b32_e32 v229, 0x7fffffff, v133
	v_pk_fma_f32 v[222:223], v[222:223], s[0:1], 1.0 op_sel_hi:[1,0,0]
	v_pk_fma_f32 v[228:229], v[228:229], s[0:1], 1.0 op_sel_hi:[1,0,0]
	v_pk_mul_f32 v[226:227], v[130:131], v[130:131]
	v_pk_mul_f32 v[232:233], v[132:133], v[132:133]
	v_rcp_f32_e32 v222, v222
	v_rcp_f32_e32 v223, v223
	v_rcp_f32_e32 v228, v228
	v_rcp_f32_e32 v229, v229
	v_pk_mul_f32 v[226:227], v[226:227], s[94:95] op_sel_hi:[1,0]
	v_pk_mul_f32 v[232:233], v[232:233], s[94:95] op_sel_hi:[1,0]
	v_pk_fma_f32 v[224:225], v[222:223], s[12:13], v[152:153] op_sel_hi:[1,0,0]
	v_pk_fma_f32 v[230:231], v[228:229], s[12:13], v[152:153] op_sel_hi:[1,0,0]
	v_exp_f32_e32 v226, v226
	v_exp_f32_e32 v227, v227
	v_exp_f32_e32 v232, v232
	v_exp_f32_e32 v233, v233
	v_pk_fma_f32 v[224:225], v[222:223], v[224:225], s[14:15] op_sel_hi:[1,1,0]
	v_pk_fma_f32 v[230:231], v[228:229], v[230:231], s[14:15] op_sel_hi:[1,1,0]
	v_pk_fma_f32 v[224:225], v[222:223], v[224:225], s[56:57] op_sel_hi:[1,1,0]
	v_pk_fma_f32 v[230:231], v[228:229], v[230:231], s[56:57] op_sel_hi:[1,1,0]
	v_pk_fma_f32 v[224:225], v[222:223], v[224:225], s[92:93] op_sel_hi:[1,1,0]
	v_pk_fma_f32 v[230:231], v[228:229], v[230:231], s[92:93] op_sel_hi:[1,1,0]
	v_pk_mul_f32 v[224:225], v[222:223], v[224:225]
	v_pk_mul_f32 v[230:231], v[228:229], v[230:231]
	v_pk_mul_f32 v[224:225], v[226:227], v[224:225]
	v_pk_mul_f32 v[230:231], v[232:233], v[230:231]
	v_pk_mul_f32 v[226:227], v[130:131], v[224:225]
	v_pk_mul_f32 v[232:233], v[132:133], v[230:231]
	v_pk_fma_f32 v[224:225], v[130:131], v[224:225], v[130:131] neg_lo:[1,0,0] neg_hi:[1,0,0]
	v_pk_fma_f32 v[230:231], v[132:133], v[230:231], v[132:133] neg_lo:[1,0,0] neg_hi:[1,0,0]
	v_cndmask_b32_e64 v130, v224, v226, s[60:61]
	v_cndmask_b32_e64 v131, v225, v227, s[62:63]
	v_cndmask_b32_e64 v132, v230, v232, s[64:65]
	v_cndmask_b32_e64 v133, v231, v233, s[66:67]
	v_mul_f32_e32 v130, v34, v130
	v_mul_f32_e32 v131, v35, v131
	v_mul_f32_e32 v132, v36, v132
	v_mul_f32_e32 v133, v37, v133
	v_cvt_pk_bf16_f32 v200, v130, v131
	v_cvt_pk_bf16_f32 v201, v132, v133
	global_store_dwordx2 v[154:155], v[200:201], off
	s_add_i32 s90, s89, 2
	s_mul_i32 s91, s90, 0x5800
	s_add_u32 s36, s6, s91
	s_addc_u32 s37, s7, 0
	s_mul_i32 s91, s90, 0x2c00
	s_add_i32 s91, s91, 0x1600
	s_add_u32 s42, s8, s91
	s_addc_u32 s43, s9, 0
	v_lshl_add_u64 v[222:223], v[148:149], 0, s[36:37]
	v_lshl_add_u64 v[224:225], v[144:145], 1, s[42:43]
	v_lshl_add_u64 v[222:223], v[144:145], 1, v[222:223]
	s_mov_b64 exec, s[54:55]
	v_cvt_pk_bf16_f32 v226, v38, v39
	v_cvt_pk_bf16_f32 v227, v40, v41
	global_store_dwordx2 v[222:223], v[226:227], off
	s_mov_b64 exec, s[52:53]
	v_cvt_pk_bf16_f32 v228, v34, v35
	v_cvt_pk_bf16_f32 v229, v36, v37
	global_store_dwordx2 v[224:225], v[228:229], off
	s_mov_b64 exec, -1
	v_pk_mul_f32 v[94:95], v[94:95], v[156:157] op_sel_hi:[1,0]
; __device__ __forceinline__ unsigned cvt_pk_bf16(float lo, float hi) { unsigned r; asm volatile("v_cvt_pk_bf16_f32 %0, %1, %2" : "=v"(r) : "v"(lo), "v"(hi)); return r; }
; __device__ __forceinline__ float dppf_prev(float cur, float below) { return __uint_as_float(dpp_prev(__float_as_uint(cur), __float_as_uint(below))); }
; __device__ __forceinline__ float dppf_next(float cur, float above) { return __uint_as_float(dpp_next(__float_as_uint(cur), __float_as_uint(above))); }
;     __device__ __forceinline__ void operator()(AccT& acc, const Unit& u, int wr, int wc, int fr, int fq) const {
;     ...
;             for (int m = 0; m < 4; ++m) { const float rstd = rsqrtf(rss[half * HALF_TOK + gidx * 64 + m * 16 + fr] * (1.0f / DM) + 1e-6f);
; #pragma unroll
;                 for (int n = 0; n < 2; ++n) { acc[ai][0][m][n] = acc[ai][0][m][n] * rstd; acc[ai][1][m][n] = acc[ai][1][m][n] * rstd; } }
; #pragma unroll
;             for (int n = 0; n < 2; ++n) {
;                 const f32x4 w0 = *(const f32x4*)(cw + fcol + 4 * n), w1 = *(const f32x4*)(cw + DFF + fcol + 4 * n), w2 = *(const f32x4*)(cw + 2 * DFF + fcol + 4 * n), b = *(const f32x4*)(cb + fcol + 4 * n);
; #pragma unroll
;                 for (int m = 0; m < 4; ++m) { const int lr = m * 16 + fr;
;                     const f32x4 gc = acc[ai][0][m][n], up = acc[ai][1][m][n]; f32x4 uu;
; #pragma unroll
;                     for (int j = 0; j < 4; ++j) { const float gp = dppf_prev(gc[j], m > 0 ? acc[ai][0][m - 1][n][j] : 0.f), gn = dppf_next(gc[j], m < 3 ? acc[ai][0][m + 1][n][j] : 0.f);
;                         uu[j] = gp * w0[j] + gc[j] * w1[j] + gn * w2[j] + b[j]; }
;                     const f32x2 ga = gelu_pk((f32x2){uu[0], uu[1]}), gb = gelu_pk((f32x2){uu[2], uu[3]});
;                     u32x2 wa; wa.x = cvt_pk_bf16(ga.x * up[0], ga.y * up[1]); wa.y = cvt_pk_bf16(gb.x * up[2], gb.y * up[3]);
;                     *(u32x2*)(ACT + (size_t)(gidx * 64 + lr) * DFF + fcol + 4 * n) = wa;
	v_pk_mul_f32 v[96:97], v[96:97], v[156:157] op_sel_hi:[1,0]
	v_pk_mul_f32 v[90:91], v[90:91], v[156:157] op_sel_hi:[1,0]
	v_pk_mul_f32 v[92:93], v[92:93], v[156:157] op_sel_hi:[1,0]
	v_pk_mul_f32 v[86:87], v[86:87], v[158:159] op_sel_hi:[1,0]
	v_pk_mul_f32 v[88:89], v[88:89], v[158:159] op_sel_hi:[1,0]
	v_pk_mul_f32 v[82:83], v[82:83], v[158:159] op_sel_hi:[1,0]
	v_pk_mul_f32 v[84:85], v[84:85], v[158:159] op_sel_hi:[1,0]
	v_pk_mul_f32 v[78:79], v[78:79], v[160:161] op_sel_hi:[1,0]
	v_pk_mul_f32 v[80:81], v[80:81], v[160:161] op_sel_hi:[1,0]
	v_pk_mul_f32 v[74:75], v[74:75], v[160:161] op_sel_hi:[1,0]
	v_pk_mul_f32 v[76:77], v[76:77], v[160:161] op_sel_hi:[1,0]
	v_pk_mul_f32 v[70:71], v[70:71], v[164:165] op_sel_hi:[1,0]
	v_pk_mul_f32 v[72:73], v[72:73], v[164:165] op_sel_hi:[1,0]
	v_pk_mul_f32 v[66:67], v[66:67], v[164:165] op_sel_hi:[1,0]
	v_pk_mul_f32 v[68:69], v[68:69], v[164:165] op_sel_hi:[1,0]
	v_mov_b64_e32 v[154:155], v[150:151]
	v_mov_b32_e32 v190, 0
	v_mov_b32_e32 v191, 0
	v_mov_b32_e32 v192, 0
	v_mov_b32_e32 v193, 0
	v_mov_b32_dpp v204, v86 row_ror:15 row_mask:0xf bank_mask:0xf
	v_mov_b32_dpp v205, v87 row_ror:15 row_mask:0xf bank_mask:0xf
	v_mov_b32_dpp v206, v88 row_ror:15 row_mask:0xf bank_mask:0xf
	v_mov_b32_dpp v207, v89 row_ror:15 row_mask:0xf bank_mask:0xf
	v_mov_b32_dpp v190, v94 row_shr:1 row_mask:0xf bank_mask:0xf
	v_mov_b32_dpp v191, v95 row_shr:1 row_mask:0xf bank_mask:0xf
	v_mov_b32_dpp v192, v96 row_shr:1 row_mask:0xf bank_mask:0xf
	v_mov_b32_dpp v193, v97 row_shr:1 row_mask:0xf bank_mask:0xf
	v_mov_b32_dpp v204, v94 row_shl:1 row_mask:0xf bank_mask:0xf
	v_mov_b32_dpp v205, v95 row_shl:1 row_mask:0xf bank_mask:0xf
	v_mov_b32_dpp v206, v96 row_shl:1 row_mask:0xf bank_mask:0xf
	v_mov_b32_dpp v207, v97 row_shl:1 row_mask:0xf bank_mask:0xf
	s_waitcnt vmcnt(10)
	v_pk_mul_f32 v[130:131], v[118:119], v[94:95]
	v_pk_mul_f32 v[132:133], v[120:121], v[96:97]
	v_pk_fma_f32 v[130:131], v[122:123], v[190:191], v[130:131]
	v_pk_fma_f32 v[132:133], v[124:125], v[192:193], v[132:133]
	s_waitcnt vmcnt(9)
	v_pk_fma_f32 v[130:131], v[110:111], v[204:205], v[130:131]
	v_pk_fma_f32 v[132:133], v[112:113], v[206:207], v[132:133]
	s_waitcnt vmcnt(8)
	v_pk_add_f32 v[130:131], v[102:103], v[130:131]
	v_pk_add_f32 v[132:133], v[104:105], v[132:133]
	v_cmp_gt_f32_e64 s[60:61], 0, v130
	v_cmp_gt_f32_e64 s[62:63], 0, v131
	v_cmp_gt_f32_e64 s[64:65], 0, v132
	v_cmp_gt_f32_e64 s[66:67], 0, v133
	v_and_b32_e32 v222, 0x7fffffff, v130
	v_and_b32_e32 v223, 0x7fffffff, v131
	v_and_b32_e32 v228, 0x7fffffff, v132
	v_and_b32_e32 v229, 0x7fffffff, v133
	v_pk_fma_f32 v[222:223], v[222:223], s[0:1], 1.0 op_sel_hi:[1,0,0]
	v_pk_fma_f32 v[228:229], v[228:229], s[0:1], 1.0 op_sel_hi:[1,0,0]
	v_pk_mul_f32 v[226:227], v[130:131], v[130:131]
	v_pk_mul_f32 v[232:233], v[132:133], v[132:133]
	v_rcp_f32_e32 v222, v222
	v_rcp_f32_e32 v223, v223
	v_rcp_f32_e32 v228, v228
	v_rcp_f32_e32 v229, v229
	v_pk_mul_f32 v[226:227], v[226:227], s[94:95] op_sel_hi:[1,0]
	v_pk_mul_f32 v[232:233], v[232:233], s[94:95] op_sel_hi:[1,0]
	v_pk_fma_f32 v[224:225], v[222:223], s[12:13], v[152:153] op_sel_hi:[1,0,0]
	v_pk_fma_f32 v[230:231], v[228:229], s[12:13], v[152:153] op_sel_hi:[1,0,0]
	v_exp_f32_e32 v226, v226
	v_exp_f32_e32 v227, v227
	v_exp_f32_e32 v232, v232
	v_exp_f32_e32 v233, v233
	v_pk_fma_f32 v[224:225], v[222:223], v[224:225], s[14:15] op_sel_hi:[1,1,0]
	v_pk_fma_f32 v[230:231], v[228:229], v[230:231], s[14:15] op_sel_hi:[1,1,0]
	v_pk_fma_f32 v[224:225], v[222:223], v[224:225], s[56:57] op_sel_hi:[1,1,0]
	v_pk_fma_f32 v[230:231], v[228:229], v[230:231], s[56:57] op_sel_hi:[1,1,0]
	v_pk_fma_f32 v[224:225], v[222:223], v[224:225], s[92:93] op_sel_hi:[1,1,0]
	v_pk_fma_f32 v[230:231], v[228:229], v[230:231], s[92:93] op_sel_hi:[1,1,0]
	v_pk_mul_f32 v[224:225], v[222:223], v[224:225]
	v_pk_mul_f32 v[230:231], v[228:229], v[230:231]
	v_pk_mul_f32 v[224:225], v[226:227], v[224:225]
	v_pk_mul_f32 v[230:231], v[232:233], v[230:231]
	v_pk_mul_f32 v[226:227], v[130:131], v[224:225]
	v_pk_mul_f32 v[232:233], v[132:133], v[230:231]
	v_pk_fma_f32 v[224:225], v[130:131], v[224:225], v[130:131] neg_lo:[1,0,0] neg_hi:[1,0,0]
	v_pk_fma_f32 v[230:231], v[132:133], v[230:231], v[132:133] neg_lo:[1,0,0] neg_hi:[1,0,0]
	v_cndmask_b32_e64 v130, v224, v226, s[60:61]
	v_cndmask_b32_e64 v131, v225, v227, s[62:63]
	v_cndmask_b32_e64 v132, v230, v232, s[64:65]
	v_cndmask_b32_e64 v133, v231, v233, s[66:67]
	v_mul_f32_e32 v130, v90, v130
	v_mul_f32_e32 v131, v91, v131
	v_mul_f32_e32 v132, v92, v132
	v_mul_f32_e32 v133, v93, v133
	v_cvt_pk_bf16_f32 v200, v130, v131
	v_cvt_pk_bf16_f32 v201, v132, v133
	global_store_dwordx2 v[154:155], v[200:201], off offset:8
	v_lshl_add_u64 v[154:155], v[154:155], 0, s[46:47]
	s_add_i32 s90, s89, 0
	s_mul_i32 s91, s90, 0x5800
	s_add_u32 s36, s6, s91
	s_addc_u32 s37, s7, 0
	s_mul_i32 s91, s90, 0x2c00
	s_add_u32 s42, s8, s91
	s_addc_u32 s43, s9, 0
	v_lshl_add_u64 v[222:223], v[146:147], 0, s[36:37]
	v_lshl_add_u64 v[224:225], v[144:145], 1, s[42:43]
	v_lshl_add_u64 v[222:223], v[144:145], 1, v[222:223]
	s_mov_b64 exec, s[50:51]
	v_cvt_pk_bf16_f32 v226, v94, v95
	v_cvt_pk_bf16_f32 v227, v96, v97
	global_store_dwordx2 v[222:223], v[226:227], off offset:8
	s_mov_b64 exec, s[48:49]
	v_cvt_pk_bf16_f32 v228, v90, v91
	v_cvt_pk_bf16_f32 v229, v92, v93
	global_store_dwordx2 v[224:225], v[228:229], off offset:8
	s_mov_b64 exec, -1
	v_mov_b32_dpp v190, v94 row_ror:1 row_mask:0xf bank_mask:0xf
	v_mov_b32_dpp v191, v95 row_ror:1 row_mask:0xf bank_mask:0xf
	v_mov_b32_dpp v192, v96 row_ror:1 row_mask:0xf bank_mask:0xf
	v_mov_b32_dpp v193, v97 row_ror:1 row_mask:0xf bank_mask:0xf
; __device__ __forceinline__ unsigned cvt_pk_bf16(float lo, float hi) { unsigned r; asm volatile("v_cvt_pk_bf16_f32 %0, %1, %2" : "=v"(r) : "v"(lo), "v"(hi)); return r; }
; __device__ __forceinline__ float dppf_prev(float cur, float below) { return __uint_as_float(dpp_prev(__float_as_uint(cur), __float_as_uint(below))); }
; __device__ __forceinline__ float dppf_next(float cur, float above) { return __uint_as_float(dpp_next(__float_as_uint(cur), __float_as_uint(above))); }
; __device__ __forceinline__ f32x2 gelu_pk(f32x2 v) {
;     const f32x2 av = __builtin_elementwise_abs(v), d = av * 0.2316418882f + 1.0f;
;     f32x2 t; t.x = __builtin_amdgcn_rcpf(d.x); t.y = __builtin_amdgcn_rcpf(d.y);
;     f32x2 q = t * 0.5307027145f + (-0.7265760135f); q = q * t + 0.7107068705f; q = q * t + (-0.142248368f); q = q * t + 0.127414796f; q = q * t;
;     const f32x2 s = (v * v) * (-0.72134752044f);
;     f32x2 e; e.x = __builtin_amdgcn_exp2f(s.x); e.y = __builtin_amdgcn_exp2f(s.y);
;     const f32x2 m = v * (q * e), r = v - m;
;     f32x2 o; o.x = v.x < 0.f ? m.x : r.x; o.y = v.y < 0.f ? m.y : r.y; return o;
;     __device__ __forceinline__ void operator()(AccT& acc, const Unit& u, int wr, int wc, int fr, int fq) const {
;     ...
;                 for (int m = 0; m < 4; ++m) { const int lr = m * 16 + fr;
;                     const f32x4 gc = acc[ai][0][m][n], up = acc[ai][1][m][n]; f32x4 uu;
; #pragma unroll
;                     for (int j = 0; j < 4; ++j) { const float gp = dppf_prev(gc[j], m > 0 ? acc[ai][0][m - 1][n][j] : 0.f), gn = dppf_next(gc[j], m < 3 ? acc[ai][0][m + 1][n][j] : 0.f);
;                         uu[j] = gp * w0[j] + gc[j] * w1[j] + gn * w2[j] + b[j]; }
;                     const f32x2 ga = gelu_pk((f32x2){uu[0], uu[1]}), gb = gelu_pk((f32x2){uu[2], uu[3]});
;                     u32x2 wa; wa.x = cvt_pk_bf16(ga.x * up[0], ga.y * up[1]); wa.y = cvt_pk_bf16(gb.x * up[2], gb.y * up[3]);
;                     *(u32x2*)(ACT + (size_t)(gidx * 64 + lr) * DFF + fcol + 4 * n) = wa;
	v_mov_b32_dpp v204, v78 row_ror:15 row_mask:0xf bank_mask:0xf
	v_mov_b32_dpp v205, v79 row_ror:15 row_mask:0xf bank_mask:0xf
	v_mov_b32_dpp v206, v80 row_ror:15 row_mask:0xf bank_mask:0xf
	v_mov_b32_dpp v207, v81 row_ror:15 row_mask:0xf bank_mask:0xf
	v_mov_b32_dpp v190, v86 row_shr:1 row_mask:0xf bank_mask:0xf
	v_mov_b32_dpp v191, v87 row_shr:1 row_mask:0xf bank_mask:0xf
	v_mov_b32_dpp v192, v88 row_shr:1 row_mask:0xf bank_mask:0xf
	v_mov_b32_dpp v193, v89 row_shr:1 row_mask:0xf bank_mask:0xf
	v_mov_b32_dpp v204, v86 row_shl:1 row_mask:0xf bank_mask:0xf
	v_mov_b32_dpp v205, v87 row_shl:1 row_mask:0xf bank_mask:0xf
	v_mov_b32_dpp v206, v88 row_shl:1 row_mask:0xf bank_mask:0xf
	v_mov_b32_dpp v207, v89 row_shl:1 row_mask:0xf bank_mask:0xf
	v_pk_mul_f32 v[130:131], v[118:119], v[86:87]
	v_pk_mul_f32 v[132:133], v[120:121], v[88:89]
	v_pk_fma_f32 v[130:131], v[122:123], v[190:191], v[130:131]
	v_pk_fma_f32 v[132:133], v[124:125], v[192:193], v[132:133]
	v_pk_fma_f32 v[130:131], v[110:111], v[204:205], v[130:131]
	v_pk_fma_f32 v[132:133], v[112:113], v[206:207], v[132:133]
	v_pk_add_f32 v[130:131], v[102:103], v[130:131]
	v_pk_add_f32 v[132:133], v[104:105], v[132:133]
	v_cmp_gt_f32_e64 s[60:61], 0, v130
	v_cmp_gt_f32_e64 s[62:63], 0, v131
	v_cmp_gt_f32_e64 s[64:65], 0, v132
	v_cmp_gt_f32_e64 s[66:67], 0, v133
	v_and_b32_e32 v222, 0x7fffffff, v130
	v_and_b32_e32 v223, 0x7fffffff, v131
	v_and_b32_e32 v228, 0x7fffffff, v132
	v_and_b32_e32 v229, 0x7fffffff, v133
	v_pk_fma_f32 v[222:223], v[222:223], s[0:1], 1.0 op_sel_hi:[1,0,0]
	v_pk_fma_f32 v[228:229], v[228:229], s[0:1], 1.0 op_sel_hi:[1,0,0]
	v_pk_mul_f32 v[226:227], v[130:131], v[130:131]
	v_pk_mul_f32 v[232:233], v[132:133], v[132:133]
	v_rcp_f32_e32 v222, v222
	v_rcp_f32_e32 v223, v223
	v_rcp_f32_e32 v228, v228
	v_rcp_f32_e32 v229, v229
	v_pk_mul_f32 v[226:227], v[226:227], s[94:95] op_sel_hi:[1,0]
	v_pk_mul_f32 v[232:233], v[232:233], s[94:95] op_sel_hi:[1,0]
	v_pk_fma_f32 v[224:225], v[222:223], s[12:13], v[152:153] op_sel_hi:[1,0,0]
	v_pk_fma_f32 v[230:231], v[228:229], s[12:13], v[152:153] op_sel_hi:[1,0,0]
	v_exp_f32_e32 v226, v226
	v_exp_f32_e32 v227, v227
	v_exp_f32_e32 v232, v232
	v_exp_f32_e32 v233, v233
	v_pk_fma_f32 v[224:225], v[222:223], v[224:225], s[14:15] op_sel_hi:[1,1,0]
	v_pk_fma_f32 v[230:231], v[228:229], v[230:231], s[14:15] op_sel_hi:[1,1,0]
	v_pk_fma_f32 v[224:225], v[222:223], v[224:225], s[56:57] op_sel_hi:[1,1,0]
	v_pk_fma_f32 v[230:231], v[228:229], v[230:231], s[56:57] op_sel_hi:[1,1,0]
	v_pk_fma_f32 v[224:225], v[222:223], v[224:225], s[92:93] op_sel_hi:[1,1,0]
	v_pk_fma_f32 v[230:231], v[228:229], v[230:231], s[92:93] op_sel_hi:[1,1,0]
	v_pk_mul_f32 v[224:225], v[222:223], v[224:225]
	v_pk_mul_f32 v[230:231], v[228:229], v[230:231]
	v_pk_mul_f32 v[224:225], v[226:227], v[224:225]
	v_pk_mul_f32 v[230:231], v[232:233], v[230:231]
	v_pk_mul_f32 v[226:227], v[130:131], v[224:225]
	v_pk_mul_f32 v[232:233], v[132:133], v[230:231]
	v_pk_fma_f32 v[224:225], v[130:131], v[224:225], v[130:131] neg_lo:[1,0,0] neg_hi:[1,0,0]
	v_pk_fma_f32 v[230:231], v[132:133], v[230:231], v[132:133] neg_lo:[1,0,0] neg_hi:[1,0,0]
	v_cndmask_b32_e64 v130, v224, v226, s[60:61]
	v_cndmask_b32_e64 v131, v225, v227, s[62:63]
	v_cndmask_b32_e64 v132, v230, v232, s[64:65]
	v_cndmask_b32_e64 v133, v231, v233, s[66:67]
	v_mul_f32_e32 v130, v82, v130
	v_mul_f32_e32 v131, v83, v131
	v_mul_f32_e32 v132, v84, v132
	v_mul_f32_e32 v133, v85, v133
	v_cvt_pk_bf16_f32 v200, v130, v131
	v_cvt_pk_bf16_f32 v201, v132, v133
	global_store_dwordx2 v[154:155], v[200:201], off offset:8
	v_lshl_add_u64 v[154:155], v[154:155], 0, s[46:47]
	v_mov_b32_dpp v190, v86 row_ror:1 row_mask:0xf bank_mask:0xf
	v_mov_b32_dpp v191, v87 row_ror:1 row_mask:0xf bank_mask:0xf
	v_mov_b32_dpp v192, v88 row_ror:1 row_mask:0xf bank_mask:0xf
	v_mov_b32_dpp v193, v89 row_ror:1 row_mask:0xf bank_mask:0xf
	v_mov_b32_dpp v204, v70 row_ror:15 row_mask:0xf bank_mask:0xf
	v_mov_b32_dpp v205, v71 row_ror:15 row_mask:0xf bank_mask:0xf
	v_mov_b32_dpp v206, v72 row_ror:15 row_mask:0xf bank_mask:0xf
	v_mov_b32_dpp v207, v73 row_ror:15 row_mask:0xf bank_mask:0xf
	v_mov_b32_dpp v190, v78 row_shr:1 row_mask:0xf bank_mask:0xf
	v_mov_b32_dpp v191, v79 row_shr:1 row_mask:0xf bank_mask:0xf
	v_mov_b32_dpp v192, v80 row_shr:1 row_mask:0xf bank_mask:0xf
	v_mov_b32_dpp v193, v81 row_shr:1 row_mask:0xf bank_mask:0xf
	v_mov_b32_dpp v204, v78 row_shl:1 row_mask:0xf bank_mask:0xf
	v_mov_b32_dpp v205, v79 row_shl:1 row_mask:0xf bank_mask:0xf
	v_mov_b32_dpp v206, v80 row_shl:1 row_mask:0xf bank_mask:0xf
	v_mov_b32_dpp v207, v81 row_shl:1 row_mask:0xf bank_mask:0xf
	v_pk_mul_f32 v[130:131], v[118:119], v[78:79]
	v_pk_mul_f32 v[132:133], v[120:121], v[80:81]
	v_pk_fma_f32 v[130:131], v[122:123], v[190:191], v[130:131]
	v_pk_fma_f32 v[132:133], v[124:125], v[192:193], v[132:133]
	v_pk_fma_f32 v[130:131], v[110:111], v[204:205], v[130:131]
	v_pk_fma_f32 v[132:133], v[112:113], v[206:207], v[132:133]
	v_pk_add_f32 v[130:131], v[102:103], v[130:131]
	v_pk_add_f32 v[132:133], v[104:105], v[132:133]
	v_cmp_gt_f32_e64 s[60:61], 0, v130
	v_cmp_gt_f32_e64 s[62:63], 0, v131
	v_cmp_gt_f32_e64 s[64:65], 0, v132
	v_cmp_gt_f32_e64 s[66:67], 0, v133
	v_and_b32_e32 v222, 0x7fffffff, v130
	v_and_b32_e32 v223, 0x7fffffff, v131
	v_and_b32_e32 v228, 0x7fffffff, v132
	v_and_b32_e32 v229, 0x7fffffff, v133
	v_pk_fma_f32 v[222:223], v[222:223], s[0:1], 1.0 op_sel_hi:[1,0,0]
	v_pk_fma_f32 v[228:229], v[228:229], s[0:1], 1.0 op_sel_hi:[1,0,0]
	v_pk_mul_f32 v[226:227], v[130:131], v[130:131]
	v_pk_mul_f32 v[232:233], v[132:133], v[132:133]
	v_rcp_f32_e32 v222, v222
	v_rcp_f32_e32 v223, v223
; __device__ __forceinline__ unsigned cvt_pk_bf16(float lo, float hi) { unsigned r; asm volatile("v_cvt_pk_bf16_f32 %0, %1, %2" : "=v"(r) : "v"(lo), "v"(hi)); return r; }
; __device__ __forceinline__ float dppf_prev(float cur, float below) { return __uint_as_float(dpp_prev(__float_as_uint(cur), __float_as_uint(below))); }
; __device__ __forceinline__ float dppf_next(float cur, float above) { return __uint_as_float(dpp_next(__float_as_uint(cur), __float_as_uint(above))); }
;     __device__ __forceinline__ void operator()(AccT& acc, const Unit& u, int wr, int wc, int fr, int fq) const {
;     ...
;                 for (int m = 0; m < 4; ++m) { const int lr = m * 16 + fr;
;                     const f32x4 gc = acc[ai][0][m][n], up = acc[ai][1][m][n]; f32x4 uu;
; #pragma unroll
;                     for (int j = 0; j < 4; ++j) { const float gp = dppf_prev(gc[j], m > 0 ? acc[ai][0][m - 1][n][j] : 0.f), gn = dppf_next(gc[j], m < 3 ? acc[ai][0][m + 1][n][j] : 0.f);
;                         uu[j] = gp * w0[j] + gc[j] * w1[j] + gn * w2[j] + b[j]; }
;                     const f32x2 ga = gelu_pk((f32x2){uu[0], uu[1]}), gb = gelu_pk((f32x2){uu[2], uu[3]});
;                     u32x2 wa; wa.x = cvt_pk_bf16(ga.x * up[0], ga.y * up[1]); wa.y = cvt_pk_bf16(gb.x * up[2], gb.y * up[3]);
;                     *(u32x2*)(ACT + (size_t)(gidx * 64 + lr) * DFF + fcol + 4 * n) = wa;
;                     if (m == 0 || m == 3) {
;                         if (lr == 0 || lr == 63) { u32x2 wu; wu.x = cvt_pk_bf16(up[0], up[1]); wu.y = cvt_pk_bf16(up[2], up[3]); *(u32x2*)(UP + (size_t)(gidx * 2 + (lr == 63 ? 1 : 0)) * DFF + fcol + 4 * n) = wu; }
;                         if (lr < 2 || lr > 61) { u32x2 wg; wg.x = cvt_pk_bf16(gc[0], gc[1]); wg.y = cvt_pk_bf16(gc[2], gc[3]); *(u32x2*)(GR + (size_t)(gidx * 4 + (lr < 2 ? lr : lr - 60)) * DFF + fcol + 4 * n) = wg; } } } }
	v_rcp_f32_e32 v228, v228
	v_rcp_f32_e32 v229, v229
	v_pk_mul_f32 v[226:227], v[226:227], s[94:95] op_sel_hi:[1,0]
	v_pk_mul_f32 v[232:233], v[232:233], s[94:95] op_sel_hi:[1,0]
	v_pk_fma_f32 v[224:225], v[222:223], s[12:13], v[152:153] op_sel_hi:[1,0,0]
	v_pk_fma_f32 v[230:231], v[228:229], s[12:13], v[152:153] op_sel_hi:[1,0,0]
	v_exp_f32_e32 v226, v226
	v_exp_f32_e32 v227, v227
	v_exp_f32_e32 v232, v232
	v_exp_f32_e32 v233, v233
	v_pk_fma_f32 v[224:225], v[222:223], v[224:225], s[14:15] op_sel_hi:[1,1,0]
	v_pk_fma_f32 v[230:231], v[228:229], v[230:231], s[14:15] op_sel_hi:[1,1,0]
	v_pk_fma_f32 v[224:225], v[222:223], v[224:225], s[56:57] op_sel_hi:[1,1,0]
	v_pk_fma_f32 v[230:231], v[228:229], v[230:231], s[56:57] op_sel_hi:[1,1,0]
	v_pk_fma_f32 v[224:225], v[222:223], v[224:225], s[92:93] op_sel_hi:[1,1,0]
	v_pk_fma_f32 v[230:231], v[228:229], v[230:231], s[92:93] op_sel_hi:[1,1,0]
	v_pk_mul_f32 v[224:225], v[222:223], v[224:225]
	v_pk_mul_f32 v[230:231], v[228:229], v[230:231]
	v_pk_mul_f32 v[224:225], v[226:227], v[224:225]
	v_pk_mul_f32 v[230:231], v[232:233], v[230:231]
	v_pk_mul_f32 v[226:227], v[130:131], v[224:225]
	v_pk_mul_f32 v[232:233], v[132:133], v[230:231]
	v_pk_fma_f32 v[224:225], v[130:131], v[224:225], v[130:131] neg_lo:[1,0,0] neg_hi:[1,0,0]
	v_pk_fma_f32 v[230:231], v[132:133], v[230:231], v[132:133] neg_lo:[1,0,0] neg_hi:[1,0,0]
	v_cndmask_b32_e64 v130, v224, v226, s[60:61]
	v_cndmask_b32_e64 v131, v225, v227, s[62:63]
	v_cndmask_b32_e64 v132, v230, v232, s[64:65]
	v_cndmask_b32_e64 v133, v231, v233, s[66:67]
	v_mul_f32_e32 v130, v74, v130
	v_mul_f32_e32 v131, v75, v131
	v_mul_f32_e32 v132, v76, v132
	v_mul_f32_e32 v133, v77, v133
	v_cvt_pk_bf16_f32 v200, v130, v131
	v_cvt_pk_bf16_f32 v201, v132, v133
	global_store_dwordx2 v[154:155], v[200:201], off offset:8
	v_lshl_add_u64 v[154:155], v[154:155], 0, s[46:47]
	v_mov_b32_dpp v190, v78 row_ror:1 row_mask:0xf bank_mask:0xf
	v_mov_b32_dpp v191, v79 row_ror:1 row_mask:0xf bank_mask:0xf
	v_mov_b32_dpp v192, v80 row_ror:1 row_mask:0xf bank_mask:0xf
	v_mov_b32_dpp v193, v81 row_ror:1 row_mask:0xf bank_mask:0xf
	v_mov_b32_e32 v204, 0
	v_mov_b32_e32 v205, 0
	v_mov_b32_e32 v206, 0
	v_mov_b32_e32 v207, 0
	v_mov_b32_dpp v190, v70 row_shr:1 row_mask:0xf bank_mask:0xf
	v_mov_b32_dpp v191, v71 row_shr:1 row_mask:0xf bank_mask:0xf
	v_mov_b32_dpp v192, v72 row_shr:1 row_mask:0xf bank_mask:0xf
	v_mov_b32_dpp v193, v73 row_shr:1 row_mask:0xf bank_mask:0xf
	v_mov_b32_dpp v204, v70 row_shl:1 row_mask:0xf bank_mask:0xf
	v_mov_b32_dpp v205, v71 row_shl:1 row_mask:0xf bank_mask:0xf
	v_mov_b32_dpp v206, v72 row_shl:1 row_mask:0xf bank_mask:0xf
	v_mov_b32_dpp v207, v73 row_shl:1 row_mask:0xf bank_mask:0xf
	v_pk_mul_f32 v[130:131], v[118:119], v[70:71]
	v_pk_mul_f32 v[132:133], v[120:121], v[72:73]
	v_pk_fma_f32 v[130:131], v[122:123], v[190:191], v[130:131]
	v_pk_fma_f32 v[132:133], v[124:125], v[192:193], v[132:133]
	v_pk_fma_f32 v[130:131], v[110:111], v[204:205], v[130:131]
	v_pk_fma_f32 v[132:133], v[112:113], v[206:207], v[132:133]
	v_pk_add_f32 v[130:131], v[102:103], v[130:131]
	v_pk_add_f32 v[132:133], v[104:105], v[132:133]
	v_cmp_gt_f32_e64 s[60:61], 0, v130
	v_cmp_gt_f32_e64 s[62:63], 0, v131
	v_cmp_gt_f32_e64 s[64:65], 0, v132
	v_cmp_gt_f32_e64 s[66:67], 0, v133
	v_and_b32_e32 v222, 0x7fffffff, v130
	v_and_b32_e32 v223, 0x7fffffff, v131
	v_and_b32_e32 v228, 0x7fffffff, v132
	v_and_b32_e32 v229, 0x7fffffff, v133
	v_pk_fma_f32 v[222:223], v[222:223], s[0:1], 1.0 op_sel_hi:[1,0,0]
	v_pk_fma_f32 v[228:229], v[228:229], s[0:1], 1.0 op_sel_hi:[1,0,0]
	v_pk_mul_f32 v[226:227], v[130:131], v[130:131]
	v_pk_mul_f32 v[232:233], v[132:133], v[132:133]
	v_rcp_f32_e32 v222, v222
	v_rcp_f32_e32 v223, v223
	v_rcp_f32_e32 v228, v228
	v_rcp_f32_e32 v229, v229
	v_pk_mul_f32 v[226:227], v[226:227], s[94:95] op_sel_hi:[1,0]
	v_pk_mul_f32 v[232:233], v[232:233], s[94:95] op_sel_hi:[1,0]
	v_pk_fma_f32 v[224:225], v[222:223], s[12:13], v[152:153] op_sel_hi:[1,0,0]
	v_pk_fma_f32 v[230:231], v[228:229], s[12:13], v[152:153] op_sel_hi:[1,0,0]
	v_exp_f32_e32 v226, v226
	v_exp_f32_e32 v227, v227
	v_exp_f32_e32 v232, v232
	v_exp_f32_e32 v233, v233
	v_pk_fma_f32 v[224:225], v[222:223], v[224:225], s[14:15] op_sel_hi:[1,1,0]
	v_pk_fma_f32 v[230:231], v[228:229], v[230:231], s[14:15] op_sel_hi:[1,1,0]
	v_pk_fma_f32 v[224:225], v[222:223], v[224:225], s[56:57] op_sel_hi:[1,1,0]
	v_pk_fma_f32 v[230:231], v[228:229], v[230:231], s[56:57] op_sel_hi:[1,1,0]
	v_pk_fma_f32 v[224:225], v[222:223], v[224:225], s[92:93] op_sel_hi:[1,1,0]
	v_pk_fma_f32 v[230:231], v[228:229], v[230:231], s[92:93] op_sel_hi:[1,1,0]
	v_pk_mul_f32 v[224:225], v[222:223], v[224:225]
	v_pk_mul_f32 v[230:231], v[228:229], v[230:231]
	v_pk_mul_f32 v[224:225], v[226:227], v[224:225]
	v_pk_mul_f32 v[230:231], v[232:233], v[230:231]
	v_pk_mul_f32 v[226:227], v[130:131], v[224:225]
	v_pk_mul_f32 v[232:233], v[132:133], v[230:231]
	v_pk_fma_f32 v[224:225], v[130:131], v[224:225], v[130:131] neg_lo:[1,0,0] neg_hi:[1,0,0]
	v_pk_fma_f32 v[230:231], v[132:133], v[230:231], v[132:133] neg_lo:[1,0,0] neg_hi:[1,0,0]
	v_cndmask_b32_e64 v130, v224, v226, s[60:61]
	v_cndmask_b32_e64 v131, v225, v227, s[62:63]
	v_cndmask_b32_e64 v132, v230, v232, s[64:65]
	v_cndmask_b32_e64 v133, v231, v233, s[66:67]
	v_mul_f32_e32 v130, v66, v130
	v_mul_f32_e32 v131, v67, v131
	v_mul_f32_e32 v132, v68, v132
	v_mul_f32_e32 v133, v69, v133
	v_cvt_pk_bf16_f32 v200, v130, v131
	v_cvt_pk_bf16_f32 v201, v132, v133
	global_store_dwordx2 v[154:155], v[200:201], off offset:8
	s_add_i32 s90, s89, 0
	s_mul_i32 s91, s90, 0x5800
	s_add_u32 s36, s6, s91
	s_addc_u32 s37, s7, 0
; __device__ __forceinline__ unsigned cvt_pk_bf16(float lo, float hi) { unsigned r; asm volatile("v_cvt_pk_bf16_f32 %0, %1, %2" : "=v"(r) : "v"(lo), "v"(hi)); return r; }
; __device__ __forceinline__ float dppf_prev(float cur, float below) { return __uint_as_float(dpp_prev(__float_as_uint(cur), __float_as_uint(below))); }
;     __device__ __forceinline__ void operator()(AccT& acc, const Unit& u, int wr, int wc, int fr, int fq) const {
;     ...
;             for (int m = 0; m < 4; ++m) { const float rstd = rsqrtf(rss[half * HALF_TOK + gidx * 64 + m * 16 + fr] * (1.0f / DM) + 1e-6f);
; #pragma unroll
;                 for (int n = 0; n < 2; ++n) { acc[ai][0][m][n] = acc[ai][0][m][n] * rstd; acc[ai][1][m][n] = acc[ai][1][m][n] * rstd; } }
; #pragma unroll
;             for (int n = 0; n < 2; ++n) {
;                 const f32x4 w0 = *(const f32x4*)(cw + fcol + 4 * n), w1 = *(const f32x4*)(cw + DFF + fcol + 4 * n), w2 = *(const f32x4*)(cw + 2 * DFF + fcol + 4 * n), b = *(const f32x4*)(cb + fcol + 4 * n);
; #pragma unroll
;                 for (int m = 0; m < 4; ++m) { const int lr = m * 16 + fr;
;                     const f32x4 gc = acc[ai][0][m][n], up = acc[ai][1][m][n]; f32x4 uu;
; #pragma unroll
;                     for (int j = 0; j < 4; ++j) { const float gp = dppf_prev(gc[j], m > 0 ? acc[ai][0][m - 1][n][j] : 0.f), gn = dppf_next(gc[j], m < 3 ? acc[ai][0][m + 1][n][j] : 0.f);
;                         uu[j] = gp * w0[j] + gc[j] * w1[j] + gn * w2[j] + b[j]; }
;                     const f32x2 ga = gelu_pk((f32x2){uu[0], uu[1]}), gb = gelu_pk((f32x2){uu[2], uu[3]});
;                     u32x2 wa; wa.x = cvt_pk_bf16(ga.x * up[0], ga.y * up[1]); wa.y = cvt_pk_bf16(gb.x * up[2], gb.y * up[3]);
;                     *(u32x2*)(ACT + (size_t)(gidx * 64 + lr) * DFF + fcol + 4 * n) = wa;
;                     if (m == 0 || m == 3) {
;                         if (lr == 0 || lr == 63) { u32x2 wu; wu.x = cvt_pk_bf16(up[0], up[1]); wu.y = cvt_pk_bf16(up[2], up[3]); *(u32x2*)(UP + (size_t)(gidx * 2 + (lr == 63 ? 1 : 0)) * DFF + fcol + 4 * n) = wu; }
;                         if (lr < 2 || lr > 61) { u32x2 wg; wg.x = cvt_pk_bf16(gc[0], gc[1]); wg.y = cvt_pk_bf16(gc[2], gc[3]); *(u32x2*)(GR + (size_t)(gidx * 4 + (lr < 2 ? lr : lr - 60)) * DFF + fcol + 4 * n) = wg; } } } }
	s_mul_i32 s91, s90, 0x2c00
	s_add_i32 s91, s91, 0x1600
	s_add_u32 s42, s8, s91
	s_addc_u32 s43, s9, 0
	v_lshl_add_u64 v[222:223], v[148:149], 0, s[36:37]
	v_lshl_add_u64 v[224:225], v[144:145], 1, s[42:43]
	v_lshl_add_u64 v[222:223], v[144:145], 1, v[222:223]
	s_mov_b64 exec, s[54:55]
	v_cvt_pk_bf16_f32 v226, v70, v71
	v_cvt_pk_bf16_f32 v227, v72, v73
	global_store_dwordx2 v[222:223], v[226:227], off offset:8
	s_mov_b64 exec, s[52:53]
	v_cvt_pk_bf16_f32 v228, v66, v67
	v_cvt_pk_bf16_f32 v229, v68, v69
	global_store_dwordx2 v[224:225], v[228:229], off offset:8
	s_mov_b64 exec, -1
	v_pk_mul_f32 v[30:31], v[30:31], v[166:167] op_sel_hi:[1,0]
	v_pk_mul_f32 v[32:33], v[32:33], v[166:167] op_sel_hi:[1,0]
	v_pk_mul_f32 v[22:23], v[22:23], v[166:167] op_sel_hi:[1,0]
	v_pk_mul_f32 v[24:25], v[24:25], v[166:167] op_sel_hi:[1,0]
	v_pk_mul_f32 v[26:27], v[26:27], v[170:171] op_sel_hi:[1,0]
	v_pk_mul_f32 v[28:29], v[28:29], v[170:171] op_sel_hi:[1,0]
	v_pk_mul_f32 v[18:19], v[18:19], v[170:171] op_sel_hi:[1,0]
	v_pk_mul_f32 v[20:21], v[20:21], v[170:171] op_sel_hi:[1,0]
	v_pk_mul_f32 v[14:15], v[14:15], v[172:173] op_sel_hi:[1,0]
	v_pk_mul_f32 v[16:17], v[16:17], v[172:173] op_sel_hi:[1,0]
	v_pk_mul_f32 v[10:11], v[10:11], v[172:173] op_sel_hi:[1,0]
	v_pk_mul_f32 v[12:13], v[12:13], v[172:173] op_sel_hi:[1,0]
	v_pk_mul_f32 v[6:7], v[6:7], v[194:195] op_sel_hi:[1,0]
	v_pk_mul_f32 v[8:9], v[8:9], v[194:195] op_sel_hi:[1,0]
	v_pk_mul_f32 v[2:3], v[2:3], v[194:195] op_sel_hi:[1,0]
	v_pk_mul_f32 v[4:5], v[4:5], v[194:195] op_sel_hi:[1,0]
	v_lshl_add_u64 v[154:155], v[150:151], 0, s[44:45]
	v_mov_b32_e32 v190, 0
	v_mov_b32_e32 v191, 0
	v_mov_b32_e32 v192, 0
	v_mov_b32_e32 v193, 0
	v_mov_b32_dpp v204, v26 row_ror:15 row_mask:0xf bank_mask:0xf
	v_mov_b32_dpp v205, v27 row_ror:15 row_mask:0xf bank_mask:0xf
	v_mov_b32_dpp v206, v28 row_ror:15 row_mask:0xf bank_mask:0xf
	v_mov_b32_dpp v207, v29 row_ror:15 row_mask:0xf bank_mask:0xf
	v_mov_b32_dpp v190, v30 row_shr:1 row_mask:0xf bank_mask:0xf
	v_mov_b32_dpp v191, v31 row_shr:1 row_mask:0xf bank_mask:0xf
	v_mov_b32_dpp v192, v32 row_shr:1 row_mask:0xf bank_mask:0xf
	v_mov_b32_dpp v193, v33 row_shr:1 row_mask:0xf bank_mask:0xf
	v_mov_b32_dpp v204, v30 row_shl:1 row_mask:0xf bank_mask:0xf
	v_mov_b32_dpp v205, v31 row_shl:1 row_mask:0xf bank_mask:0xf
	v_mov_b32_dpp v206, v32 row_shl:1 row_mask:0xf bank_mask:0xf
	v_mov_b32_dpp v207, v33 row_shl:1 row_mask:0xf bank_mask:0xf
	v_pk_mul_f32 v[130:131], v[118:119], v[30:31]
	v_pk_mul_f32 v[132:133], v[120:121], v[32:33]
	v_pk_fma_f32 v[130:131], v[122:123], v[190:191], v[130:131]
	v_pk_fma_f32 v[132:133], v[124:125], v[192:193], v[132:133]
	v_pk_fma_f32 v[130:131], v[110:111], v[204:205], v[130:131]
	v_pk_fma_f32 v[132:133], v[112:113], v[206:207], v[132:133]
	v_pk_add_f32 v[130:131], v[102:103], v[130:131]
	v_pk_add_f32 v[132:133], v[104:105], v[132:133]
	v_cmp_gt_f32_e64 s[60:61], 0, v130
	v_cmp_gt_f32_e64 s[62:63], 0, v131
	v_cmp_gt_f32_e64 s[64:65], 0, v132
	v_cmp_gt_f32_e64 s[66:67], 0, v133
	v_and_b32_e32 v222, 0x7fffffff, v130
	v_and_b32_e32 v223, 0x7fffffff, v131
	v_and_b32_e32 v228, 0x7fffffff, v132
	v_and_b32_e32 v229, 0x7fffffff, v133
	v_pk_fma_f32 v[222:223], v[222:223], s[0:1], 1.0 op_sel_hi:[1,0,0]
	v_pk_fma_f32 v[228:229], v[228:229], s[0:1], 1.0 op_sel_hi:[1,0,0]
	v_pk_mul_f32 v[226:227], v[130:131], v[130:131]
	v_pk_mul_f32 v[232:233], v[132:133], v[132:133]
	v_rcp_f32_e32 v222, v222
	v_rcp_f32_e32 v223, v223
	v_rcp_f32_e32 v228, v228
	v_rcp_f32_e32 v229, v229
	v_pk_mul_f32 v[226:227], v[226:227], s[94:95] op_sel_hi:[1,0]
	v_pk_mul_f32 v[232:233], v[232:233], s[94:95] op_sel_hi:[1,0]
	v_pk_fma_f32 v[224:225], v[222:223], s[12:13], v[152:153] op_sel_hi:[1,0,0]
	v_pk_fma_f32 v[230:231], v[228:229], s[12:13], v[152:153] op_sel_hi:[1,0,0]
	v_exp_f32_e32 v226, v226
	v_exp_f32_e32 v227, v227
	v_exp_f32_e32 v232, v232
	v_exp_f32_e32 v233, v233
	v_pk_fma_f32 v[224:225], v[222:223], v[224:225], s[14:15] op_sel_hi:[1,1,0]
	v_pk_fma_f32 v[230:231], v[228:229], v[230:231], s[14:15] op_sel_hi:[1,1,0]
	v_pk_fma_f32 v[224:225], v[222:223], v[224:225], s[56:57] op_sel_hi:[1,1,0]
	v_pk_fma_f32 v[230:231], v[228:229], v[230:231], s[56:57] op_sel_hi:[1,1,0]
	v_pk_fma_f32 v[224:225], v[222:223], v[224:225], s[92:93] op_sel_hi:[1,1,0]
	v_pk_fma_f32 v[230:231], v[228:229], v[230:231], s[92:93] op_sel_hi:[1,1,0]
	v_pk_mul_f32 v[224:225], v[222:223], v[224:225]
	v_pk_mul_f32 v[230:231], v[228:229], v[230:231]
	v_pk_mul_f32 v[224:225], v[226:227], v[224:225]
	v_pk_mul_f32 v[230:231], v[232:233], v[230:231]
	v_pk_mul_f32 v[226:227], v[130:131], v[224:225]
	v_pk_mul_f32 v[232:233], v[132:133], v[230:231]
	v_pk_fma_f32 v[224:225], v[130:131], v[224:225], v[130:131] neg_lo:[1,0,0] neg_hi:[1,0,0]
	v_pk_fma_f32 v[230:231], v[132:133], v[230:231], v[132:133] neg_lo:[1,0,0] neg_hi:[1,0,0]
	v_cndmask_b32_e64 v130, v224, v226, s[60:61]
	v_cndmask_b32_e64 v131, v225, v227, s[62:63]
	v_cndmask_b32_e64 v132, v230, v232, s[64:65]
	v_cndmask_b32_e64 v133, v231, v233, s[66:67]
	v_mul_f32_e32 v130, v22, v130
	v_mul_f32_e32 v131, v23, v131
	v_mul_f32_e32 v132, v24, v132
	v_mul_f32_e32 v133, v25, v133
	v_cvt_pk_bf16_f32 v200, v130, v131
	v_cvt_pk_bf16_f32 v201, v132, v133
	global_store_dwordx2 v[154:155], v[200:201], off offset:8
	v_lshl_add_u64 v[154:155], v[154:155], 0, s[46:47]
	s_add_i32 s90, s89, 2
	s_mul_i32 s91, s90, 0x5800
	s_add_u32 s36, s6, s91
	s_addc_u32 s37, s7, 0
	s_mul_i32 s91, s90, 0x2c00
	s_add_u32 s42, s8, s91
	s_addc_u32 s43, s9, 0
	v_lshl_add_u64 v[222:223], v[146:147], 0, s[36:37]
	v_lshl_add_u64 v[224:225], v[144:145], 1, s[42:43]
	v_lshl_add_u64 v[222:223], v[144:145], 1, v[222:223]
; __device__ __forceinline__ unsigned cvt_pk_bf16(float lo, float hi) { unsigned r; asm volatile("v_cvt_pk_bf16_f32 %0, %1, %2" : "=v"(r) : "v"(lo), "v"(hi)); return r; }
; __device__ __forceinline__ float dppf_prev(float cur, float below) { return __uint_as_float(dpp_prev(__float_as_uint(cur), __float_as_uint(below))); }
; __device__ __forceinline__ float dppf_next(float cur, float above) { return __uint_as_float(dpp_next(__float_as_uint(cur), __float_as_uint(above))); }
;     __device__ __forceinline__ void operator()(AccT& acc, const Unit& u, int wr, int wc, int fr, int fq) const {
;     ...
;                 for (int m = 0; m < 4; ++m) { const int lr = m * 16 + fr;
;                     const f32x4 gc = acc[ai][0][m][n], up = acc[ai][1][m][n]; f32x4 uu;
; #pragma unroll
;                     for (int j = 0; j < 4; ++j) { const float gp = dppf_prev(gc[j], m > 0 ? acc[ai][0][m - 1][n][j] : 0.f), gn = dppf_next(gc[j], m < 3 ? acc[ai][0][m + 1][n][j] : 0.f);
;                         uu[j] = gp * w0[j] + gc[j] * w1[j] + gn * w2[j] + b[j]; }
;                     const f32x2 ga = gelu_pk((f32x2){uu[0], uu[1]}), gb = gelu_pk((f32x2){uu[2], uu[3]});
;                     u32x2 wa; wa.x = cvt_pk_bf16(ga.x * up[0], ga.y * up[1]); wa.y = cvt_pk_bf16(gb.x * up[2], gb.y * up[3]);
;                     *(u32x2*)(ACT + (size_t)(gidx * 64 + lr) * DFF + fcol + 4 * n) = wa;
;                     if (m == 0 || m == 3) {
;                         if (lr == 0 || lr == 63) { u32x2 wu; wu.x = cvt_pk_bf16(up[0], up[1]); wu.y = cvt_pk_bf16(up[2], up[3]); *(u32x2*)(UP + (size_t)(gidx * 2 + (lr == 63 ? 1 : 0)) * DFF + fcol + 4 * n) = wu; }
;                         if (lr < 2 || lr > 61) { u32x2 wg; wg.x = cvt_pk_bf16(gc[0], gc[1]); wg.y = cvt_pk_bf16(gc[2], gc[3]); *(u32x2*)(GR + (size_t)(gidx * 4 + (lr < 2 ? lr : lr - 60)) * DFF + fcol + 4 * n) = wg; } } } }
	s_mov_b64 exec, s[50:51]
	v_cvt_pk_bf16_f32 v226, v30, v31
	v_cvt_pk_bf16_f32 v227, v32, v33
	global_store_dwordx2 v[222:223], v[226:227], off offset:8
	s_mov_b64 exec, s[48:49]
	v_cvt_pk_bf16_f32 v228, v22, v23
	v_cvt_pk_bf16_f32 v229, v24, v25
	global_store_dwordx2 v[224:225], v[228:229], off offset:8
	s_mov_b64 exec, -1
	v_mov_b32_dpp v190, v30 row_ror:1 row_mask:0xf bank_mask:0xf
	v_mov_b32_dpp v191, v31 row_ror:1 row_mask:0xf bank_mask:0xf
	v_mov_b32_dpp v192, v32 row_ror:1 row_mask:0xf bank_mask:0xf
	v_mov_b32_dpp v193, v33 row_ror:1 row_mask:0xf bank_mask:0xf
	v_mov_b32_dpp v204, v14 row_ror:15 row_mask:0xf bank_mask:0xf
	v_mov_b32_dpp v205, v15 row_ror:15 row_mask:0xf bank_mask:0xf
	v_mov_b32_dpp v206, v16 row_ror:15 row_mask:0xf bank_mask:0xf
	v_mov_b32_dpp v207, v17 row_ror:15 row_mask:0xf bank_mask:0xf
	v_mov_b32_dpp v190, v26 row_shr:1 row_mask:0xf bank_mask:0xf
	v_mov_b32_dpp v191, v27 row_shr:1 row_mask:0xf bank_mask:0xf
	v_mov_b32_dpp v192, v28 row_shr:1 row_mask:0xf bank_mask:0xf
	v_mov_b32_dpp v193, v29 row_shr:1 row_mask:0xf bank_mask:0xf
	v_mov_b32_dpp v204, v26 row_shl:1 row_mask:0xf bank_mask:0xf
	v_mov_b32_dpp v205, v27 row_shl:1 row_mask:0xf bank_mask:0xf
	v_mov_b32_dpp v206, v28 row_shl:1 row_mask:0xf bank_mask:0xf
	v_mov_b32_dpp v207, v29 row_shl:1 row_mask:0xf bank_mask:0xf
	v_pk_mul_f32 v[130:131], v[118:119], v[26:27]
	v_pk_mul_f32 v[132:133], v[120:121], v[28:29]
	v_pk_fma_f32 v[130:131], v[122:123], v[190:191], v[130:131]
	v_pk_fma_f32 v[132:133], v[124:125], v[192:193], v[132:133]
	v_pk_fma_f32 v[130:131], v[110:111], v[204:205], v[130:131]
	v_pk_fma_f32 v[132:133], v[112:113], v[206:207], v[132:133]
	v_pk_add_f32 v[130:131], v[102:103], v[130:131]
	v_pk_add_f32 v[132:133], v[104:105], v[132:133]
	v_cmp_gt_f32_e64 s[60:61], 0, v130
	v_cmp_gt_f32_e64 s[62:63], 0, v131
	v_cmp_gt_f32_e64 s[64:65], 0, v132
	v_cmp_gt_f32_e64 s[66:67], 0, v133
	v_and_b32_e32 v222, 0x7fffffff, v130
	v_and_b32_e32 v223, 0x7fffffff, v131
	v_and_b32_e32 v228, 0x7fffffff, v132
	v_and_b32_e32 v229, 0x7fffffff, v133
	v_pk_fma_f32 v[222:223], v[222:223], s[0:1], 1.0 op_sel_hi:[1,0,0]
	v_pk_fma_f32 v[228:229], v[228:229], s[0:1], 1.0 op_sel_hi:[1,0,0]
	v_pk_mul_f32 v[226:227], v[130:131], v[130:131]
	v_pk_mul_f32 v[232:233], v[132:133], v[132:133]
	v_rcp_f32_e32 v222, v222
	v_rcp_f32_e32 v223, v223
	v_rcp_f32_e32 v228, v228
	v_rcp_f32_e32 v229, v229
	v_pk_mul_f32 v[226:227], v[226:227], s[94:95] op_sel_hi:[1,0]
	v_pk_mul_f32 v[232:233], v[232:233], s[94:95] op_sel_hi:[1,0]
	v_pk_fma_f32 v[224:225], v[222:223], s[12:13], v[152:153] op_sel_hi:[1,0,0]
	v_pk_fma_f32 v[230:231], v[228:229], s[12:13], v[152:153] op_sel_hi:[1,0,0]
	v_exp_f32_e32 v226, v226
	v_exp_f32_e32 v227, v227
	v_exp_f32_e32 v232, v232
	v_exp_f32_e32 v233, v233
	v_pk_fma_f32 v[224:225], v[222:223], v[224:225], s[14:15] op_sel_hi:[1,1,0]
	v_pk_fma_f32 v[230:231], v[228:229], v[230:231], s[14:15] op_sel_hi:[1,1,0]
	v_pk_fma_f32 v[224:225], v[222:223], v[224:225], s[56:57] op_sel_hi:[1,1,0]
	v_pk_fma_f32 v[230:231], v[228:229], v[230:231], s[56:57] op_sel_hi:[1,1,0]
	v_pk_fma_f32 v[224:225], v[222:223], v[224:225], s[92:93] op_sel_hi:[1,1,0]
	v_pk_fma_f32 v[230:231], v[228:229], v[230:231], s[92:93] op_sel_hi:[1,1,0]
	v_pk_mul_f32 v[224:225], v[222:223], v[224:225]
	v_pk_mul_f32 v[230:231], v[228:229], v[230:231]
	v_pk_mul_f32 v[224:225], v[226:227], v[224:225]
	v_pk_mul_f32 v[230:231], v[232:233], v[230:231]
	v_pk_mul_f32 v[226:227], v[130:131], v[224:225]
	v_pk_mul_f32 v[232:233], v[132:133], v[230:231]
	v_pk_fma_f32 v[224:225], v[130:131], v[224:225], v[130:131] neg_lo:[1,0,0] neg_hi:[1,0,0]
	v_pk_fma_f32 v[230:231], v[132:133], v[230:231], v[132:133] neg_lo:[1,0,0] neg_hi:[1,0,0]
	v_cndmask_b32_e64 v130, v224, v226, s[60:61]
	v_cndmask_b32_e64 v131, v225, v227, s[62:63]
	v_cndmask_b32_e64 v132, v230, v232, s[64:65]
	v_cndmask_b32_e64 v133, v231, v233, s[66:67]
	v_mul_f32_e32 v130, v18, v130
	v_mul_f32_e32 v131, v19, v131
	v_mul_f32_e32 v132, v20, v132
	v_mul_f32_e32 v133, v21, v133
	v_cvt_pk_bf16_f32 v200, v130, v131
	v_cvt_pk_bf16_f32 v201, v132, v133
	global_store_dwordx2 v[154:155], v[200:201], off offset:8
	v_lshl_add_u64 v[154:155], v[154:155], 0, s[46:47]
	v_mov_b32_dpp v190, v26 row_ror:1 row_mask:0xf bank_mask:0xf
	v_mov_b32_dpp v191, v27 row_ror:1 row_mask:0xf bank_mask:0xf
	v_mov_b32_dpp v192, v28 row_ror:1 row_mask:0xf bank_mask:0xf
	v_mov_b32_dpp v193, v29 row_ror:1 row_mask:0xf bank_mask:0xf
	v_mov_b32_dpp v204, v6 row_ror:15 row_mask:0xf bank_mask:0xf
	v_mov_b32_dpp v205, v7 row_ror:15 row_mask:0xf bank_mask:0xf
	v_mov_b32_dpp v206, v8 row_ror:15 row_mask:0xf bank_mask:0xf
	v_mov_b32_dpp v207, v9 row_ror:15 row_mask:0xf bank_mask:0xf
	v_mov_b32_dpp v190, v14 row_shr:1 row_mask:0xf bank_mask:0xf
	v_mov_b32_dpp v191, v15 row_shr:1 row_mask:0xf bank_mask:0xf
	v_mov_b32_dpp v192, v16 row_shr:1 row_mask:0xf bank_mask:0xf
	v_mov_b32_dpp v193, v17 row_shr:1 row_mask:0xf bank_mask:0xf
	v_mov_b32_dpp v204, v14 row_shl:1 row_mask:0xf bank_mask:0xf
	v_mov_b32_dpp v205, v15 row_shl:1 row_mask:0xf bank_mask:0xf
	v_mov_b32_dpp v206, v16 row_shl:1 row_mask:0xf bank_mask:0xf
	v_mov_b32_dpp v207, v17 row_shl:1 row_mask:0xf bank_mask:0xf
	v_pk_mul_f32 v[130:131], v[118:119], v[14:15]
	v_pk_mul_f32 v[132:133], v[120:121], v[16:17]
	v_pk_fma_f32 v[130:131], v[122:123], v[190:191], v[130:131]
	v_pk_fma_f32 v[132:133], v[124:125], v[192:193], v[132:133]
	v_pk_fma_f32 v[130:131], v[110:111], v[204:205], v[130:131]
	v_pk_fma_f32 v[132:133], v[112:113], v[206:207], v[132:133]
	v_pk_add_f32 v[130:131], v[102:103], v[130:131]
	v_pk_add_f32 v[132:133], v[104:105], v[132:133]
; __device__ __forceinline__ unsigned cvt_pk_bf16(float lo, float hi) { unsigned r; asm volatile("v_cvt_pk_bf16_f32 %0, %1, %2" : "=v"(r) : "v"(lo), "v"(hi)); return r; }
; __device__ __forceinline__ float dppf_prev(float cur, float below) { return __uint_as_float(dpp_prev(__float_as_uint(cur), __float_as_uint(below))); }
; __device__ __forceinline__ float dppf_next(float cur, float above) { return __uint_as_float(dpp_next(__float_as_uint(cur), __float_as_uint(above))); }
;     __device__ __forceinline__ void operator()(AccT& acc, const Unit& u, int wr, int wc, int fr, int fq) const {
;     ...
;                 for (int m = 0; m < 4; ++m) { const int lr = m * 16 + fr;
;                     const f32x4 gc = acc[ai][0][m][n], up = acc[ai][1][m][n]; f32x4 uu;
; #pragma unroll
;                     for (int j = 0; j < 4; ++j) { const float gp = dppf_prev(gc[j], m > 0 ? acc[ai][0][m - 1][n][j] : 0.f), gn = dppf_next(gc[j], m < 3 ? acc[ai][0][m + 1][n][j] : 0.f);
;                         uu[j] = gp * w0[j] + gc[j] * w1[j] + gn * w2[j] + b[j]; }
;                     const f32x2 ga = gelu_pk((f32x2){uu[0], uu[1]}), gb = gelu_pk((f32x2){uu[2], uu[3]});
;                     u32x2 wa; wa.x = cvt_pk_bf16(ga.x * up[0], ga.y * up[1]); wa.y = cvt_pk_bf16(gb.x * up[2], gb.y * up[3]);
;                     *(u32x2*)(ACT + (size_t)(gidx * 64 + lr) * DFF + fcol + 4 * n) = wa;
;                     if (m == 0 || m == 3) {
;                         if (lr == 0 || lr == 63) { u32x2 wu; wu.x = cvt_pk_bf16(up[0], up[1]); wu.y = cvt_pk_bf16(up[2], up[3]); *(u32x2*)(UP + (size_t)(gidx * 2 + (lr == 63 ? 1 : 0)) * DFF + fcol + 4 * n) = wu; }
;                         if (lr < 2 || lr > 61) { u32x2 wg; wg.x = cvt_pk_bf16(gc[0], gc[1]); wg.y = cvt_pk_bf16(gc[2], gc[3]); *(u32x2*)(GR + (size_t)(gidx * 4 + (lr < 2 ? lr : lr - 60)) * DFF + fcol + 4 * n) = wg; } } } }
	v_cmp_gt_f32_e64 s[60:61], 0, v130
	v_cmp_gt_f32_e64 s[62:63], 0, v131
	v_cmp_gt_f32_e64 s[64:65], 0, v132
	v_cmp_gt_f32_e64 s[66:67], 0, v133
	v_and_b32_e32 v222, 0x7fffffff, v130
	v_and_b32_e32 v223, 0x7fffffff, v131
	v_and_b32_e32 v228, 0x7fffffff, v132
	v_and_b32_e32 v229, 0x7fffffff, v133
	v_pk_fma_f32 v[222:223], v[222:223], s[0:1], 1.0 op_sel_hi:[1,0,0]
	v_pk_fma_f32 v[228:229], v[228:229], s[0:1], 1.0 op_sel_hi:[1,0,0]
	v_pk_mul_f32 v[226:227], v[130:131], v[130:131]
	v_pk_mul_f32 v[232:233], v[132:133], v[132:133]
	v_rcp_f32_e32 v222, v222
	v_rcp_f32_e32 v223, v223
	v_rcp_f32_e32 v228, v228
	v_rcp_f32_e32 v229, v229
	v_pk_mul_f32 v[226:227], v[226:227], s[94:95] op_sel_hi:[1,0]
	v_pk_mul_f32 v[232:233], v[232:233], s[94:95] op_sel_hi:[1,0]
	v_pk_fma_f32 v[224:225], v[222:223], s[12:13], v[152:153] op_sel_hi:[1,0,0]
	v_pk_fma_f32 v[230:231], v[228:229], s[12:13], v[152:153] op_sel_hi:[1,0,0]
	v_exp_f32_e32 v226, v226
	v_exp_f32_e32 v227, v227
	v_exp_f32_e32 v232, v232
	v_exp_f32_e32 v233, v233
	v_pk_fma_f32 v[224:225], v[222:223], v[224:225], s[14:15] op_sel_hi:[1,1,0]
	v_pk_fma_f32 v[230:231], v[228:229], v[230:231], s[14:15] op_sel_hi:[1,1,0]
	v_pk_fma_f32 v[224:225], v[222:223], v[224:225], s[56:57] op_sel_hi:[1,1,0]
	v_pk_fma_f32 v[230:231], v[228:229], v[230:231], s[56:57] op_sel_hi:[1,1,0]
	v_pk_fma_f32 v[224:225], v[222:223], v[224:225], s[92:93] op_sel_hi:[1,1,0]
	v_pk_fma_f32 v[230:231], v[228:229], v[230:231], s[92:93] op_sel_hi:[1,1,0]
	v_pk_mul_f32 v[224:225], v[222:223], v[224:225]
	v_pk_mul_f32 v[230:231], v[228:229], v[230:231]
	v_pk_mul_f32 v[224:225], v[226:227], v[224:225]
	v_pk_mul_f32 v[230:231], v[232:233], v[230:231]
	v_pk_mul_f32 v[226:227], v[130:131], v[224:225]
	v_pk_mul_f32 v[232:233], v[132:133], v[230:231]
	v_pk_fma_f32 v[224:225], v[130:131], v[224:225], v[130:131] neg_lo:[1,0,0] neg_hi:[1,0,0]
	v_pk_fma_f32 v[230:231], v[132:133], v[230:231], v[132:133] neg_lo:[1,0,0] neg_hi:[1,0,0]
	v_cndmask_b32_e64 v130, v224, v226, s[60:61]
	v_cndmask_b32_e64 v131, v225, v227, s[62:63]
	v_cndmask_b32_e64 v132, v230, v232, s[64:65]
	v_cndmask_b32_e64 v133, v231, v233, s[66:67]
	v_mul_f32_e32 v130, v10, v130
	v_mul_f32_e32 v131, v11, v131
	v_mul_f32_e32 v132, v12, v132
	v_mul_f32_e32 v133, v13, v133
	v_cvt_pk_bf16_f32 v200, v130, v131
	v_cvt_pk_bf16_f32 v201, v132, v133
	global_store_dwordx2 v[154:155], v[200:201], off offset:8
	v_lshl_add_u64 v[154:155], v[154:155], 0, s[46:47]
	v_mov_b32_dpp v190, v14 row_ror:1 row_mask:0xf bank_mask:0xf
	v_mov_b32_dpp v191, v15 row_ror:1 row_mask:0xf bank_mask:0xf
	v_mov_b32_dpp v192, v16 row_ror:1 row_mask:0xf bank_mask:0xf
	v_mov_b32_dpp v193, v17 row_ror:1 row_mask:0xf bank_mask:0xf
	v_mov_b32_e32 v204, 0
	v_mov_b32_e32 v205, 0
	v_mov_b32_e32 v206, 0
	v_mov_b32_e32 v207, 0
	v_mov_b32_dpp v190, v6 row_shr:1 row_mask:0xf bank_mask:0xf
	v_mov_b32_dpp v191, v7 row_shr:1 row_mask:0xf bank_mask:0xf
	v_mov_b32_dpp v192, v8 row_shr:1 row_mask:0xf bank_mask:0xf
	v_mov_b32_dpp v193, v9 row_shr:1 row_mask:0xf bank_mask:0xf
	v_mov_b32_dpp v204, v6 row_shl:1 row_mask:0xf bank_mask:0xf
	v_mov_b32_dpp v205, v7 row_shl:1 row_mask:0xf bank_mask:0xf
	v_mov_b32_dpp v206, v8 row_shl:1 row_mask:0xf bank_mask:0xf
	v_mov_b32_dpp v207, v9 row_shl:1 row_mask:0xf bank_mask:0xf
	v_pk_mul_f32 v[130:131], v[118:119], v[6:7]
	v_pk_mul_f32 v[132:133], v[120:121], v[8:9]
	v_pk_fma_f32 v[130:131], v[122:123], v[190:191], v[130:131]
	v_pk_fma_f32 v[132:133], v[124:125], v[192:193], v[132:133]
	v_pk_fma_f32 v[130:131], v[110:111], v[204:205], v[130:131]
	v_pk_fma_f32 v[132:133], v[112:113], v[206:207], v[132:133]
	v_pk_add_f32 v[130:131], v[102:103], v[130:131]
	v_pk_add_f32 v[132:133], v[104:105], v[132:133]
	v_cmp_gt_f32_e64 s[60:61], 0, v130
	v_cmp_gt_f32_e64 s[62:63], 0, v131
	v_cmp_gt_f32_e64 s[64:65], 0, v132
	v_cmp_gt_f32_e64 s[66:67], 0, v133
	v_and_b32_e32 v222, 0x7fffffff, v130
	v_and_b32_e32 v223, 0x7fffffff, v131
	v_and_b32_e32 v228, 0x7fffffff, v132
	v_and_b32_e32 v229, 0x7fffffff, v133
	v_pk_fma_f32 v[222:223], v[222:223], s[0:1], 1.0 op_sel_hi:[1,0,0]
	v_pk_fma_f32 v[228:229], v[228:229], s[0:1], 1.0 op_sel_hi:[1,0,0]
	v_pk_mul_f32 v[226:227], v[130:131], v[130:131]
	v_pk_mul_f32 v[232:233], v[132:133], v[132:133]
	v_rcp_f32_e32 v222, v222
	v_rcp_f32_e32 v223, v223
	v_rcp_f32_e32 v228, v228
	v_rcp_f32_e32 v229, v229
	v_pk_mul_f32 v[226:227], v[226:227], s[94:95] op_sel_hi:[1,0]
	v_pk_mul_f32 v[232:233], v[232:233], s[94:95] op_sel_hi:[1,0]
	v_pk_fma_f32 v[224:225], v[222:223], s[12:13], v[152:153] op_sel_hi:[1,0,0]
	v_pk_fma_f32 v[230:231], v[228:229], s[12:13], v[152:153] op_sel_hi:[1,0,0]
	v_exp_f32_e32 v226, v226
	v_exp_f32_e32 v227, v227
	v_exp_f32_e32 v232, v232
	v_exp_f32_e32 v233, v233
	v_pk_fma_f32 v[224:225], v[222:223], v[224:225], s[14:15] op_sel_hi:[1,1,0]
	v_pk_fma_f32 v[230:231], v[228:229], v[230:231], s[14:15] op_sel_hi:[1,1,0]
	v_pk_fma_f32 v[224:225], v[222:223], v[224:225], s[56:57] op_sel_hi:[1,1,0]
	v_pk_fma_f32 v[230:231], v[228:229], v[230:231], s[56:57] op_sel_hi:[1,1,0]
	v_pk_fma_f32 v[224:225], v[222:223], v[224:225], s[92:93] op_sel_hi:[1,1,0]
	v_pk_fma_f32 v[230:231], v[228:229], v[230:231], s[92:93] op_sel_hi:[1,1,0]
	v_pk_mul_f32 v[224:225], v[222:223], v[224:225]
	v_pk_mul_f32 v[230:231], v[228:229], v[230:231]
	v_pk_mul_f32 v[224:225], v[226:227], v[224:225]
	v_pk_mul_f32 v[230:231], v[232:233], v[230:231]
	v_pk_mul_f32 v[226:227], v[130:131], v[224:225]
	v_pk_mul_f32 v[232:233], v[132:133], v[230:231]
	v_pk_fma_f32 v[224:225], v[130:131], v[224:225], v[130:131] neg_lo:[1,0,0] neg_hi:[1,0,0]
	v_pk_fma_f32 v[230:231], v[132:133], v[230:231], v[132:133] neg_lo:[1,0,0] neg_hi:[1,0,0]
	v_cndmask_b32_e64 v130, v224, v226, s[60:61]
	v_cndmask_b32_e64 v131, v225, v227, s[62:63]
	v_cndmask_b32_e64 v132, v230, v232, s[64:65]
	v_cndmask_b32_e64 v133, v231, v233, s[66:67]
	v_mul_f32_e32 v130, v2, v130
	v_mul_f32_e32 v131, v3, v131
	v_mul_f32_e32 v132, v4, v132
	v_mul_f32_e32 v133, v5, v133
	v_cvt_pk_bf16_f32 v200, v130, v131
	v_cvt_pk_bf16_f32 v201, v132, v133
	global_store_dwordx2 v[154:155], v[200:201], off offset:8
	s_add_i32 s90, s89, 2
	s_mul_i32 s91, s90, 0x5800
	s_add_u32 s36, s6, s91
	s_addc_u32 s37, s7, 0
	s_mul_i32 s91, s90, 0x2c00
	s_add_i32 s91, s91, 0x1600
	s_add_u32 s42, s8, s91
	s_addc_u32 s43, s9, 0
	v_lshl_add_u64 v[222:223], v[148:149], 0, s[36:37]
	v_lshl_add_u64 v[224:225], v[144:145], 1, s[42:43]
	v_lshl_add_u64 v[222:223], v[144:145], 1, v[222:223]
	s_mov_b64 exec, s[54:55]
	v_cvt_pk_bf16_f32 v226, v6, v7
	v_cvt_pk_bf16_f32 v227, v8, v9
	global_store_dwordx2 v[222:223], v[226:227], off offset:8
	s_mov_b64 exec, s[52:53]
	v_cvt_pk_bf16_f32 v228, v2, v3
	v_cvt_pk_bf16_f32 v229, v4, v5
	global_store_dwordx2 v[224:225], v[228:229], off offset:8
	s_mov_b64 exec, -1
	s_branch .LBB0_879

; __device__ void phase0(const Params& P, LAS unsigned char* lds, const int G, const int bid) {
;     ...
;       for (int i = bid * 512 + tid; i < 8192 * 64; i += G * 512) { const int pos = i >> 6, f = i & 63;
;           const float inv = powf(10000.0f, -(float)(2 * f) / 128.0f); const float ang = (float)pos * inv; float s, c; sincosf(ang, &s, &c); rope[i] = (f32x2){c, s}; } }
.LBB0_1035:
	v_and_b32_e32 v6, 0x7e, v3
	v_cvt_f32_ubyte0_e32 v6, v6
	v_mul_f32_e32 v19, 0xbc000000, v6
	v_cmp_eq_f32_e32 vcc, 0, v19
	v_mov_b32_e32 v6, 0x461c4000
	s_mov_b32 s5, 0x3f2aaaab
	v_cndmask_b32_e64 v16, v6, 1.0, vcc
	v_frexp_mant_f32_e32 v6, v16
	v_cmp_gt_f32_e64 s[40:41], s5, v6
	s_mov_b32 s5, 0x3f317218
	s_movk_i32 s12, 0x204
	v_cndmask_b32_e64 v7, 1.0, 2.0, s[40:41]
	v_mul_f32_e32 v6, v6, v7
	v_add_f32_e32 v9, 1.0, v6
	v_rcp_f32_e32 v14, v9
	v_add_f32_e32 v7, -1.0, v9
	v_sub_f32_e32 v11, v6, v7
	v_add_f32_e32 v7, -1.0, v6
	v_mul_f32_e32 v15, v7, v14
	v_mul_f32_e32 v8, v9, v15
	v_fma_f32 v10, v15, v9, -v8
	v_fmac_f32_e32 v10, v15, v11
	v_add_f32_e32 v6, v8, v10
	v_sub_f32_e32 v9, v7, v6
	v_pk_add_f32 v[12:13], v[6:7], v[8:9] neg_lo:[0,1] neg_hi:[0,1]
	v_mov_b32_e32 v11, v6
	v_pk_add_f32 v[6:7], v[12:13], v[10:11] neg_lo:[0,1] neg_hi:[0,1]
	v_mov_b32_e32 v10, 0x3e91f4c4
	v_add_f32_e32 v6, v6, v7
	v_add_f32_e32 v6, v9, v6
	v_mul_f32_e32 v7, v14, v6
	v_add_f32_e32 v6, v15, v7
	v_sub_f32_e32 v8, v6, v15
	v_sub_f32_e32 v17, v7, v8
	v_mul_f32_e32 v7, v6, v6
	v_fma_f32 v9, v6, v6, -v7
	v_add_f32_e32 v8, v17, v17
	v_fmac_f32_e32 v9, v6, v8
	v_add_f32_e32 v8, v7, v9
	v_fmamk_f32 v10, v8, 0x3e76c4e1, v10
	v_fmaak_f32 v10, v8, v10, 0x3ecccdef
	v_sub_f32_e32 v7, v8, v7
	v_sub_f32_e32 v20, v9, v7
	v_mul_f32_e32 v7, v8, v10
	v_fma_f32 v9, v8, v10, -v7
	v_fmac_f32_e32 v9, v20, v10
	v_add_f32_e32 v10, v7, v9
	v_add_f32_e32 v11, 0x3f2aaaaa, v10
	v_sub_f32_e32 v7, v10, v7
	v_sub_f32_e32 v7, v9, v7
	v_add_f32_e32 v9, 0xbf2aaaaa, v11
	v_add_f32_e32 v7, 0x31739010, v7
	v_sub_f32_e32 v9, v10, v9
	v_pk_mul_f32 v[12:13], v[6:7], v[8:9]
	v_pk_add_f32 v[14:15], v[6:7], v[8:9]
	v_fma_f32 v10, v8, v6, -v12
	v_fmac_f32_e32 v10, v8, v17
	v_mov_b32_e32 v13, v15
	v_fmac_f32_e32 v10, v20, v6
	v_pk_add_f32 v[8:9], v[12:13], v[10:11]
	v_ldexp_f32 v20, v17, 1
	v_sub_f32_e32 v7, v8, v12
	v_sub_f32_e32 v7, v10, v7
	v_sub_f32_e32 v10, v11, v9
	v_add_f32_e32 v14, v15, v10
	v_pk_mul_f32 v[10:11], v[8:9], v[8:9] op_sel:[0,1] op_sel_hi:[1,0]
	v_cvt_f64_f32_e32 v[12:13], v16
	v_frexp_exp_i32_f64_e32 v11, v[12:13]
	v_subbrev_co_u32_e64 v11, s[40:41], 0, v11, s[40:41]
	v_cvt_f32_i32_e32 v11, v11
	v_fma_f32 v12, v8, v9, -v10
	v_fmac_f32_e32 v12, v8, v14
	v_fmac_f32_e32 v12, v7, v9
	v_mul_f32_e32 v8, 0x3f317218, v11
	v_fma_f32 v14, v11, s5, -v8
	v_fmac_f32_e32 v14, 0xb102e308, v11
	v_ldexp_f32 v15, v6, 1
	v_add_f32_e32 v9, v10, v12
	v_pk_add_f32 v[6:7], v[8:9], v[14:15]
	v_mov_b32_e32 v16, v9
	v_mov_b32_e32 v17, v7
	v_mov_b32_e32 v11, v15
	v_pk_add_f32 v[10:11], v[16:17], v[10:11] neg_lo:[0,1] neg_hi:[0,1]
	v_mov_b32_e32 v13, v9
	v_pk_add_f32 v[10:11], v[12:13], v[10:11] neg_lo:[0,1] neg_hi:[0,1]
	v_mov_b32_e32 v15, v6
	v_add_f32_e32 v9, v20, v10
	v_add_f32_e32 v9, v9, v11
	v_pk_add_f32 v[10:11], v[6:7], v[8:9] neg_lo:[0,1] neg_hi:[0,1]
	v_pk_add_f32 v[12:13], v[6:7], v[8:9]
	v_mov_b32_e32 v8, v9
	v_mov_b32_e32 v11, v13
	v_pk_add_f32 v[16:17], v[14:15], v[10:11] neg_lo:[0,1] neg_hi:[0,1]
	v_pk_add_f32 v[10:11], v[14:15], v[10:11]
	v_mov_b32_e32 v9, v6
	v_pk_add_f32 v[14:15], v[10:11], v[6:7] op_sel:[1,0] op_sel_hi:[0,1] neg_lo:[0,1] neg_hi:[0,1]
	s_nop 0
	v_pk_add_f32 v[20:21], v[12:13], v[14:15] op_sel_hi:[1,0] neg_lo:[0,1] neg_hi:[0,1]
	v_mov_b32_e32 v12, v13
	v_mov_b32_e32 v13, v11
	v_pk_mov_b32 v[14:15], v[6:7], v[14:15] op_sel:[1,0]
	v_mov_b32_e32 v20, v16
	v_pk_add_f32 v[12:13], v[12:13], v[14:15] neg_lo:[0,1] neg_hi:[0,1]
	v_mov_b32_e32 v17, v11
	v_pk_add_f32 v[6:7], v[8:9], v[12:13] neg_lo:[0,1] neg_hi:[0,1]
	s_mov_b32 s10, 0x42b17218
	v_pk_add_f32 v[8:9], v[20:21], v[6:7]
	s_mov_b32 s5, 0x3fb8aa3b
	v_pk_add_f32 v[12:13], v[8:9], v[8:9] op_sel:[0,1] op_sel_hi:[1,0]
	v_ashrrev_i32_e32 v0, 6, v2
	v_pk_add_f32 v[10:11], v[10:11], v[12:13] op_sel:[1,0] op_sel_hi:[0,1]
	s_nop 0
	v_mov_b32_e32 v9, v10
	v_pk_add_f32 v[14:15], v[8:9], v[16:17] neg_lo:[0,1] neg_hi:[0,1]
	v_mov_b32_e32 v7, v12
	v_sub_f32_e32 v8, v8, v14
	v_pk_add_f32 v[6:7], v[6:7], v[14:15] neg_lo:[0,1] neg_hi:[0,1]
	v_sub_f32_e32 v8, v16, v8
	v_add_f32_e32 v6, v6, v8
	v_add_f32_e32 v6, v6, v7
	v_add_f32_e32 v7, v10, v6
	v_sub_f32_e32 v8, v7, v10
	v_sub_f32_e32 v6, v6, v8
	v_mul_f32_e32 v8, v19, v7
	v_fma_f32 v7, v19, v7, -v8
	v_fmac_f32_e32 v7, v19, v6
	v_add_f32_e32 v6, v8, v7
	v_cmp_class_f32_e64 s[40:41], v8, s12
	v_sub_f32_e32 v9, v6, v8
	v_sub_f32_e32 v7, v7, v9
	v_cndmask_b32_e64 v6, v6, v8, s[40:41]
	v_cmp_eq_f32_e64 s[40:41], s10, v6
	v_mov_b32_e32 v8, 0x37000000
	v_cvt_f32_i32_e32 v0, v0
	v_cndmask_b32_e64 v8, 0, v8, s[40:41]
	v_sub_f32_e32 v9, v6, v8
	v_mul_f32_e32 v10, 0x3fb8aa3b, v9
	v_fma_f32 v11, v9, s5, -v10
	v_rndne_f32_e32 v12, v10
	v_fmac_f32_e32 v11, 0x32a5705f, v9
	v_sub_f32_e32 v10, v10, v12
	v_add_f32_e32 v10, v10, v11
	v_exp_f32_e32 v10, v10
	v_cvt_i32_f32_e32 v11, v12
	s_mov_b32 s5, 0x7f800000
	v_cmp_neq_f32_e64 s[40:41], |v6|, s5
	s_mov_b32 s5, 0xc2ce8ed0
	s_nop 0
	v_cndmask_b32_e64 v6, 0, v7, s[40:41]
	v_ldexp_f32 v7, v10, v11
	v_cmp_ngt_f32_e64 s[40:41], s5, v9
	v_add_f32_e32 v6, v8, v6
	s_brev_b32 s5, 18
	v_cndmask_b32_e64 v7, 0, v7, s[40:41]
	v_cmp_nlt_f32_e64 s[40:41], s10, v9
	v_cmp_neq_f32_e64 s[10:11], v19, |v19|
	s_nop 0
	v_cndmask_b32_e64 v7, v212, v7, s[40:41]
	v_fma_f32 v6, v7, v6, v7
	v_cmp_class_f32_e64 s[40:41], v7, s12
	s_nop 1
	v_cndmask_b32_e64 v6, v6, v7, s[40:41]
	v_cndmask_b32_e64 v7, v212, 0, s[10:11]
	v_cndmask_b32_e64 v7, v7, 1.0, vcc
	v_cmp_class_f32_e64 s[10:11], v19, s12
	s_nop 1
	v_cndmask_b32_e64 v6, |v6|, v7, s[10:11]
	v_mul_f32_e32 v6, v6, v0
	v_and_b32_e32 v7, 0x7fffffff, v6
	v_cmp_nlt_f32_e64 s[10:11], |v6|, s5
	s_and_saveexec_b64 s[12:13], s[10:11]
	s_xor_b64 s[10:11], exec, s[12:13]
	s_cbranch_execz .LBB0_1037
; __device__ void phase0(const Params& P, LAS unsigned char* lds, const int G, const int bid) {
;     ...
;           const float inv = powf(10000.0f, -(float)(2 * f) / 128.0f); const float ang = (float)pos * inv; float s, c; sincosf(ang, &s, &c); rope[i] = (f32x2){c, s}; } }
	v_lshrrev_b32_e32 v0, 23, v7
	v_add_u32_e32 v0, 0xffffff88, v0
	v_cmp_lt_u32_e32 vcc, 63, v0
	v_not_b32_e32 v8, 63
	s_mov_b32 s5, 0xfe5163ab
	v_cndmask_b32_e32 v8, 0, v8, vcc
	v_add_u32_e32 v0, v8, v0
	v_cmp_lt_u32_e64 s[40:41], 31, v0
	s_nop 1
	v_cndmask_b32_e64 v8, 0, v221, s[40:41]
	v_add_u32_e32 v0, v8, v0
	v_cmp_lt_u32_e64 s[42:43], 31, v0
	s_nop 1
	v_cndmask_b32_e64 v8, 0, v221, s[42:43]
	v_add_u32_e32 v19, v8, v0
	v_and_b32_e32 v0, 0x7fffff, v7
	v_or_b32_e32 v22, 0x800000, v0
	v_mad_u64_u32 v[8:9], s[12:13], v22, s5, 0
	v_mov_b32_e32 v0, v9
	s_mov_b32 s5, 0x3c439041
	v_mad_u64_u32 v[10:11], s[12:13], v22, s5, v[0:1]
	v_mov_b32_e32 v0, v11
	s_mov_b32 s5, 0xdb629599
	v_mad_u64_u32 v[12:13], s[12:13], v22, s5, v[0:1]
	v_mov_b32_e32 v0, v13
	s_mov_b32 s5, 0xf534ddc0
	v_mad_u64_u32 v[14:15], s[12:13], v22, s5, v[0:1]
	v_mov_b32_e32 v0, v15
	s_mov_b32 s5, 0xfc2757d1
	v_mad_u64_u32 v[16:17], s[12:13], v22, s5, v[0:1]
	v_mov_b32_e32 v0, v17
	s_mov_b32 s5, 0x4e441529
	v_mad_u64_u32 v[20:21], s[12:13], v22, s5, v[0:1]
	v_mov_b32_e32 v0, v21
	s_mov_b32 s5, 0xa2f9836e
	v_mad_u64_u32 v[22:23], s[12:13], v22, s5, v[0:1]
	v_cndmask_b32_e32 v9, v20, v14, vcc
	v_cndmask_b32_e32 v0, v22, v16, vcc
	v_cndmask_b32_e32 v13, v23, v20, vcc
	v_cndmask_b32_e64 v11, v0, v9, s[40:41]
	v_cndmask_b32_e64 v0, v13, v0, s[40:41]
	v_cndmask_b32_e32 v13, v16, v12, vcc
	v_cndmask_b32_e64 v9, v9, v13, s[40:41]
	v_cndmask_b32_e64 v0, v0, v11, s[42:43]
	v_cndmask_b32_e64 v11, v11, v9, s[42:43]
	v_sub_u32_e32 v15, 32, v19
	v_alignbit_b32 v16, v0, v11, v15
	v_cmp_eq_u32_e64 s[44:45], 0, v19
	v_cndmask_b32_e32 v8, v12, v8, vcc
	s_mov_b32 s5, 0x3fc90fda
	v_cndmask_b32_e64 v16, v16, v0, s[44:45]
	v_cndmask_b32_e32 v0, v14, v10, vcc
	v_cndmask_b32_e64 v10, v13, v0, s[40:41]
	v_cndmask_b32_e64 v9, v9, v10, s[42:43]
	v_alignbit_b32 v13, v11, v9, v15
	v_cndmask_b32_e64 v11, v13, v11, s[44:45]
	v_bfe_u32 v17, v16, 29, 1
	v_cndmask_b32_e64 v0, v0, v8, s[40:41]
	v_alignbit_b32 v13, v16, v11, 30
	v_sub_u32_e32 v19, 0, v17
	v_cndmask_b32_e64 v0, v10, v0, s[42:43]
	v_xor_b32_e32 v13, v13, v19
	v_alignbit_b32 v8, v9, v0, v15
	v_cndmask_b32_e64 v8, v8, v9, s[44:45]
	v_ffbh_u32_e32 v10, v13
	v_alignbit_b32 v9, v11, v8, 30
	v_min_u32_e32 v10, 32, v10
	v_alignbit_b32 v0, v8, v0, 30
	v_xor_b32_e32 v9, v9, v19
	v_sub_u32_e32 v11, 31, v10
	v_xor_b32_e32 v0, v0, v19
	v_alignbit_b32 v12, v13, v9, v11
	v_alignbit_b32 v0, v9, v0, v11
	v_alignbit_b32 v8, v12, v0, 9
	v_ffbh_u32_e32 v9, v8
	v_min_u32_e32 v9, 32, v9
	v_lshrrev_b32_e32 v14, 29, v16
	v_not_b32_e32 v11, v9
	v_alignbit_b32 v0, v8, v0, v11
	v_lshlrev_b32_e32 v8, 31, v14
	v_or_b32_e32 v11, 0x33000000, v8
	v_add_lshl_u32 v9, v9, v10, 23
	v_lshrrev_b32_e32 v0, 9, v0
	v_sub_u32_e32 v9, v11, v9
	v_or_b32_e32 v8, 0.5, v8
	v_lshlrev_b32_e32 v10, 23, v10
	v_or_b32_e32 v0, v9, v0
	v_lshrrev_b32_e32 v9, 9, v12
	v_sub_u32_e32 v8, v8, v10
	v_or_b32_e32 v8, v9, v8
	v_mul_f32_e32 v9, 0x3fc90fda, v8
	v_fma_f32 v10, v8, s5, -v9
	v_fmac_f32_e32 v10, 0x33a22168, v8
	v_fmac_f32_e32 v10, 0x3fc90fda, v0
	v_lshrrev_b32_e32 v8, 30, v16
	v_add_f32_e32 v0, v9, v10
	v_add_u32_e32 v8, v17, v8

; #define LAS __attribute__((address_space(3)))
; __device__ __forceinline__ unsigned cvt_pk_bf16(float lo, float hi) { unsigned r; asm volatile("v_cvt_pk_bf16_f32 %0, %1, %2" : "=v"(r) : "v"(lo), "v"(hi)); return r; }
; __device__ void phase0(const Params& P, LAS unsigned char* lds, const int G, const int bid) {
;     ...
;       for (int row0 = bid * 8 + wid; row0 < NTOK; row0 += G * 8 * 4) {
;           f32x4 vv[4][4];
; #pragma unroll
;           for (int rr = 0; rr < 4; ++rr) { const int row = row0 + rr * G * 8; const float* xr = xrow(P, row < NTOK ? row : row0);
; #pragma unroll
;               for (int i = 0; i < 4; ++i) vv[rr][i] = __builtin_nontemporal_load((const f32x4*)(xr + 4 * lane + 256 * i)); }
; #pragma unroll
;           for (int rr = 0; rr < 4; ++rr) { const int row = row0 + rr * G * 8; if (row >= NTOK) continue;
;               f32x4 (&v)[4] = vv[rr]; float ss = 0.f;
; #pragma unroll
;               for (int i = 0; i < 4; ++i)
; #pragma unroll
;                   for (int j = 0; j < 4; ++j) ss += v[i][j] * v[i][j];
; #pragma unroll
;               for (int o = 32; o >= 1; o >>= 1) ss += __shfl_xor(ss, o);
;               const float rstd = rsqrtf(ss * (1.0f / DM) + 1e-6f);
;               float ga[16];
; #pragma unroll
;               for (int c = 0; c < 16; ++c) ga[c] = 0.f;
; #pragma unroll
;               for (int i = 0; i < 4; ++i) { v[i] = v[i] * rstd * w4[i];
;                   u32x2 w; w.x = cvt_pk_bf16(v[i][0], v[i][1]); w.y = cvt_pk_bf16(v[i][2], v[i][3]);
;                   *(u32x2*)(abf + (size_t)row * DM + 4 * lane + 256 * i) = w;
; #pragma unroll
;                   for (int j = 0; j < 4; ++j) { const LAS float* wr_ = wg + (j * 256 + i * 64 + lane) * 20; const float a = v[i][j];
; #pragma unroll
;                       for (int q = 0; q < 4; ++q) { const f32x4 wv = *(const LAS f32x4*)(wr_ + 4 * q);
;                           ga[4 * q] += a * wv[0]; ga[4 * q + 1] += a * wv[1]; ga[4 * q + 2] += a * wv[2]; ga[4 * q + 3] += a * wv[3]; } } }
.LBB0_1046:
	v_readlane_b32 s60, v254, 34
	v_ashrrev_i32_e32 v89, 31, v88
	v_readlane_b32 s61, v254, 35
	v_readlane_b32 s62, v254, 36
	v_readlane_b32 s63, v254, 37
	v_cmp_gt_i32_e64 s[50:51], s14, v88
	s_waitcnt vmcnt(4)
	v_add_u32_e32 v20, 0xffffc000, v88
	v_mov_b32_e32 v28, s63
	v_mov_b32_e32 v29, s61
	v_mov_b32_e32 v30, s62
	v_mov_b32_e32 v31, s60
	v_cndmask_b32_e64 v21, 0, v89, s[50:51]
	v_cndmask_b32_e64 v20, v20, v88, s[50:51]
	s_waitcnt lgkmcnt(0)
	v_cndmask_b32_e64 v19, v28, v29, s[50:51]
	v_cndmask_b32_e64 v18, v30, v31, s[50:51]
	v_lshlrev_b64 v[20:21], 12, v[20:21]
	v_lshl_add_u64 v[18:19], v[18:19], 0, v[20:21]
	v_lshl_add_u64 v[18:19], v[18:19], 0, v[0:1]
	global_load_dwordx4 v[92:95], v[18:19], off nt
	global_load_dwordx4 v[66:69], v[18:19], off offset:3072 nt
	global_load_dwordx4 v[74:77], v[18:19], off offset:1024 nt
	global_load_dwordx4 v[70:73], v[18:19], off offset:2048 nt
	v_add_u32_e32 v82, s0, v88
	v_add_u32_e32 v86, s10, v88
	v_cmp_gt_i32_e64 s[50:51], s15, v82
	v_add_u32_e32 v84, s11, v88
	v_readlane_b32 s64, v254, 38
	v_cndmask_b32_e64 v18, v88, v82, s[50:51]
	v_cmp_gt_i32_e64 s[50:51], s15, v86
	v_add_u32_e32 v20, 0xffffc000, v18
	v_ashrrev_i32_e32 v19, 31, v18
	v_cndmask_b32_e64 v22, v88, v86, s[50:51]
	v_cmp_gt_i32_e64 s[50:51], s15, v84
	v_add_u32_e32 v24, 0xffffc000, v22
	v_ashrrev_i32_e32 v23, 31, v22
	v_cndmask_b32_e64 v32, v88, v84, s[50:51]
	v_cmp_gt_i32_e64 s[50:51], s14, v18
	v_ashrrev_i32_e32 v34, 31, v32
	v_add_u32_e32 v33, 0xffffc000, v32
	v_cndmask_b32_e64 v19, 0, v19, s[50:51]
	v_cndmask_b32_e64 v18, v20, v18, s[50:51]
	v_cndmask_b32_e64 v21, v28, v29, s[50:51]
	v_cndmask_b32_e64 v20, v30, v31, s[50:51]
	v_cmp_gt_i32_e64 s[50:51], s14, v22
	v_lshlrev_b64 v[18:19], 12, v[18:19]
	v_lshl_add_u64 v[18:19], v[20:21], 0, v[18:19]
	v_cndmask_b32_e64 v22, v24, v22, s[50:51]
	v_cndmask_b32_e64 v23, 0, v23, s[50:51]
	v_lshlrev_b64 v[22:23], 12, v[22:23]
	v_lshl_add_u64 v[18:19], v[18:19], 0, v[0:1]
	global_load_dwordx4 v[62:65], v[18:19], off nt
	global_load_dwordx4 v[58:61], v[18:19], off offset:1024 nt
	global_load_dwordx4 v[54:57], v[18:19], off offset:2048 nt
	global_load_dwordx4 v[50:53], v[18:19], off offset:3072 nt
	v_readlane_b32 s65, v254, 39
	v_readlane_b32 s66, v254, 40
	v_readlane_b32 s67, v254, 41
	v_readlane_b32 s68, v254, 42
	v_readlane_b32 s69, v254, 43
	v_readlane_b32 s70, v254, 44
	v_readlane_b32 s71, v254, 45
	v_readlane_b32 s72, v254, 46
	v_readlane_b32 s73, v254, 47
	v_readlane_b32 s74, v254, 48
	v_readlane_b32 s75, v254, 49
	s_waitcnt vmcnt(7)
	v_mul_f32_e32 v35, v93, v93
	v_fmac_f32_e32 v35, v92, v92
	v_fmac_f32_e32 v35, v94, v94
	v_fmac_f32_e32 v35, v95, v95
	s_waitcnt vmcnt(5)
	v_fmac_f32_e32 v35, v74, v74
	v_fmac_f32_e32 v35, v75, v75
	v_fmac_f32_e32 v35, v76, v76
	v_fmac_f32_e32 v35, v77, v77
	s_waitcnt vmcnt(4)
	v_fmac_f32_e32 v35, v70, v70
	v_fmac_f32_e32 v35, v71, v71
	v_fmac_f32_e32 v35, v72, v72
	v_pk_mul_f32 v[26:27], v[66:67], v[66:67]
	v_fmac_f32_e32 v35, v73, v73
	v_add_f32_e32 v26, v26, v35
	v_pk_mul_f32 v[24:25], v[68:69], v[68:69]
	v_add_f32_e32 v26, v27, v26
	v_add_f32_e32 v24, v24, v26
	v_add_f32_e32 v26, v25, v24
	ds_bpermute_b32 v35, v96, v26
	v_cndmask_b32_e64 v25, v28, v29, s[50:51]
	v_cndmask_b32_e64 v24, v30, v31, s[50:51]
	v_cmp_gt_i32_e64 s[50:51], s14, v32
	v_lshl_add_u64 v[20:21], v[24:25], 0, v[22:23]
	v_lshl_add_u64 v[20:21], v[20:21], 0, v[0:1]
	v_cndmask_b32_e64 v27, 0, v34, s[50:51]
	s_waitcnt lgkmcnt(0)
	v_add_f32_e32 v34, v26, v35
	ds_bpermute_b32 v35, v97, v34
	v_cndmask_b32_e64 v29, v28, v29, s[50:51]
	v_cndmask_b32_e64 v28, v30, v31, s[50:51]
	v_cndmask_b32_e64 v26, v33, v32, s[50:51]
	v_lshlrev_b64 v[26:27], 12, v[26:27]
	s_waitcnt lgkmcnt(0)
	v_add_f32_e32 v30, v34, v35
	ds_bpermute_b32 v31, v98, v30
	v_lshl_add_u64 v[22:23], v[28:29], 0, v[26:27]
	v_lshl_add_u64 v[116:117], v[22:23], 0, v[0:1]
	global_load_dwordx4 v[46:49], v[20:21], off nt
	global_load_dwordx4 v[42:45], v[20:21], off offset:1024 nt
	global_load_dwordx4 v[38:41], v[20:21], off offset:2048 nt
	global_load_dwordx4 v[34:37], v[20:21], off offset:3072 nt
	s_waitcnt lgkmcnt(0)
	v_add_f32_e32 v24, v30, v31
	ds_bpermute_b32 v25, v99, v24
	s_waitcnt lgkmcnt(0)
	v_add_f32_e32 v22, v24, v25
	ds_bpermute_b32 v23, v100, v22
	s_waitcnt lgkmcnt(0)
	v_add_f32_e32 v18, v22, v23
	ds_bpermute_b32 v19, v101, v18
	s_waitcnt lgkmcnt(0)
	v_add_f32_e32 v18, v18, v19
	v_fmamk_f32 v18, v18, 0x3a800000, v210
	v_mul_f32_e32 v19, 0x4b800000, v18
	v_cmp_gt_f32_e64 s[50:51], s30, v18
	s_nop 1
	v_cndmask_b32_e64 v18, v18, v19, s[50:51]
	v_rsq_f32_e32 v83, v18
	global_load_dwordx4 v[30:33], v[116:117], off nt
	global_load_dwordx4 v[26:29], v[116:117], off offset:1024 nt
	global_load_dwordx4 v[22:25], v[116:117], off offset:2048 nt
	global_load_dwordx4 v[18:21], v[116:117], off offset:3072 nt
	v_mul_f32_e32 v85, 0x45800000, v83
	v_cndmask_b32_e64 v90, v83, v85, s[50:51]
	v_pk_mul_f32 v[116:117], v[92:93], v[90:91] op_sel_hi:[1,0]
	v_pk_mul_f32 v[92:93], v[94:95], v[90:91] op_sel_hi:[1,0]
	v_pk_mul_f32 v[138:139], v[2:3], v[116:117]
	v_pk_mul_f32 v[92:93], v[4:5], v[92:93]
	v_cvt_pk_bf16_f32 v94, v138, v139
	v_pk_mul_f32 v[74:75], v[74:75], v[90:91] op_sel_hi:[1,0]
	v_cvt_pk_bf16_f32 v95, v92, v93
	ds_read_b128 v[116:119], v102 offset:40960
	ds_read_b128 v[120:123], v102 offset:40976
	ds_read_b128 v[124:127], v102 offset:61440
	ds_read_b128 v[128:131], v102 offset:61456
	v_pk_mul_f32 v[76:77], v[76:77], v[90:91] op_sel_hi:[1,0]
	v_pk_mul_f32 v[70:71], v[70:71], v[90:91] op_sel_hi:[1,0]
	s_waitcnt lgkmcnt(3)
	v_fma_f32 v87, v117, v138, 0
	v_fma_f32 v85, v118, v138, 0
	v_fma_f32 v83, v119, v138, 0
	s_waitcnt lgkmcnt(2)
; #define LAS __attribute__((address_space(3)))
; __device__ __forceinline__ unsigned cvt_pk_bf16(float lo, float hi) { unsigned r; asm volatile("v_cvt_pk_bf16_f32 %0, %1, %2" : "=v"(r) : "v"(lo), "v"(hi)); return r; }
; __device__ void phase0(const Params& P, LAS unsigned char* lds, const int G, const int bid) {
;     ...
;               for (int i = 0; i < 4; ++i) { v[i] = v[i] * rstd * w4[i];
;                   u32x2 w; w.x = cvt_pk_bf16(v[i][0], v[i][1]); w.y = cvt_pk_bf16(v[i][2], v[i][3]);
;                   *(u32x2*)(abf + (size_t)row * DM + 4 * lane + 256 * i) = w;
; #pragma unroll
;                   for (int j = 0; j < 4; ++j) { const LAS float* wr_ = wg + (j * 256 + i * 64 + lane) * 20; const float a = v[i][j];
; #pragma unroll
;                       for (int q = 0; q < 4; ++q) { const f32x4 wv = *(const LAS f32x4*)(wr_ + 4 * q);
;                           ga[4 * q] += a * wv[0]; ga[4 * q + 1] += a * wv[1]; ga[4 * q + 2] += a * wv[2]; ga[4 * q + 3] += a * wv[3]; } } }
	v_fma_f32 v120, v120, v138, 0
	v_fma_f32 v119, v121, v138, 0
	v_fma_f32 v118, v122, v138, 0
	v_fma_f32 v117, v123, v138, 0
	s_waitcnt lgkmcnt(1)
	v_fmac_f32_e32 v85, v126, v139
	v_fmac_f32_e32 v83, v127, v139
	s_waitcnt lgkmcnt(0)
	v_fmac_f32_e32 v120, v128, v139
	v_fmac_f32_e32 v119, v129, v139
	v_fmac_f32_e32 v118, v130, v139
	v_fmac_f32_e32 v117, v131, v139
	ds_read_b128 v[126:129], v102 offset:40992
	ds_read_b128 v[130:133], v102 offset:41008
	v_fmac_f32_e32 v87, v125, v139
	v_fma_f32 v116, v116, v138, 0
	v_fmac_f32_e32 v116, v124, v139
	s_waitcnt lgkmcnt(1)
	v_fma_f32 v125, v126, v138, 0
	v_fma_f32 v123, v127, v138, 0
	v_fma_f32 v122, v128, v138, 0
	v_fma_f32 v121, v129, v138, 0
	ds_read_b128 v[126:129], v102 offset:61472
	ds_read_b128 v[134:137], v102 offset:61488
	s_waitcnt lgkmcnt(2)
	v_fma_f32 v124, v133, v138, 0
	v_pk_mul_f32 v[76:77], v[8:9], v[76:77]
	v_pk_mul_f32 v[72:73], v[72:73], v[90:91] op_sel_hi:[1,0]
	s_waitcnt lgkmcnt(1)
	v_fmac_f32_e32 v125, v126, v139
	v_fmac_f32_e32 v123, v127, v139
	v_fmac_f32_e32 v122, v128, v139
	v_fma_f32 v128, v130, v138, 0
	v_fma_f32 v127, v131, v138, 0
	v_fma_f32 v126, v132, v138, 0
	s_waitcnt lgkmcnt(0)
	v_fmac_f32_e32 v128, v134, v139
	v_fmac_f32_e32 v127, v135, v139
	v_fmac_f32_e32 v126, v136, v139
	v_fmac_f32_e32 v124, v137, v139
	ds_read_b128 v[130:133], v103 offset:40960
	ds_read_b128 v[134:137], v103 offset:40976
	v_fmac_f32_e32 v121, v129, v139
	v_pk_mul_f32 v[72:73], v[12:13], v[72:73]
	v_pk_mul_f32 v[66:67], v[66:67], v[90:91] op_sel_hi:[1,0]
	s_waitcnt lgkmcnt(1)
	v_fmac_f32_e32 v116, v130, v92
	v_fmac_f32_e32 v87, v131, v92
	v_fmac_f32_e32 v85, v132, v92
	v_fmac_f32_e32 v83, v133, v92
	s_waitcnt lgkmcnt(0)
	v_fmac_f32_e32 v120, v134, v92
	v_fmac_f32_e32 v119, v135, v92
	v_fmac_f32_e32 v118, v136, v92
	v_fmac_f32_e32 v117, v137, v92
	ds_read_b128 v[130:133], v103 offset:40992
	ds_read_b128 v[134:137], v103 offset:41008
	v_pk_mul_f32 v[68:69], v[68:69], v[90:91] op_sel_hi:[1,0]
	s_waitcnt lgkmcnt(1)
	v_fmac_f32_e32 v125, v130, v92
	v_fmac_f32_e32 v123, v131, v92
	v_fmac_f32_e32 v122, v132, v92
	v_fmac_f32_e32 v121, v133, v92
	s_waitcnt lgkmcnt(0)
	v_fmac_f32_e32 v128, v134, v92
	v_fmac_f32_e32 v127, v135, v92
	v_fmac_f32_e32 v126, v136, v92
	v_fmac_f32_e32 v124, v137, v92
	ds_read_b128 v[130:133], v103 offset:61440
	ds_read_b128 v[134:137], v103 offset:61456
	v_pk_mul_f32 v[68:69], v[16:17], v[68:69]
	s_waitcnt lgkmcnt(1)
	v_fmac_f32_e32 v116, v130, v93
	v_fmac_f32_e32 v87, v131, v93
	v_fmac_f32_e32 v85, v132, v93
	v_fmac_f32_e32 v83, v133, v93
	s_waitcnt lgkmcnt(0)
	v_fmac_f32_e32 v120, v134, v93
	v_fmac_f32_e32 v119, v135, v93
	v_fmac_f32_e32 v118, v136, v93
	v_fmac_f32_e32 v117, v137, v93
	ds_read_b128 v[130:133], v103 offset:61472
	ds_read_b128 v[134:137], v103 offset:61488
	s_waitcnt lgkmcnt(1)
	v_fmac_f32_e32 v125, v130, v93
	v_fmac_f32_e32 v123, v131, v93
	v_fmac_f32_e32 v122, v132, v93
	v_fmac_f32_e32 v121, v133, v93
	s_waitcnt lgkmcnt(0)
	v_fmac_f32_e32 v128, v134, v93
	v_fmac_f32_e32 v127, v135, v93
	v_fmac_f32_e32 v126, v136, v93
	v_fmac_f32_e32 v124, v137, v93
	v_lshlrev_b64 v[92:93], 11, v[88:89]
	v_lshl_add_u64 v[92:93], v[80:81], 0, v[92:93]
	global_store_dwordx2 v[92:93], v[94:95], off
	v_pk_mul_f32 v[94:95], v[6:7], v[74:75]
	s_nop 0
	v_cvt_pk_bf16_f32 v74, v94, v95
	v_cvt_pk_bf16_f32 v75, v76, v77
	ds_read_b128 v[130:133], v102 offset:46080
	ds_read_b128 v[134:137], v102 offset:46096
	s_waitcnt lgkmcnt(1)
	v_fmac_f32_e32 v116, v130, v94
	v_fmac_f32_e32 v87, v131, v94
	v_fmac_f32_e32 v85, v132, v94
	v_fmac_f32_e32 v83, v133, v94
	s_waitcnt lgkmcnt(0)
	v_fmac_f32_e32 v120, v134, v94
	v_fmac_f32_e32 v119, v135, v94
	v_fmac_f32_e32 v118, v136, v94
	v_fmac_f32_e32 v117, v137, v94
	ds_read_b128 v[130:133], v102 offset:46112
	ds_read_b128 v[134:137], v102 offset:46128
	s_waitcnt lgkmcnt(1)
	v_fmac_f32_e32 v125, v130, v94
	v_fmac_f32_e32 v123, v131, v94
	v_fmac_f32_e32 v122, v132, v94
	v_fmac_f32_e32 v121, v133, v94
	s_waitcnt lgkmcnt(0)
	v_fmac_f32_e32 v128, v134, v94
	v_fmac_f32_e32 v127, v135, v94
	v_fmac_f32_e32 v126, v136, v94
	v_fmac_f32_e32 v124, v137, v94
	ds_read_b128 v[130:133], v103 offset:25600
	ds_read_b128 v[134:137], v103 offset:25616
	s_waitcnt lgkmcnt(1)
	v_fmac_f32_e32 v116, v130, v95
	v_fmac_f32_e32 v87, v131, v95
	v_fmac_f32_e32 v85, v132, v95
	v_fmac_f32_e32 v83, v133, v95
	s_waitcnt lgkmcnt(0)
	v_fmac_f32_e32 v120, v134, v95
	v_fmac_f32_e32 v119, v135, v95
	v_fmac_f32_e32 v118, v136, v95
	v_fmac_f32_e32 v117, v137, v95
	ds_read_b128 v[130:133], v103 offset:25632
	ds_read_b128 v[134:137], v103 offset:25648
	s_waitcnt lgkmcnt(1)
	v_fmac_f32_e32 v125, v95, v130
	v_fmac_f32_e32 v123, v95, v131
	v_fmac_f32_e32 v122, v95, v132
	v_fmac_f32_e32 v121, v95, v133
	s_waitcnt lgkmcnt(0)
	v_fmac_f32_e32 v128, v95, v134
	v_fmac_f32_e32 v127, v95, v135
	v_fmac_f32_e32 v126, v95, v136
	v_fmac_f32_e32 v124, v95, v137
	ds_read_b128 v[130:133], v103 offset:46080
	ds_read_b128 v[134:137], v103 offset:46096
	v_pk_mul_f32 v[94:95], v[10:11], v[70:71]
	s_waitcnt lgkmcnt(1)
	v_fmac_f32_e32 v116, v76, v130
	v_fmac_f32_e32 v87, v76, v131
	v_fmac_f32_e32 v85, v76, v132
	v_fmac_f32_e32 v83, v76, v133
	s_waitcnt lgkmcnt(0)
	v_fmac_f32_e32 v120, v76, v134
	v_fmac_f32_e32 v119, v76, v135
	v_fmac_f32_e32 v118, v76, v136
	v_fmac_f32_e32 v117, v76, v137
	ds_read_b128 v[130:133], v103 offset:46112
	ds_read_b128 v[134:137], v103 offset:46128
	s_waitcnt lgkmcnt(1)
	v_fmac_f32_e32 v125, v76, v130
	v_fmac_f32_e32 v123, v76, v131
	v_fmac_f32_e32 v122, v76, v132
	v_fmac_f32_e32 v121, v76, v133
	s_waitcnt lgkmcnt(0)
; #define LAS __attribute__((address_space(3)))
; __device__ __forceinline__ unsigned cvt_pk_bf16(float lo, float hi) { unsigned r; asm volatile("v_cvt_pk_bf16_f32 %0, %1, %2" : "=v"(r) : "v"(lo), "v"(hi)); return r; }
; __device__ void phase0(const Params& P, LAS unsigned char* lds, const int G, const int bid) {
;     ...
;               for (int i = 0; i < 4; ++i) { v[i] = v[i] * rstd * w4[i];
;                   u32x2 w; w.x = cvt_pk_bf16(v[i][0], v[i][1]); w.y = cvt_pk_bf16(v[i][2], v[i][3]);
;                   *(u32x2*)(abf + (size_t)row * DM + 4 * lane + 256 * i) = w;
; #pragma unroll
;                   for (int j = 0; j < 4; ++j) { const LAS float* wr_ = wg + (j * 256 + i * 64 + lane) * 20; const float a = v[i][j];
; #pragma unroll
;                       for (int q = 0; q < 4; ++q) { const f32x4 wv = *(const LAS f32x4*)(wr_ + 4 * q);
;                           ga[4 * q] += a * wv[0]; ga[4 * q + 1] += a * wv[1]; ga[4 * q + 2] += a * wv[2]; ga[4 * q + 3] += a * wv[3]; } } }
	v_fmac_f32_e32 v128, v76, v134
	v_fmac_f32_e32 v127, v76, v135
	v_fmac_f32_e32 v126, v76, v136
	v_fmac_f32_e32 v124, v76, v137
	ds_read_b128 v[130:133], v104
	ds_read_b128 v[134:137], v105
	s_waitcnt lgkmcnt(1)
	v_fmac_f32_e32 v116, v77, v130
	v_fmac_f32_e32 v87, v77, v131
	v_fmac_f32_e32 v85, v77, v132
	v_fmac_f32_e32 v83, v77, v133
	s_waitcnt lgkmcnt(0)
	v_fmac_f32_e32 v120, v77, v134
	v_fmac_f32_e32 v119, v77, v135
	v_fmac_f32_e32 v118, v77, v136
	v_fmac_f32_e32 v117, v77, v137
	ds_read_b128 v[130:133], v106
	ds_read_b128 v[134:137], v107
	global_store_dwordx2 v[92:93], v[74:75], off offset:512
	v_cvt_pk_bf16_f32 v70, v94, v95
	v_cvt_pk_bf16_f32 v71, v72, v73
	s_waitcnt lgkmcnt(1)
	v_fmac_f32_e32 v125, v77, v130
	v_fmac_f32_e32 v123, v77, v131
	v_fmac_f32_e32 v122, v77, v132
	v_fmac_f32_e32 v121, v77, v133
	s_waitcnt lgkmcnt(0)
	v_fmac_f32_e32 v128, v77, v134
	v_fmac_f32_e32 v127, v77, v135
	v_fmac_f32_e32 v126, v77, v136
	v_fmac_f32_e32 v124, v77, v137
	ds_read_b128 v[74:77], v102 offset:51200
	ds_read_b128 v[130:133], v102 offset:51216
	s_waitcnt lgkmcnt(1)
	v_fmac_f32_e32 v116, v94, v74
	v_fmac_f32_e32 v87, v94, v75
	v_fmac_f32_e32 v85, v94, v76
	v_fmac_f32_e32 v83, v94, v77
	s_waitcnt lgkmcnt(0)
	v_fmac_f32_e32 v120, v94, v130
	v_fmac_f32_e32 v119, v94, v131
	v_fmac_f32_e32 v118, v94, v132
	v_fmac_f32_e32 v117, v94, v133
	ds_read_b128 v[74:77], v102 offset:51232
	ds_read_b128 v[130:133], v102 offset:51248
	s_waitcnt lgkmcnt(1)
	v_fmac_f32_e32 v125, v94, v74
	v_fmac_f32_e32 v123, v94, v75
	v_fmac_f32_e32 v122, v94, v76
	v_fmac_f32_e32 v121, v94, v77
	s_waitcnt lgkmcnt(0)
	v_fmac_f32_e32 v128, v94, v130
	v_fmac_f32_e32 v127, v94, v131
	v_fmac_f32_e32 v126, v94, v132
	v_fmac_f32_e32 v124, v94, v133
	ds_read_b128 v[74:77], v103 offset:30720
	ds_read_b128 v[130:133], v103 offset:30736
	s_waitcnt lgkmcnt(1)
	v_fmac_f32_e32 v116, v95, v74
	v_fmac_f32_e32 v87, v95, v75
	v_fmac_f32_e32 v85, v95, v76
	v_fmac_f32_e32 v83, v95, v77
	s_waitcnt lgkmcnt(0)
	v_fmac_f32_e32 v120, v95, v130
	v_fmac_f32_e32 v119, v95, v131
	v_fmac_f32_e32 v118, v95, v132
	v_fmac_f32_e32 v117, v95, v133
	ds_read_b128 v[74:77], v103 offset:30752
	ds_read_b128 v[130:133], v103 offset:30768
	s_waitcnt lgkmcnt(1)
	v_fmac_f32_e32 v125, v95, v74
	v_fmac_f32_e32 v123, v95, v75
	v_fmac_f32_e32 v122, v95, v76
	v_fmac_f32_e32 v121, v95, v77
	s_waitcnt lgkmcnt(0)
	v_fmac_f32_e32 v128, v95, v130
	v_fmac_f32_e32 v127, v95, v131
	v_fmac_f32_e32 v126, v95, v132
	v_fmac_f32_e32 v124, v95, v133
	ds_read_b128 v[74:77], v103 offset:51200
	ds_read_b128 v[130:133], v103 offset:51216
	v_pk_mul_f32 v[94:95], v[14:15], v[66:67]
	s_waitcnt lgkmcnt(1)
	v_fmac_f32_e32 v116, v72, v74
	v_fmac_f32_e32 v87, v72, v75
	v_fmac_f32_e32 v85, v72, v76
	v_fmac_f32_e32 v83, v72, v77
	s_waitcnt lgkmcnt(0)
	v_fmac_f32_e32 v120, v72, v130
	v_fmac_f32_e32 v119, v72, v131
	v_fmac_f32_e32 v118, v72, v132
	v_fmac_f32_e32 v117, v72, v133
	ds_read_b128 v[74:77], v103 offset:51232
	ds_read_b128 v[130:133], v103 offset:51248
	s_waitcnt lgkmcnt(1)
	v_fmac_f32_e32 v125, v72, v74
	v_fmac_f32_e32 v123, v72, v75
	v_fmac_f32_e32 v122, v72, v76
	v_fmac_f32_e32 v121, v72, v77
	s_waitcnt lgkmcnt(0)
	v_fmac_f32_e32 v128, v72, v130
	v_fmac_f32_e32 v127, v72, v131
	v_fmac_f32_e32 v126, v72, v132
	v_fmac_f32_e32 v124, v72, v133
	ds_read_b128 v[74:77], v108
	ds_read_b128 v[130:133], v109
	s_waitcnt lgkmcnt(1)
	v_fmac_f32_e32 v116, v73, v74
	v_fmac_f32_e32 v87, v73, v75
	v_fmac_f32_e32 v85, v73, v76
	v_fmac_f32_e32 v83, v73, v77
	s_waitcnt lgkmcnt(0)
	v_fmac_f32_e32 v120, v73, v130
	v_fmac_f32_e32 v119, v73, v131
	v_fmac_f32_e32 v118, v73, v132
	v_fmac_f32_e32 v117, v73, v133
	ds_read_b128 v[74:77], v110
	ds_read_b128 v[130:133], v111
	global_store_dwordx2 v[92:93], v[70:71], off offset:1024
	v_cvt_pk_bf16_f32 v66, v94, v95
	v_cvt_pk_bf16_f32 v67, v68, v69
	s_waitcnt lgkmcnt(1)
	v_fmac_f32_e32 v125, v73, v74
	v_fmac_f32_e32 v123, v73, v75
	v_fmac_f32_e32 v122, v73, v76
	v_fmac_f32_e32 v121, v73, v77
	s_waitcnt lgkmcnt(0)
	v_fmac_f32_e32 v128, v73, v130
	v_fmac_f32_e32 v127, v73, v131
	v_fmac_f32_e32 v126, v73, v132
	v_fmac_f32_e32 v124, v73, v133
	ds_read_b128 v[70:73], v102 offset:56320
	ds_read_b128 v[74:77], v102 offset:56336
	s_waitcnt lgkmcnt(1)
	v_fmac_f32_e32 v116, v94, v70
	v_fmac_f32_e32 v87, v94, v71
	v_fmac_f32_e32 v85, v94, v72
	v_fmac_f32_e32 v83, v94, v73
	s_waitcnt lgkmcnt(0)
	v_fmac_f32_e32 v120, v94, v74
	v_fmac_f32_e32 v119, v94, v75
	v_fmac_f32_e32 v118, v94, v76
	v_fmac_f32_e32 v117, v94, v77
	ds_read_b128 v[70:73], v102 offset:56352
	ds_read_b128 v[74:77], v102 offset:56368
	s_waitcnt lgkmcnt(1)
	v_fmac_f32_e32 v125, v94, v70
	v_fmac_f32_e32 v123, v94, v71
	v_fmac_f32_e32 v122, v94, v72
	v_fmac_f32_e32 v121, v94, v73
	s_waitcnt lgkmcnt(0)
	v_fmac_f32_e32 v128, v94, v74
	v_fmac_f32_e32 v127, v94, v75
	v_fmac_f32_e32 v126, v94, v76
	v_fmac_f32_e32 v124, v94, v77
	ds_read_b128 v[70:73], v103 offset:35840
	ds_read_b128 v[74:77], v103 offset:35856
	s_waitcnt lgkmcnt(1)
	v_fmac_f32_e32 v116, v95, v70
	v_fmac_f32_e32 v87, v95, v71
	v_fmac_f32_e32 v85, v95, v72
	v_fmac_f32_e32 v83, v95, v73
	s_waitcnt lgkmcnt(0)
	v_fmac_f32_e32 v120, v95, v74
	v_fmac_f32_e32 v119, v95, v75
	v_fmac_f32_e32 v118, v95, v76
	v_fmac_f32_e32 v117, v95, v77
	ds_read_b128 v[70:73], v103 offset:35872
	ds_read_b128 v[74:77], v103 offset:35888
	s_waitcnt lgkmcnt(1)
	v_fmac_f32_e32 v125, v95, v70
	v_fmac_f32_e32 v123, v95, v71
	v_fmac_f32_e32 v122, v95, v72
	v_fmac_f32_e32 v121, v95, v73
	s_waitcnt lgkmcnt(0)
	v_fmac_f32_e32 v128, v95, v74
	v_fmac_f32_e32 v127, v95, v75
	v_fmac_f32_e32 v126, v95, v76
	v_fmac_f32_e32 v124, v95, v77
	ds_read_b128 v[70:73], v103 offset:56320
	ds_read_b128 v[74:77], v103 offset:56336
	s_waitcnt lgkmcnt(1)
; #define LAS __attribute__((address_space(3)))
; __device__ __forceinline__ float logsigmoidf_(float x) { return fminf(x, 0.0f) - log1pf(__expf(-fabsf(x))); }
; __device__ void phase0(const Params& P, LAS unsigned char* lds, const int G, const int bid) {
;     ...
;                   for (int j = 0; j < 4; ++j) { const LAS float* wr_ = wg + (j * 256 + i * 64 + lane) * 20; const float a = v[i][j];
; #pragma unroll
;                       for (int q = 0; q < 4; ++q) { const f32x4 wv = *(const LAS f32x4*)(wr_ + 4 * q);
;                           ga[4 * q] += a * wv[0]; ga[4 * q + 1] += a * wv[1]; ga[4 * q + 2] += a * wv[2]; ga[4 * q + 3] += a * wv[3]; } } }
;               float r8[8], r4[4], r2[2], r1;
; #pragma unroll
;               for (int c = 0; c < 8; ++c) { const bool hi = (lane & 32) != 0; const float send = hi ? ga[c] : ga[c + 8], keep = hi ? ga[c + 8] : ga[c]; r8[c] = keep + __shfl_xor(send, 32); }
; #pragma unroll
;               for (int c = 0; c < 4; ++c) { const bool hi = (lane & 16) != 0; const float send = hi ? r8[c] : r8[c + 4], keep = hi ? r8[c + 4] : r8[c]; r4[c] = keep + __shfl_xor(send, 16); }
; #pragma unroll
;               for (int c = 0; c < 2; ++c) { const bool hi = (lane & 8) != 0; const float send = hi ? r4[c] : r4[c + 2], keep = hi ? r4[c + 2] : r4[c]; r2[c] = keep + __shfl_xor(send, 8); }
;               { const bool hi = (lane & 4) != 0; const float send = hi ? r2[0] : r2[1], keep = hi ? r2[1] : r2[0]; r1 = keep + __shfl_xor(send, 4); }
;               r1 += __shfl_xor(r1, 2); r1 += __shfl_xor(r1, 1);
;               if ((lane & 3) == 0) { float gv = r1 + gbias; if (gcol >= 8) gv = logsigmoidf_(gv); gates[(size_t)row * 16 + gcol] = gv; }
	v_fmac_f32_e32 v116, v68, v70
	v_fmac_f32_e32 v87, v68, v71
	v_fmac_f32_e32 v85, v68, v72
	v_fmac_f32_e32 v83, v68, v73
	s_waitcnt lgkmcnt(0)
	v_fmac_f32_e32 v120, v68, v74
	v_fmac_f32_e32 v119, v68, v75
	v_fmac_f32_e32 v118, v68, v76
	v_fmac_f32_e32 v117, v68, v77
	ds_read_b128 v[70:73], v103 offset:56352
	ds_read_b128 v[74:77], v103 offset:56368
	s_waitcnt lgkmcnt(1)
	v_fmac_f32_e32 v125, v68, v70
	v_fmac_f32_e32 v123, v68, v71
	v_fmac_f32_e32 v122, v68, v72
	v_fmac_f32_e32 v121, v68, v73
	s_waitcnt lgkmcnt(0)
	v_fmac_f32_e32 v128, v68, v74
	v_fmac_f32_e32 v127, v68, v75
	v_fmac_f32_e32 v126, v68, v76
	v_fmac_f32_e32 v124, v68, v77
	ds_read_b128 v[70:73], v112
	ds_read_b128 v[74:77], v113
	s_waitcnt lgkmcnt(1)
	v_fmac_f32_e32 v116, v69, v70
	v_fmac_f32_e32 v87, v69, v71
	v_fmac_f32_e32 v85, v69, v72
	v_fmac_f32_e32 v83, v69, v73
	s_waitcnt lgkmcnt(0)
	v_fmac_f32_e32 v120, v69, v74
	v_fmac_f32_e32 v119, v69, v75
	v_fmac_f32_e32 v118, v69, v76
	v_fmac_f32_e32 v117, v69, v77
	ds_read_b128 v[70:73], v114
	ds_read_b128 v[74:77], v115
	global_store_dwordx2 v[92:93], v[66:67], off offset:1536
	s_waitcnt lgkmcnt(1)
	v_fmac_f32_e32 v125, v69, v70
	v_fmac_f32_e32 v123, v69, v71
	v_cndmask_b32_e32 v68, v116, v125, vcc
	v_fmac_f32_e32 v122, v69, v72
	ds_bpermute_b32 v68, v96, v68
	v_cndmask_b32_e32 v70, v87, v123, vcc
	ds_bpermute_b32 v70, v96, v70
	v_cndmask_b32_e32 v71, v85, v122, vcc
	ds_bpermute_b32 v71, v96, v71
	v_fmac_f32_e32 v121, v69, v73
	s_waitcnt lgkmcnt(3)
	v_fmac_f32_e32 v128, v69, v74
	v_fmac_f32_e32 v127, v69, v75
	v_fmac_f32_e32 v126, v69, v76
	v_fmac_f32_e32 v124, v69, v77
	v_cndmask_b32_e32 v69, v125, v116, vcc
	s_waitcnt lgkmcnt(2)
	v_add_f32_e32 v68, v69, v68
	v_cndmask_b32_e32 v69, v123, v87, vcc
	s_waitcnt lgkmcnt(1)
	v_add_f32_e32 v69, v69, v70
	v_cndmask_b32_e32 v70, v122, v85, vcc
	s_waitcnt lgkmcnt(0)
	v_add_f32_e32 v70, v70, v71
	v_cndmask_b32_e32 v71, v83, v121, vcc
	ds_bpermute_b32 v71, v96, v71
	v_cndmask_b32_e32 v73, v120, v128, vcc
	ds_bpermute_b32 v73, v96, v73
	v_cndmask_b32_e32 v74, v119, v127, vcc
	ds_bpermute_b32 v74, v96, v74
	v_cndmask_b32_e32 v72, v121, v83, vcc
	s_waitcnt lgkmcnt(2)
	v_add_f32_e32 v71, v72, v71
	v_cndmask_b32_e32 v72, v128, v120, vcc
	s_waitcnt lgkmcnt(1)
	v_add_f32_e32 v72, v72, v73
	v_cndmask_b32_e32 v73, v127, v119, vcc
	s_waitcnt lgkmcnt(0)
	v_add_f32_e32 v73, v73, v74
	v_cndmask_b32_e32 v74, v118, v126, vcc
	ds_bpermute_b32 v74, v96, v74
	v_cndmask_b32_e32 v76, v117, v124, vcc
	ds_bpermute_b32 v76, v96, v76
	v_cndmask_b32_e32 v75, v126, v118, vcc
	v_cndmask_b32_e64 v77, v68, v72, s[42:43]
	s_waitcnt lgkmcnt(1)
	v_add_f32_e32 v74, v75, v74
	v_cndmask_b32_e32 v75, v124, v117, vcc
	s_waitcnt lgkmcnt(0)
	v_add_f32_e32 v75, v75, v76
	v_cndmask_b32_e64 v68, v72, v68, s[42:43]
	v_cndmask_b32_e64 v72, v69, v73, s[42:43]
	v_cndmask_b32_e64 v69, v73, v69, s[42:43]
	v_cndmask_b32_e64 v73, v70, v74, s[42:43]
	v_cndmask_b32_e64 v76, v71, v75, s[42:43]
	ds_bpermute_b32 v77, v97, v77
	ds_bpermute_b32 v72, v97, v72
	ds_bpermute_b32 v73, v97, v73
	ds_bpermute_b32 v76, v97, v76
	v_cndmask_b32_e64 v70, v74, v70, s[42:43]
	v_cndmask_b32_e64 v71, v75, v71, s[42:43]
	s_waitcnt lgkmcnt(3)
	v_add_f32_e32 v68, v68, v77
	s_waitcnt lgkmcnt(2)
	v_add_f32_e32 v69, v69, v72
	s_waitcnt lgkmcnt(1)
	v_add_f32_e32 v70, v70, v73
	s_waitcnt lgkmcnt(0)
	v_add_f32_e32 v71, v71, v76
	v_cndmask_b32_e64 v72, v68, v70, s[44:45]
	v_cndmask_b32_e64 v73, v69, v71, s[44:45]
	ds_bpermute_b32 v72, v98, v72
	ds_bpermute_b32 v73, v98, v73
	v_cndmask_b32_e64 v68, v70, v68, s[44:45]
	v_cndmask_b32_e64 v69, v71, v69, s[44:45]
	s_waitcnt lgkmcnt(1)
	v_add_f32_e32 v68, v68, v72
	s_waitcnt lgkmcnt(0)
	v_add_f32_e32 v69, v69, v73
	v_cndmask_b32_e64 v70, v68, v69, s[46:47]
	ds_bpermute_b32 v70, v99, v70
	v_cndmask_b32_e64 v68, v69, v68, s[46:47]
	s_waitcnt lgkmcnt(0)
	v_add_f32_e32 v68, v68, v70
	ds_bpermute_b32 v69, v100, v68
	s_waitcnt lgkmcnt(0)
	v_add_f32_e32 v68, v68, v69
	ds_bpermute_b32 v69, v101, v68
	s_and_saveexec_b64 s[6:7], s[48:49]
	s_cbranch_execz .LBB0_1050
	s_waitcnt lgkmcnt(0)
	v_add_f32_e32 v66, v68, v69
	v_add_f32_e32 v66, v91, v66
	s_and_saveexec_b64 s[8:9], s[40:41]
	s_cbranch_execz .LBB0_1049
; __device__ __forceinline__ float logsigmoidf_(float x) { return fminf(x, 0.0f) - log1pf(__expf(-fabsf(x))); }
; __device__ void phase0(const Params& P, LAS unsigned char* lds, const int G, const int bid) {
;     ...
;               if ((lane & 3) == 0) { float gv = r1 + gbias; if (gcol >= 8) gv = logsigmoidf_(gv); gates[(size_t)row * 16 + gcol] = gv; }
	s_mov_b32 s12, 0xbfb8aa3b
	v_mul_f32_e64 v67, |v66|, s12
	v_exp_f32_e32 v83, v67
	v_max_f32_e32 v66, v66, v66
	v_min_f32_e32 v85, 0, v66
	s_mov_b32 s12, 0x3f2aaaab
	v_add_f32_e32 v68, 1.0, v83
	v_add_f32_e32 v66, -1.0, v68
	v_sub_f32_e32 v67, v66, v68
	v_sub_f32_e32 v66, v83, v66
	v_add_f32_e32 v67, 1.0, v67
	v_add_f32_e32 v69, v66, v67
	v_frexp_mant_f32_e32 v70, v68
	v_cvt_f64_f32_e32 v[66:67], v68
	v_frexp_exp_i32_f64_e32 v66, v[66:67]
	v_cmp_gt_f32_e64 s[50:51], s12, v70
	s_mov_b32 s12, 0x3f317218
	s_nop 0
	v_subbrev_co_u32_e64 v74, s[50:51], 0, v66, s[50:51]
	v_sub_u32_e32 v66, 0, v74
	v_ldexp_f32 v67, v68, v66
	v_add_f32_e32 v68, -1.0, v67
	v_add_f32_e32 v70, 1.0, v67
	v_ldexp_f32 v66, v69, v66
	v_add_f32_e32 v69, 1.0, v68
	v_add_f32_e32 v71, -1.0, v70
	v_sub_f32_e32 v69, v67, v69
	v_sub_f32_e32 v67, v67, v71
	v_add_f32_e32 v69, v66, v69
	v_add_f32_e32 v66, v66, v67
	v_add_f32_e32 v75, v70, v66
	v_rcp_f32_e32 v77, v75
	v_sub_f32_e32 v67, v75, v70
	v_sub_f32_e32 v76, v66, v67
	v_add_f32_e32 v67, v68, v69
	v_mul_f32_e32 v90, v67, v77
	v_sub_f32_e32 v66, v67, v68
	v_mul_f32_e32 v68, v75, v90
	v_fma_f32 v70, v90, v75, -v68
	v_fmac_f32_e32 v70, v90, v76
	v_sub_f32_e32 v87, v69, v66
	v_add_f32_e32 v66, v68, v70
	v_sub_f32_e32 v69, v67, v66
	v_pk_add_f32 v[72:73], v[66:67], v[68:69] neg_lo:[0,1] neg_hi:[0,1]
	v_mov_b32_e32 v71, v66
	v_pk_add_f32 v[66:67], v[72:73], v[70:71] neg_lo:[0,1] neg_hi:[0,1]
	s_nop 0
	v_add_f32_e32 v67, v87, v67
	v_add_f32_e32 v66, v66, v67
	v_add_f32_e32 v67, v69, v66
	v_mul_f32_e32 v87, v77, v67
	v_mul_f32_e32 v68, v75, v87
	v_fma_f32 v70, v87, v75, -v68
	v_fmac_f32_e32 v70, v87, v76
	v_sub_f32_e32 v69, v69, v67
	v_add_f32_e32 v75, v66, v69
	v_add_f32_e32 v66, v68, v70
	v_sub_f32_e32 v69, v67, v66
	v_pk_add_f32 v[72:73], v[66:67], v[68:69] neg_lo:[0,1] neg_hi:[0,1]
	v_mov_b32_e32 v71, v66
	v_pk_add_f32 v[66:67], v[72:73], v[70:71] neg_lo:[0,1] neg_hi:[0,1]
	s_nop 0
	v_add_f32_e32 v67, v75, v67
	v_add_f32_e32 v66, v66, v67
	v_add_f32_e32 v67, v90, v87
	v_add_f32_e32 v66, v69, v66
	v_sub_f32_e32 v68, v67, v90
	v_mul_f32_e32 v66, v77, v66
	v_sub_f32_e32 v68, v87, v68
	v_add_f32_e32 v68, v68, v66
	v_add_f32_e32 v70, v67, v68
	v_mul_f32_e32 v71, v70, v70
	v_fmamk_f32 v66, v71, 0x3e9b6dac, v208
	v_fmaak_f32 v169, v71, v66, 0x3f2aaada
	v_cvt_f32_i32_e32 v66, v74
	v_sub_f32_e32 v67, v70, v67
	v_sub_f32_e32 v67, v68, v67
	v_ldexp_f32 v72, v67, 1
	v_mul_f32_e32 v67, v70, v71
	v_ldexp_f32 v69, v70, 1
	v_pk_mul_f32 v[70:71], v[66:67], v[168:169]
	s_nop 0
	v_fma_f32 v68, v66, s12, -v70
	v_fmac_f32_e32 v68, 0xb102e308, v66
	v_pk_add_f32 v[66:67], v[70:71], v[68:69]
	s_mov_b32 s12, 0x7f800000
	v_sub_f32_e32 v69, v67, v69
	v_sub_f32_e32 v69, v71, v69
	v_add_f32_e32 v73, v72, v69
	v_mov_b32_e32 v72, v70
	v_pk_add_f32 v[70:71], v[66:67], v[70:71] neg_lo:[0,1] neg_hi:[0,1]
	v_pk_add_f32 v[74:75], v[66:67], v[72:73]
	v_mov_b32_e32 v69, v66
	v_mov_b32_e32 v71, v75
	v_pk_add_f32 v[76:77], v[68:69], v[70:71] neg_lo:[0,1] neg_hi:[0,1]
	v_pk_add_f32 v[68:69], v[68:69], v[70:71]
	v_mov_b32_e32 v72, v73
	v_pk_add_f32 v[70:71], v[68:69], v[66:67] op_sel:[1,0] op_sel_hi:[0,1] neg_lo:[0,1] neg_hi:[0,1]
	s_nop 0
	v_pk_add_f32 v[92:93], v[74:75], v[70:71] op_sel_hi:[1,0] neg_lo:[0,1] neg_hi:[0,1]
	v_mov_b32_e32 v74, v75
	v_mov_b32_e32 v75, v69
	v_pk_mov_b32 v[70:71], v[66:67], v[70:71] op_sel:[1,0]
	v_mov_b32_e32 v73, v66
	v_pk_add_f32 v[70:71], v[74:75], v[70:71] neg_lo:[0,1] neg_hi:[0,1]
	v_mov_b32_e32 v92, v76
	v_pk_add_f32 v[66:67], v[72:73], v[70:71] neg_lo:[0,1] neg_hi:[0,1]
	v_mov_b32_e32 v77, v69
	v_pk_add_f32 v[70:71], v[92:93], v[66:67]
	v_cmp_neq_f32_e64 s[50:51], s12, v83
	v_pk_add_f32 v[72:73], v[70:71], v[70:71] op_sel:[0,1] op_sel_hi:[1,0]
	s_mov_b32 s12, 0x33800000
	v_pk_add_f32 v[68:69], v[68:69], v[72:73] op_sel:[1,0] op_sel_hi:[0,1]
	s_nop 0
	v_mov_b32_e32 v71, v68
	v_pk_add_f32 v[74:75], v[70:71], v[76:77] neg_lo:[0,1] neg_hi:[0,1]
	v_mov_b32_e32 v67, v72
	v_sub_f32_e32 v69, v70, v74
	v_pk_add_f32 v[66:67], v[66:67], v[74:75] neg_lo:[0,1] neg_hi:[0,1]
	v_sub_f32_e32 v69, v76, v69
	v_add_f32_e32 v66, v66, v69
	v_add_f32_e32 v66, v66, v67
	v_add_f32_e32 v66, v68, v66
	v_cndmask_b32_e64 v66, v212, v66, s[50:51]
	v_cmp_ngt_f32_e64 s[50:51], -1.0, v83
	s_nop 1
	v_cndmask_b32_e64 v66, v213, v66, s[50:51]
	v_cmp_neq_f32_e64 s[50:51], -1.0, v83
	s_nop 1
	v_cndmask_b32_e64 v66, v214, v66, s[50:51]
	v_cmp_lt_f32_e64 s[50:51], |v83|, s12
	s_nop 1
	v_cndmask_b32_e64 v66, v66, v83, s[50:51]
	v_sub_f32_e32 v66, v85, v66

; #define LAS __attribute__((address_space(3)))
; __device__ __forceinline__ unsigned cvt_pk_bf16(float lo, float hi) { unsigned r; asm volatile("v_cvt_pk_bf16_f32 %0, %1, %2" : "=v"(r) : "v"(lo), "v"(hi)); return r; }
; __device__ void phase0(const Params& P, LAS unsigned char* lds, const int G, const int bid) {
;     ...
;           for (int rr = 0; rr < 4; ++rr) { const int row = row0 + rr * G * 8; if (row >= NTOK) continue;
;               f32x4 (&v)[4] = vv[rr]; float ss = 0.f;
; #pragma unroll
;               for (int i = 0; i < 4; ++i)
; #pragma unroll
;                   for (int j = 0; j < 4; ++j) ss += v[i][j] * v[i][j];
; #pragma unroll
;               for (int o = 32; o >= 1; o >>= 1) ss += __shfl_xor(ss, o);
;               const float rstd = rsqrtf(ss * (1.0f / DM) + 1e-6f);
;               float ga[16];
; #pragma unroll
;               for (int c = 0; c < 16; ++c) ga[c] = 0.f;
; #pragma unroll
;               for (int i = 0; i < 4; ++i) { v[i] = v[i] * rstd * w4[i];
;                   u32x2 w; w.x = cvt_pk_bf16(v[i][0], v[i][1]); w.y = cvt_pk_bf16(v[i][2], v[i][3]);
;                   *(u32x2*)(abf + (size_t)row * DM + 4 * lane + 256 * i) = w;
; #pragma unroll
;                   for (int j = 0; j < 4; ++j) { const LAS float* wr_ = wg + (j * 256 + i * 64 + lane) * 20; const float a = v[i][j];
; #pragma unroll
;                       for (int q = 0; q < 4; ++q) { const f32x4 wv = *(const LAS f32x4*)(wr_ + 4 * q);
;                           ga[4 * q] += a * wv[0]; ga[4 * q + 1] += a * wv[1]; ga[4 * q + 2] += a * wv[2]; ga[4 * q + 3] += a * wv[3]; } } }
.LBB0_1050:
	s_or_b64 exec, exec, s[6:7]
	v_cmp_gt_i32_e64 s[50:51], s15, v82
	s_and_saveexec_b64 s[6:7], s[50:51]
	s_cbranch_execz .LBB0_1055
	s_waitcnt vmcnt(15)
	v_mul_f32_e32 v70, v63, v63
	v_fmac_f32_e32 v70, v62, v62
	v_fmac_f32_e32 v70, v64, v64
	v_fmac_f32_e32 v70, v65, v65
	s_waitcnt vmcnt(14)
	v_fmac_f32_e32 v70, v58, v58
	v_fmac_f32_e32 v70, v59, v59
	v_fmac_f32_e32 v70, v60, v60
	v_fmac_f32_e32 v70, v61, v61
	s_waitcnt vmcnt(13)
	v_fmac_f32_e32 v70, v54, v54
	v_fmac_f32_e32 v70, v55, v55
	v_fmac_f32_e32 v70, v56, v56
	v_fmac_f32_e32 v70, v57, v57
	s_waitcnt vmcnt(12) lgkmcnt(0)
	v_pk_mul_f32 v[68:69], v[50:51], v[50:51]
	v_pk_mul_f32 v[66:67], v[52:53], v[52:53]
	v_add_f32_e32 v68, v68, v70
	v_add_f32_e32 v68, v69, v68
	v_add_f32_e32 v66, v66, v68
	v_add_f32_e32 v66, v67, v66
	ds_bpermute_b32 v67, v96, v66
	v_ashrrev_i32_e32 v83, 31, v82
	v_lshlrev_b64 v[68:69], 11, v[82:83]
	v_lshl_add_u64 v[68:69], v[80:81], 0, v[68:69]
	s_waitcnt lgkmcnt(0)
	v_add_f32_e32 v66, v66, v67
	ds_bpermute_b32 v67, v97, v66
	s_waitcnt lgkmcnt(0)
	v_add_f32_e32 v66, v66, v67
	ds_bpermute_b32 v67, v98, v66
	s_waitcnt lgkmcnt(0)
	v_add_f32_e32 v66, v66, v67
	ds_bpermute_b32 v67, v99, v66
	s_waitcnt lgkmcnt(0)
	v_add_f32_e32 v66, v66, v67
	ds_bpermute_b32 v67, v100, v66
	s_waitcnt lgkmcnt(0)
	v_add_f32_e32 v66, v66, v67
	ds_bpermute_b32 v67, v101, v66
	s_waitcnt lgkmcnt(0)
	v_add_f32_e32 v66, v66, v67
	v_fmamk_f32 v66, v66, 0x3a800000, v210
	v_cmp_gt_f32_e64 s[50:51], s30, v66
	v_mul_f32_e32 v67, 0x4b800000, v66
	s_nop 0
	v_cndmask_b32_e64 v66, v66, v67, s[50:51]
	v_rsq_f32_e32 v66, v66
	s_nop 0
	v_mul_f32_e32 v67, 0x45800000, v66
	v_cndmask_b32_e64 v66, v66, v67, s[50:51]
	v_pk_mul_f32 v[70:71], v[62:63], v[66:67] op_sel_hi:[1,0]
	v_pk_mul_f32 v[62:63], v[64:65], v[66:67] op_sel_hi:[1,0]
	v_pk_mul_f32 v[64:65], v[2:3], v[70:71]
	v_pk_mul_f32 v[62:63], v[4:5], v[62:63]
	v_cvt_pk_bf16_f32 v70, v64, v65
	s_nop 0
	v_cvt_pk_bf16_f32 v71, v62, v63
	global_store_dwordx2 v[68:69], v[70:71], off
	ds_read_b128 v[70:73], v102 offset:40960
	ds_read_b128 v[92:95], v102 offset:40976
	ds_read_b128 v[116:119], v102 offset:40992
	ds_read_b128 v[120:123], v102 offset:41008
	s_waitcnt lgkmcnt(3)
	v_fma_f32 v89, v70, v64, 0
	s_waitcnt lgkmcnt(2)
	v_fma_f32 v74, v92, v64, 0
	s_waitcnt lgkmcnt(1)
	v_fma_f32 v92, v116, v64, 0
	v_fma_f32 v90, v117, v64, 0
	v_fma_f32 v87, v118, v64, 0
	v_fma_f32 v77, v119, v64, 0
	ds_read_b128 v[116:119], v102 offset:61440
	v_fma_f32 v88, v71, v64, 0
	v_fma_f32 v85, v72, v64, 0
	v_fma_f32 v75, v73, v64, 0
	v_fma_f32 v72, v93, v64, 0
	s_waitcnt lgkmcnt(0)
	v_fmac_f32_e32 v89, v116, v65
	v_fmac_f32_e32 v88, v117, v65
	v_fmac_f32_e32 v85, v118, v65
	v_fmac_f32_e32 v75, v119, v65
	ds_read_b128 v[116:119], v102 offset:61456
	v_fma_f32 v70, v94, v64, 0
	v_fma_f32 v67, v95, v64, 0
	v_fma_f32 v76, v120, v64, 0
	v_fma_f32 v73, v121, v64, 0
	s_waitcnt lgkmcnt(0)
	v_fmac_f32_e32 v74, v116, v65
	v_fmac_f32_e32 v72, v117, v65
	v_fmac_f32_e32 v70, v118, v65
	v_fmac_f32_e32 v67, v119, v65
	ds_read_b128 v[116:119], v102 offset:61472
	v_fma_f32 v71, v122, v64, 0
	v_fma_f32 v64, v123, v64, 0
	s_waitcnt lgkmcnt(0)
	v_fmac_f32_e32 v92, v116, v65
	v_fmac_f32_e32 v90, v117, v65
	v_fmac_f32_e32 v87, v118, v65
	v_fmac_f32_e32 v77, v119, v65
	ds_read_b128 v[116:119], v102 offset:61488
	s_waitcnt lgkmcnt(0)
	v_fmac_f32_e32 v76, v116, v65
	v_fmac_f32_e32 v73, v117, v65
	v_fmac_f32_e32 v71, v118, v65
	v_fmac_f32_e32 v64, v119, v65
	ds_read_b128 v[116:119], v103 offset:40960
	ds_read_b128 v[120:123], v103 offset:40976
	ds_read_b128 v[124:127], v103 offset:40992
	ds_read_b128 v[128:131], v103 offset:41008
	s_waitcnt lgkmcnt(3)
	v_fmac_f32_e32 v89, v116, v62
	v_fmac_f32_e32 v88, v117, v62
	v_fmac_f32_e32 v85, v118, v62
	v_fmac_f32_e32 v75, v119, v62
	ds_read_b128 v[116:119], v103 offset:61440
	s_waitcnt lgkmcnt(3)
	v_fmac_f32_e32 v74, v62, v120
	v_fmac_f32_e32 v72, v62, v121
	v_fmac_f32_e32 v70, v62, v122
	v_fmac_f32_e32 v67, v62, v123
	s_waitcnt lgkmcnt(0)
	v_fmac_f32_e32 v89, v63, v116
	v_fmac_f32_e32 v88, v63, v117
	v_fmac_f32_e32 v85, v63, v118
	v_fmac_f32_e32 v75, v63, v119
	ds_read_b128 v[116:119], v103 offset:61456
	v_fmac_f32_e32 v92, v62, v124
	v_fmac_f32_e32 v90, v62, v125
	v_fmac_f32_e32 v87, v62, v126
	v_fmac_f32_e32 v77, v62, v127
	s_waitcnt lgkmcnt(0)
	v_fmac_f32_e32 v74, v63, v116
	v_fmac_f32_e32 v72, v63, v117
	v_fmac_f32_e32 v70, v63, v118
	v_fmac_f32_e32 v67, v63, v119
	ds_read_b128 v[116:119], v103 offset:61472
	v_fmac_f32_e32 v76, v62, v128
	v_fmac_f32_e32 v73, v62, v129
	v_fmac_f32_e32 v71, v62, v130
	v_fmac_f32_e32 v64, v62, v131
	s_waitcnt lgkmcnt(0)
	v_fmac_f32_e32 v92, v63, v116
	v_fmac_f32_e32 v90, v63, v117
	v_fmac_f32_e32 v87, v63, v118
	v_fmac_f32_e32 v77, v63, v119
	ds_read_b128 v[116:119], v103 offset:61488
	s_waitcnt lgkmcnt(0)
	v_fmac_f32_e32 v76, v63, v116
	v_fmac_f32_e32 v73, v63, v117
	v_fmac_f32_e32 v71, v63, v118
	v_fmac_f32_e32 v64, v63, v119
	v_pk_mul_f32 v[62:63], v[58:59], v[66:67] op_sel_hi:[1,0]
	v_pk_mul_f32 v[58:59], v[60:61], v[66:67] op_sel_hi:[1,0]
	v_pk_mul_f32 v[94:95], v[6:7], v[62:63]
	v_pk_mul_f32 v[58:59], v[8:9], v[58:59]
	v_cvt_pk_bf16_f32 v60, v94, v95
	s_nop 0
	v_cvt_pk_bf16_f32 v61, v58, v59
	global_store_dwordx2 v[68:69], v[60:61], off offset:512
	ds_read_b128 v[60:63], v102 offset:46080
	ds_read_b128 v[116:119], v102 offset:46096
	ds_read_b128 v[120:123], v102 offset:46112
	ds_read_b128 v[124:127], v102 offset:46128
	s_waitcnt lgkmcnt(3)
	v_fmac_f32_e32 v89, v94, v60
	v_fmac_f32_e32 v88, v94, v61
	v_fmac_f32_e32 v85, v94, v62
	v_fmac_f32_e32 v75, v94, v63
	s_waitcnt lgkmcnt(2)
; #define LAS __attribute__((address_space(3)))
; __device__ __forceinline__ unsigned cvt_pk_bf16(float lo, float hi) { unsigned r; asm volatile("v_cvt_pk_bf16_f32 %0, %1, %2" : "=v"(r) : "v"(lo), "v"(hi)); return r; }
; __device__ void phase0(const Params& P, LAS unsigned char* lds, const int G, const int bid) {
;     ...
;               for (int i = 0; i < 4; ++i) { v[i] = v[i] * rstd * w4[i];
;                   u32x2 w; w.x = cvt_pk_bf16(v[i][0], v[i][1]); w.y = cvt_pk_bf16(v[i][2], v[i][3]);
;                   *(u32x2*)(abf + (size_t)row * DM + 4 * lane + 256 * i) = w;
; #pragma unroll
;                   for (int j = 0; j < 4; ++j) { const LAS float* wr_ = wg + (j * 256 + i * 64 + lane) * 20; const float a = v[i][j];
; #pragma unroll
;                       for (int q = 0; q < 4; ++q) { const f32x4 wv = *(const LAS f32x4*)(wr_ + 4 * q);
;                           ga[4 * q] += a * wv[0]; ga[4 * q + 1] += a * wv[1]; ga[4 * q + 2] += a * wv[2]; ga[4 * q + 3] += a * wv[3]; } } }
	v_fmac_f32_e32 v74, v94, v116
	v_fmac_f32_e32 v72, v94, v117
	v_fmac_f32_e32 v70, v94, v118
	v_fmac_f32_e32 v67, v94, v119
	s_waitcnt lgkmcnt(1)
	v_fmac_f32_e32 v92, v94, v120
	v_fmac_f32_e32 v90, v94, v121
	v_fmac_f32_e32 v87, v94, v122
	v_fmac_f32_e32 v77, v94, v123
	s_waitcnt lgkmcnt(0)
	v_fmac_f32_e32 v76, v94, v124
	v_fmac_f32_e32 v73, v94, v125
	v_fmac_f32_e32 v71, v94, v126
	v_fmac_f32_e32 v64, v94, v127
	ds_read_b128 v[60:63], v103 offset:25600
	ds_read_b128 v[116:119], v103 offset:25616
	ds_read_b128 v[120:123], v103 offset:25632
	ds_read_b128 v[124:127], v103 offset:25648
	s_waitcnt lgkmcnt(3)
	v_fmac_f32_e32 v89, v95, v60
	v_fmac_f32_e32 v88, v95, v61
	v_fmac_f32_e32 v85, v95, v62
	v_fmac_f32_e32 v75, v95, v63
	ds_read_b128 v[60:63], v103 offset:46080
	s_waitcnt lgkmcnt(3)
	v_fmac_f32_e32 v74, v95, v116
	v_fmac_f32_e32 v72, v95, v117
	v_fmac_f32_e32 v70, v95, v118
	v_fmac_f32_e32 v67, v95, v119
	s_waitcnt lgkmcnt(0)
	v_fmac_f32_e32 v89, v58, v60
	v_fmac_f32_e32 v88, v58, v61
	v_fmac_f32_e32 v85, v58, v62
	v_fmac_f32_e32 v75, v58, v63
	ds_read_b128 v[60:63], v103 offset:46096
	v_fmac_f32_e32 v92, v95, v120
	v_fmac_f32_e32 v90, v95, v121
	v_fmac_f32_e32 v87, v95, v122
	v_fmac_f32_e32 v77, v95, v123
	s_waitcnt lgkmcnt(0)
	v_fmac_f32_e32 v74, v58, v60
	v_fmac_f32_e32 v72, v58, v61
	v_fmac_f32_e32 v70, v58, v62
	v_fmac_f32_e32 v67, v58, v63
	ds_read_b128 v[60:63], v103 offset:46112
	v_fmac_f32_e32 v76, v95, v124
	v_fmac_f32_e32 v73, v95, v125
	v_fmac_f32_e32 v71, v95, v126
	v_fmac_f32_e32 v64, v95, v127
	s_waitcnt lgkmcnt(0)
	v_fmac_f32_e32 v92, v58, v60
	v_fmac_f32_e32 v90, v58, v61
	v_fmac_f32_e32 v87, v58, v62
	v_fmac_f32_e32 v77, v58, v63
	ds_read_b128 v[60:63], v103 offset:46128
	s_waitcnt lgkmcnt(0)
	v_fmac_f32_e32 v76, v58, v60
	v_fmac_f32_e32 v73, v58, v61
	v_fmac_f32_e32 v71, v58, v62
	v_fmac_f32_e32 v64, v58, v63
	ds_read_b128 v[60:63], v104
	s_waitcnt lgkmcnt(0)
	v_fmac_f32_e32 v89, v59, v60
	v_fmac_f32_e32 v88, v59, v61
	v_fmac_f32_e32 v85, v59, v62
	v_fmac_f32_e32 v75, v59, v63
	ds_read_b128 v[60:63], v105
	s_waitcnt lgkmcnt(0)
	v_fmac_f32_e32 v74, v59, v60
	v_fmac_f32_e32 v72, v59, v61
	v_fmac_f32_e32 v70, v59, v62
	v_fmac_f32_e32 v67, v59, v63
	ds_read_b128 v[60:63], v106
	s_waitcnt lgkmcnt(0)
	v_fmac_f32_e32 v92, v59, v60
	v_fmac_f32_e32 v90, v59, v61
	v_fmac_f32_e32 v87, v59, v62
	v_fmac_f32_e32 v77, v59, v63
	ds_read_b128 v[60:63], v107
	s_waitcnt lgkmcnt(0)
	v_fmac_f32_e32 v76, v59, v60
	v_fmac_f32_e32 v73, v59, v61
	v_fmac_f32_e32 v71, v59, v62
	v_fmac_f32_e32 v64, v59, v63
	v_pk_mul_f32 v[58:59], v[54:55], v[66:67] op_sel_hi:[1,0]
	v_pk_mul_f32 v[54:55], v[56:57], v[66:67] op_sel_hi:[1,0]
	v_pk_mul_f32 v[94:95], v[10:11], v[58:59]
	v_pk_mul_f32 v[54:55], v[12:13], v[54:55]
	v_cvt_pk_bf16_f32 v56, v94, v95
	s_nop 0
	v_cvt_pk_bf16_f32 v57, v54, v55
	global_store_dwordx2 v[68:69], v[56:57], off offset:1024
	ds_read_b128 v[56:59], v102 offset:51200
	ds_read_b128 v[60:63], v102 offset:51216
	ds_read_b128 v[116:119], v102 offset:51232
	ds_read_b128 v[120:123], v102 offset:51248
	s_waitcnt lgkmcnt(3)
	v_fmac_f32_e32 v89, v94, v56
	v_fmac_f32_e32 v88, v94, v57
	v_fmac_f32_e32 v85, v94, v58
	v_fmac_f32_e32 v75, v94, v59
	s_waitcnt lgkmcnt(2)
	v_fmac_f32_e32 v74, v94, v60
	v_fmac_f32_e32 v72, v94, v61
	v_fmac_f32_e32 v70, v94, v62
	v_fmac_f32_e32 v67, v94, v63
	s_waitcnt lgkmcnt(1)
	v_fmac_f32_e32 v92, v94, v116
	v_fmac_f32_e32 v90, v94, v117
	v_fmac_f32_e32 v87, v94, v118
	v_fmac_f32_e32 v77, v94, v119
	s_waitcnt lgkmcnt(0)
	v_fmac_f32_e32 v76, v94, v120
	v_fmac_f32_e32 v73, v94, v121
	v_fmac_f32_e32 v71, v94, v122
	v_fmac_f32_e32 v64, v94, v123
	ds_read_b128 v[56:59], v103 offset:30720
	ds_read_b128 v[60:63], v103 offset:30736
	ds_read_b128 v[116:119], v103 offset:30752
	ds_read_b128 v[120:123], v103 offset:30768
	s_waitcnt lgkmcnt(3)
	v_fmac_f32_e32 v89, v95, v56
	v_fmac_f32_e32 v88, v95, v57
	v_fmac_f32_e32 v85, v95, v58
	v_fmac_f32_e32 v75, v95, v59
	ds_read_b128 v[56:59], v103 offset:51200
	s_waitcnt lgkmcnt(3)
	v_fmac_f32_e32 v74, v95, v60
	v_fmac_f32_e32 v72, v95, v61
	v_fmac_f32_e32 v70, v95, v62
	v_fmac_f32_e32 v67, v95, v63
	s_waitcnt lgkmcnt(0)
	v_fmac_f32_e32 v89, v54, v56
	v_fmac_f32_e32 v88, v54, v57
	v_fmac_f32_e32 v85, v54, v58
	v_fmac_f32_e32 v75, v54, v59
	ds_read_b128 v[56:59], v103 offset:51216
	v_fmac_f32_e32 v92, v95, v116
	v_fmac_f32_e32 v90, v95, v117
	v_fmac_f32_e32 v87, v95, v118
	v_fmac_f32_e32 v77, v95, v119
	s_waitcnt lgkmcnt(0)
	v_fmac_f32_e32 v74, v54, v56
	v_fmac_f32_e32 v72, v54, v57
	v_fmac_f32_e32 v70, v54, v58
	v_fmac_f32_e32 v67, v54, v59
	ds_read_b128 v[56:59], v103 offset:51232
	v_fmac_f32_e32 v76, v95, v120
	v_fmac_f32_e32 v73, v95, v121
	v_fmac_f32_e32 v71, v95, v122
	v_fmac_f32_e32 v64, v95, v123
	s_waitcnt lgkmcnt(0)
	v_fmac_f32_e32 v92, v54, v56
	v_fmac_f32_e32 v90, v54, v57
	v_fmac_f32_e32 v87, v54, v58
	v_fmac_f32_e32 v77, v54, v59
	ds_read_b128 v[56:59], v103 offset:51248
	s_waitcnt lgkmcnt(0)
	v_fmac_f32_e32 v76, v54, v56
	v_fmac_f32_e32 v73, v54, v57
	v_fmac_f32_e32 v71, v54, v58
	v_fmac_f32_e32 v64, v54, v59
	ds_read_b128 v[56:59], v108
	s_waitcnt lgkmcnt(0)
	v_fmac_f32_e32 v89, v55, v56
	v_fmac_f32_e32 v88, v55, v57
	v_fmac_f32_e32 v85, v55, v58
	v_fmac_f32_e32 v75, v55, v59
	ds_read_b128 v[56:59], v109
	s_waitcnt lgkmcnt(0)
	v_fmac_f32_e32 v74, v55, v56
	v_fmac_f32_e32 v72, v55, v57
	v_fmac_f32_e32 v70, v55, v58
	v_fmac_f32_e32 v67, v55, v59
	ds_read_b128 v[56:59], v110
	s_waitcnt lgkmcnt(0)
	v_fmac_f32_e32 v92, v55, v56
	v_fmac_f32_e32 v90, v55, v57
	v_fmac_f32_e32 v87, v55, v58
	v_fmac_f32_e32 v77, v55, v59
	ds_read_b128 v[56:59], v111
	s_waitcnt lgkmcnt(0)
; #define LAS __attribute__((address_space(3)))
; __device__ __forceinline__ unsigned cvt_pk_bf16(float lo, float hi) { unsigned r; asm volatile("v_cvt_pk_bf16_f32 %0, %1, %2" : "=v"(r) : "v"(lo), "v"(hi)); return r; }
; __device__ __forceinline__ float logsigmoidf_(float x) { return fminf(x, 0.0f) - log1pf(__expf(-fabsf(x))); }
; __device__ void phase0(const Params& P, LAS unsigned char* lds, const int G, const int bid) {
;     ...
;               for (int i = 0; i < 4; ++i) { v[i] = v[i] * rstd * w4[i];
;                   u32x2 w; w.x = cvt_pk_bf16(v[i][0], v[i][1]); w.y = cvt_pk_bf16(v[i][2], v[i][3]);
;                   *(u32x2*)(abf + (size_t)row * DM + 4 * lane + 256 * i) = w;
; #pragma unroll
;                   for (int j = 0; j < 4; ++j) { const LAS float* wr_ = wg + (j * 256 + i * 64 + lane) * 20; const float a = v[i][j];
; #pragma unroll
;                       for (int q = 0; q < 4; ++q) { const f32x4 wv = *(const LAS f32x4*)(wr_ + 4 * q);
;                           ga[4 * q] += a * wv[0]; ga[4 * q + 1] += a * wv[1]; ga[4 * q + 2] += a * wv[2]; ga[4 * q + 3] += a * wv[3]; } } }
;               float r8[8], r4[4], r2[2], r1;
; #pragma unroll
;               for (int c = 0; c < 8; ++c) { const bool hi = (lane & 32) != 0; const float send = hi ? ga[c] : ga[c + 8], keep = hi ? ga[c + 8] : ga[c]; r8[c] = keep + __shfl_xor(send, 32); }
; #pragma unroll
;               for (int c = 0; c < 4; ++c) { const bool hi = (lane & 16) != 0; const float send = hi ? r8[c] : r8[c + 4], keep = hi ? r8[c + 4] : r8[c]; r4[c] = keep + __shfl_xor(send, 16); }
; #pragma unroll
;               for (int c = 0; c < 2; ++c) { const bool hi = (lane & 8) != 0; const float send = hi ? r4[c] : r4[c + 2], keep = hi ? r4[c + 2] : r4[c]; r2[c] = keep + __shfl_xor(send, 8); }
;               { const bool hi = (lane & 4) != 0; const float send = hi ? r2[0] : r2[1], keep = hi ? r2[1] : r2[0]; r1 = keep + __shfl_xor(send, 4); }
;               r1 += __shfl_xor(r1, 2); r1 += __shfl_xor(r1, 1);
;               if ((lane & 3) == 0) { float gv = r1 + gbias; if (gcol >= 8) gv = logsigmoidf_(gv); gates[(size_t)row * 16 + gcol] = gv; }
	v_fmac_f32_e32 v76, v55, v56
	v_fmac_f32_e32 v73, v55, v57
	v_fmac_f32_e32 v71, v55, v58
	v_fmac_f32_e32 v64, v55, v59
	v_pk_mul_f32 v[54:55], v[50:51], v[66:67] op_sel_hi:[1,0]
	v_pk_mul_f32 v[50:51], v[52:53], v[66:67] op_sel_hi:[1,0]
	v_pk_mul_f32 v[94:95], v[14:15], v[54:55]
	v_pk_mul_f32 v[50:51], v[16:17], v[50:51]
	v_cvt_pk_bf16_f32 v52, v94, v95
	s_nop 0
	v_cvt_pk_bf16_f32 v53, v50, v51
	global_store_dwordx2 v[68:69], v[52:53], off offset:1536
	ds_read_b128 v[52:55], v102 offset:56320
	ds_read_b128 v[56:59], v102 offset:56336
	ds_read_b128 v[60:63], v102 offset:56352
	ds_read_b128 v[116:119], v102 offset:56368
	s_waitcnt lgkmcnt(3)
	v_fmac_f32_e32 v89, v94, v52
	v_fmac_f32_e32 v88, v94, v53
	v_fmac_f32_e32 v85, v94, v54
	v_fmac_f32_e32 v75, v94, v55
	s_waitcnt lgkmcnt(2)
	v_fmac_f32_e32 v74, v94, v56
	v_fmac_f32_e32 v72, v94, v57
	v_fmac_f32_e32 v70, v94, v58
	v_fmac_f32_e32 v67, v94, v59
	s_waitcnt lgkmcnt(1)
	v_fmac_f32_e32 v92, v94, v60
	v_fmac_f32_e32 v90, v94, v61
	v_fmac_f32_e32 v87, v94, v62
	v_fmac_f32_e32 v77, v94, v63
	s_waitcnt lgkmcnt(0)
	v_fmac_f32_e32 v76, v94, v116
	v_fmac_f32_e32 v73, v94, v117
	v_fmac_f32_e32 v71, v94, v118
	v_fmac_f32_e32 v64, v94, v119
	ds_read_b128 v[52:55], v103 offset:35840
	ds_read_b128 v[56:59], v103 offset:35856
	ds_read_b128 v[60:63], v103 offset:35872
	ds_read_b128 v[116:119], v103 offset:35888
	s_waitcnt lgkmcnt(3)
	v_fmac_f32_e32 v89, v95, v52
	v_fmac_f32_e32 v88, v95, v53
	v_fmac_f32_e32 v85, v95, v54
	v_fmac_f32_e32 v75, v95, v55
	ds_read_b128 v[52:55], v103 offset:56320
	s_waitcnt lgkmcnt(3)
	v_fmac_f32_e32 v74, v95, v56
	v_fmac_f32_e32 v72, v95, v57
	v_fmac_f32_e32 v70, v95, v58
	v_fmac_f32_e32 v67, v95, v59
	s_waitcnt lgkmcnt(0)
	v_fmac_f32_e32 v89, v50, v52
	v_fmac_f32_e32 v88, v50, v53
	v_fmac_f32_e32 v85, v50, v54
	v_fmac_f32_e32 v75, v50, v55
	ds_read_b128 v[52:55], v103 offset:56336
	v_fmac_f32_e32 v92, v95, v60
	v_fmac_f32_e32 v90, v95, v61
	v_fmac_f32_e32 v87, v95, v62
	v_fmac_f32_e32 v77, v95, v63
	s_waitcnt lgkmcnt(0)
	v_fmac_f32_e32 v74, v50, v52
	v_fmac_f32_e32 v72, v50, v53
	v_fmac_f32_e32 v70, v50, v54
	v_fmac_f32_e32 v67, v50, v55
	ds_read_b128 v[52:55], v103 offset:56352
	v_fmac_f32_e32 v76, v95, v116
	v_fmac_f32_e32 v73, v95, v117
	v_fmac_f32_e32 v71, v95, v118
	v_fmac_f32_e32 v64, v95, v119
	s_waitcnt lgkmcnt(0)
	v_fmac_f32_e32 v92, v50, v52
	v_fmac_f32_e32 v90, v50, v53
	v_fmac_f32_e32 v87, v50, v54
	v_fmac_f32_e32 v77, v50, v55
	ds_read_b128 v[52:55], v103 offset:56368
	s_waitcnt lgkmcnt(0)
	v_fmac_f32_e32 v76, v50, v52
	v_fmac_f32_e32 v73, v50, v53
	v_fmac_f32_e32 v71, v50, v54
	v_fmac_f32_e32 v64, v50, v55
	ds_read_b128 v[52:55], v112
	s_waitcnt lgkmcnt(0)
	v_fmac_f32_e32 v89, v51, v52
	v_fmac_f32_e32 v88, v51, v53
	v_fmac_f32_e32 v85, v51, v54
	v_fmac_f32_e32 v75, v51, v55
	ds_read_b128 v[52:55], v113
	s_waitcnt lgkmcnt(0)
	v_fmac_f32_e32 v74, v51, v52
	v_fmac_f32_e32 v72, v51, v53
	v_fmac_f32_e32 v70, v51, v54
	v_fmac_f32_e32 v67, v51, v55
	ds_read_b128 v[52:55], v114
	s_waitcnt lgkmcnt(0)
	v_fmac_f32_e32 v92, v51, v52
	v_fmac_f32_e32 v90, v51, v53
	v_fmac_f32_e32 v87, v51, v54
	v_fmac_f32_e32 v77, v51, v55
	ds_read_b128 v[52:55], v115
	v_cndmask_b32_e32 v50, v89, v92, vcc
	ds_bpermute_b32 v50, v96, v50
	s_waitcnt lgkmcnt(1)
	v_fmac_f32_e32 v76, v51, v52
	v_fmac_f32_e32 v73, v51, v53
	v_fmac_f32_e32 v71, v51, v54
	v_fmac_f32_e32 v64, v51, v55
	v_cndmask_b32_e32 v51, v92, v89, vcc
	s_waitcnt lgkmcnt(0)
	v_add_f32_e32 v50, v51, v50
	v_cndmask_b32_e32 v51, v88, v90, vcc
	ds_bpermute_b32 v51, v96, v51
	v_cndmask_b32_e32 v52, v90, v88, vcc
	v_cndmask_b32_e32 v53, v87, v85, vcc
	v_cndmask_b32_e32 v54, v77, v75, vcc
	v_cndmask_b32_e32 v55, v76, v74, vcc
	s_waitcnt lgkmcnt(0)
	v_add_f32_e32 v51, v52, v51
	v_cndmask_b32_e32 v52, v85, v87, vcc
	ds_bpermute_b32 v52, v96, v52
	v_cndmask_b32_e32 v56, v73, v72, vcc
	v_cndmask_b32_e32 v57, v71, v70, vcc
	v_cndmask_b32_e32 v58, v64, v67, vcc
	s_waitcnt lgkmcnt(0)
	v_add_f32_e32 v52, v53, v52
	v_cndmask_b32_e32 v53, v75, v77, vcc
	ds_bpermute_b32 v53, v96, v53
	s_waitcnt lgkmcnt(0)
	v_add_f32_e32 v53, v54, v53
	v_cndmask_b32_e32 v54, v74, v76, vcc
	ds_bpermute_b32 v54, v96, v54
	s_waitcnt lgkmcnt(0)
	v_add_f32_e32 v54, v55, v54
	v_cndmask_b32_e32 v55, v72, v73, vcc
	ds_bpermute_b32 v55, v96, v55
	s_waitcnt lgkmcnt(0)
	v_add_f32_e32 v55, v56, v55
	v_cndmask_b32_e32 v56, v70, v71, vcc
	ds_bpermute_b32 v56, v96, v56
	s_waitcnt lgkmcnt(0)
	v_add_f32_e32 v56, v57, v56
	v_cndmask_b32_e32 v57, v67, v64, vcc
	ds_bpermute_b32 v57, v96, v57
	s_waitcnt lgkmcnt(0)
	v_add_f32_e32 v57, v58, v57
	v_cndmask_b32_e64 v58, v50, v54, s[42:43]
	v_cndmask_b32_e64 v50, v54, v50, s[42:43]
	ds_bpermute_b32 v54, v97, v58
	s_waitcnt lgkmcnt(0)
	v_add_f32_e32 v50, v50, v54
	v_cndmask_b32_e64 v54, v51, v55, s[42:43]
	ds_bpermute_b32 v54, v97, v54
	v_cndmask_b32_e64 v51, v55, v51, s[42:43]
	s_waitcnt lgkmcnt(0)
	v_add_f32_e32 v51, v51, v54
	v_cndmask_b32_e64 v54, v52, v56, s[42:43]
	ds_bpermute_b32 v54, v97, v54
	v_cndmask_b32_e64 v52, v56, v52, s[42:43]
	s_waitcnt lgkmcnt(0)
	v_add_f32_e32 v52, v52, v54
	v_cndmask_b32_e64 v54, v53, v57, s[42:43]
	ds_bpermute_b32 v54, v97, v54
	v_cndmask_b32_e64 v53, v57, v53, s[42:43]
	s_waitcnt lgkmcnt(0)
	v_add_f32_e32 v53, v53, v54
	v_cndmask_b32_e64 v54, v50, v52, s[44:45]
	v_cndmask_b32_e64 v50, v52, v50, s[44:45]
	ds_bpermute_b32 v52, v98, v54
	s_waitcnt lgkmcnt(0)
	v_add_f32_e32 v50, v50, v52
	v_cndmask_b32_e64 v52, v51, v53, s[44:45]
	ds_bpermute_b32 v52, v98, v52
	v_cndmask_b32_e64 v51, v53, v51, s[44:45]
	s_waitcnt lgkmcnt(0)
	v_add_f32_e32 v51, v51, v52
	v_cndmask_b32_e64 v52, v50, v51, s[46:47]
	v_cndmask_b32_e64 v50, v51, v50, s[46:47]
	ds_bpermute_b32 v51, v99, v52
	s_waitcnt lgkmcnt(0)
	v_add_f32_e32 v50, v50, v51
	ds_bpermute_b32 v51, v100, v50
	s_waitcnt lgkmcnt(0)
	v_add_f32_e32 v50, v50, v51
	ds_bpermute_b32 v51, v101, v50
	s_and_b64 exec, exec, s[48:49]
	s_cbranch_execz .LBB0_1055
; __device__ __forceinline__ float logsigmoidf_(float x) { return fminf(x, 0.0f) - log1pf(__expf(-fabsf(x))); }
; __device__ void phase0(const Params& P, LAS unsigned char* lds, const int G, const int bid) {
;     ...
;               if ((lane & 3) == 0) { float gv = r1 + gbias; if (gcol >= 8) gv = logsigmoidf_(gv); gates[(size_t)row * 16 + gcol] = gv; }
	s_waitcnt lgkmcnt(0)
	v_add_f32_e32 v50, v50, v51
	v_add_f32_e32 v50, v91, v50
	s_and_saveexec_b64 s[8:9], s[40:41]
	s_cbranch_execz .LBB0_1054
	s_mov_b32 s12, 0xbfb8aa3b
	v_mul_f32_e64 v51, |v50|, s12
	v_exp_f32_e32 v64, v51
	v_max_f32_e32 v50, v50, v50
	v_min_f32_e32 v65, 0, v50
	s_mov_b32 s12, 0x3f2aaaab
	v_add_f32_e32 v52, 1.0, v64
	v_add_f32_e32 v50, -1.0, v52
	v_sub_f32_e32 v51, v50, v52
	v_sub_f32_e32 v50, v64, v50
	v_add_f32_e32 v51, 1.0, v51
	v_add_f32_e32 v53, v50, v51
	v_frexp_mant_f32_e32 v54, v52
	v_cvt_f64_f32_e32 v[50:51], v52
	v_frexp_exp_i32_f64_e32 v50, v[50:51]
	v_cmp_gt_f32_e64 s[50:51], s12, v54
	s_mov_b32 s12, 0x3f317218
	s_nop 0
	v_subbrev_co_u32_e64 v58, s[50:51], 0, v50, s[50:51]
	v_sub_u32_e32 v50, 0, v58
	v_ldexp_f32 v51, v52, v50
	v_add_f32_e32 v52, -1.0, v51
	v_add_f32_e32 v54, 1.0, v51
	v_ldexp_f32 v50, v53, v50
	v_add_f32_e32 v53, 1.0, v52
	v_add_f32_e32 v55, -1.0, v54
	v_sub_f32_e32 v53, v51, v53
	v_sub_f32_e32 v51, v51, v55
	v_add_f32_e32 v53, v50, v53
	v_add_f32_e32 v50, v50, v51
	v_add_f32_e32 v59, v54, v50
	v_rcp_f32_e32 v61, v59
	v_sub_f32_e32 v51, v59, v54
	v_sub_f32_e32 v60, v50, v51
	v_add_f32_e32 v51, v52, v53
	v_mul_f32_e32 v63, v51, v61
	v_sub_f32_e32 v50, v51, v52
	v_mul_f32_e32 v52, v59, v63
	v_fma_f32 v54, v63, v59, -v52
	v_fmac_f32_e32 v54, v63, v60
	v_sub_f32_e32 v62, v53, v50
	v_add_f32_e32 v50, v52, v54
	v_sub_f32_e32 v53, v51, v50
	v_pk_add_f32 v[56:57], v[50:51], v[52:53] neg_lo:[0,1] neg_hi:[0,1]
	v_mov_b32_e32 v55, v50
	v_pk_add_f32 v[50:51], v[56:57], v[54:55] neg_lo:[0,1] neg_hi:[0,1]
	s_nop 0
	v_add_f32_e32 v51, v62, v51
	v_add_f32_e32 v50, v50, v51
	v_add_f32_e32 v51, v53, v50
	v_mul_f32_e32 v62, v61, v51
	v_mul_f32_e32 v52, v59, v62
	v_fma_f32 v54, v62, v59, -v52
	v_fmac_f32_e32 v54, v62, v60
	v_sub_f32_e32 v53, v53, v51
	v_add_f32_e32 v59, v50, v53
	v_add_f32_e32 v50, v52, v54
	v_sub_f32_e32 v53, v51, v50
	v_pk_add_f32 v[56:57], v[50:51], v[52:53] neg_lo:[0,1] neg_hi:[0,1]
	v_mov_b32_e32 v55, v50
	v_pk_add_f32 v[50:51], v[56:57], v[54:55] neg_lo:[0,1] neg_hi:[0,1]
	s_nop 0
	v_add_f32_e32 v51, v59, v51
	v_add_f32_e32 v50, v50, v51
	v_add_f32_e32 v51, v63, v62
	v_add_f32_e32 v50, v53, v50
	v_sub_f32_e32 v52, v51, v63
	v_mul_f32_e32 v50, v61, v50
	v_sub_f32_e32 v52, v62, v52
	v_add_f32_e32 v52, v52, v50
	v_add_f32_e32 v54, v51, v52
	v_mul_f32_e32 v55, v54, v54
	v_fmamk_f32 v50, v55, 0x3e9b6dac, v208
	v_fmaak_f32 v169, v55, v50, 0x3f2aaada
	v_cvt_f32_i32_e32 v50, v58
	v_sub_f32_e32 v51, v54, v51
	v_sub_f32_e32 v51, v52, v51
	v_ldexp_f32 v56, v51, 1
	v_mul_f32_e32 v51, v54, v55
	v_ldexp_f32 v53, v54, 1
	v_pk_mul_f32 v[54:55], v[50:51], v[168:169]
	s_nop 0
	v_fma_f32 v52, v50, s12, -v54
	v_fmac_f32_e32 v52, 0xb102e308, v50
	v_pk_add_f32 v[50:51], v[54:55], v[52:53]
	s_mov_b32 s12, 0x7f800000
	v_sub_f32_e32 v53, v51, v53
	v_sub_f32_e32 v53, v55, v53
	v_add_f32_e32 v57, v56, v53
	v_mov_b32_e32 v56, v54
	v_pk_add_f32 v[54:55], v[50:51], v[54:55] neg_lo:[0,1] neg_hi:[0,1]
	v_pk_add_f32 v[58:59], v[50:51], v[56:57]
	v_mov_b32_e32 v53, v50
	v_mov_b32_e32 v55, v59
	v_pk_add_f32 v[60:61], v[52:53], v[54:55] neg_lo:[0,1] neg_hi:[0,1]
	v_pk_add_f32 v[52:53], v[52:53], v[54:55]
	v_mov_b32_e32 v56, v57
	v_pk_add_f32 v[54:55], v[52:53], v[50:51] op_sel:[1,0] op_sel_hi:[0,1] neg_lo:[0,1] neg_hi:[0,1]
	s_nop 0
	v_pk_add_f32 v[62:63], v[58:59], v[54:55] op_sel_hi:[1,0] neg_lo:[0,1] neg_hi:[0,1]
	v_mov_b32_e32 v58, v59
	v_mov_b32_e32 v59, v53
	v_pk_mov_b32 v[54:55], v[50:51], v[54:55] op_sel:[1,0]
	v_mov_b32_e32 v57, v50
	v_pk_add_f32 v[54:55], v[58:59], v[54:55] neg_lo:[0,1] neg_hi:[0,1]
	v_mov_b32_e32 v62, v60
	v_pk_add_f32 v[50:51], v[56:57], v[54:55] neg_lo:[0,1] neg_hi:[0,1]
	v_mov_b32_e32 v61, v53
	v_pk_add_f32 v[54:55], v[62:63], v[50:51]
	v_cmp_neq_f32_e64 s[50:51], s12, v64
	v_pk_add_f32 v[56:57], v[54:55], v[54:55] op_sel:[0,1] op_sel_hi:[1,0]
	s_mov_b32 s12, 0x33800000
	v_pk_add_f32 v[52:53], v[52:53], v[56:57] op_sel:[1,0] op_sel_hi:[0,1]
	s_nop 0
	v_mov_b32_e32 v55, v52
	v_pk_add_f32 v[58:59], v[54:55], v[60:61] neg_lo:[0,1] neg_hi:[0,1]
	v_mov_b32_e32 v51, v56
	v_sub_f32_e32 v53, v54, v58
	v_pk_add_f32 v[50:51], v[50:51], v[58:59] neg_lo:[0,1] neg_hi:[0,1]
	v_sub_f32_e32 v53, v60, v53
	v_add_f32_e32 v50, v50, v53
	v_add_f32_e32 v50, v50, v51
	v_add_f32_e32 v50, v52, v50
	v_cndmask_b32_e64 v50, v212, v50, s[50:51]
	v_cmp_ngt_f32_e64 s[50:51], -1.0, v64
	s_nop 1
	v_cndmask_b32_e64 v50, v213, v50, s[50:51]
	v_cmp_neq_f32_e64 s[50:51], -1.0, v64
	s_nop 1
	v_cndmask_b32_e64 v50, v214, v50, s[50:51]
	v_cmp_lt_f32_e64 s[50:51], |v64|, s12
	s_nop 1
	v_cndmask_b32_e64 v50, v50, v64, s[50:51]
	v_sub_f32_e32 v50, v65, v50

; #define LAS __attribute__((address_space(3)))
; __device__ __forceinline__ unsigned cvt_pk_bf16(float lo, float hi) { unsigned r; asm volatile("v_cvt_pk_bf16_f32 %0, %1, %2" : "=v"(r) : "v"(lo), "v"(hi)); return r; }
; __device__ void phase0(const Params& P, LAS unsigned char* lds, const int G, const int bid) {
;     ...
;           for (int rr = 0; rr < 4; ++rr) { const int row = row0 + rr * G * 8; if (row >= NTOK) continue;
;               f32x4 (&v)[4] = vv[rr]; float ss = 0.f;
; #pragma unroll
;               for (int i = 0; i < 4; ++i)
; #pragma unroll
;                   for (int j = 0; j < 4; ++j) ss += v[i][j] * v[i][j];
; #pragma unroll
;               for (int o = 32; o >= 1; o >>= 1) ss += __shfl_xor(ss, o);
;               const float rstd = rsqrtf(ss * (1.0f / DM) + 1e-6f);
;               float ga[16];
; #pragma unroll
;               for (int c = 0; c < 16; ++c) ga[c] = 0.f;
; #pragma unroll
;               for (int i = 0; i < 4; ++i) { v[i] = v[i] * rstd * w4[i];
;                   u32x2 w; w.x = cvt_pk_bf16(v[i][0], v[i][1]); w.y = cvt_pk_bf16(v[i][2], v[i][3]);
;                   *(u32x2*)(abf + (size_t)row * DM + 4 * lane + 256 * i) = w;
; #pragma unroll
;                   for (int j = 0; j < 4; ++j) { const LAS float* wr_ = wg + (j * 256 + i * 64 + lane) * 20; const float a = v[i][j];
; #pragma unroll
;                       for (int q = 0; q < 4; ++q) { const f32x4 wv = *(const LAS f32x4*)(wr_ + 4 * q);
;                           ga[4 * q] += a * wv[0]; ga[4 * q + 1] += a * wv[1]; ga[4 * q + 2] += a * wv[2]; ga[4 * q + 3] += a * wv[3]; } } }
.LBB0_1055:
	s_or_b64 exec, exec, s[6:7]
	v_cmp_gt_i32_e64 s[50:51], s15, v86
	s_and_saveexec_b64 s[6:7], s[50:51]
	s_cbranch_execz .LBB0_1060
	s_waitcnt vmcnt(11)
	v_mul_f32_e32 v54, v47, v47
	v_fmac_f32_e32 v54, v46, v46
	v_fmac_f32_e32 v54, v48, v48
	v_fmac_f32_e32 v54, v49, v49
	s_waitcnt vmcnt(10)
	v_fmac_f32_e32 v54, v42, v42
	v_fmac_f32_e32 v54, v43, v43
	v_fmac_f32_e32 v54, v44, v44
	v_fmac_f32_e32 v54, v45, v45
	s_waitcnt vmcnt(9)
	v_fmac_f32_e32 v54, v38, v38
	v_fmac_f32_e32 v54, v39, v39
	v_fmac_f32_e32 v54, v40, v40
	v_fmac_f32_e32 v54, v41, v41
	s_waitcnt vmcnt(8)
	v_pk_mul_f32 v[52:53], v[34:35], v[34:35]
	s_waitcnt lgkmcnt(0)
	v_pk_mul_f32 v[50:51], v[36:37], v[36:37]
	v_add_f32_e32 v52, v52, v54
	v_add_f32_e32 v52, v53, v52
	v_add_f32_e32 v50, v50, v52
	v_add_f32_e32 v50, v51, v50
	ds_bpermute_b32 v51, v96, v50
	v_ashrrev_i32_e32 v87, 31, v86
	v_lshlrev_b64 v[52:53], 11, v[86:87]
	v_lshl_add_u64 v[52:53], v[80:81], 0, v[52:53]
	s_waitcnt lgkmcnt(0)
	v_add_f32_e32 v50, v50, v51
	ds_bpermute_b32 v51, v97, v50
	s_waitcnt lgkmcnt(0)
	v_add_f32_e32 v50, v50, v51
	ds_bpermute_b32 v51, v98, v50
	s_waitcnt lgkmcnt(0)
	v_add_f32_e32 v50, v50, v51
	ds_bpermute_b32 v51, v99, v50
	s_waitcnt lgkmcnt(0)
	v_add_f32_e32 v50, v50, v51
	ds_bpermute_b32 v51, v100, v50
	s_waitcnt lgkmcnt(0)
	v_add_f32_e32 v50, v50, v51
	ds_bpermute_b32 v51, v101, v50
	s_waitcnt lgkmcnt(0)
	v_add_f32_e32 v50, v50, v51
	v_fmamk_f32 v50, v50, 0x3a800000, v210
	v_cmp_gt_f32_e64 s[50:51], s30, v50
	v_mul_f32_e32 v51, 0x4b800000, v50
	s_nop 0
	v_cndmask_b32_e64 v50, v50, v51, s[50:51]
	v_rsq_f32_e32 v50, v50
	s_nop 0
	v_mul_f32_e32 v51, 0x45800000, v50
	v_cndmask_b32_e64 v50, v50, v51, s[50:51]
	v_pk_mul_f32 v[54:55], v[46:47], v[50:51] op_sel_hi:[1,0]
	v_pk_mul_f32 v[46:47], v[48:49], v[50:51] op_sel_hi:[1,0]
	v_pk_mul_f32 v[48:49], v[2:3], v[54:55]
	v_pk_mul_f32 v[46:47], v[4:5], v[46:47]
	v_cvt_pk_bf16_f32 v54, v48, v49
	s_nop 0
	v_cvt_pk_bf16_f32 v55, v46, v47
	global_store_dwordx2 v[52:53], v[54:55], off
	ds_read_b128 v[54:57], v102 offset:40960
	ds_read_b128 v[66:69], v102 offset:40976
	ds_read_b128 v[70:73], v102 offset:40992
	ds_read_b128 v[74:77], v102 offset:41008
	s_waitcnt lgkmcnt(3)
	v_fma_f32 v65, v54, v48, 0
	v_fma_f32 v62, v56, v48, 0
	s_waitcnt lgkmcnt(2)
	v_fma_f32 v58, v66, v48, 0
	v_fma_f32 v56, v67, v48, 0
	v_fma_f32 v54, v68, v48, 0
	v_fma_f32 v51, v69, v48, 0
	s_waitcnt lgkmcnt(1)
	v_fma_f32 v67, v70, v48, 0
	v_fma_f32 v66, v71, v48, 0
	ds_read_b128 v[68:71], v102 offset:61440
	v_fma_f32 v64, v55, v48, 0
	v_fma_f32 v59, v57, v48, 0
	v_fma_f32 v63, v72, v48, 0
	v_fma_f32 v61, v73, v48, 0
	s_waitcnt lgkmcnt(0)
	v_fmac_f32_e32 v65, v68, v49
	v_fmac_f32_e32 v64, v69, v49
	v_fmac_f32_e32 v62, v70, v49
	v_fmac_f32_e32 v59, v71, v49
	ds_read_b128 v[68:71], v102 offset:61456
	v_fma_f32 v60, v74, v48, 0
	v_fma_f32 v57, v75, v48, 0
	v_fma_f32 v55, v76, v48, 0
	v_fma_f32 v48, v77, v48, 0
	s_waitcnt lgkmcnt(0)
	v_fmac_f32_e32 v58, v68, v49
	v_fmac_f32_e32 v56, v69, v49
	v_fmac_f32_e32 v54, v70, v49
	v_fmac_f32_e32 v51, v71, v49
	ds_read_b128 v[68:71], v102 offset:61472
	s_waitcnt lgkmcnt(0)
	v_fmac_f32_e32 v67, v68, v49
	v_fmac_f32_e32 v66, v69, v49
	v_fmac_f32_e32 v63, v70, v49
	v_fmac_f32_e32 v61, v71, v49
	ds_read_b128 v[68:71], v102 offset:61488
	s_waitcnt lgkmcnt(0)
	v_fmac_f32_e32 v60, v68, v49
	v_fmac_f32_e32 v57, v69, v49
	v_fmac_f32_e32 v55, v70, v49
	v_fmac_f32_e32 v48, v71, v49
	ds_read_b128 v[68:71], v103 offset:40960
	ds_read_b128 v[72:75], v103 offset:40976
	ds_read_b128 v[92:95], v103 offset:40992
	ds_read_b128 v[116:119], v103 offset:41008
	s_waitcnt lgkmcnt(3)
	v_fmac_f32_e32 v65, v68, v46
	v_fmac_f32_e32 v64, v69, v46
	v_fmac_f32_e32 v62, v70, v46
	v_fmac_f32_e32 v59, v71, v46
	ds_read_b128 v[68:71], v103 offset:61440
	s_waitcnt lgkmcnt(3)
	v_fmac_f32_e32 v58, v46, v72
	v_fmac_f32_e32 v56, v46, v73
	v_fmac_f32_e32 v54, v46, v74
	v_fmac_f32_e32 v51, v46, v75
	s_waitcnt lgkmcnt(0)
	v_fmac_f32_e32 v65, v47, v68
	v_fmac_f32_e32 v64, v47, v69
	v_fmac_f32_e32 v62, v47, v70
	v_fmac_f32_e32 v59, v47, v71
	ds_read_b128 v[68:71], v103 offset:61456
	v_fmac_f32_e32 v67, v46, v92
	v_fmac_f32_e32 v66, v46, v93
	v_fmac_f32_e32 v63, v46, v94
	v_fmac_f32_e32 v61, v46, v95
	s_waitcnt lgkmcnt(0)
	v_fmac_f32_e32 v58, v47, v68
	v_fmac_f32_e32 v56, v47, v69
	v_fmac_f32_e32 v54, v47, v70
	v_fmac_f32_e32 v51, v47, v71
	ds_read_b128 v[68:71], v103 offset:61472
	v_fmac_f32_e32 v60, v46, v116
	v_fmac_f32_e32 v57, v46, v117
	v_fmac_f32_e32 v55, v46, v118
	v_fmac_f32_e32 v48, v46, v119
	s_waitcnt lgkmcnt(0)
	v_fmac_f32_e32 v67, v47, v68
	v_fmac_f32_e32 v66, v47, v69
	v_fmac_f32_e32 v63, v47, v70
	v_fmac_f32_e32 v61, v47, v71
	ds_read_b128 v[68:71], v103 offset:61488
	s_waitcnt lgkmcnt(0)
	v_fmac_f32_e32 v60, v47, v68
	v_fmac_f32_e32 v57, v47, v69
	v_fmac_f32_e32 v55, v47, v70
	v_fmac_f32_e32 v48, v47, v71
	v_pk_mul_f32 v[46:47], v[42:43], v[50:51] op_sel_hi:[1,0]
	v_pk_mul_f32 v[42:43], v[44:45], v[50:51] op_sel_hi:[1,0]
	v_pk_mul_f32 v[76:77], v[6:7], v[46:47]
	v_pk_mul_f32 v[42:43], v[8:9], v[42:43]
	v_cvt_pk_bf16_f32 v44, v76, v77
	s_nop 0
	v_cvt_pk_bf16_f32 v45, v42, v43
	global_store_dwordx2 v[52:53], v[44:45], off offset:512
	ds_read_b128 v[44:47], v102 offset:46080
	ds_read_b128 v[68:71], v102 offset:46096
	ds_read_b128 v[72:75], v102 offset:46112
	ds_read_b128 v[92:95], v102 offset:46128
	s_waitcnt lgkmcnt(3)
	v_fmac_f32_e32 v65, v76, v44
	v_fmac_f32_e32 v64, v76, v45
	v_fmac_f32_e32 v62, v76, v46
	v_fmac_f32_e32 v59, v76, v47
	s_waitcnt lgkmcnt(2)
	v_fmac_f32_e32 v58, v76, v68
	v_fmac_f32_e32 v56, v76, v69
	v_fmac_f32_e32 v54, v76, v70
	v_fmac_f32_e32 v51, v76, v71
	s_waitcnt lgkmcnt(1)
; #define LAS __attribute__((address_space(3)))
; __device__ __forceinline__ unsigned cvt_pk_bf16(float lo, float hi) { unsigned r; asm volatile("v_cvt_pk_bf16_f32 %0, %1, %2" : "=v"(r) : "v"(lo), "v"(hi)); return r; }
; __device__ void phase0(const Params& P, LAS unsigned char* lds, const int G, const int bid) {
;     ...
;               for (int i = 0; i < 4; ++i) { v[i] = v[i] * rstd * w4[i];
;                   u32x2 w; w.x = cvt_pk_bf16(v[i][0], v[i][1]); w.y = cvt_pk_bf16(v[i][2], v[i][3]);
;                   *(u32x2*)(abf + (size_t)row * DM + 4 * lane + 256 * i) = w;
; #pragma unroll
;                   for (int j = 0; j < 4; ++j) { const LAS float* wr_ = wg + (j * 256 + i * 64 + lane) * 20; const float a = v[i][j];
; #pragma unroll
;                       for (int q = 0; q < 4; ++q) { const f32x4 wv = *(const LAS f32x4*)(wr_ + 4 * q);
;                           ga[4 * q] += a * wv[0]; ga[4 * q + 1] += a * wv[1]; ga[4 * q + 2] += a * wv[2]; ga[4 * q + 3] += a * wv[3]; } } }
	v_fmac_f32_e32 v67, v76, v72
	v_fmac_f32_e32 v66, v76, v73
	v_fmac_f32_e32 v63, v76, v74
	v_fmac_f32_e32 v61, v76, v75
	s_waitcnt lgkmcnt(0)
	v_fmac_f32_e32 v60, v76, v92
	v_fmac_f32_e32 v57, v76, v93
	v_fmac_f32_e32 v55, v76, v94
	v_fmac_f32_e32 v48, v76, v95
	ds_read_b128 v[44:47], v103 offset:25600
	ds_read_b128 v[68:71], v103 offset:25616
	ds_read_b128 v[72:75], v103 offset:25632
	ds_read_b128 v[92:95], v103 offset:25648
	s_waitcnt lgkmcnt(3)
	v_fmac_f32_e32 v65, v77, v44
	v_fmac_f32_e32 v64, v77, v45
	v_fmac_f32_e32 v62, v77, v46
	v_fmac_f32_e32 v59, v77, v47
	ds_read_b128 v[44:47], v103 offset:46080
	s_waitcnt lgkmcnt(3)
	v_fmac_f32_e32 v58, v77, v68
	v_fmac_f32_e32 v56, v77, v69
	v_fmac_f32_e32 v54, v77, v70
	v_fmac_f32_e32 v51, v77, v71
	s_waitcnt lgkmcnt(0)
	v_fmac_f32_e32 v65, v42, v44
	v_fmac_f32_e32 v64, v42, v45
	v_fmac_f32_e32 v62, v42, v46
	v_fmac_f32_e32 v59, v42, v47
	ds_read_b128 v[44:47], v103 offset:46096
	v_fmac_f32_e32 v67, v77, v72
	v_fmac_f32_e32 v66, v77, v73
	v_fmac_f32_e32 v63, v77, v74
	v_fmac_f32_e32 v61, v77, v75
	s_waitcnt lgkmcnt(0)
	v_fmac_f32_e32 v58, v42, v44
	v_fmac_f32_e32 v56, v42, v45
	v_fmac_f32_e32 v54, v42, v46
	v_fmac_f32_e32 v51, v42, v47
	ds_read_b128 v[44:47], v103 offset:46112
	v_fmac_f32_e32 v60, v77, v92
	v_fmac_f32_e32 v57, v77, v93
	v_fmac_f32_e32 v55, v77, v94
	v_fmac_f32_e32 v48, v77, v95
	s_waitcnt lgkmcnt(0)
	v_fmac_f32_e32 v67, v42, v44
	v_fmac_f32_e32 v66, v42, v45
	v_fmac_f32_e32 v63, v42, v46
	v_fmac_f32_e32 v61, v42, v47
	ds_read_b128 v[44:47], v103 offset:46128
	s_waitcnt lgkmcnt(0)
	v_fmac_f32_e32 v60, v42, v44
	v_fmac_f32_e32 v57, v42, v45
	v_fmac_f32_e32 v55, v42, v46
	v_fmac_f32_e32 v48, v42, v47
	ds_read_b128 v[44:47], v104
	s_waitcnt lgkmcnt(0)
	v_fmac_f32_e32 v65, v43, v44
	v_fmac_f32_e32 v64, v43, v45
	v_fmac_f32_e32 v62, v43, v46
	v_fmac_f32_e32 v59, v43, v47
	ds_read_b128 v[44:47], v105
	s_waitcnt lgkmcnt(0)
	v_fmac_f32_e32 v58, v43, v44
	v_fmac_f32_e32 v56, v43, v45
	v_fmac_f32_e32 v54, v43, v46
	v_fmac_f32_e32 v51, v43, v47
	ds_read_b128 v[44:47], v106
	s_waitcnt lgkmcnt(0)
	v_fmac_f32_e32 v67, v43, v44
	v_fmac_f32_e32 v66, v43, v45
	v_fmac_f32_e32 v63, v43, v46
	v_fmac_f32_e32 v61, v43, v47
	ds_read_b128 v[44:47], v107
	s_waitcnt lgkmcnt(0)
	v_fmac_f32_e32 v60, v43, v44
	v_fmac_f32_e32 v57, v43, v45
	v_fmac_f32_e32 v55, v43, v46
	v_fmac_f32_e32 v48, v43, v47
	v_pk_mul_f32 v[42:43], v[38:39], v[50:51] op_sel_hi:[1,0]
	v_pk_mul_f32 v[38:39], v[40:41], v[50:51] op_sel_hi:[1,0]
	v_pk_mul_f32 v[76:77], v[10:11], v[42:43]
	v_pk_mul_f32 v[38:39], v[12:13], v[38:39]
	v_cvt_pk_bf16_f32 v40, v76, v77
	s_nop 0
	v_cvt_pk_bf16_f32 v41, v38, v39
	global_store_dwordx2 v[52:53], v[40:41], off offset:1024
	ds_read_b128 v[40:43], v102 offset:51200
	ds_read_b128 v[44:47], v102 offset:51216
	ds_read_b128 v[68:71], v102 offset:51232
	ds_read_b128 v[72:75], v102 offset:51248
	s_waitcnt lgkmcnt(3)
	v_fmac_f32_e32 v65, v76, v40
	v_fmac_f32_e32 v64, v76, v41
	v_fmac_f32_e32 v62, v76, v42
	v_fmac_f32_e32 v59, v76, v43
	s_waitcnt lgkmcnt(2)
	v_fmac_f32_e32 v58, v76, v44
	v_fmac_f32_e32 v56, v76, v45
	v_fmac_f32_e32 v54, v76, v46
	v_fmac_f32_e32 v51, v76, v47
	s_waitcnt lgkmcnt(1)
	v_fmac_f32_e32 v67, v76, v68
	v_fmac_f32_e32 v66, v76, v69
	v_fmac_f32_e32 v63, v76, v70
	v_fmac_f32_e32 v61, v76, v71
	s_waitcnt lgkmcnt(0)
	v_fmac_f32_e32 v60, v76, v72
	v_fmac_f32_e32 v57, v76, v73
	v_fmac_f32_e32 v55, v76, v74
	v_fmac_f32_e32 v48, v76, v75
	ds_read_b128 v[40:43], v103 offset:30720
	ds_read_b128 v[44:47], v103 offset:30736
	ds_read_b128 v[68:71], v103 offset:30752
	ds_read_b128 v[72:75], v103 offset:30768
	s_waitcnt lgkmcnt(3)
	v_fmac_f32_e32 v65, v77, v40
	v_fmac_f32_e32 v64, v77, v41
	v_fmac_f32_e32 v62, v77, v42
	v_fmac_f32_e32 v59, v77, v43
	ds_read_b128 v[40:43], v103 offset:51200
	s_waitcnt lgkmcnt(3)
	v_fmac_f32_e32 v58, v77, v44
	v_fmac_f32_e32 v56, v77, v45
	v_fmac_f32_e32 v54, v77, v46
	v_fmac_f32_e32 v51, v77, v47
	s_waitcnt lgkmcnt(0)
	v_fmac_f32_e32 v65, v38, v40
	v_fmac_f32_e32 v64, v38, v41
	v_fmac_f32_e32 v62, v38, v42
	v_fmac_f32_e32 v59, v38, v43
	ds_read_b128 v[40:43], v103 offset:51216
	v_fmac_f32_e32 v67, v77, v68
	v_fmac_f32_e32 v66, v77, v69
	v_fmac_f32_e32 v63, v77, v70
	v_fmac_f32_e32 v61, v77, v71
	s_waitcnt lgkmcnt(0)
	v_fmac_f32_e32 v58, v38, v40
	v_fmac_f32_e32 v56, v38, v41
	v_fmac_f32_e32 v54, v38, v42
	v_fmac_f32_e32 v51, v38, v43
	ds_read_b128 v[40:43], v103 offset:51232
	v_fmac_f32_e32 v60, v77, v72
	v_fmac_f32_e32 v57, v77, v73
	v_fmac_f32_e32 v55, v77, v74
	v_fmac_f32_e32 v48, v77, v75
	s_waitcnt lgkmcnt(0)
	v_fmac_f32_e32 v67, v38, v40
	v_fmac_f32_e32 v66, v38, v41
	v_fmac_f32_e32 v63, v38, v42
	v_fmac_f32_e32 v61, v38, v43
	ds_read_b128 v[40:43], v103 offset:51248
	s_waitcnt lgkmcnt(0)
	v_fmac_f32_e32 v60, v38, v40
	v_fmac_f32_e32 v57, v38, v41
	v_fmac_f32_e32 v55, v38, v42
	v_fmac_f32_e32 v48, v38, v43
	ds_read_b128 v[40:43], v108
	s_waitcnt lgkmcnt(0)
	v_fmac_f32_e32 v65, v39, v40
	v_fmac_f32_e32 v64, v39, v41
	v_fmac_f32_e32 v62, v39, v42
	v_fmac_f32_e32 v59, v39, v43
	ds_read_b128 v[40:43], v109
	s_waitcnt lgkmcnt(0)
	v_fmac_f32_e32 v58, v39, v40
	v_fmac_f32_e32 v56, v39, v41
	v_fmac_f32_e32 v54, v39, v42
	v_fmac_f32_e32 v51, v39, v43
	ds_read_b128 v[40:43], v110
	s_waitcnt lgkmcnt(0)
	v_fmac_f32_e32 v67, v39, v40
	v_fmac_f32_e32 v66, v39, v41
	v_fmac_f32_e32 v63, v39, v42
	v_fmac_f32_e32 v61, v39, v43
	ds_read_b128 v[40:43], v111
	s_waitcnt lgkmcnt(0)
; #define LAS __attribute__((address_space(3)))
; __device__ __forceinline__ unsigned cvt_pk_bf16(float lo, float hi) { unsigned r; asm volatile("v_cvt_pk_bf16_f32 %0, %1, %2" : "=v"(r) : "v"(lo), "v"(hi)); return r; }
; __device__ __forceinline__ float logsigmoidf_(float x) { return fminf(x, 0.0f) - log1pf(__expf(-fabsf(x))); }
; __device__ void phase0(const Params& P, LAS unsigned char* lds, const int G, const int bid) {
;     ...
;               for (int i = 0; i < 4; ++i) { v[i] = v[i] * rstd * w4[i];
;                   u32x2 w; w.x = cvt_pk_bf16(v[i][0], v[i][1]); w.y = cvt_pk_bf16(v[i][2], v[i][3]);
;                   *(u32x2*)(abf + (size_t)row * DM + 4 * lane + 256 * i) = w;
; #pragma unroll
;                   for (int j = 0; j < 4; ++j) { const LAS float* wr_ = wg + (j * 256 + i * 64 + lane) * 20; const float a = v[i][j];
; #pragma unroll
;                       for (int q = 0; q < 4; ++q) { const f32x4 wv = *(const LAS f32x4*)(wr_ + 4 * q);
;                           ga[4 * q] += a * wv[0]; ga[4 * q + 1] += a * wv[1]; ga[4 * q + 2] += a * wv[2]; ga[4 * q + 3] += a * wv[3]; } } }
;               float r8[8], r4[4], r2[2], r1;
; #pragma unroll
;               for (int c = 0; c < 8; ++c) { const bool hi = (lane & 32) != 0; const float send = hi ? ga[c] : ga[c + 8], keep = hi ? ga[c + 8] : ga[c]; r8[c] = keep + __shfl_xor(send, 32); }
; #pragma unroll
;               for (int c = 0; c < 4; ++c) { const bool hi = (lane & 16) != 0; const float send = hi ? r8[c] : r8[c + 4], keep = hi ? r8[c + 4] : r8[c]; r4[c] = keep + __shfl_xor(send, 16); }
; #pragma unroll
;               for (int c = 0; c < 2; ++c) { const bool hi = (lane & 8) != 0; const float send = hi ? r4[c] : r4[c + 2], keep = hi ? r4[c + 2] : r4[c]; r2[c] = keep + __shfl_xor(send, 8); }
;               { const bool hi = (lane & 4) != 0; const float send = hi ? r2[0] : r2[1], keep = hi ? r2[1] : r2[0]; r1 = keep + __shfl_xor(send, 4); }
;               r1 += __shfl_xor(r1, 2); r1 += __shfl_xor(r1, 1);
;               if ((lane & 3) == 0) { float gv = r1 + gbias; if (gcol >= 8) gv = logsigmoidf_(gv); gates[(size_t)row * 16 + gcol] = gv; }
	v_fmac_f32_e32 v60, v39, v40
	v_fmac_f32_e32 v57, v39, v41
	v_fmac_f32_e32 v55, v39, v42
	v_fmac_f32_e32 v48, v39, v43
	v_pk_mul_f32 v[38:39], v[34:35], v[50:51] op_sel_hi:[1,0]
	v_pk_mul_f32 v[34:35], v[36:37], v[50:51] op_sel_hi:[1,0]
	v_pk_mul_f32 v[72:73], v[14:15], v[38:39]
	v_pk_mul_f32 v[34:35], v[16:17], v[34:35]
	v_cvt_pk_bf16_f32 v36, v72, v73
	s_nop 0
	v_cvt_pk_bf16_f32 v37, v34, v35
	global_store_dwordx2 v[52:53], v[36:37], off offset:1536
	ds_read_b128 v[36:39], v102 offset:56320
	ds_read_b128 v[40:43], v102 offset:56336
	ds_read_b128 v[44:47], v102 offset:56352
	ds_read_b128 v[68:71], v102 offset:56368
	s_waitcnt lgkmcnt(3)
	v_fmac_f32_e32 v65, v72, v36
	v_fmac_f32_e32 v64, v72, v37
	v_fmac_f32_e32 v62, v72, v38
	v_fmac_f32_e32 v59, v72, v39
	s_waitcnt lgkmcnt(2)
	v_fmac_f32_e32 v58, v72, v40
	v_fmac_f32_e32 v56, v72, v41
	v_fmac_f32_e32 v54, v72, v42
	v_fmac_f32_e32 v51, v72, v43
	s_waitcnt lgkmcnt(1)
	v_fmac_f32_e32 v67, v72, v44
	v_fmac_f32_e32 v66, v72, v45
	v_fmac_f32_e32 v63, v72, v46
	v_fmac_f32_e32 v61, v72, v47
	s_waitcnt lgkmcnt(0)
	v_fmac_f32_e32 v60, v72, v68
	v_fmac_f32_e32 v57, v72, v69
	v_fmac_f32_e32 v55, v72, v70
	v_fmac_f32_e32 v48, v72, v71
	ds_read_b128 v[36:39], v103 offset:35840
	ds_read_b128 v[40:43], v103 offset:35856
	ds_read_b128 v[44:47], v103 offset:35872
	ds_read_b128 v[68:71], v103 offset:35888
	s_waitcnt lgkmcnt(3)
	v_fmac_f32_e32 v65, v73, v36
	v_fmac_f32_e32 v64, v73, v37
	v_fmac_f32_e32 v62, v73, v38
	v_fmac_f32_e32 v59, v73, v39
	ds_read_b128 v[36:39], v103 offset:56320
	s_waitcnt lgkmcnt(3)
	v_fmac_f32_e32 v58, v73, v40
	v_fmac_f32_e32 v56, v73, v41
	v_fmac_f32_e32 v54, v73, v42
	v_fmac_f32_e32 v51, v73, v43
	s_waitcnt lgkmcnt(0)
	v_fmac_f32_e32 v65, v34, v36
	v_fmac_f32_e32 v64, v34, v37
	v_fmac_f32_e32 v62, v34, v38
	v_fmac_f32_e32 v59, v34, v39
	ds_read_b128 v[36:39], v103 offset:56336
	v_fmac_f32_e32 v67, v73, v44
	v_fmac_f32_e32 v66, v73, v45
	v_fmac_f32_e32 v63, v73, v46
	v_fmac_f32_e32 v61, v73, v47
	s_waitcnt lgkmcnt(0)
	v_fmac_f32_e32 v58, v34, v36
	v_fmac_f32_e32 v56, v34, v37
	v_fmac_f32_e32 v54, v34, v38
	v_fmac_f32_e32 v51, v34, v39
	ds_read_b128 v[36:39], v103 offset:56352
	v_fmac_f32_e32 v60, v73, v68
	v_fmac_f32_e32 v57, v73, v69
	v_fmac_f32_e32 v55, v73, v70
	v_fmac_f32_e32 v48, v73, v71
	s_waitcnt lgkmcnt(0)
	v_fmac_f32_e32 v67, v34, v36
	v_fmac_f32_e32 v66, v34, v37
	v_fmac_f32_e32 v63, v34, v38
	v_fmac_f32_e32 v61, v34, v39
	ds_read_b128 v[36:39], v103 offset:56368
	s_waitcnt lgkmcnt(0)
	v_fmac_f32_e32 v60, v34, v36
	v_fmac_f32_e32 v57, v34, v37
	v_fmac_f32_e32 v55, v34, v38
	v_fmac_f32_e32 v48, v34, v39
	ds_read_b128 v[36:39], v112
	s_waitcnt lgkmcnt(0)
	v_fmac_f32_e32 v65, v35, v36
	v_fmac_f32_e32 v64, v35, v37
	v_fmac_f32_e32 v62, v35, v38
	v_fmac_f32_e32 v59, v35, v39
	ds_read_b128 v[36:39], v113
	s_waitcnt lgkmcnt(0)
	v_fmac_f32_e32 v58, v35, v36
	v_fmac_f32_e32 v56, v35, v37
	v_fmac_f32_e32 v54, v35, v38
	v_fmac_f32_e32 v51, v35, v39
	ds_read_b128 v[36:39], v114
	s_waitcnt lgkmcnt(0)
	v_fmac_f32_e32 v67, v35, v36
	v_fmac_f32_e32 v66, v35, v37
	v_fmac_f32_e32 v63, v35, v38
	v_fmac_f32_e32 v61, v35, v39
	ds_read_b128 v[36:39], v115
	v_cndmask_b32_e32 v34, v65, v67, vcc
	ds_bpermute_b32 v34, v96, v34
	s_waitcnt lgkmcnt(1)
	v_fmac_f32_e32 v60, v35, v36
	v_fmac_f32_e32 v57, v35, v37
	v_fmac_f32_e32 v55, v35, v38
	v_fmac_f32_e32 v48, v35, v39
	v_cndmask_b32_e32 v35, v67, v65, vcc
	s_waitcnt lgkmcnt(0)
	v_add_f32_e32 v34, v35, v34
	v_cndmask_b32_e32 v35, v64, v66, vcc
	ds_bpermute_b32 v35, v96, v35
	v_cndmask_b32_e32 v36, v66, v64, vcc
	v_cndmask_b32_e32 v37, v63, v62, vcc
	v_cndmask_b32_e32 v38, v61, v59, vcc
	v_cndmask_b32_e32 v39, v60, v58, vcc
	s_waitcnt lgkmcnt(0)
	v_add_f32_e32 v35, v36, v35
	v_cndmask_b32_e32 v36, v62, v63, vcc
	ds_bpermute_b32 v36, v96, v36
	v_cndmask_b32_e32 v40, v57, v56, vcc
	v_cndmask_b32_e32 v41, v55, v54, vcc
	v_cndmask_b32_e32 v42, v48, v51, vcc
	s_waitcnt lgkmcnt(0)
	v_add_f32_e32 v36, v37, v36
	v_cndmask_b32_e32 v37, v59, v61, vcc
	ds_bpermute_b32 v37, v96, v37
	s_waitcnt lgkmcnt(0)
	v_add_f32_e32 v37, v38, v37
	v_cndmask_b32_e32 v38, v58, v60, vcc
	ds_bpermute_b32 v38, v96, v38
	s_waitcnt lgkmcnt(0)
	v_add_f32_e32 v38, v39, v38
	v_cndmask_b32_e32 v39, v56, v57, vcc
	ds_bpermute_b32 v39, v96, v39
	s_waitcnt lgkmcnt(0)
	v_add_f32_e32 v39, v40, v39
	v_cndmask_b32_e32 v40, v54, v55, vcc
	ds_bpermute_b32 v40, v96, v40
	s_waitcnt lgkmcnt(0)
	v_add_f32_e32 v40, v41, v40
	v_cndmask_b32_e32 v41, v51, v48, vcc
	ds_bpermute_b32 v41, v96, v41
	s_waitcnt lgkmcnt(0)
	v_add_f32_e32 v41, v42, v41
	v_cndmask_b32_e64 v42, v34, v38, s[42:43]
	v_cndmask_b32_e64 v34, v38, v34, s[42:43]
	ds_bpermute_b32 v38, v97, v42
	s_waitcnt lgkmcnt(0)
	v_add_f32_e32 v34, v34, v38
	v_cndmask_b32_e64 v38, v35, v39, s[42:43]
	ds_bpermute_b32 v38, v97, v38
	v_cndmask_b32_e64 v35, v39, v35, s[42:43]
	s_waitcnt lgkmcnt(0)
	v_add_f32_e32 v35, v35, v38
	v_cndmask_b32_e64 v38, v36, v40, s[42:43]
	ds_bpermute_b32 v38, v97, v38
	v_cndmask_b32_e64 v36, v40, v36, s[42:43]
	s_waitcnt lgkmcnt(0)
	v_add_f32_e32 v36, v36, v38
	v_cndmask_b32_e64 v38, v37, v41, s[42:43]
	ds_bpermute_b32 v38, v97, v38
	v_cndmask_b32_e64 v37, v41, v37, s[42:43]
	s_waitcnt lgkmcnt(0)
	v_add_f32_e32 v37, v37, v38
	v_cndmask_b32_e64 v38, v34, v36, s[44:45]
	v_cndmask_b32_e64 v34, v36, v34, s[44:45]
	ds_bpermute_b32 v36, v98, v38
	s_waitcnt lgkmcnt(0)
	v_add_f32_e32 v34, v34, v36
	v_cndmask_b32_e64 v36, v35, v37, s[44:45]
	ds_bpermute_b32 v36, v98, v36
	v_cndmask_b32_e64 v35, v37, v35, s[44:45]
	s_waitcnt lgkmcnt(0)
	v_add_f32_e32 v35, v35, v36
	v_cndmask_b32_e64 v36, v34, v35, s[46:47]
	v_cndmask_b32_e64 v34, v35, v34, s[46:47]
	ds_bpermute_b32 v35, v99, v36
	s_waitcnt lgkmcnt(0)
	v_add_f32_e32 v34, v34, v35
	ds_bpermute_b32 v35, v100, v34
	s_waitcnt lgkmcnt(0)
	v_add_f32_e32 v34, v34, v35
	ds_bpermute_b32 v35, v101, v34
	s_and_b64 exec, exec, s[48:49]
	s_cbranch_execz .LBB0_1060
; __device__ __forceinline__ float logsigmoidf_(float x) { return fminf(x, 0.0f) - log1pf(__expf(-fabsf(x))); }
; __device__ void phase0(const Params& P, LAS unsigned char* lds, const int G, const int bid) {
;     ...
;               if ((lane & 3) == 0) { float gv = r1 + gbias; if (gcol >= 8) gv = logsigmoidf_(gv); gates[(size_t)row * 16 + gcol] = gv; }
	s_waitcnt lgkmcnt(0)
	v_add_f32_e32 v34, v34, v35
	v_add_f32_e32 v34, v91, v34
	s_and_saveexec_b64 s[8:9], s[40:41]
	s_cbranch_execz .LBB0_1059
	s_mov_b32 s12, 0xbfb8aa3b
	v_mul_f32_e64 v35, |v34|, s12
	v_exp_f32_e32 v48, v35
	v_max_f32_e32 v34, v34, v34
	v_min_f32_e32 v49, 0, v34
	s_mov_b32 s12, 0x3f2aaaab
	v_add_f32_e32 v36, 1.0, v48
	v_add_f32_e32 v34, -1.0, v36
	v_sub_f32_e32 v35, v34, v36
	v_sub_f32_e32 v34, v48, v34
	v_add_f32_e32 v35, 1.0, v35
	v_add_f32_e32 v37, v34, v35
	v_frexp_mant_f32_e32 v38, v36
	v_cvt_f64_f32_e32 v[34:35], v36
	v_frexp_exp_i32_f64_e32 v34, v[34:35]
	v_cmp_gt_f32_e64 s[50:51], s12, v38
	s_mov_b32 s12, 0x3f317218
	s_nop 0
	v_subbrev_co_u32_e64 v42, s[50:51], 0, v34, s[50:51]
	v_sub_u32_e32 v34, 0, v42
	v_ldexp_f32 v35, v36, v34
	v_add_f32_e32 v36, -1.0, v35
	v_add_f32_e32 v38, 1.0, v35
	v_ldexp_f32 v34, v37, v34
	v_add_f32_e32 v37, 1.0, v36
	v_add_f32_e32 v39, -1.0, v38
	v_sub_f32_e32 v37, v35, v37
	v_sub_f32_e32 v35, v35, v39
	v_add_f32_e32 v37, v34, v37
	v_add_f32_e32 v34, v34, v35
	v_add_f32_e32 v43, v38, v34
	v_rcp_f32_e32 v45, v43
	v_sub_f32_e32 v35, v43, v38
	v_sub_f32_e32 v44, v34, v35
	v_add_f32_e32 v35, v36, v37
	v_mul_f32_e32 v47, v35, v45
	v_sub_f32_e32 v34, v35, v36
	v_mul_f32_e32 v36, v43, v47
	v_fma_f32 v38, v47, v43, -v36
	v_fmac_f32_e32 v38, v47, v44
	v_sub_f32_e32 v46, v37, v34
	v_add_f32_e32 v34, v36, v38
	v_sub_f32_e32 v37, v35, v34
	v_pk_add_f32 v[40:41], v[34:35], v[36:37] neg_lo:[0,1] neg_hi:[0,1]
	v_mov_b32_e32 v39, v34
	v_pk_add_f32 v[34:35], v[40:41], v[38:39] neg_lo:[0,1] neg_hi:[0,1]
	s_nop 0
	v_add_f32_e32 v35, v46, v35
	v_add_f32_e32 v34, v34, v35
	v_add_f32_e32 v35, v37, v34
	v_mul_f32_e32 v46, v45, v35
	v_mul_f32_e32 v36, v43, v46
	v_fma_f32 v38, v46, v43, -v36
	v_fmac_f32_e32 v38, v46, v44
	v_sub_f32_e32 v37, v37, v35
	v_add_f32_e32 v43, v34, v37
	v_add_f32_e32 v34, v36, v38
	v_sub_f32_e32 v37, v35, v34
	v_pk_add_f32 v[40:41], v[34:35], v[36:37] neg_lo:[0,1] neg_hi:[0,1]
	v_mov_b32_e32 v39, v34
	v_pk_add_f32 v[34:35], v[40:41], v[38:39] neg_lo:[0,1] neg_hi:[0,1]
	s_nop 0
	v_add_f32_e32 v35, v43, v35
	v_add_f32_e32 v34, v34, v35
	v_add_f32_e32 v35, v47, v46
	v_add_f32_e32 v34, v37, v34
	v_sub_f32_e32 v36, v35, v47
	v_mul_f32_e32 v34, v45, v34
	v_sub_f32_e32 v36, v46, v36
	v_add_f32_e32 v36, v36, v34
	v_add_f32_e32 v38, v35, v36
	v_mul_f32_e32 v39, v38, v38
	v_fmamk_f32 v34, v39, 0x3e9b6dac, v208
	v_fmaak_f32 v169, v39, v34, 0x3f2aaada
	v_cvt_f32_i32_e32 v34, v42
	v_sub_f32_e32 v35, v38, v35
	v_sub_f32_e32 v35, v36, v35
	v_ldexp_f32 v40, v35, 1
	v_mul_f32_e32 v35, v38, v39
	v_ldexp_f32 v37, v38, 1
	v_pk_mul_f32 v[38:39], v[34:35], v[168:169]
	s_nop 0
	v_fma_f32 v36, v34, s12, -v38
	v_fmac_f32_e32 v36, 0xb102e308, v34
	v_pk_add_f32 v[34:35], v[38:39], v[36:37]
	s_mov_b32 s12, 0x7f800000
	v_sub_f32_e32 v37, v35, v37
	v_sub_f32_e32 v37, v39, v37
	v_add_f32_e32 v41, v40, v37
	v_mov_b32_e32 v40, v38
	v_pk_add_f32 v[38:39], v[34:35], v[38:39] neg_lo:[0,1] neg_hi:[0,1]
	v_pk_add_f32 v[42:43], v[34:35], v[40:41]
	v_mov_b32_e32 v37, v34
	v_mov_b32_e32 v39, v43
	v_pk_add_f32 v[44:45], v[36:37], v[38:39] neg_lo:[0,1] neg_hi:[0,1]
	v_pk_add_f32 v[36:37], v[36:37], v[38:39]
	v_mov_b32_e32 v40, v41
	v_pk_add_f32 v[38:39], v[36:37], v[34:35] op_sel:[1,0] op_sel_hi:[0,1] neg_lo:[0,1] neg_hi:[0,1]
	s_nop 0
	v_pk_add_f32 v[46:47], v[42:43], v[38:39] op_sel_hi:[1,0] neg_lo:[0,1] neg_hi:[0,1]
	v_mov_b32_e32 v42, v43
	v_mov_b32_e32 v43, v37
	v_pk_mov_b32 v[38:39], v[34:35], v[38:39] op_sel:[1,0]
	v_mov_b32_e32 v41, v34
	v_pk_add_f32 v[38:39], v[42:43], v[38:39] neg_lo:[0,1] neg_hi:[0,1]
	v_mov_b32_e32 v46, v44
	v_pk_add_f32 v[34:35], v[40:41], v[38:39] neg_lo:[0,1] neg_hi:[0,1]
	v_mov_b32_e32 v45, v37
	v_pk_add_f32 v[38:39], v[46:47], v[34:35]
	v_cmp_neq_f32_e64 s[50:51], s12, v48
	v_pk_add_f32 v[40:41], v[38:39], v[38:39] op_sel:[0,1] op_sel_hi:[1,0]
	s_mov_b32 s12, 0x33800000
	v_pk_add_f32 v[36:37], v[36:37], v[40:41] op_sel:[1,0] op_sel_hi:[0,1]
	s_nop 0
	v_mov_b32_e32 v39, v36
	v_pk_add_f32 v[42:43], v[38:39], v[44:45] neg_lo:[0,1] neg_hi:[0,1]
	v_mov_b32_e32 v35, v40
	v_sub_f32_e32 v37, v38, v42
	v_pk_add_f32 v[34:35], v[34:35], v[42:43] neg_lo:[0,1] neg_hi:[0,1]
	v_sub_f32_e32 v37, v44, v37
	v_add_f32_e32 v34, v34, v37
	v_add_f32_e32 v34, v34, v35
	v_add_f32_e32 v34, v36, v34
	v_cndmask_b32_e64 v34, v212, v34, s[50:51]
	v_cmp_ngt_f32_e64 s[50:51], -1.0, v48
	s_nop 1
	v_cndmask_b32_e64 v34, v213, v34, s[50:51]
	v_cmp_neq_f32_e64 s[50:51], -1.0, v48
	s_nop 1
	v_cndmask_b32_e64 v34, v214, v34, s[50:51]
	v_cmp_lt_f32_e64 s[50:51], |v48|, s12
	s_nop 1
	v_cndmask_b32_e64 v34, v34, v48, s[50:51]
	v_sub_f32_e32 v34, v49, v34

; #define LAS __attribute__((address_space(3)))
; __device__ __forceinline__ unsigned cvt_pk_bf16(float lo, float hi) { unsigned r; asm volatile("v_cvt_pk_bf16_f32 %0, %1, %2" : "=v"(r) : "v"(lo), "v"(hi)); return r; }
; __device__ void phase0(const Params& P, LAS unsigned char* lds, const int G, const int bid) {
;     ...
;           for (int rr = 0; rr < 4; ++rr) { const int row = row0 + rr * G * 8; if (row >= NTOK) continue;
;               f32x4 (&v)[4] = vv[rr]; float ss = 0.f;
; #pragma unroll
;               for (int i = 0; i < 4; ++i)
; #pragma unroll
;                   for (int j = 0; j < 4; ++j) ss += v[i][j] * v[i][j];
; #pragma unroll
;               for (int o = 32; o >= 1; o >>= 1) ss += __shfl_xor(ss, o);
;               const float rstd = rsqrtf(ss * (1.0f / DM) + 1e-6f);
;               float ga[16];
; #pragma unroll
;               for (int c = 0; c < 16; ++c) ga[c] = 0.f;
; #pragma unroll
;               for (int i = 0; i < 4; ++i) { v[i] = v[i] * rstd * w4[i];
;                   u32x2 w; w.x = cvt_pk_bf16(v[i][0], v[i][1]); w.y = cvt_pk_bf16(v[i][2], v[i][3]);
;                   *(u32x2*)(abf + (size_t)row * DM + 4 * lane + 256 * i) = w;
; #pragma unroll
;                   for (int j = 0; j < 4; ++j) { const LAS float* wr_ = wg + (j * 256 + i * 64 + lane) * 20; const float a = v[i][j];
; #pragma unroll
;                       for (int q = 0; q < 4; ++q) { const f32x4 wv = *(const LAS f32x4*)(wr_ + 4 * q);
;                           ga[4 * q] += a * wv[0]; ga[4 * q + 1] += a * wv[1]; ga[4 * q + 2] += a * wv[2]; ga[4 * q + 3] += a * wv[3]; } } }
.LBB0_1060:
	s_or_b64 exec, exec, s[6:7]
	v_cmp_gt_i32_e64 s[50:51], s15, v84
	s_and_saveexec_b64 s[6:7], s[50:51]
	s_cbranch_execz .LBB0_1045
	s_waitcnt vmcnt(7)
	v_mul_f32_e32 v38, v31, v31
	v_fmac_f32_e32 v38, v30, v30
	v_fmac_f32_e32 v38, v32, v32
	v_fmac_f32_e32 v38, v33, v33
	s_waitcnt vmcnt(6)
	v_fmac_f32_e32 v38, v26, v26
	v_fmac_f32_e32 v38, v27, v27
	v_fmac_f32_e32 v38, v28, v28
	v_fmac_f32_e32 v38, v29, v29
	s_waitcnt vmcnt(5)
	v_fmac_f32_e32 v38, v22, v22
	v_fmac_f32_e32 v38, v23, v23
	v_fmac_f32_e32 v38, v24, v24
	v_fmac_f32_e32 v38, v25, v25
	s_waitcnt vmcnt(4)
	v_pk_mul_f32 v[36:37], v[18:19], v[18:19]
	s_waitcnt lgkmcnt(0)
	v_pk_mul_f32 v[34:35], v[20:21], v[20:21]
	v_add_f32_e32 v36, v36, v38
	v_add_f32_e32 v36, v37, v36
	v_add_f32_e32 v34, v34, v36
	v_add_f32_e32 v34, v35, v34
	ds_bpermute_b32 v35, v96, v34
	v_ashrrev_i32_e32 v85, 31, v84
	v_lshlrev_b64 v[36:37], 11, v[84:85]
	v_lshl_add_u64 v[36:37], v[80:81], 0, v[36:37]
	s_waitcnt lgkmcnt(0)
	v_add_f32_e32 v34, v34, v35
	ds_bpermute_b32 v35, v97, v34
	s_waitcnt lgkmcnt(0)
	v_add_f32_e32 v34, v34, v35
	ds_bpermute_b32 v35, v98, v34
	s_waitcnt lgkmcnt(0)
	v_add_f32_e32 v34, v34, v35
	ds_bpermute_b32 v35, v99, v34
	s_waitcnt lgkmcnt(0)
	v_add_f32_e32 v34, v34, v35
	ds_bpermute_b32 v35, v100, v34
	s_waitcnt lgkmcnt(0)
	v_add_f32_e32 v34, v34, v35
	ds_bpermute_b32 v35, v101, v34
	s_waitcnt lgkmcnt(0)
	v_add_f32_e32 v34, v34, v35
	v_fmamk_f32 v34, v34, 0x3a800000, v210
	v_cmp_gt_f32_e64 s[50:51], s30, v34
	v_mul_f32_e32 v35, 0x4b800000, v34
	s_nop 0
	v_cndmask_b32_e64 v34, v34, v35, s[50:51]
	v_rsq_f32_e32 v34, v34
	s_nop 0
	v_mul_f32_e32 v35, 0x45800000, v34
	v_cndmask_b32_e64 v34, v34, v35, s[50:51]
	v_pk_mul_f32 v[38:39], v[30:31], v[34:35] op_sel_hi:[1,0]
	v_pk_mul_f32 v[30:31], v[32:33], v[34:35] op_sel_hi:[1,0]
	v_pk_mul_f32 v[32:33], v[2:3], v[38:39]
	v_pk_mul_f32 v[30:31], v[4:5], v[30:31]
	v_cvt_pk_bf16_f32 v38, v32, v33
	s_nop 0
	v_cvt_pk_bf16_f32 v39, v30, v31
	global_store_dwordx2 v[36:37], v[38:39], off
	ds_read_b128 v[38:41], v102 offset:40960
	ds_read_b128 v[50:53], v102 offset:40976
	ds_read_b128 v[54:57], v102 offset:40992
	ds_read_b128 v[58:61], v102 offset:41008
	s_waitcnt lgkmcnt(3)
	v_fma_f32 v49, v38, v32, 0
	v_fma_f32 v46, v40, v32, 0
	s_waitcnt lgkmcnt(2)
	v_fma_f32 v42, v50, v32, 0
	v_fma_f32 v40, v51, v32, 0
	v_fma_f32 v38, v52, v32, 0
	v_fma_f32 v35, v53, v32, 0
	s_waitcnt lgkmcnt(1)
	v_fma_f32 v51, v54, v32, 0
	v_fma_f32 v50, v55, v32, 0
	ds_read_b128 v[52:55], v102 offset:61440
	v_fma_f32 v48, v39, v32, 0
	v_fma_f32 v43, v41, v32, 0
	v_fma_f32 v47, v56, v32, 0
	v_fma_f32 v45, v57, v32, 0
	s_waitcnt lgkmcnt(0)
	v_fmac_f32_e32 v49, v52, v33
	v_fmac_f32_e32 v48, v53, v33
	v_fmac_f32_e32 v46, v54, v33
	v_fmac_f32_e32 v43, v55, v33
	ds_read_b128 v[52:55], v102 offset:61456
	v_fma_f32 v44, v58, v32, 0
	v_fma_f32 v41, v59, v32, 0
	v_fma_f32 v39, v60, v32, 0
	v_fma_f32 v32, v61, v32, 0
	s_waitcnt lgkmcnt(0)
	v_fmac_f32_e32 v42, v52, v33
	v_fmac_f32_e32 v40, v53, v33
	v_fmac_f32_e32 v38, v54, v33
	v_fmac_f32_e32 v35, v55, v33
	ds_read_b128 v[52:55], v102 offset:61472
	s_waitcnt lgkmcnt(0)
	v_fmac_f32_e32 v51, v52, v33
	v_fmac_f32_e32 v50, v53, v33
	v_fmac_f32_e32 v47, v54, v33
	v_fmac_f32_e32 v45, v55, v33
	ds_read_b128 v[52:55], v102 offset:61488
	s_waitcnt lgkmcnt(0)
	v_fmac_f32_e32 v44, v52, v33
	v_fmac_f32_e32 v41, v53, v33
	v_fmac_f32_e32 v39, v54, v33
	v_fmac_f32_e32 v32, v55, v33
	ds_read_b128 v[52:55], v103 offset:40960
	ds_read_b128 v[56:59], v103 offset:40976
	ds_read_b128 v[60:63], v103 offset:40992
	ds_read_b128 v[64:67], v103 offset:41008
	s_waitcnt lgkmcnt(3)
	v_fmac_f32_e32 v49, v52, v30
	v_fmac_f32_e32 v48, v53, v30
	v_fmac_f32_e32 v46, v54, v30
	v_fmac_f32_e32 v43, v55, v30
	ds_read_b128 v[52:55], v103 offset:61440
	s_waitcnt lgkmcnt(3)
	v_fmac_f32_e32 v42, v30, v56
	v_fmac_f32_e32 v40, v30, v57
	v_fmac_f32_e32 v38, v30, v58
	v_fmac_f32_e32 v35, v30, v59
	s_waitcnt lgkmcnt(0)
	v_fmac_f32_e32 v49, v31, v52
	v_fmac_f32_e32 v48, v31, v53
	v_fmac_f32_e32 v46, v31, v54
	v_fmac_f32_e32 v43, v31, v55
	ds_read_b128 v[52:55], v103 offset:61456
	v_fmac_f32_e32 v51, v30, v60
	v_fmac_f32_e32 v50, v30, v61
	v_fmac_f32_e32 v47, v30, v62
	v_fmac_f32_e32 v45, v30, v63
	s_waitcnt lgkmcnt(0)
	v_fmac_f32_e32 v42, v31, v52
	v_fmac_f32_e32 v40, v31, v53
	v_fmac_f32_e32 v38, v31, v54
	v_fmac_f32_e32 v35, v31, v55
	ds_read_b128 v[52:55], v103 offset:61472
	v_fmac_f32_e32 v44, v30, v64
	v_fmac_f32_e32 v41, v30, v65
	v_fmac_f32_e32 v39, v30, v66
	v_fmac_f32_e32 v32, v30, v67
	s_waitcnt lgkmcnt(0)
	v_fmac_f32_e32 v51, v31, v52
	v_fmac_f32_e32 v50, v31, v53
	v_fmac_f32_e32 v47, v31, v54
	v_fmac_f32_e32 v45, v31, v55
	ds_read_b128 v[52:55], v103 offset:61488
	s_waitcnt lgkmcnt(0)
	v_fmac_f32_e32 v44, v31, v52
	v_fmac_f32_e32 v41, v31, v53
	v_fmac_f32_e32 v39, v31, v54
	v_fmac_f32_e32 v32, v31, v55
	v_pk_mul_f32 v[30:31], v[26:27], v[34:35] op_sel_hi:[1,0]
	v_pk_mul_f32 v[26:27], v[28:29], v[34:35] op_sel_hi:[1,0]
	v_pk_mul_f32 v[64:65], v[6:7], v[30:31]
	v_pk_mul_f32 v[26:27], v[8:9], v[26:27]
	v_cvt_pk_bf16_f32 v28, v64, v65
	s_nop 0
	v_cvt_pk_bf16_f32 v29, v26, v27
	global_store_dwordx2 v[36:37], v[28:29], off offset:512
	ds_read_b128 v[28:31], v102 offset:46080
	ds_read_b128 v[52:55], v102 offset:46096
	ds_read_b128 v[56:59], v102 offset:46112
	ds_read_b128 v[60:63], v102 offset:46128
	s_waitcnt lgkmcnt(3)
	v_fmac_f32_e32 v49, v64, v28
	v_fmac_f32_e32 v48, v64, v29
	v_fmac_f32_e32 v46, v64, v30
	v_fmac_f32_e32 v43, v64, v31
	s_waitcnt lgkmcnt(2)
	v_fmac_f32_e32 v42, v64, v52
	v_fmac_f32_e32 v40, v64, v53
	v_fmac_f32_e32 v38, v64, v54
	v_fmac_f32_e32 v35, v64, v55
	s_waitcnt lgkmcnt(1)
; #define LAS __attribute__((address_space(3)))
; __device__ __forceinline__ unsigned cvt_pk_bf16(float lo, float hi) { unsigned r; asm volatile("v_cvt_pk_bf16_f32 %0, %1, %2" : "=v"(r) : "v"(lo), "v"(hi)); return r; }
; __device__ void phase0(const Params& P, LAS unsigned char* lds, const int G, const int bid) {
;     ...
;               for (int i = 0; i < 4; ++i) { v[i] = v[i] * rstd * w4[i];
;                   u32x2 w; w.x = cvt_pk_bf16(v[i][0], v[i][1]); w.y = cvt_pk_bf16(v[i][2], v[i][3]);
;                   *(u32x2*)(abf + (size_t)row * DM + 4 * lane + 256 * i) = w;
; #pragma unroll
;                   for (int j = 0; j < 4; ++j) { const LAS float* wr_ = wg + (j * 256 + i * 64 + lane) * 20; const float a = v[i][j];
; #pragma unroll
;                       for (int q = 0; q < 4; ++q) { const f32x4 wv = *(const LAS f32x4*)(wr_ + 4 * q);
;                           ga[4 * q] += a * wv[0]; ga[4 * q + 1] += a * wv[1]; ga[4 * q + 2] += a * wv[2]; ga[4 * q + 3] += a * wv[3]; } } }
	v_fmac_f32_e32 v51, v64, v56
	v_fmac_f32_e32 v50, v64, v57
	v_fmac_f32_e32 v47, v64, v58
	v_fmac_f32_e32 v45, v64, v59
	s_waitcnt lgkmcnt(0)
	v_fmac_f32_e32 v44, v64, v60
	v_fmac_f32_e32 v41, v64, v61
	v_fmac_f32_e32 v39, v64, v62
	v_fmac_f32_e32 v32, v64, v63
	ds_read_b128 v[28:31], v103 offset:25600
	ds_read_b128 v[52:55], v103 offset:25616
	ds_read_b128 v[56:59], v103 offset:25632
	ds_read_b128 v[60:63], v103 offset:25648
	s_waitcnt lgkmcnt(3)
	v_fmac_f32_e32 v49, v65, v28
	v_fmac_f32_e32 v48, v65, v29
	v_fmac_f32_e32 v46, v65, v30
	v_fmac_f32_e32 v43, v65, v31
	ds_read_b128 v[28:31], v103 offset:46080
	s_waitcnt lgkmcnt(3)
	v_fmac_f32_e32 v42, v65, v52
	v_fmac_f32_e32 v40, v65, v53
	v_fmac_f32_e32 v38, v65, v54
	v_fmac_f32_e32 v35, v65, v55
	s_waitcnt lgkmcnt(0)
	v_fmac_f32_e32 v49, v26, v28
	v_fmac_f32_e32 v48, v26, v29
	v_fmac_f32_e32 v46, v26, v30
	v_fmac_f32_e32 v43, v26, v31
	ds_read_b128 v[28:31], v103 offset:46096
	v_fmac_f32_e32 v51, v65, v56
	v_fmac_f32_e32 v50, v65, v57
	v_fmac_f32_e32 v47, v65, v58
	v_fmac_f32_e32 v45, v65, v59
	s_waitcnt lgkmcnt(0)
	v_fmac_f32_e32 v42, v26, v28
	v_fmac_f32_e32 v40, v26, v29
	v_fmac_f32_e32 v38, v26, v30
	v_fmac_f32_e32 v35, v26, v31
	ds_read_b128 v[28:31], v103 offset:46112
	v_fmac_f32_e32 v44, v65, v60
	v_fmac_f32_e32 v41, v65, v61
	v_fmac_f32_e32 v39, v65, v62
	v_fmac_f32_e32 v32, v65, v63
	s_waitcnt lgkmcnt(0)
	v_fmac_f32_e32 v51, v26, v28
	v_fmac_f32_e32 v50, v26, v29
	v_fmac_f32_e32 v47, v26, v30
	v_fmac_f32_e32 v45, v26, v31
	ds_read_b128 v[28:31], v103 offset:46128
	s_waitcnt lgkmcnt(0)
	v_fmac_f32_e32 v44, v26, v28
	v_fmac_f32_e32 v41, v26, v29
	v_fmac_f32_e32 v39, v26, v30
	v_fmac_f32_e32 v32, v26, v31
	ds_read_b128 v[28:31], v104
	s_waitcnt lgkmcnt(0)
	v_fmac_f32_e32 v49, v27, v28
	v_fmac_f32_e32 v48, v27, v29
	v_fmac_f32_e32 v46, v27, v30
	v_fmac_f32_e32 v43, v27, v31
	ds_read_b128 v[28:31], v105
	s_waitcnt lgkmcnt(0)
	v_fmac_f32_e32 v42, v27, v28
	v_fmac_f32_e32 v40, v27, v29
	v_fmac_f32_e32 v38, v27, v30
	v_fmac_f32_e32 v35, v27, v31
	ds_read_b128 v[28:31], v106
	s_waitcnt lgkmcnt(0)
	v_fmac_f32_e32 v51, v27, v28
	v_fmac_f32_e32 v50, v27, v29
	v_fmac_f32_e32 v47, v27, v30
	v_fmac_f32_e32 v45, v27, v31
	ds_read_b128 v[28:31], v107
	s_waitcnt lgkmcnt(0)
	v_fmac_f32_e32 v44, v27, v28
	v_fmac_f32_e32 v41, v27, v29
	v_fmac_f32_e32 v39, v27, v30
	v_fmac_f32_e32 v32, v27, v31
	v_pk_mul_f32 v[26:27], v[22:23], v[34:35] op_sel_hi:[1,0]
	v_pk_mul_f32 v[22:23], v[24:25], v[34:35] op_sel_hi:[1,0]
	v_pk_mul_f32 v[60:61], v[10:11], v[26:27]
	v_pk_mul_f32 v[22:23], v[12:13], v[22:23]
	v_cvt_pk_bf16_f32 v24, v60, v61
	s_nop 0
	v_cvt_pk_bf16_f32 v25, v22, v23
	global_store_dwordx2 v[36:37], v[24:25], off offset:1024
	ds_read_b128 v[24:27], v102 offset:51200
	ds_read_b128 v[28:31], v102 offset:51216
	ds_read_b128 v[52:55], v102 offset:51232
	ds_read_b128 v[56:59], v102 offset:51248
	s_waitcnt lgkmcnt(3)
	v_fmac_f32_e32 v49, v60, v24
	v_fmac_f32_e32 v48, v60, v25
	v_fmac_f32_e32 v46, v60, v26
	v_fmac_f32_e32 v43, v60, v27
	s_waitcnt lgkmcnt(2)
	v_fmac_f32_e32 v42, v60, v28
	v_fmac_f32_e32 v40, v60, v29
	v_fmac_f32_e32 v38, v60, v30
	v_fmac_f32_e32 v35, v60, v31
	s_waitcnt lgkmcnt(1)
	v_fmac_f32_e32 v51, v60, v52
	v_fmac_f32_e32 v50, v60, v53
	v_fmac_f32_e32 v47, v60, v54
	v_fmac_f32_e32 v45, v60, v55
	s_waitcnt lgkmcnt(0)
	v_fmac_f32_e32 v44, v60, v56
	v_fmac_f32_e32 v41, v60, v57
	v_fmac_f32_e32 v39, v60, v58
	v_fmac_f32_e32 v32, v60, v59
	ds_read_b128 v[24:27], v103 offset:30720
	ds_read_b128 v[28:31], v103 offset:30736
	ds_read_b128 v[52:55], v103 offset:30752
	ds_read_b128 v[56:59], v103 offset:30768
	s_waitcnt lgkmcnt(3)
	v_fmac_f32_e32 v49, v61, v24
	v_fmac_f32_e32 v48, v61, v25
	v_fmac_f32_e32 v46, v61, v26
	v_fmac_f32_e32 v43, v61, v27
	ds_read_b128 v[24:27], v103 offset:51200
	s_waitcnt lgkmcnt(3)
	v_fmac_f32_e32 v42, v61, v28
	v_fmac_f32_e32 v40, v61, v29
	v_fmac_f32_e32 v38, v61, v30
	v_fmac_f32_e32 v35, v61, v31
	s_waitcnt lgkmcnt(0)
	v_fmac_f32_e32 v49, v22, v24
	v_fmac_f32_e32 v48, v22, v25
	v_fmac_f32_e32 v46, v22, v26
	v_fmac_f32_e32 v43, v22, v27
	ds_read_b128 v[24:27], v103 offset:51216
	v_fmac_f32_e32 v51, v61, v52
	v_fmac_f32_e32 v50, v61, v53
	v_fmac_f32_e32 v47, v61, v54
	v_fmac_f32_e32 v45, v61, v55
	s_waitcnt lgkmcnt(0)
	v_fmac_f32_e32 v42, v22, v24
	v_fmac_f32_e32 v40, v22, v25
	v_fmac_f32_e32 v38, v22, v26
	v_fmac_f32_e32 v35, v22, v27
	ds_read_b128 v[24:27], v103 offset:51232
	v_fmac_f32_e32 v44, v61, v56
	v_fmac_f32_e32 v41, v61, v57
	v_fmac_f32_e32 v39, v61, v58
	v_fmac_f32_e32 v32, v61, v59
	s_waitcnt lgkmcnt(0)
	v_fmac_f32_e32 v51, v22, v24
	v_fmac_f32_e32 v50, v22, v25
	v_fmac_f32_e32 v47, v22, v26
	v_fmac_f32_e32 v45, v22, v27
	ds_read_b128 v[24:27], v103 offset:51248
	s_waitcnt lgkmcnt(0)
	v_fmac_f32_e32 v44, v22, v24
	v_fmac_f32_e32 v41, v22, v25
	v_fmac_f32_e32 v39, v22, v26
	v_fmac_f32_e32 v32, v22, v27
	ds_read_b128 v[24:27], v108
	s_waitcnt lgkmcnt(0)
	v_fmac_f32_e32 v49, v23, v24
	v_fmac_f32_e32 v48, v23, v25
	v_fmac_f32_e32 v46, v23, v26
	v_fmac_f32_e32 v43, v23, v27
	ds_read_b128 v[24:27], v109
	s_waitcnt lgkmcnt(0)
	v_fmac_f32_e32 v42, v23, v24
	v_fmac_f32_e32 v40, v23, v25
	v_fmac_f32_e32 v38, v23, v26
	v_fmac_f32_e32 v35, v23, v27
	ds_read_b128 v[24:27], v110
	s_waitcnt lgkmcnt(0)
	v_fmac_f32_e32 v51, v23, v24
	v_fmac_f32_e32 v50, v23, v25
	v_fmac_f32_e32 v47, v23, v26
	v_fmac_f32_e32 v45, v23, v27
	ds_read_b128 v[24:27], v111
	s_waitcnt lgkmcnt(0)
; #define LAS __attribute__((address_space(3)))
; __device__ __forceinline__ unsigned cvt_pk_bf16(float lo, float hi) { unsigned r; asm volatile("v_cvt_pk_bf16_f32 %0, %1, %2" : "=v"(r) : "v"(lo), "v"(hi)); return r; }
; __device__ __forceinline__ float logsigmoidf_(float x) { return fminf(x, 0.0f) - log1pf(__expf(-fabsf(x))); }
; __device__ void phase0(const Params& P, LAS unsigned char* lds, const int G, const int bid) {
;     ...
;               for (int i = 0; i < 4; ++i) { v[i] = v[i] * rstd * w4[i];
;                   u32x2 w; w.x = cvt_pk_bf16(v[i][0], v[i][1]); w.y = cvt_pk_bf16(v[i][2], v[i][3]);
;                   *(u32x2*)(abf + (size_t)row * DM + 4 * lane + 256 * i) = w;
; #pragma unroll
;                   for (int j = 0; j < 4; ++j) { const LAS float* wr_ = wg + (j * 256 + i * 64 + lane) * 20; const float a = v[i][j];
; #pragma unroll
;                       for (int q = 0; q < 4; ++q) { const f32x4 wv = *(const LAS f32x4*)(wr_ + 4 * q);
;                           ga[4 * q] += a * wv[0]; ga[4 * q + 1] += a * wv[1]; ga[4 * q + 2] += a * wv[2]; ga[4 * q + 3] += a * wv[3]; } } }
;               float r8[8], r4[4], r2[2], r1;
; #pragma unroll
;               for (int c = 0; c < 8; ++c) { const bool hi = (lane & 32) != 0; const float send = hi ? ga[c] : ga[c + 8], keep = hi ? ga[c + 8] : ga[c]; r8[c] = keep + __shfl_xor(send, 32); }
; #pragma unroll
;               for (int c = 0; c < 4; ++c) { const bool hi = (lane & 16) != 0; const float send = hi ? r8[c] : r8[c + 4], keep = hi ? r8[c + 4] : r8[c]; r4[c] = keep + __shfl_xor(send, 16); }
; #pragma unroll
;               for (int c = 0; c < 2; ++c) { const bool hi = (lane & 8) != 0; const float send = hi ? r4[c] : r4[c + 2], keep = hi ? r4[c + 2] : r4[c]; r2[c] = keep + __shfl_xor(send, 8); }
;               { const bool hi = (lane & 4) != 0; const float send = hi ? r2[0] : r2[1], keep = hi ? r2[1] : r2[0]; r1 = keep + __shfl_xor(send, 4); }
;               r1 += __shfl_xor(r1, 2); r1 += __shfl_xor(r1, 1);
;               if ((lane & 3) == 0) { float gv = r1 + gbias; if (gcol >= 8) gv = logsigmoidf_(gv); gates[(size_t)row * 16 + gcol] = gv; }
	v_fmac_f32_e32 v44, v23, v24
	v_fmac_f32_e32 v41, v23, v25
	v_fmac_f32_e32 v39, v23, v26
	v_fmac_f32_e32 v32, v23, v27
	v_pk_mul_f32 v[22:23], v[18:19], v[34:35] op_sel_hi:[1,0]
	v_pk_mul_f32 v[18:19], v[20:21], v[34:35] op_sel_hi:[1,0]
	v_pk_mul_f32 v[56:57], v[14:15], v[22:23]
	v_pk_mul_f32 v[18:19], v[16:17], v[18:19]
	v_cvt_pk_bf16_f32 v20, v56, v57
	s_nop 0
	v_cvt_pk_bf16_f32 v21, v18, v19
	global_store_dwordx2 v[36:37], v[20:21], off offset:1536
	ds_read_b128 v[20:23], v102 offset:56320
	ds_read_b128 v[24:27], v102 offset:56336
	ds_read_b128 v[28:31], v102 offset:56352
	ds_read_b128 v[52:55], v102 offset:56368
	s_waitcnt lgkmcnt(3)
	v_fmac_f32_e32 v49, v56, v20
	v_fmac_f32_e32 v48, v56, v21
	v_fmac_f32_e32 v46, v56, v22
	v_fmac_f32_e32 v43, v56, v23
	s_waitcnt lgkmcnt(2)
	v_fmac_f32_e32 v42, v56, v24
	v_fmac_f32_e32 v40, v56, v25
	v_fmac_f32_e32 v38, v56, v26
	v_fmac_f32_e32 v35, v56, v27
	s_waitcnt lgkmcnt(1)
	v_fmac_f32_e32 v51, v56, v28
	v_fmac_f32_e32 v50, v56, v29
	v_fmac_f32_e32 v47, v56, v30
	v_fmac_f32_e32 v45, v56, v31
	s_waitcnt lgkmcnt(0)
	v_fmac_f32_e32 v44, v56, v52
	v_fmac_f32_e32 v41, v56, v53
	v_fmac_f32_e32 v39, v56, v54
	v_fmac_f32_e32 v32, v56, v55
	ds_read_b128 v[20:23], v103 offset:35840
	ds_read_b128 v[24:27], v103 offset:35856
	ds_read_b128 v[28:31], v103 offset:35872
	ds_read_b128 v[52:55], v103 offset:35888
	s_waitcnt lgkmcnt(3)
	v_fmac_f32_e32 v49, v57, v20
	v_fmac_f32_e32 v48, v57, v21
	v_fmac_f32_e32 v46, v57, v22
	v_fmac_f32_e32 v43, v57, v23
	ds_read_b128 v[20:23], v103 offset:56320
	s_waitcnt lgkmcnt(3)
	v_fmac_f32_e32 v42, v57, v24
	v_fmac_f32_e32 v40, v57, v25
	v_fmac_f32_e32 v38, v57, v26
	v_fmac_f32_e32 v35, v57, v27
	s_waitcnt lgkmcnt(0)
	v_fmac_f32_e32 v49, v18, v20
	v_fmac_f32_e32 v48, v18, v21
	v_fmac_f32_e32 v46, v18, v22
	v_fmac_f32_e32 v43, v18, v23
	ds_read_b128 v[20:23], v103 offset:56336
	v_fmac_f32_e32 v51, v57, v28
	v_fmac_f32_e32 v50, v57, v29
	v_fmac_f32_e32 v47, v57, v30
	v_fmac_f32_e32 v45, v57, v31
	s_waitcnt lgkmcnt(0)
	v_fmac_f32_e32 v42, v18, v20
	v_fmac_f32_e32 v40, v18, v21
	v_fmac_f32_e32 v38, v18, v22
	v_fmac_f32_e32 v35, v18, v23
	ds_read_b128 v[20:23], v103 offset:56352
	v_fmac_f32_e32 v44, v57, v52
	v_fmac_f32_e32 v41, v57, v53
	v_fmac_f32_e32 v39, v57, v54
	v_fmac_f32_e32 v32, v57, v55
	s_waitcnt lgkmcnt(0)
	v_fmac_f32_e32 v51, v18, v20
	v_fmac_f32_e32 v50, v18, v21
	v_fmac_f32_e32 v47, v18, v22
	v_fmac_f32_e32 v45, v18, v23
	ds_read_b128 v[20:23], v103 offset:56368
	s_waitcnt lgkmcnt(0)
	v_fmac_f32_e32 v44, v18, v20
	v_fmac_f32_e32 v41, v18, v21
	v_fmac_f32_e32 v39, v18, v22
	v_fmac_f32_e32 v32, v18, v23
	ds_read_b128 v[20:23], v112
	s_waitcnt lgkmcnt(0)
	v_fmac_f32_e32 v49, v19, v20
	v_fmac_f32_e32 v48, v19, v21
	v_fmac_f32_e32 v46, v19, v22
	v_fmac_f32_e32 v43, v19, v23
	ds_read_b128 v[20:23], v113
	s_waitcnt lgkmcnt(0)
	v_fmac_f32_e32 v42, v19, v20
	v_fmac_f32_e32 v40, v19, v21
	v_fmac_f32_e32 v38, v19, v22
	v_fmac_f32_e32 v35, v19, v23
	ds_read_b128 v[20:23], v114
	s_waitcnt lgkmcnt(0)
	v_fmac_f32_e32 v51, v19, v20
	v_fmac_f32_e32 v50, v19, v21
	v_fmac_f32_e32 v47, v19, v22
	v_fmac_f32_e32 v45, v19, v23
	ds_read_b128 v[20:23], v115
	v_cndmask_b32_e32 v18, v49, v51, vcc
	ds_bpermute_b32 v18, v96, v18
	s_waitcnt lgkmcnt(1)
	v_fmac_f32_e32 v44, v19, v20
	v_fmac_f32_e32 v41, v19, v21
	v_fmac_f32_e32 v39, v19, v22
	v_fmac_f32_e32 v32, v19, v23
	v_cndmask_b32_e32 v19, v51, v49, vcc
	s_waitcnt lgkmcnt(0)
	v_add_f32_e32 v18, v19, v18
	v_cndmask_b32_e32 v19, v48, v50, vcc
	ds_bpermute_b32 v19, v96, v19
	v_cndmask_b32_e32 v20, v50, v48, vcc
	v_cndmask_b32_e32 v21, v47, v46, vcc
	v_cndmask_b32_e32 v22, v45, v43, vcc
	v_cndmask_b32_e32 v23, v44, v42, vcc
	s_waitcnt lgkmcnt(0)
	v_add_f32_e32 v19, v20, v19
	v_cndmask_b32_e32 v20, v46, v47, vcc
	ds_bpermute_b32 v20, v96, v20
	v_cndmask_b32_e32 v24, v41, v40, vcc
	v_cndmask_b32_e32 v25, v39, v38, vcc
	v_cndmask_b32_e32 v26, v32, v35, vcc
	s_waitcnt lgkmcnt(0)
	v_add_f32_e32 v20, v21, v20
	v_cndmask_b32_e32 v21, v43, v45, vcc
	ds_bpermute_b32 v21, v96, v21
	s_waitcnt lgkmcnt(0)
	v_add_f32_e32 v21, v22, v21
	v_cndmask_b32_e32 v22, v42, v44, vcc
	ds_bpermute_b32 v22, v96, v22
	s_waitcnt lgkmcnt(0)
	v_add_f32_e32 v22, v23, v22
	v_cndmask_b32_e32 v23, v40, v41, vcc
	ds_bpermute_b32 v23, v96, v23
	s_waitcnt lgkmcnt(0)
	v_add_f32_e32 v23, v24, v23
	v_cndmask_b32_e32 v24, v38, v39, vcc
	ds_bpermute_b32 v24, v96, v24
	s_waitcnt lgkmcnt(0)
	v_add_f32_e32 v24, v25, v24
	v_cndmask_b32_e32 v25, v35, v32, vcc
	ds_bpermute_b32 v25, v96, v25
	s_waitcnt lgkmcnt(0)
	v_add_f32_e32 v25, v26, v25
	v_cndmask_b32_e64 v26, v18, v22, s[42:43]
	v_cndmask_b32_e64 v18, v22, v18, s[42:43]
	ds_bpermute_b32 v22, v97, v26
	s_waitcnt lgkmcnt(0)
	v_add_f32_e32 v18, v18, v22
	v_cndmask_b32_e64 v22, v19, v23, s[42:43]
	ds_bpermute_b32 v22, v97, v22
	v_cndmask_b32_e64 v19, v23, v19, s[42:43]
	s_waitcnt lgkmcnt(0)
	v_add_f32_e32 v19, v19, v22
	v_cndmask_b32_e64 v22, v20, v24, s[42:43]
	ds_bpermute_b32 v22, v97, v22
	v_cndmask_b32_e64 v20, v24, v20, s[42:43]
	s_waitcnt lgkmcnt(0)
	v_add_f32_e32 v20, v20, v22
	v_cndmask_b32_e64 v22, v21, v25, s[42:43]
	ds_bpermute_b32 v22, v97, v22
	v_cndmask_b32_e64 v21, v25, v21, s[42:43]
	s_waitcnt lgkmcnt(0)
	v_add_f32_e32 v21, v21, v22
	v_cndmask_b32_e64 v22, v18, v20, s[44:45]
	v_cndmask_b32_e64 v18, v20, v18, s[44:45]
	ds_bpermute_b32 v20, v98, v22
	s_waitcnt lgkmcnt(0)
	v_add_f32_e32 v18, v18, v20
	v_cndmask_b32_e64 v20, v19, v21, s[44:45]
	ds_bpermute_b32 v20, v98, v20
	v_cndmask_b32_e64 v19, v21, v19, s[44:45]
	s_waitcnt lgkmcnt(0)
	v_add_f32_e32 v19, v19, v20
	v_cndmask_b32_e64 v20, v18, v19, s[46:47]
	v_cndmask_b32_e64 v18, v19, v18, s[46:47]
	ds_bpermute_b32 v19, v99, v20
	s_waitcnt lgkmcnt(0)
	v_add_f32_e32 v18, v18, v19
	ds_bpermute_b32 v19, v100, v18
	s_waitcnt lgkmcnt(0)
	v_add_f32_e32 v18, v18, v19
	ds_bpermute_b32 v19, v101, v18
	s_and_b64 exec, exec, s[48:49]
	s_cbranch_execz .LBB0_1045
; __device__ __forceinline__ float logsigmoidf_(float x) { return fminf(x, 0.0f) - log1pf(__expf(-fabsf(x))); }
; __device__ void phase0(const Params& P, LAS unsigned char* lds, const int G, const int bid) {
;     ...
;               if ((lane & 3) == 0) { float gv = r1 + gbias; if (gcol >= 8) gv = logsigmoidf_(gv); gates[(size_t)row * 16 + gcol] = gv; }
	s_waitcnt lgkmcnt(0)
	v_add_f32_e32 v18, v18, v19
	v_add_f32_e32 v18, v91, v18
	s_and_saveexec_b64 s[8:9], s[40:41]
	s_cbranch_execz .LBB0_1044
	s_mov_b32 s12, 0xbfb8aa3b
	v_mul_f32_e64 v19, |v18|, s12
	v_exp_f32_e32 v32, v19
	v_max_f32_e32 v18, v18, v18
	v_min_f32_e32 v33, 0, v18
	s_mov_b32 s12, 0x3f2aaaab
	v_add_f32_e32 v20, 1.0, v32
	v_add_f32_e32 v18, -1.0, v20
	v_sub_f32_e32 v19, v18, v20
	v_sub_f32_e32 v18, v32, v18
	v_add_f32_e32 v19, 1.0, v19
	v_add_f32_e32 v21, v18, v19
	v_frexp_mant_f32_e32 v22, v20
	v_cvt_f64_f32_e32 v[18:19], v20
	v_frexp_exp_i32_f64_e32 v18, v[18:19]
	v_cmp_gt_f32_e64 s[50:51], s12, v22
	s_mov_b32 s12, 0x3f317218
	s_nop 0
	v_subbrev_co_u32_e64 v26, s[50:51], 0, v18, s[50:51]
	v_sub_u32_e32 v18, 0, v26
	v_ldexp_f32 v19, v20, v18
	v_add_f32_e32 v20, -1.0, v19
	v_add_f32_e32 v22, 1.0, v19
	v_ldexp_f32 v18, v21, v18
	v_add_f32_e32 v21, 1.0, v20
	v_add_f32_e32 v23, -1.0, v22
	v_sub_f32_e32 v21, v19, v21
	v_sub_f32_e32 v19, v19, v23
	v_add_f32_e32 v21, v18, v21
	v_add_f32_e32 v18, v18, v19
	v_add_f32_e32 v27, v22, v18
	v_rcp_f32_e32 v29, v27
	v_sub_f32_e32 v19, v27, v22
	v_sub_f32_e32 v28, v18, v19
	v_add_f32_e32 v19, v20, v21
	v_mul_f32_e32 v31, v19, v29
	v_sub_f32_e32 v18, v19, v20
	v_mul_f32_e32 v20, v27, v31
	v_fma_f32 v22, v31, v27, -v20
	v_fmac_f32_e32 v22, v31, v28
	v_sub_f32_e32 v30, v21, v18
	v_add_f32_e32 v18, v20, v22
	v_sub_f32_e32 v21, v19, v18
	v_pk_add_f32 v[24:25], v[18:19], v[20:21] neg_lo:[0,1] neg_hi:[0,1]
	v_mov_b32_e32 v23, v18
	v_pk_add_f32 v[18:19], v[24:25], v[22:23] neg_lo:[0,1] neg_hi:[0,1]
	s_nop 0
	v_add_f32_e32 v19, v30, v19
	v_add_f32_e32 v18, v18, v19
	v_add_f32_e32 v19, v21, v18
	v_mul_f32_e32 v30, v29, v19
	v_mul_f32_e32 v20, v27, v30
	v_fma_f32 v22, v30, v27, -v20
	v_fmac_f32_e32 v22, v30, v28
	v_sub_f32_e32 v21, v21, v19
	v_add_f32_e32 v27, v18, v21
	v_add_f32_e32 v18, v20, v22
	v_sub_f32_e32 v21, v19, v18
	v_pk_add_f32 v[24:25], v[18:19], v[20:21] neg_lo:[0,1] neg_hi:[0,1]
	v_mov_b32_e32 v23, v18
	v_pk_add_f32 v[18:19], v[24:25], v[22:23] neg_lo:[0,1] neg_hi:[0,1]
	s_nop 0
	v_add_f32_e32 v19, v27, v19
	v_add_f32_e32 v18, v18, v19
	v_add_f32_e32 v19, v31, v30
	v_add_f32_e32 v18, v21, v18
	v_sub_f32_e32 v20, v19, v31
	v_mul_f32_e32 v18, v29, v18
	v_sub_f32_e32 v20, v30, v20
	v_add_f32_e32 v20, v20, v18
	v_add_f32_e32 v22, v19, v20
	v_mul_f32_e32 v23, v22, v22
	v_fmamk_f32 v18, v23, 0x3e9b6dac, v208
	v_fmaak_f32 v169, v23, v18, 0x3f2aaada
	v_cvt_f32_i32_e32 v18, v26
	v_sub_f32_e32 v19, v22, v19
	v_sub_f32_e32 v19, v20, v19
	v_ldexp_f32 v24, v19, 1
	v_mul_f32_e32 v19, v22, v23
	v_ldexp_f32 v21, v22, 1
	v_pk_mul_f32 v[22:23], v[18:19], v[168:169]
	s_nop 0
	v_fma_f32 v20, v18, s12, -v22
	v_fmac_f32_e32 v20, 0xb102e308, v18
	v_pk_add_f32 v[18:19], v[22:23], v[20:21]
	s_mov_b32 s12, 0x7f800000
	v_sub_f32_e32 v21, v19, v21
	v_sub_f32_e32 v21, v23, v21
	v_add_f32_e32 v25, v24, v21
	v_mov_b32_e32 v24, v22
	v_pk_add_f32 v[22:23], v[18:19], v[22:23] neg_lo:[0,1] neg_hi:[0,1]
	v_pk_add_f32 v[26:27], v[18:19], v[24:25]
	v_mov_b32_e32 v21, v18
	v_mov_b32_e32 v23, v27
	v_pk_add_f32 v[28:29], v[20:21], v[22:23] neg_lo:[0,1] neg_hi:[0,1]
	v_pk_add_f32 v[20:21], v[20:21], v[22:23]
	v_mov_b32_e32 v24, v25
	v_pk_add_f32 v[22:23], v[20:21], v[18:19] op_sel:[1,0] op_sel_hi:[0,1] neg_lo:[0,1] neg_hi:[0,1]
	s_nop 0
	v_pk_add_f32 v[30:31], v[26:27], v[22:23] op_sel_hi:[1,0] neg_lo:[0,1] neg_hi:[0,1]
	v_mov_b32_e32 v26, v27
	v_mov_b32_e32 v27, v21
	v_pk_mov_b32 v[22:23], v[18:19], v[22:23] op_sel:[1,0]
	v_mov_b32_e32 v25, v18
	v_pk_add_f32 v[22:23], v[26:27], v[22:23] neg_lo:[0,1] neg_hi:[0,1]
	v_mov_b32_e32 v30, v28
	v_pk_add_f32 v[18:19], v[24:25], v[22:23] neg_lo:[0,1] neg_hi:[0,1]
	v_mov_b32_e32 v29, v21
	v_pk_add_f32 v[22:23], v[30:31], v[18:19]
	v_cmp_neq_f32_e64 s[50:51], s12, v32
	v_pk_add_f32 v[24:25], v[22:23], v[22:23] op_sel:[0,1] op_sel_hi:[1,0]
	s_mov_b32 s12, 0x33800000
	v_pk_add_f32 v[20:21], v[20:21], v[24:25] op_sel:[1,0] op_sel_hi:[0,1]
	s_nop 0
	v_mov_b32_e32 v23, v20
	v_pk_add_f32 v[26:27], v[22:23], v[28:29] neg_lo:[0,1] neg_hi:[0,1]
	v_mov_b32_e32 v19, v24
	v_sub_f32_e32 v21, v22, v26
	v_pk_add_f32 v[18:19], v[18:19], v[26:27] neg_lo:[0,1] neg_hi:[0,1]
	v_sub_f32_e32 v21, v28, v21
	v_add_f32_e32 v18, v18, v21
	v_add_f32_e32 v18, v18, v19
	v_add_f32_e32 v18, v20, v18
	v_cndmask_b32_e64 v18, v212, v18, s[50:51]
	v_cmp_ngt_f32_e64 s[50:51], -1.0, v32
	s_nop 1
	v_cndmask_b32_e64 v18, v213, v18, s[50:51]
	v_cmp_neq_f32_e64 s[50:51], -1.0, v32
	s_nop 1
	v_cndmask_b32_e64 v18, v214, v18, s[50:51]
	v_cmp_lt_f32_e64 s[50:51], |v32|, s12
	s_nop 1
	v_cndmask_b32_e64 v18, v18, v32, s[50:51]
	v_sub_f32_e32 v18, v33, v18
	s_branch .LBB0_1044
